# epilogues: remaining bit-trick bf16 packs -> v_cvt_pk_bf16_f32 (placed where both sources are still intact), splat-copy v_mov pairs folded into existing (x,x) register pairs
# speedup vs baseline: 1.0605x; 1.0015x over previous
.LBB0_141:
	s_lshl_b32 s1, s2, 8
	s_lshl_b32 s0, s0, 8
	v_mov_b32_e32 v64, v208
	v_mov_b32_e32 v160, v179
	s_add_i32 s1, s1, s78
	s_or_b32 s0, s0, s79
	s_nop 0
	v_lshl_add_u32 v196, v64, 3, s0
	v_add_u32_e32 v198, s1, v160
	v_ashrrev_i32_e32 v197, 31, v196
	v_ashrrev_i32_e32 v199, 31, v198
	v_lshlrev_b64 v[64:65], 2, v[196:197]
	v_lshlrev_b64 v[160:161], 5, v[198:199]
	v_lshl_add_u64 v[66:67], s[54:55], 0, v[64:65]
	v_lshl_add_u64 v[64:65], s[58:59], 0, v[64:65]
	v_lshl_add_u64 v[164:165], s[56:57], 0, v[160:161]
	global_load_dwordx4 v[100:103], v[66:67], off offset:16
	global_load_dwordx4 v[92:95], v[66:67], off
	global_load_dwordx4 v[96:99], v[64:65], off offset:16
	global_load_dwordx4 v[88:91], v[64:65], off
	global_load_dwordx4 v[76:79], v[66:67], off offset:528
	global_load_dwordx4 v[68:71], v[66:67], off offset:512
	global_load_dwordx4 v[72:75], v[64:65], off offset:528
	s_nop 0
	global_load_dwordx4 v[64:67], v[64:65], off offset:512
	s_nop 0
	global_load_dwordx4 v[160:163], v[164:165], off offset:16
	s_nop 0
	global_load_dwordx4 v[164:167], v[164:165], off
	s_mov_b32 s0, 0x3a800000
	v_add_u32_e32 v200, 16, v198
	v_ashrrev_i32_e32 v201, 31, v200
	v_lshlrev_b64 v[206:207], 13, v[198:199]
	v_lshl_add_u64 v[206:207], s[24:25], 0, v[206:207]
	v_lshl_add_u64 v[206:207], v[196:197], 1, v[206:207]
	s_waitcnt vmcnt(0)
	v_xor_b32_e32 v103, 0x80000000, v103
	v_xor_b32_e32 v102, 0x80000000, v102
	v_pk_add_f32 v[160:161], v[160:161], v[162:163]
	v_pk_add_f32 v[164:165], v[164:165], v[166:167]
	v_xor_b32_e32 v95, 0x80000000, v95
	v_pk_add_f32 v[160:161], v[164:165], v[160:161]
	v_xor_b32_e32 v94, 0x80000000, v94
	v_pk_mul_f32 v[202:203], v[160:161], s[0:1] op_sel_hi:[1,0]
	s_mov_b32 s0, 0x800000
	v_fma_f32 v160, -v202, v202, v203
	v_max_f32_e32 v160, 0, v160
	v_add_f32_e32 v160, 0x3727c5ac, v160
	v_cmp_gt_f32_e32 vcc, s0, v160
	v_mul_f32_e32 v161, 0x4b800000, v160
	v_mov_b32_e32 v203, v202
	v_cndmask_b32_e32 v160, v160, v161, vcc
	v_rsq_f32_e32 v160, v160
	s_nop 0
	v_mul_f32_e32 v161, 0x45800000, v160
	v_cndmask_b32_e32 v204, v160, v161, vcc
	v_lshlrev_b64 v[160:161], 5, v[200:201]
	v_lshl_add_u64 v[164:165], s[56:57], 0, v[160:161]
	global_load_dwordx4 v[160:163], v[164:165], off offset:16
	s_nop 0
	global_load_dwordx4 v[164:167], v[164:165], off
	v_mov_b32_e32 v205, v204
	v_cmp_gt_i32_e32 vcc, 2.0, v196
	s_and_saveexec_b64 s[0:1], vcc
	s_cbranch_execz .LBB0_143
	v_pk_fma_f32 v[152:153], v[92:93], v[202:203], v[152:153] neg_lo:[1,0,0] neg_hi:[1,0,0]
	v_pk_fma_f32 v[152:153], v[152:153], v[204:205], v[88:89]
	v_max_f32_e32 v152, 0, v152
	v_max_f32_e32 v153, 0, v153
	v_pk_mul_f32 v[152:153], v[152:153], v[152:153]
	v_pk_fma_f32 v[154:155], v[94:95], v[202:203], v[154:155]
	v_pk_fma_f32 v[154:155], v[154:155], v[204:205], v[90:91]
	v_max_f32_e32 v154, 0, v154
	v_max_f32_e32 v155, 0, v155
	v_pk_fma_f32 v[156:157], v[100:101], v[202:203], v[156:157] neg_lo:[1,0,0] neg_hi:[1,0,0]
	v_pk_mul_f32 v[154:155], v[154:155], v[154:155]
	v_pk_fma_f32 v[156:157], v[156:157], v[204:205], v[96:97]
	v_cvt_pk_bf16_f32 v152, v152, v153
	v_cvt_pk_bf16_f32 v153, v154, v155
	v_pk_fma_f32 v[158:159], v[102:103], v[202:203], v[158:159]
	v_max_f32_e32 v156, 0, v156
	v_max_f32_e32 v157, 0, v157
	v_pk_fma_f32 v[158:159], v[158:159], v[204:205], v[98:99]
	v_pk_mul_f32 v[156:157], v[156:157], v[156:157]
	v_max_f32_e32 v158, 0, v158
	v_max_f32_e32 v159, 0, v159
	v_pk_mul_f32 v[158:159], v[158:159], v[158:159]
	v_cvt_pk_bf16_f32 v154, v156, v157
	v_cvt_pk_bf16_f32 v155, v158, v159
	global_store_dwordx4 v[206:207], v[152:155], off
.LBB0_143:
	s_or_b64 exec, exec, s[0:1]
	s_mov_b32 s0, 0x3fffff80
	v_cmp_gt_i32_e64 s[40:41], s0, v196
	v_xor_b32_e32 v153, 0x80000000, v79
	v_xor_b32_e32 v152, 0x80000000, v78
	v_xor_b32_e32 v71, 0x80000000, v71
	v_xor_b32_e32 v70, 0x80000000, v70
	s_and_saveexec_b64 s[0:1], s[40:41]
	s_cbranch_execz .LBB0_145
	v_pk_fma_f32 v[144:145], v[68:69], v[202:203], v[144:145] neg_lo:[1,0,0] neg_hi:[1,0,0]
	v_pk_fma_f32 v[144:145], v[144:145], v[204:205], v[64:65]
	v_max_f32_e32 v144, 0, v144
	v_max_f32_e32 v145, 0, v145
	v_pk_mul_f32 v[144:145], v[144:145], v[144:145]
	v_pk_fma_f32 v[150:151], v[152:153], v[202:203], v[150:151]
	v_pk_fma_f32 v[78:79], v[70:71], v[202:203], v[146:147]
	v_pk_fma_f32 v[78:79], v[78:79], v[204:205], v[66:67]
	v_max_f32_e32 v78, 0, v78
	v_max_f32_e32 v79, 0, v79
	v_pk_mul_f32 v[78:79], v[78:79], v[78:79]
	v_pk_fma_f32 v[148:149], v[76:77], v[202:203], v[148:149] neg_lo:[1,0,0] neg_hi:[1,0,0]
	v_cvt_pk_bf16_f32 v144, v144, v145
	v_pk_fma_f32 v[148:149], v[148:149], v[204:205], v[72:73]
	v_max_f32_e32 v148, 0, v148
	v_max_f32_e32 v149, 0, v149
	v_pk_mul_f32 v[148:149], v[148:149], v[148:149]
	v_pk_fma_f32 v[150:151], v[150:151], v[204:205], v[74:75]
	v_cvt_pk_bf16_f32 v145, v78, v79
	v_max_f32_e32 v150, 0, v150
	v_max_f32_e32 v151, 0, v151
	v_pk_mul_f32 v[150:151], v[150:151], v[150:151]
	v_cvt_pk_bf16_f32 v146, v148, v149
	v_cvt_pk_bf16_f32 v147, v150, v151
	global_store_dwordx4 v[206:207], v[144:147], off offset:256
.LBB0_145:
	s_or_b64 exec, exec, s[0:1]
	s_waitcnt vmcnt(2)
	v_pk_add_f32 v[78:79], v[164:165], v[166:167]
	v_pk_add_f32 v[144:145], v[160:161], v[162:163]
	s_mov_b32 s0, 0x3a800000
	v_pk_add_f32 v[78:79], v[78:79], v[144:145]
	v_lshlrev_b64 v[158:159], 13, v[200:201]
	v_pk_mul_f32 v[154:155], v[78:79], s[0:1] op_sel_hi:[1,0]
	s_mov_b32 s0, 0x800000
	v_fma_f32 v78, -v154, v154, v155
	v_max_f32_e32 v78, 0, v78
	v_add_f32_e32 v78, 0x3727c5ac, v78
	v_cmp_gt_f32_e64 s[0:1], s0, v78
	v_mul_f32_e32 v79, 0x4b800000, v78
	v_lshl_add_u64 v[158:159], s[24:25], 0, v[158:159]
	v_cndmask_b32_e64 v78, v78, v79, s[0:1]
	v_rsq_f32_e32 v78, v78
	v_lshl_add_u64 v[158:159], v[196:197], 1, v[158:159]
	v_mov_b32_e32 v155, v154
	v_mul_f32_e32 v79, 0x45800000, v78
	v_cndmask_b32_e64 v156, v78, v79, s[0:1]
	v_add_u32_e32 v78, 32, v198
	v_ashrrev_i32_e32 v79, 31, v78
	v_lshlrev_b64 v[144:145], 5, v[78:79]
	v_lshl_add_u64 v[148:149], s[56:57], 0, v[144:145]
	global_load_dwordx4 v[144:147], v[148:149], off offset:16
	s_nop 0
	global_load_dwordx4 v[148:151], v[148:149], off
	v_mov_b32_e32 v157, v156
	s_and_saveexec_b64 s[0:1], vcc
	s_cbranch_execz .LBB0_147
	v_pk_fma_f32 v[136:137], v[92:93], v[154:155], v[136:137] neg_lo:[1,0,0] neg_hi:[1,0,0]
	v_pk_fma_f32 v[136:137], v[136:137], v[156:157], v[88:89]
	v_max_f32_e32 v136, 0, v136
	v_max_f32_e32 v137, 0, v137
	v_pk_mul_f32 v[136:137], v[136:137], v[136:137]
	v_pk_fma_f32 v[142:143], v[102:103], v[154:155], v[142:143]
	v_pk_fma_f32 v[138:139], v[94:95], v[154:155], v[138:139]
	v_pk_fma_f32 v[138:139], v[138:139], v[156:157], v[90:91]
	v_max_f32_e32 v138, 0, v138
	v_max_f32_e32 v139, 0, v139
	v_pk_fma_f32 v[140:141], v[100:101], v[154:155], v[140:141] neg_lo:[1,0,0] neg_hi:[1,0,0]
	v_pk_mul_f32 v[138:139], v[138:139], v[138:139]
	v_pk_fma_f32 v[140:141], v[140:141], v[156:157], v[96:97]
	v_cvt_pk_bf16_f32 v136, v136, v137
	v_cvt_pk_bf16_f32 v137, v138, v139
	v_max_f32_e32 v140, 0, v140
	v_max_f32_e32 v141, 0, v141
	v_pk_fma_f32 v[142:143], v[142:143], v[156:157], v[98:99]
	v_pk_mul_f32 v[140:141], v[140:141], v[140:141]
	v_max_f32_e32 v142, 0, v142
	v_max_f32_e32 v143, 0, v143
	v_pk_mul_f32 v[142:143], v[142:143], v[142:143]
	v_cvt_pk_bf16_f32 v138, v140, v141
	v_cvt_pk_bf16_f32 v139, v142, v143
	global_store_dwordx4 v[158:159], v[136:139], off
.LBB0_147:
	s_or_b64 exec, exec, s[0:1]
	s_and_saveexec_b64 s[0:1], s[40:41]
	s_cbranch_execz .LBB0_149
	v_pk_fma_f32 v[128:129], v[68:69], v[154:155], v[128:129] neg_lo:[1,0,0] neg_hi:[1,0,0]
	v_pk_fma_f32 v[128:129], v[128:129], v[156:157], v[64:65]
	v_max_f32_e32 v128, 0, v128
	v_max_f32_e32 v129, 0, v129
	v_pk_mul_f32 v[128:129], v[128:129], v[128:129]
	v_pk_fma_f32 v[134:135], v[152:153], v[154:155], v[134:135]
	v_pk_fma_f32 v[130:131], v[70:71], v[154:155], v[130:131]
	v_pk_fma_f32 v[130:131], v[130:131], v[156:157], v[66:67]
	v_max_f32_e32 v130, 0, v130
	v_max_f32_e32 v131, 0, v131
	v_pk_fma_f32 v[132:133], v[76:77], v[154:155], v[132:133] neg_lo:[1,0,0] neg_hi:[1,0,0]
	v_pk_mul_f32 v[130:131], v[130:131], v[130:131]
	v_pk_fma_f32 v[132:133], v[132:133], v[156:157], v[72:73]
	v_cvt_pk_bf16_f32 v128, v128, v129
	v_cvt_pk_bf16_f32 v129, v130, v131
	v_max_f32_e32 v132, 0, v132
	v_max_f32_e32 v133, 0, v133
	v_pk_fma_f32 v[134:135], v[134:135], v[156:157], v[74:75]
	v_pk_mul_f32 v[132:133], v[132:133], v[132:133]
	v_max_f32_e32 v134, 0, v134
	v_max_f32_e32 v135, 0, v135
	v_pk_mul_f32 v[134:135], v[134:135], v[134:135]
	v_cvt_pk_bf16_f32 v130, v132, v133
	v_cvt_pk_bf16_f32 v131, v134, v135
	global_store_dwordx4 v[158:159], v[128:131], off offset:256
.LBB0_149:
	s_or_b64 exec, exec, s[0:1]
	s_waitcnt vmcnt(2)
	v_pk_add_f32 v[128:129], v[148:149], v[150:151]
	v_pk_add_f32 v[130:131], v[144:145], v[146:147]
	s_mov_b32 s0, 0x3a800000
	v_pk_add_f32 v[128:129], v[128:129], v[130:131]
	v_add_u32_e32 v136, 48, v198
	v_pk_mul_f32 v[138:139], v[128:129], s[0:1] op_sel_hi:[1,0]
	s_mov_b32 s0, 0x800000
	v_fma_f32 v128, -v138, v138, v139
	v_max_f32_e32 v128, 0, v128
	v_add_f32_e32 v128, 0x3727c5ac, v128
	v_cmp_gt_f32_e64 s[0:1], s0, v128
	v_mul_f32_e32 v129, 0x4b800000, v128
	v_ashrrev_i32_e32 v137, 31, v136
	v_cndmask_b32_e64 v128, v128, v129, s[0:1]
	v_rsq_f32_e32 v128, v128
	v_lshlrev_b64 v[78:79], 13, v[78:79]
	v_lshl_add_u64 v[78:79], s[24:25], 0, v[78:79]
	v_mul_f32_e32 v129, 0x45800000, v128
	v_cndmask_b32_e64 v140, v128, v129, s[0:1]
	v_lshlrev_b64 v[128:129], 5, v[136:137]
	v_lshl_add_u64 v[132:133], s[56:57], 0, v[128:129]
	global_load_dwordx4 v[128:131], v[132:133], off offset:16
	s_nop 0
	global_load_dwordx4 v[132:135], v[132:133], off
	v_lshl_add_u64 v[78:79], v[196:197], 1, v[78:79]
	v_mov_b32_e32 v139, v138
	v_mov_b32_e32 v141, v140
	s_and_saveexec_b64 s[0:1], vcc
	s_cbranch_execz .LBB0_151
	v_pk_fma_f32 v[120:121], v[92:93], v[138:139], v[120:121] neg_lo:[1,0,0] neg_hi:[1,0,0]
	v_pk_fma_f32 v[120:121], v[120:121], v[140:141], v[88:89]
	v_max_f32_e32 v120, 0, v120
	v_max_f32_e32 v121, 0, v121
	v_pk_mul_f32 v[120:121], v[120:121], v[120:121]
	v_pk_fma_f32 v[126:127], v[102:103], v[138:139], v[126:127]
	v_pk_fma_f32 v[122:123], v[94:95], v[138:139], v[122:123]
	v_pk_fma_f32 v[122:123], v[122:123], v[140:141], v[90:91]
	v_max_f32_e32 v122, 0, v122
	v_max_f32_e32 v123, 0, v123
	v_pk_fma_f32 v[124:125], v[100:101], v[138:139], v[124:125] neg_lo:[1,0,0] neg_hi:[1,0,0]
	v_pk_mul_f32 v[122:123], v[122:123], v[122:123]
	v_pk_fma_f32 v[124:125], v[124:125], v[140:141], v[96:97]
	v_cvt_pk_bf16_f32 v120, v120, v121
	v_cvt_pk_bf16_f32 v121, v122, v123
	v_max_f32_e32 v124, 0, v124
	v_max_f32_e32 v125, 0, v125
	v_pk_fma_f32 v[126:127], v[126:127], v[140:141], v[98:99]
	v_pk_mul_f32 v[124:125], v[124:125], v[124:125]
	v_max_f32_e32 v126, 0, v126
	v_max_f32_e32 v127, 0, v127
	v_pk_mul_f32 v[126:127], v[126:127], v[126:127]
	v_cvt_pk_bf16_f32 v122, v124, v125
	v_cvt_pk_bf16_f32 v123, v126, v127
	global_store_dwordx4 v[78:79], v[120:123], off
.LBB0_151:
	s_or_b64 exec, exec, s[0:1]
	s_and_saveexec_b64 s[0:1], s[40:41]
	s_cbranch_execz .LBB0_153
	v_pk_fma_f32 v[112:113], v[68:69], v[138:139], v[112:113] neg_lo:[1,0,0] neg_hi:[1,0,0]
	v_pk_fma_f32 v[112:113], v[112:113], v[140:141], v[64:65]
	v_max_f32_e32 v112, 0, v112
	v_max_f32_e32 v113, 0, v113
	v_pk_mul_f32 v[112:113], v[112:113], v[112:113]
	v_pk_fma_f32 v[118:119], v[152:153], v[138:139], v[118:119]
	v_pk_fma_f32 v[114:115], v[70:71], v[138:139], v[114:115]
	v_pk_fma_f32 v[114:115], v[114:115], v[140:141], v[66:67]
	v_max_f32_e32 v114, 0, v114
	v_max_f32_e32 v115, 0, v115
	v_pk_fma_f32 v[116:117], v[76:77], v[138:139], v[116:117] neg_lo:[1,0,0] neg_hi:[1,0,0]
	v_pk_mul_f32 v[114:115], v[114:115], v[114:115]
	v_pk_fma_f32 v[116:117], v[116:117], v[140:141], v[72:73]
	v_cvt_pk_bf16_f32 v112, v112, v113
	v_cvt_pk_bf16_f32 v113, v114, v115
	v_max_f32_e32 v116, 0, v116
	v_max_f32_e32 v117, 0, v117
	v_pk_fma_f32 v[118:119], v[118:119], v[140:141], v[74:75]
	v_pk_mul_f32 v[116:117], v[116:117], v[116:117]
	v_max_f32_e32 v118, 0, v118
	v_max_f32_e32 v119, 0, v119
	v_pk_mul_f32 v[118:119], v[118:119], v[118:119]
	v_cvt_pk_bf16_f32 v114, v116, v117
	v_cvt_pk_bf16_f32 v115, v118, v119
	global_store_dwordx4 v[78:79], v[112:115], off offset:256
.LBB0_153:
	s_or_b64 exec, exec, s[0:1]
	s_waitcnt vmcnt(2)
	v_pk_add_f32 v[78:79], v[132:133], v[134:135]
	v_pk_add_f32 v[112:113], v[128:129], v[130:131]
	s_mov_b32 s0, 0x3a800000
	v_pk_add_f32 v[78:79], v[78:79], v[112:113]
	v_add_u32_e32 v120, 0x80, v198
	v_pk_mul_f32 v[78:79], v[78:79], s[0:1] op_sel_hi:[1,0]
	s_mov_b32 s0, 0x800000
	v_fma_f32 v79, -v78, v78, v79
	v_max_f32_e32 v79, 0, v79
	v_add_f32_e32 v79, 0x3727c5ac, v79
	v_cmp_gt_f32_e64 s[0:1], s0, v79
	v_mul_f32_e32 v112, 0x4b800000, v79
	v_ashrrev_i32_e32 v121, 31, v120
	v_cndmask_b32_e64 v79, v79, v112, s[0:1]
	v_rsq_f32_e32 v79, v79
	v_lshlrev_b64 v[124:125], 13, v[136:137]
	v_lshl_add_u64 v[124:125], s[24:25], 0, v[124:125]
	v_mul_f32_e32 v112, 0x45800000, v79
	v_cndmask_b32_e64 v122, v79, v112, s[0:1]
	v_lshlrev_b64 v[112:113], 5, v[120:121]
	v_lshl_add_u64 v[116:117], s[56:57], 0, v[112:113]
	global_load_dwordx4 v[112:115], v[116:117], off offset:16
	s_nop 0
	global_load_dwordx4 v[116:119], v[116:117], off
	v_lshl_add_u64 v[124:125], v[196:197], 1, v[124:125]
	v_mov_b32_e32 v79, v78
	v_mov_b32_e32 v123, v122
	s_and_saveexec_b64 s[0:1], vcc
	s_cbranch_execz .LBB0_155
	v_pk_fma_f32 v[104:105], v[92:93], v[78:79], v[104:105] neg_lo:[1,0,0] neg_hi:[1,0,0]
	v_pk_fma_f32 v[104:105], v[104:105], v[122:123], v[88:89]
	v_max_f32_e32 v104, 0, v104
	v_max_f32_e32 v105, 0, v105
	v_pk_mul_f32 v[104:105], v[104:105], v[104:105]
	v_pk_fma_f32 v[110:111], v[102:103], v[78:79], v[110:111]
	v_pk_fma_f32 v[106:107], v[94:95], v[78:79], v[106:107]
	v_pk_fma_f32 v[106:107], v[106:107], v[122:123], v[90:91]
	v_max_f32_e32 v106, 0, v106
	v_max_f32_e32 v107, 0, v107
	v_pk_fma_f32 v[108:109], v[100:101], v[78:79], v[108:109] neg_lo:[1,0,0] neg_hi:[1,0,0]
	v_pk_mul_f32 v[106:107], v[106:107], v[106:107]
	v_pk_fma_f32 v[108:109], v[108:109], v[122:123], v[96:97]
	v_cvt_pk_bf16_f32 v104, v104, v105
	v_cvt_pk_bf16_f32 v105, v106, v107
	v_max_f32_e32 v108, 0, v108
	v_max_f32_e32 v109, 0, v109
	v_pk_fma_f32 v[110:111], v[110:111], v[122:123], v[98:99]
	v_pk_mul_f32 v[108:109], v[108:109], v[108:109]
	v_max_f32_e32 v110, 0, v110
	v_max_f32_e32 v111, 0, v111
	v_pk_mul_f32 v[110:111], v[110:111], v[110:111]
	v_cvt_pk_bf16_f32 v106, v108, v109
	v_cvt_pk_bf16_f32 v107, v110, v111
	global_store_dwordx4 v[124:125], v[104:107], off
.LBB0_155:
	s_or_b64 exec, exec, s[0:1]
	s_and_saveexec_b64 s[0:1], s[40:41]
	s_cbranch_execz .LBB0_157
	v_mov_b32_e32 v104, v78
	v_mov_b32_e32 v105, v78
	v_pk_fma_f32 v[84:85], v[76:77], v[78:79], v[84:85] neg_lo:[1,0,0] neg_hi:[1,0,0]
	v_pk_fma_f32 v[78:79], v[68:69], v[78:79], v[80:81] neg_lo:[1,0,0] neg_hi:[1,0,0]
	v_pk_fma_f32 v[78:79], v[78:79], v[122:123], v[64:65]
	v_max_f32_e32 v78, 0, v78
	v_max_f32_e32 v79, 0, v79
	v_pk_fma_f32 v[82:83], v[70:71], v[104:105], v[82:83]
	v_pk_mul_f32 v[78:79], v[78:79], v[78:79]
	v_pk_fma_f32 v[80:81], v[82:83], v[122:123], v[66:67]
	v_max_f32_e32 v80, 0, v80
	v_max_f32_e32 v81, 0, v81
	v_pk_mul_f32 v[80:81], v[80:81], v[80:81]
	v_pk_fma_f32 v[84:85], v[84:85], v[122:123], v[72:73]
	v_cvt_pk_bf16_f32 v78, v78, v79
	v_cvt_pk_bf16_f32 v79, v80, v81
	v_pk_fma_f32 v[86:87], v[152:153], v[104:105], v[86:87]
	v_max_f32_e32 v84, 0, v84
	v_max_f32_e32 v85, 0, v85
	v_pk_fma_f32 v[86:87], v[86:87], v[122:123], v[74:75]
	v_pk_mul_f32 v[84:85], v[84:85], v[84:85]
	v_max_f32_e32 v86, 0, v86
	v_max_f32_e32 v87, 0, v87
	v_pk_mul_f32 v[86:87], v[86:87], v[86:87]
	v_cvt_pk_bf16_f32 v80, v84, v85
	v_cvt_pk_bf16_f32 v81, v86, v87
	global_store_dwordx4 v[124:125], v[78:81], off offset:256
.LBB0_157:
	s_or_b64 exec, exec, s[0:1]
	s_waitcnt vmcnt(2)
	v_pk_add_f32 v[78:79], v[116:117], v[118:119]
	v_pk_add_f32 v[80:81], v[112:113], v[114:115]
	s_mov_b32 s0, 0x3a800000
	v_pk_add_f32 v[78:79], v[78:79], v[80:81]
	v_add_u32_e32 v86, 0x90, v198
	v_pk_mul_f32 v[104:105], v[78:79], s[0:1] op_sel_hi:[1,0]
	s_mov_b32 s0, 0x800000
	v_fma_f32 v78, -v104, v104, v105
	v_max_f32_e32 v78, 0, v78
	v_add_f32_e32 v78, 0x3727c5ac, v78
	v_cmp_gt_f32_e64 s[0:1], s0, v78
	v_mul_f32_e32 v79, 0x4b800000, v78
	v_ashrrev_i32_e32 v87, 31, v86
	v_cndmask_b32_e64 v78, v78, v79, s[0:1]
	v_rsq_f32_e32 v78, v78
	v_lshlrev_b64 v[108:109], 13, v[120:121]
	v_lshl_add_u64 v[108:109], s[24:25], 0, v[108:109]
	v_mul_f32_e32 v79, 0x45800000, v78
	v_cndmask_b32_e64 v106, v78, v79, s[0:1]
	v_lshlrev_b64 v[78:79], 5, v[86:87]
	v_lshl_add_u64 v[82:83], s[56:57], 0, v[78:79]
	global_load_dwordx4 v[78:81], v[82:83], off offset:16
	s_nop 0
	global_load_dwordx4 v[82:85], v[82:83], off
	v_lshl_add_u64 v[108:109], v[196:197], 1, v[108:109]
	v_mov_b32_e32 v105, v104
	v_mov_b32_e32 v107, v106
	s_and_saveexec_b64 s[0:1], vcc
	s_cbranch_execz .LBB0_159
	v_pk_fma_f32 v[56:57], v[92:93], v[104:105], v[56:57] neg_lo:[1,0,0] neg_hi:[1,0,0]
	v_pk_fma_f32 v[56:57], v[56:57], v[106:107], v[88:89]
	v_max_f32_e32 v56, 0, v56
	v_max_f32_e32 v57, 0, v57
	v_pk_mul_f32 v[56:57], v[56:57], v[56:57]
	v_pk_fma_f32 v[62:63], v[102:103], v[104:105], v[62:63]
	v_pk_fma_f32 v[58:59], v[94:95], v[104:105], v[58:59]
	v_pk_fma_f32 v[58:59], v[58:59], v[106:107], v[90:91]
	v_max_f32_e32 v58, 0, v58
	v_max_f32_e32 v59, 0, v59
	v_pk_fma_f32 v[60:61], v[100:101], v[104:105], v[60:61] neg_lo:[1,0,0] neg_hi:[1,0,0]
	v_pk_mul_f32 v[58:59], v[58:59], v[58:59]
	v_pk_fma_f32 v[60:61], v[60:61], v[106:107], v[96:97]
	v_cvt_pk_bf16_f32 v56, v56, v57
	v_cvt_pk_bf16_f32 v57, v58, v59
	v_max_f32_e32 v60, 0, v60
	v_max_f32_e32 v61, 0, v61
	v_pk_fma_f32 v[62:63], v[62:63], v[106:107], v[98:99]
	v_pk_mul_f32 v[60:61], v[60:61], v[60:61]
	v_max_f32_e32 v62, 0, v62
	v_max_f32_e32 v63, 0, v63
	v_pk_mul_f32 v[62:63], v[62:63], v[62:63]
	v_cvt_pk_bf16_f32 v58, v60, v61
	v_cvt_pk_bf16_f32 v59, v62, v63
	global_store_dwordx4 v[108:109], v[56:59], off
.LBB0_159:
	s_or_b64 exec, exec, s[0:1]
	s_and_saveexec_b64 s[0:1], s[40:41]
	s_cbranch_execz .LBB0_161
	v_pk_fma_f32 v[48:49], v[68:69], v[104:105], v[48:49] neg_lo:[1,0,0] neg_hi:[1,0,0]
	v_pk_fma_f32 v[48:49], v[48:49], v[106:107], v[64:65]
	v_max_f32_e32 v48, 0, v48
	v_max_f32_e32 v49, 0, v49
	v_pk_mul_f32 v[48:49], v[48:49], v[48:49]
	v_pk_fma_f32 v[54:55], v[152:153], v[104:105], v[54:55]
	v_pk_fma_f32 v[50:51], v[70:71], v[104:105], v[50:51]
	v_pk_fma_f32 v[50:51], v[50:51], v[106:107], v[66:67]
	v_max_f32_e32 v50, 0, v50
	v_max_f32_e32 v51, 0, v51
	v_pk_fma_f32 v[52:53], v[76:77], v[104:105], v[52:53] neg_lo:[1,0,0] neg_hi:[1,0,0]
	v_pk_mul_f32 v[50:51], v[50:51], v[50:51]
	v_pk_fma_f32 v[52:53], v[52:53], v[106:107], v[72:73]
	v_cvt_pk_bf16_f32 v48, v48, v49
	v_cvt_pk_bf16_f32 v49, v50, v51
	v_max_f32_e32 v52, 0, v52
	v_max_f32_e32 v53, 0, v53
	v_pk_fma_f32 v[54:55], v[54:55], v[106:107], v[74:75]
	v_pk_mul_f32 v[52:53], v[52:53], v[52:53]
	v_max_f32_e32 v54, 0, v54
	v_max_f32_e32 v55, 0, v55
	v_pk_mul_f32 v[54:55], v[54:55], v[54:55]
	v_cvt_pk_bf16_f32 v50, v52, v53
	v_cvt_pk_bf16_f32 v51, v54, v55
	global_store_dwordx4 v[108:109], v[48:51], off offset:256
.LBB0_161:
	s_or_b64 exec, exec, s[0:1]
	s_waitcnt vmcnt(2)
	v_pk_add_f32 v[48:49], v[82:83], v[84:85]
	v_pk_add_f32 v[50:51], v[78:79], v[80:81]
	s_mov_b32 s0, 0x3a800000
	v_pk_add_f32 v[48:49], v[48:49], v[50:51]
	v_add_u32_e32 v56, 0xa0, v198
	v_pk_mul_f32 v[58:59], v[48:49], s[0:1] op_sel_hi:[1,0]
	s_mov_b32 s0, 0x800000
	v_fma_f32 v48, -v58, v58, v59
	v_max_f32_e32 v48, 0, v48
	v_add_f32_e32 v48, 0x3727c5ac, v48
	v_cmp_gt_f32_e64 s[0:1], s0, v48
	v_mul_f32_e32 v49, 0x4b800000, v48
	v_ashrrev_i32_e32 v57, 31, v56
	v_cndmask_b32_e64 v48, v48, v49, s[0:1]
	v_rsq_f32_e32 v48, v48
	v_lshlrev_b64 v[62:63], 13, v[86:87]
	v_lshl_add_u64 v[62:63], s[24:25], 0, v[62:63]
	v_mul_f32_e32 v49, 0x45800000, v48
	v_cndmask_b32_e64 v60, v48, v49, s[0:1]
	v_lshlrev_b64 v[48:49], 5, v[56:57]
	v_lshl_add_u64 v[52:53], s[56:57], 0, v[48:49]
	global_load_dwordx4 v[48:51], v[52:53], off offset:16
	s_nop 0
	global_load_dwordx4 v[52:55], v[52:53], off
	v_lshl_add_u64 v[62:63], v[196:197], 1, v[62:63]
	v_mov_b32_e32 v59, v58
	v_mov_b32_e32 v61, v60
	s_and_saveexec_b64 s[0:1], vcc
	s_cbranch_execz .LBB0_163
	v_pk_fma_f32 v[40:41], v[92:93], v[58:59], v[40:41] neg_lo:[1,0,0] neg_hi:[1,0,0]
	v_pk_fma_f32 v[40:41], v[40:41], v[60:61], v[88:89]
	v_max_f32_e32 v40, 0, v40
	v_max_f32_e32 v41, 0, v41
	v_pk_mul_f32 v[40:41], v[40:41], v[40:41]
	v_pk_fma_f32 v[46:47], v[102:103], v[58:59], v[46:47]
	v_pk_fma_f32 v[42:43], v[94:95], v[58:59], v[42:43]
	v_pk_fma_f32 v[42:43], v[42:43], v[60:61], v[90:91]
	v_max_f32_e32 v42, 0, v42
	v_max_f32_e32 v43, 0, v43
	v_pk_fma_f32 v[44:45], v[100:101], v[58:59], v[44:45] neg_lo:[1,0,0] neg_hi:[1,0,0]
	v_pk_mul_f32 v[42:43], v[42:43], v[42:43]
	v_pk_fma_f32 v[44:45], v[44:45], v[60:61], v[96:97]
	v_cvt_pk_bf16_f32 v40, v40, v41
	v_cvt_pk_bf16_f32 v41, v42, v43
	v_max_f32_e32 v44, 0, v44
	v_max_f32_e32 v45, 0, v45
	v_pk_fma_f32 v[46:47], v[46:47], v[60:61], v[98:99]
	v_pk_mul_f32 v[44:45], v[44:45], v[44:45]
	v_max_f32_e32 v46, 0, v46
	v_max_f32_e32 v47, 0, v47
	v_pk_mul_f32 v[46:47], v[46:47], v[46:47]
	v_cvt_pk_bf16_f32 v42, v44, v45
	v_cvt_pk_bf16_f32 v43, v46, v47
	global_store_dwordx4 v[62:63], v[40:43], off
.LBB0_163:
	s_or_b64 exec, exec, s[0:1]
	s_and_saveexec_b64 s[0:1], s[40:41]
	s_cbranch_execz .LBB0_165
	v_pk_fma_f32 v[32:33], v[68:69], v[58:59], v[32:33] neg_lo:[1,0,0] neg_hi:[1,0,0]
	v_pk_fma_f32 v[32:33], v[32:33], v[60:61], v[64:65]
	v_max_f32_e32 v32, 0, v32
	v_max_f32_e32 v33, 0, v33
	v_pk_mul_f32 v[32:33], v[32:33], v[32:33]
	v_pk_fma_f32 v[38:39], v[152:153], v[58:59], v[38:39]
	v_pk_fma_f32 v[34:35], v[70:71], v[58:59], v[34:35]
	v_pk_fma_f32 v[34:35], v[34:35], v[60:61], v[66:67]
	v_max_f32_e32 v34, 0, v34
	v_max_f32_e32 v35, 0, v35
	v_pk_fma_f32 v[36:37], v[76:77], v[58:59], v[36:37] neg_lo:[1,0,0] neg_hi:[1,0,0]
	v_pk_mul_f32 v[34:35], v[34:35], v[34:35]
	v_pk_fma_f32 v[36:37], v[36:37], v[60:61], v[72:73]
	v_cvt_pk_bf16_f32 v32, v32, v33
	v_cvt_pk_bf16_f32 v33, v34, v35
	v_max_f32_e32 v36, 0, v36
	v_max_f32_e32 v37, 0, v37
	v_pk_fma_f32 v[38:39], v[38:39], v[60:61], v[74:75]
	v_pk_mul_f32 v[36:37], v[36:37], v[36:37]
	v_max_f32_e32 v38, 0, v38
	v_max_f32_e32 v39, 0, v39
	v_pk_mul_f32 v[38:39], v[38:39], v[38:39]
	v_cvt_pk_bf16_f32 v34, v36, v37
	v_cvt_pk_bf16_f32 v35, v38, v39
	global_store_dwordx4 v[62:63], v[32:35], off offset:256
.LBB0_165:
	s_or_b64 exec, exec, s[0:1]
	s_waitcnt vmcnt(2)
	v_pk_add_f32 v[32:33], v[52:53], v[54:55]
	v_pk_add_f32 v[34:35], v[48:49], v[50:51]
	s_mov_b32 s0, 0x3a800000
	v_pk_add_f32 v[32:33], v[32:33], v[34:35]
	v_add_u32_e32 v40, 0xb0, v198
	v_pk_mul_f32 v[42:43], v[32:33], s[0:1] op_sel_hi:[1,0]
	s_mov_b32 s0, 0x800000
	v_fma_f32 v32, -v42, v42, v43
	v_max_f32_e32 v32, 0, v32
	v_add_f32_e32 v32, 0x3727c5ac, v32
	v_cmp_gt_f32_e64 s[0:1], s0, v32
	v_mul_f32_e32 v33, 0x4b800000, v32
	v_ashrrev_i32_e32 v41, 31, v40
	v_cndmask_b32_e64 v32, v32, v33, s[0:1]
	v_rsq_f32_e32 v32, v32
	v_lshlrev_b64 v[46:47], 13, v[56:57]
	v_lshl_add_u64 v[46:47], s[24:25], 0, v[46:47]
	v_mul_f32_e32 v33, 0x45800000, v32
	v_cndmask_b32_e64 v44, v32, v33, s[0:1]
	v_lshlrev_b64 v[32:33], 5, v[40:41]
	v_lshl_add_u64 v[32:33], s[56:57], 0, v[32:33]
	global_load_dwordx4 v[36:39], v[32:33], off offset:16
	s_nop 0
	global_load_dwordx4 v[32:35], v[32:33], off
	v_lshl_add_u64 v[46:47], v[196:197], 1, v[46:47]
	v_mov_b32_e32 v43, v42
	v_mov_b32_e32 v45, v44
	s_and_saveexec_b64 s[0:1], vcc
	s_cbranch_execz .LBB0_167
	v_pk_fma_f32 v[24:25], v[92:93], v[42:43], v[24:25] neg_lo:[1,0,0] neg_hi:[1,0,0]
	v_mov_b32_e32 v48, v42
	v_pk_fma_f32 v[24:25], v[24:25], v[44:45], v[88:89]
	v_mov_b32_e32 v49, v42
	v_max_f32_e32 v24, 0, v24
	v_max_f32_e32 v25, 0, v25
	v_pk_mul_f32 v[24:25], v[24:25], v[24:25]
	v_pk_fma_f32 v[30:31], v[102:103], v[42:43], v[30:31]
	v_mov_b32_e32 v50, v44
	v_mov_b32_e32 v51, v44
	v_pk_fma_f32 v[26:27], v[94:95], v[42:43], v[26:27]
	v_pk_fma_f32 v[26:27], v[26:27], v[44:45], v[90:91]
	v_max_f32_e32 v26, 0, v26
	v_max_f32_e32 v27, 0, v27
	v_pk_fma_f32 v[28:29], v[100:101], v[42:43], v[28:29] neg_lo:[1,0,0] neg_hi:[1,0,0]
	v_pk_mul_f32 v[26:27], v[26:27], v[26:27]
	v_pk_fma_f32 v[28:29], v[28:29], v[44:45], v[96:97]
	v_cvt_pk_bf16_f32 v24, v24, v25
	v_cvt_pk_bf16_f32 v25, v26, v27
	v_max_f32_e32 v28, 0, v28
	v_max_f32_e32 v29, 0, v29
	v_pk_fma_f32 v[30:31], v[30:31], v[44:45], v[98:99]
	v_pk_mul_f32 v[28:29], v[28:29], v[28:29]
	v_max_f32_e32 v30, 0, v30
	v_max_f32_e32 v31, 0, v31
	v_pk_mul_f32 v[30:31], v[30:31], v[30:31]
	v_cvt_pk_bf16_f32 v26, v28, v29
	v_cvt_pk_bf16_f32 v27, v30, v31
	global_store_dwordx4 v[46:47], v[24:27], off
.LBB0_167:
	s_or_b64 exec, exec, s[0:1]
	s_and_saveexec_b64 s[0:1], s[40:41]
	s_cbranch_execz .LBB0_169
	v_pk_fma_f32 v[16:17], v[68:69], v[42:43], v[16:17] neg_lo:[1,0,0] neg_hi:[1,0,0]
	v_pk_fma_f32 v[16:17], v[16:17], v[44:45], v[64:65]
	v_max_f32_e32 v16, 0, v16
	v_max_f32_e32 v17, 0, v17
	v_pk_mul_f32 v[16:17], v[16:17], v[16:17]
	v_pk_fma_f32 v[22:23], v[152:153], v[42:43], v[22:23]
	v_pk_fma_f32 v[18:19], v[70:71], v[42:43], v[18:19]
	v_pk_fma_f32 v[18:19], v[18:19], v[44:45], v[66:67]
	v_max_f32_e32 v18, 0, v18
	v_max_f32_e32 v19, 0, v19
	v_pk_fma_f32 v[20:21], v[76:77], v[42:43], v[20:21] neg_lo:[1,0,0] neg_hi:[1,0,0]
	v_pk_mul_f32 v[18:19], v[18:19], v[18:19]
	v_pk_fma_f32 v[20:21], v[20:21], v[44:45], v[72:73]
	v_cvt_pk_bf16_f32 v16, v16, v17
	v_cvt_pk_bf16_f32 v17, v18, v19
	v_max_f32_e32 v20, 0, v20
	v_max_f32_e32 v21, 0, v21
	v_pk_fma_f32 v[22:23], v[22:23], v[44:45], v[74:75]
	v_pk_mul_f32 v[20:21], v[20:21], v[20:21]
	v_max_f32_e32 v22, 0, v22
	v_max_f32_e32 v23, 0, v23
	v_pk_mul_f32 v[22:23], v[22:23], v[22:23]
	v_cvt_pk_bf16_f32 v18, v20, v21
	v_cvt_pk_bf16_f32 v19, v22, v23
	global_store_dwordx4 v[46:47], v[16:19], off offset:256
.LBB0_169:
	s_or_b64 exec, exec, s[0:1]
	s_waitcnt vmcnt(2)
	v_pk_add_f32 v[16:17], v[36:37], v[38:39]
	v_pk_add_f32 v[18:19], v[32:33], v[34:35]
	s_mov_b32 s0, 0x3a800000
	v_pk_add_f32 v[16:17], v[18:19], v[16:17]
	s_nop 0
	v_pk_mul_f32 v[18:19], v[16:17], s[0:1] op_sel_hi:[1,0]
	s_mov_b32 s0, 0x800000
	v_fma_f32 v16, -v18, v18, v19
	v_max_f32_e32 v16, 0, v16
	v_add_f32_e32 v16, 0x3727c5ac, v16
	v_mul_f32_e32 v17, 0x4b800000, v16
	v_cmp_gt_f32_e64 s[0:1], s0, v16
	v_mov_b32_e32 v19, v18
	s_nop 0
	v_cndmask_b32_e64 v16, v16, v17, s[0:1]
	v_rsq_f32_e32 v16, v16
	s_nop 0
	v_mul_f32_e32 v17, 0x45800000, v16
	v_cndmask_b32_e64 v20, v16, v17, s[0:1]
	v_lshlrev_b64 v[16:17], 13, v[40:41]
	v_lshl_add_u64 v[16:17], s[24:25], 0, v[16:17]
	v_lshl_add_u64 v[16:17], v[196:197], 1, v[16:17]
	v_mov_b32_e32 v21, v20
	s_and_saveexec_b64 s[0:1], vcc
	s_cbranch_execz .LBB0_171
	v_pk_fma_f32 v[8:9], v[92:93], v[18:19], v[8:9] neg_lo:[1,0,0] neg_hi:[1,0,0]
	v_pk_fma_f32 v[8:9], v[8:9], v[20:21], v[88:89]
	v_max_f32_e32 v8, 0, v8
	v_max_f32_e32 v9, 0, v9
	v_pk_mul_f32 v[8:9], v[8:9], v[8:9]
	v_pk_fma_f32 v[14:15], v[102:103], v[18:19], v[14:15]
	v_pk_fma_f32 v[10:11], v[94:95], v[18:19], v[10:11]
	v_pk_fma_f32 v[10:11], v[10:11], v[20:21], v[90:91]
	v_max_f32_e32 v10, 0, v10
	v_max_f32_e32 v11, 0, v11
	v_pk_fma_f32 v[12:13], v[100:101], v[18:19], v[12:13] neg_lo:[1,0,0] neg_hi:[1,0,0]
	v_pk_mul_f32 v[10:11], v[10:11], v[10:11]
	v_pk_fma_f32 v[12:13], v[12:13], v[20:21], v[96:97]
	v_cvt_pk_bf16_f32 v8, v8, v9
	v_cvt_pk_bf16_f32 v9, v10, v11
	v_max_f32_e32 v12, 0, v12
	v_max_f32_e32 v13, 0, v13
	v_pk_fma_f32 v[14:15], v[14:15], v[20:21], v[98:99]
	v_pk_mul_f32 v[12:13], v[12:13], v[12:13]
	v_max_f32_e32 v14, 0, v14
	v_max_f32_e32 v15, 0, v15
	v_pk_mul_f32 v[14:15], v[14:15], v[14:15]
	v_cvt_pk_bf16_f32 v10, v12, v13
	v_cvt_pk_bf16_f32 v11, v14, v15
	global_store_dwordx4 v[16:17], v[8:11], off
.LBB0_171:
	s_or_b64 exec, exec, s[0:1]
	s_and_saveexec_b64 s[0:1], s[40:41]
	s_cbranch_execz .LBB0_173
	v_pk_fma_f32 v[0:1], v[68:69], v[18:19], v[0:1] neg_lo:[1,0,0] neg_hi:[1,0,0]
	v_pk_fma_f32 v[0:1], v[0:1], v[20:21], v[64:65]
	v_max_f32_e32 v0, 0, v0
	v_max_f32_e32 v1, 0, v1
	v_pk_mul_f32 v[0:1], v[0:1], v[0:1]
	v_pk_fma_f32 v[6:7], v[152:153], v[18:19], v[6:7]
	v_pk_fma_f32 v[2:3], v[70:71], v[18:19], v[2:3]
	v_pk_fma_f32 v[2:3], v[2:3], v[20:21], v[66:67]
	v_max_f32_e32 v2, 0, v2
	v_max_f32_e32 v3, 0, v3
	v_pk_fma_f32 v[4:5], v[76:77], v[18:19], v[4:5] neg_lo:[1,0,0] neg_hi:[1,0,0]
	v_pk_mul_f32 v[2:3], v[2:3], v[2:3]
	v_pk_fma_f32 v[4:5], v[4:5], v[20:21], v[72:73]
	v_cvt_pk_bf16_f32 v0, v0, v1
	v_cvt_pk_bf16_f32 v1, v2, v3
	v_max_f32_e32 v4, 0, v4
	v_max_f32_e32 v5, 0, v5
	v_pk_fma_f32 v[6:7], v[6:7], v[20:21], v[74:75]
	v_pk_mul_f32 v[4:5], v[4:5], v[4:5]
	v_max_f32_e32 v6, 0, v6
	v_max_f32_e32 v7, 0, v7
	v_pk_mul_f32 v[6:7], v[6:7], v[6:7]
	v_cvt_pk_bf16_f32 v2, v4, v5
	v_cvt_pk_bf16_f32 v3, v6, v7
	global_store_dwordx4 v[16:17], v[0:3], off offset:256

.LBB0_352:
	s_or_b64 exec, exec, s[2:3]
	s_waitcnt lgkmcnt(0)
	v_add_u32_e32 v3, s70, v146
	v_lshl_add_u32 v2, v3, 4, 0
	s_waitcnt lgkmcnt(0)
	s_barrier
	v_add_u32_e32 v10, 0x21000, v2
	ds_read_b128 v[148:151], v10
	s_ashr_i32 s67, s66, 31
	s_lshl_b64 s[2:3], s[66:67], 24
	s_add_u32 s20, s63, s2
	s_addc_u32 s21, s68, s3
	s_ashr_i32 s65, s64, 31
	v_lshl_add_u32 v2, v147, 3, s71
	s_waitcnt lgkmcnt(0)
	v_mov_b32_e32 v146, v149
	v_mov_b32_e32 v147, v150
	v_mov_b32_e32 v149, v151
	s_lshl_b64 s[2:3], s[64:65], 9
	v_pk_add_f32 v[146:147], v[146:147], v[148:149]
	s_add_u32 s2, s20, s2
	v_add_f32_e32 v11, v146, v147
	s_addc_u32 s3, s21, s3
	v_div_scale_f32 v147, s[20:21], v11, v11, 1.0
	v_rcp_f32_e32 v148, v147
	v_lshl_add_u32 v146, s62, 8, v3
	v_ashrrev_i32_e32 v3, 31, v2
	v_lshl_add_u64 v[2:3], v[2:3], 1, s[2:3]
	v_fma_f32 v149, -v147, v148, 1.0
	v_fmac_f32_e32 v148, v149, v148
	v_div_scale_f32 v149, vcc, 1.0, v11, 1.0
	v_mul_f32_e32 v150, v149, v148
	v_fma_f32 v151, -v147, v150, v149
	v_fmac_f32_e32 v150, v151, v148
	v_fma_f32 v147, -v147, v150, v149
	v_div_fmas_f32 v147, v147, v148, v150
	v_div_fixup_f32 v148, v147, v11, 1.0
	v_ashrrev_i32_e32 v147, 31, v146
	v_lshlrev_b64 v[146:147], 11, v[146:147]
	v_pk_mul_f32 v[124:125], v[124:125], v[148:149] op_sel_hi:[1,0]
	v_pk_mul_f32 v[126:127], v[126:127], v[148:149] op_sel_hi:[1,0]
	v_lshl_add_u64 v[2:3], v[2:3], 0, v[146:147]
	v_pk_mul_f32 v[138:139], v[138:139], v[148:149] op_sel_hi:[1,0]
	v_pk_mul_f32 v[140:141], v[140:141], v[148:149] op_sel_hi:[1,0]
	v_bfe_u32 v11, v127, 16, 1
	v_add3_u32 v11, v127, v11, s96
	v_bfe_u32 v149, v141, 16, 1
	v_add3_u32 v141, v141, v149, s96
	v_lshrrev_b32_e32 v127, 16, v141
	v_and_or_b32 v127, v11, s97, v127
	v_cvt_pk_bf16_f32 v126, v140, v126
	v_cvt_pk_bf16_f32 v125, v139, v125
	v_cvt_pk_bf16_f32 v124, v138, v124
	v_pk_mul_f32 v[116:117], v[116:117], v[148:149] op_sel_hi:[1,0]
	v_pk_mul_f32 v[118:119], v[118:119], v[148:149] op_sel_hi:[1,0]
	global_store_dwordx4 v[2:3], v[124:127], off
	v_pk_mul_f32 v[120:121], v[120:121], v[148:149] op_sel_hi:[1,0]
	v_pk_mul_f32 v[122:123], v[122:123], v[148:149] op_sel_hi:[1,0]
	v_bfe_u32 v11, v119, 16, 1
	v_add3_u32 v11, v119, v11, s96
	v_bfe_u32 v126, v123, 16, 1
	v_add3_u32 v123, v123, v126, s96
	v_lshrrev_b32_e32 v119, 16, v123
	v_and_or_b32 v119, v11, s97, v119
	v_cvt_pk_bf16_f32 v118, v122, v118
	v_cvt_pk_bf16_f32 v117, v121, v117
	v_cvt_pk_bf16_f32 v116, v120, v116
	global_store_dwordx4 v[2:3], v[116:119], off offset:256
	ds_read_b128 v[116:119], v10 offset:256
	s_waitcnt lgkmcnt(0)
	v_mov_b32_e32 v120, v117
	v_mov_b32_e32 v121, v118
	v_mov_b32_e32 v117, v119
	v_pk_add_f32 v[116:117], v[120:121], v[116:117]
	s_nop 0
	v_add_f32_e32 v11, v116, v117
	v_div_scale_f32 v116, s[2:3], v11, v11, 1.0
	v_rcp_f32_e32 v117, v116
	s_mov_b64 s[2:3], 0x8000
	v_fma_f32 v118, -v116, v117, 1.0
	v_fmac_f32_e32 v117, v118, v117
	v_div_scale_f32 v118, vcc, 1.0, v11, 1.0
	v_mul_f32_e32 v119, v118, v117
	v_fma_f32 v120, -v116, v119, v118
	v_fmac_f32_e32 v119, v120, v117
	v_fma_f32 v116, -v116, v119, v118
	v_div_fmas_f32 v116, v116, v117, v119
	v_div_fixup_f32 v116, v116, v11, 1.0
	v_pk_mul_f32 v[110:111], v[110:111], v[116:117] op_sel_hi:[1,0]
	v_pk_mul_f32 v[112:113], v[112:113], v[116:117] op_sel_hi:[1,0]
	v_pk_mul_f32 v[108:109], v[108:109], v[116:117] op_sel_hi:[1,0]
	v_pk_mul_f32 v[114:115], v[114:115], v[116:117] op_sel_hi:[1,0]
	v_bfe_u32 v120, v109, 16, 1
	v_add3_u32 v109, v109, v120, s96
	v_bfe_u32 v117, v113, 16, 1
	v_lshl_add_u64 v[118:119], v[2:3], 0, s[2:3]
	v_add3_u32 v113, v113, v117, s96
	s_mov_b32 s2, 0x8000
	v_lshrrev_b32_e32 v113, 16, v113
	v_cvt_pk_bf16_f32 v108, v112, v108
	v_add_co_u32_e32 v112, vcc, s2, v2
	v_cvt_pk_bf16_f32 v111, v115, v111
	v_cvt_pk_bf16_f32 v110, v114, v110
	v_and_or_b32 v109, v109, s97, v113
	v_addc_co_u32_e32 v113, vcc, 0, v3, vcc
	v_pk_mul_f32 v[100:101], v[100:101], v[116:117] op_sel_hi:[1,0]
	v_pk_mul_f32 v[102:103], v[102:103], v[116:117] op_sel_hi:[1,0]
	global_store_dwordx4 v[112:113], v[108:111], off
	v_pk_mul_f32 v[104:105], v[104:105], v[116:117] op_sel_hi:[1,0]
	v_pk_mul_f32 v[106:107], v[106:107], v[116:117] op_sel_hi:[1,0]
	v_bfe_u32 v11, v103, 16, 1
	v_add3_u32 v11, v103, v11, s96
	v_bfe_u32 v110, v107, 16, 1
	v_add3_u32 v107, v107, v110, s96
	v_lshrrev_b32_e32 v103, 16, v107
	v_and_or_b32 v103, v11, s97, v103
	v_cvt_pk_bf16_f32 v102, v106, v102
	v_cvt_pk_bf16_f32 v101, v105, v101
	v_cvt_pk_bf16_f32 v100, v104, v100
	global_store_dwordx4 v[118:119], v[100:103], off offset:256
	ds_read_b128 v[100:103], v10 offset:512
	s_waitcnt lgkmcnt(0)
	v_mov_b32_e32 v104, v101
	v_mov_b32_e32 v105, v102
	v_mov_b32_e32 v101, v103
	v_pk_add_f32 v[100:101], v[104:105], v[100:101]
	s_nop 0
	v_add_f32_e32 v11, v100, v101
	v_div_scale_f32 v100, s[2:3], v11, v11, 1.0
	v_rcp_f32_e32 v101, v100
	s_mov_b64 s[2:3], 0x10000
	v_fma_f32 v102, -v100, v101, 1.0
	v_fmac_f32_e32 v101, v102, v101
	v_div_scale_f32 v102, vcc, 1.0, v11, 1.0
	v_mul_f32_e32 v103, v102, v101
	v_fma_f32 v104, -v100, v103, v102
	v_fmac_f32_e32 v103, v104, v101
	v_fma_f32 v100, -v100, v103, v102
	v_div_fmas_f32 v100, v100, v101, v103
	v_div_fixup_f32 v100, v100, v11, 1.0
	v_pk_mul_f32 v[94:95], v[94:95], v[100:101] op_sel_hi:[1,0]
	v_pk_mul_f32 v[96:97], v[96:97], v[100:101] op_sel_hi:[1,0]
	v_pk_mul_f32 v[92:93], v[92:93], v[100:101] op_sel_hi:[1,0]
	v_pk_mul_f32 v[98:99], v[98:99], v[100:101] op_sel_hi:[1,0]
	v_bfe_u32 v104, v93, 16, 1
	v_add3_u32 v93, v93, v104, s96
	v_bfe_u32 v101, v97, 16, 1
	v_lshl_add_u64 v[102:103], v[2:3], 0, s[2:3]
	v_add3_u32 v97, v97, v101, s96
	s_mov_b32 s2, 0x10000
	v_lshrrev_b32_e32 v97, 16, v97
	v_cvt_pk_bf16_f32 v92, v96, v92
	v_add_co_u32_e32 v96, vcc, s2, v2
	v_cvt_pk_bf16_f32 v95, v99, v95
	v_cvt_pk_bf16_f32 v94, v98, v94
	v_and_or_b32 v93, v93, s97, v97
	v_addc_co_u32_e32 v97, vcc, 0, v3, vcc
	v_pk_mul_f32 v[84:85], v[84:85], v[100:101] op_sel_hi:[1,0]
	v_pk_mul_f32 v[86:87], v[86:87], v[100:101] op_sel_hi:[1,0]
	global_store_dwordx4 v[96:97], v[92:95], off
	v_pk_mul_f32 v[88:89], v[88:89], v[100:101] op_sel_hi:[1,0]
	v_pk_mul_f32 v[90:91], v[90:91], v[100:101] op_sel_hi:[1,0]
	v_bfe_u32 v11, v87, 16, 1
	v_add3_u32 v11, v87, v11, s96
	v_bfe_u32 v94, v91, 16, 1
	v_add3_u32 v91, v91, v94, s96
	v_lshrrev_b32_e32 v87, 16, v91
	v_and_or_b32 v87, v11, s97, v87
	v_cvt_pk_bf16_f32 v86, v90, v86
	v_cvt_pk_bf16_f32 v85, v89, v85
	v_cvt_pk_bf16_f32 v84, v88, v84
	global_store_dwordx4 v[102:103], v[84:87], off offset:256
	ds_read_b128 v[84:87], v10 offset:768
	s_waitcnt lgkmcnt(0)
	v_mov_b32_e32 v88, v85
	v_mov_b32_e32 v89, v86
	v_mov_b32_e32 v85, v87
	v_pk_add_f32 v[84:85], v[88:89], v[84:85]
	s_nop 0
	v_add_f32_e32 v11, v84, v85
	v_div_scale_f32 v84, s[2:3], v11, v11, 1.0
	v_rcp_f32_e32 v85, v84
	s_mov_b64 s[2:3], 0x18000
	v_fma_f32 v86, -v84, v85, 1.0
	v_fmac_f32_e32 v85, v86, v85
	v_div_scale_f32 v86, vcc, 1.0, v11, 1.0
	v_mul_f32_e32 v87, v86, v85
	v_fma_f32 v88, -v84, v87, v86
	v_fmac_f32_e32 v87, v88, v85
	v_fma_f32 v84, -v84, v87, v86
	v_div_fmas_f32 v84, v84, v85, v87
	v_div_fixup_f32 v84, v84, v11, 1.0
	v_pk_mul_f32 v[78:79], v[78:79], v[84:85] op_sel_hi:[1,0]
	v_pk_mul_f32 v[80:81], v[80:81], v[84:85] op_sel_hi:[1,0]
	v_pk_mul_f32 v[76:77], v[76:77], v[84:85] op_sel_hi:[1,0]
	v_pk_mul_f32 v[82:83], v[82:83], v[84:85] op_sel_hi:[1,0]
	v_bfe_u32 v88, v77, 16, 1
	v_add3_u32 v77, v77, v88, s96
	v_bfe_u32 v85, v81, 16, 1
	v_lshl_add_u64 v[86:87], v[2:3], 0, s[2:3]
	v_add3_u32 v81, v81, v85, s96
	s_mov_b32 s2, 0x18000
	v_lshrrev_b32_e32 v81, 16, v81
	v_cvt_pk_bf16_f32 v76, v80, v76
	v_add_co_u32_e32 v80, vcc, s2, v2
	v_cvt_pk_bf16_f32 v79, v83, v79
	v_cvt_pk_bf16_f32 v78, v82, v78
	v_and_or_b32 v77, v77, s97, v81
	v_addc_co_u32_e32 v81, vcc, 0, v3, vcc
	v_pk_mul_f32 v[68:69], v[68:69], v[84:85] op_sel_hi:[1,0]
	v_pk_mul_f32 v[70:71], v[70:71], v[84:85] op_sel_hi:[1,0]
	global_store_dwordx4 v[80:81], v[76:79], off
	v_pk_mul_f32 v[72:73], v[72:73], v[84:85] op_sel_hi:[1,0]
	v_pk_mul_f32 v[74:75], v[74:75], v[84:85] op_sel_hi:[1,0]
	v_bfe_u32 v11, v71, 16, 1
	v_add3_u32 v11, v71, v11, s96
	v_bfe_u32 v78, v75, 16, 1
	v_add3_u32 v75, v75, v78, s96
	v_lshrrev_b32_e32 v71, 16, v75
	v_and_or_b32 v71, v11, s97, v71
	v_cvt_pk_bf16_f32 v70, v74, v70
	v_cvt_pk_bf16_f32 v69, v73, v69
	v_cvt_pk_bf16_f32 v68, v72, v68
	global_store_dwordx4 v[86:87], v[68:71], off offset:256
	ds_read_b128 v[68:71], v10 offset:2048
	s_waitcnt lgkmcnt(0)
	v_mov_b32_e32 v72, v69
	v_mov_b32_e32 v73, v70
	v_mov_b32_e32 v69, v71
	v_pk_add_f32 v[68:69], v[72:73], v[68:69]
	s_nop 0
	v_add_f32_e32 v11, v68, v69
	v_div_scale_f32 v68, s[2:3], v11, v11, 1.0
	v_rcp_f32_e32 v69, v68
	s_mov_b64 s[2:3], 0x40000
	v_fma_f32 v70, -v68, v69, 1.0
	v_fmac_f32_e32 v69, v70, v69
	v_div_scale_f32 v70, vcc, 1.0, v11, 1.0
	v_mul_f32_e32 v71, v70, v69
	v_fma_f32 v72, -v68, v71, v70
	v_fmac_f32_e32 v71, v72, v69
	v_fma_f32 v68, -v68, v71, v70
	v_div_fmas_f32 v68, v68, v69, v71
	v_div_fixup_f32 v68, v68, v11, 1.0
	v_pk_mul_f32 v[62:63], v[62:63], v[68:69] op_sel_hi:[1,0]
	v_pk_mul_f32 v[64:65], v[64:65], v[68:69] op_sel_hi:[1,0]
	v_pk_mul_f32 v[60:61], v[60:61], v[68:69] op_sel_hi:[1,0]
	v_pk_mul_f32 v[66:67], v[66:67], v[68:69] op_sel_hi:[1,0]
	v_bfe_u32 v72, v61, 16, 1
	v_add3_u32 v61, v61, v72, s96
	v_bfe_u32 v69, v65, 16, 1
	v_lshl_add_u64 v[70:71], v[2:3], 0, s[2:3]
	v_add3_u32 v65, v65, v69, s96
	s_mov_b32 s2, 0x40000
	v_lshrrev_b32_e32 v65, 16, v65
	v_cvt_pk_bf16_f32 v60, v64, v60
	v_add_co_u32_e32 v64, vcc, s2, v2
	v_cvt_pk_bf16_f32 v63, v67, v63
	v_cvt_pk_bf16_f32 v62, v66, v62
	v_and_or_b32 v61, v61, s97, v65
	v_addc_co_u32_e32 v65, vcc, 0, v3, vcc
	v_pk_mul_f32 v[52:53], v[52:53], v[68:69] op_sel_hi:[1,0]
	v_pk_mul_f32 v[54:55], v[54:55], v[68:69] op_sel_hi:[1,0]
	global_store_dwordx4 v[64:65], v[60:63], off
	v_pk_mul_f32 v[56:57], v[56:57], v[68:69] op_sel_hi:[1,0]
	v_pk_mul_f32 v[58:59], v[58:59], v[68:69] op_sel_hi:[1,0]
	v_bfe_u32 v11, v55, 16, 1
	v_add3_u32 v11, v55, v11, s96
	v_bfe_u32 v62, v59, 16, 1
	v_add3_u32 v59, v59, v62, s96
	v_lshrrev_b32_e32 v55, 16, v59
	v_and_or_b32 v55, v11, s97, v55
	v_cvt_pk_bf16_f32 v54, v58, v54
	v_cvt_pk_bf16_f32 v53, v57, v53
	v_cvt_pk_bf16_f32 v52, v56, v52
	global_store_dwordx4 v[70:71], v[52:55], off offset:256
	ds_read_b128 v[52:55], v10 offset:2304
	s_waitcnt lgkmcnt(0)
	v_mov_b32_e32 v56, v53
	v_mov_b32_e32 v57, v54
	v_mov_b32_e32 v53, v55
	v_pk_add_f32 v[52:53], v[56:57], v[52:53]
	s_nop 0
	v_add_f32_e32 v11, v52, v53
	v_div_scale_f32 v52, s[2:3], v11, v11, 1.0
	v_rcp_f32_e32 v53, v52
	s_mov_b64 s[2:3], 0x48000
	v_fma_f32 v54, -v52, v53, 1.0
	v_fmac_f32_e32 v53, v54, v53
	v_div_scale_f32 v54, vcc, 1.0, v11, 1.0
	v_mul_f32_e32 v55, v54, v53
	v_fma_f32 v56, -v52, v55, v54
	v_fmac_f32_e32 v55, v56, v53
	v_fma_f32 v52, -v52, v55, v54
	v_div_fmas_f32 v52, v52, v53, v55
	v_div_fixup_f32 v52, v52, v11, 1.0
	v_pk_mul_f32 v[46:47], v[46:47], v[52:53] op_sel_hi:[1,0]
	v_pk_mul_f32 v[48:49], v[48:49], v[52:53] op_sel_hi:[1,0]
	v_pk_mul_f32 v[44:45], v[44:45], v[52:53] op_sel_hi:[1,0]
	v_pk_mul_f32 v[50:51], v[50:51], v[52:53] op_sel_hi:[1,0]
	v_bfe_u32 v56, v45, 16, 1
	v_add3_u32 v45, v45, v56, s96
	v_bfe_u32 v53, v49, 16, 1
	v_lshl_add_u64 v[54:55], v[2:3], 0, s[2:3]
	v_add3_u32 v49, v49, v53, s96
	s_mov_b32 s2, 0x48000
	v_lshrrev_b32_e32 v49, 16, v49
	v_cvt_pk_bf16_f32 v44, v48, v44
	v_add_co_u32_e32 v48, vcc, s2, v2
	v_cvt_pk_bf16_f32 v47, v51, v47
	v_cvt_pk_bf16_f32 v46, v50, v46
	v_and_or_b32 v45, v45, s97, v49
	v_addc_co_u32_e32 v49, vcc, 0, v3, vcc
	v_pk_mul_f32 v[36:37], v[36:37], v[52:53] op_sel_hi:[1,0]
	v_pk_mul_f32 v[38:39], v[38:39], v[52:53] op_sel_hi:[1,0]
	global_store_dwordx4 v[48:49], v[44:47], off
	v_pk_mul_f32 v[40:41], v[40:41], v[52:53] op_sel_hi:[1,0]
	v_pk_mul_f32 v[42:43], v[42:43], v[52:53] op_sel_hi:[1,0]
	v_bfe_u32 v11, v39, 16, 1
	v_add3_u32 v11, v39, v11, s96
	v_bfe_u32 v46, v43, 16, 1
	v_add3_u32 v43, v43, v46, s96
	v_lshrrev_b32_e32 v39, 16, v43
	v_and_or_b32 v39, v11, s97, v39
	v_cvt_pk_bf16_f32 v38, v42, v38
	v_cvt_pk_bf16_f32 v37, v41, v37
	v_cvt_pk_bf16_f32 v36, v40, v36
	global_store_dwordx4 v[54:55], v[36:39], off offset:256
	ds_read_b128 v[36:39], v10 offset:2560
	s_waitcnt lgkmcnt(0)
	v_mov_b32_e32 v40, v37
	v_mov_b32_e32 v41, v38
	v_mov_b32_e32 v37, v39
	v_pk_add_f32 v[36:37], v[40:41], v[36:37]
	s_nop 0
	v_add_f32_e32 v11, v36, v37
	v_div_scale_f32 v36, s[2:3], v11, v11, 1.0
	v_rcp_f32_e32 v37, v36
	s_mov_b64 s[2:3], 0x50000
	v_fma_f32 v38, -v36, v37, 1.0
	v_fmac_f32_e32 v37, v38, v37
	v_div_scale_f32 v38, vcc, 1.0, v11, 1.0
	v_mul_f32_e32 v39, v38, v37
	v_fma_f32 v40, -v36, v39, v38
	v_fmac_f32_e32 v39, v40, v37
	v_fma_f32 v36, -v36, v39, v38
	v_div_fmas_f32 v36, v36, v37, v39
	v_div_fixup_f32 v36, v36, v11, 1.0
	v_pk_mul_f32 v[30:31], v[30:31], v[36:37] op_sel_hi:[1,0]
	v_pk_mul_f32 v[32:33], v[32:33], v[36:37] op_sel_hi:[1,0]
	v_pk_mul_f32 v[28:29], v[28:29], v[36:37] op_sel_hi:[1,0]
	v_pk_mul_f32 v[34:35], v[34:35], v[36:37] op_sel_hi:[1,0]
	v_bfe_u32 v40, v29, 16, 1
	v_add3_u32 v29, v29, v40, s96
	v_bfe_u32 v37, v33, 16, 1
	v_lshl_add_u64 v[38:39], v[2:3], 0, s[2:3]
	v_add3_u32 v33, v33, v37, s96
	s_mov_b32 s2, 0x50000
	v_lshrrev_b32_e32 v33, 16, v33
	v_cvt_pk_bf16_f32 v28, v32, v28
	v_add_co_u32_e32 v32, vcc, s2, v2
	v_cvt_pk_bf16_f32 v31, v35, v31
	v_cvt_pk_bf16_f32 v30, v34, v30
	v_and_or_b32 v29, v29, s97, v33
	v_addc_co_u32_e32 v33, vcc, 0, v3, vcc
	v_pk_mul_f32 v[20:21], v[20:21], v[36:37] op_sel_hi:[1,0]
	v_pk_mul_f32 v[22:23], v[22:23], v[36:37] op_sel_hi:[1,0]
	global_store_dwordx4 v[32:33], v[28:31], off
	v_pk_mul_f32 v[24:25], v[24:25], v[36:37] op_sel_hi:[1,0]
	v_pk_mul_f32 v[26:27], v[26:27], v[36:37] op_sel_hi:[1,0]
	v_bfe_u32 v11, v23, 16, 1
	v_add3_u32 v11, v23, v11, s96
	v_bfe_u32 v30, v27, 16, 1
	v_add3_u32 v27, v27, v30, s96
	v_lshrrev_b32_e32 v23, 16, v27
	v_and_or_b32 v23, v11, s97, v23
	v_cvt_pk_bf16_f32 v22, v26, v22
	v_cvt_pk_bf16_f32 v21, v25, v21
	v_cvt_pk_bf16_f32 v20, v24, v20
	global_store_dwordx4 v[38:39], v[20:23], off offset:256
	ds_read_b128 v[20:23], v10 offset:2816
	s_waitcnt lgkmcnt(0)
	v_mov_b32_e32 v10, v21
	v_mov_b32_e32 v11, v22
	v_mov_b32_e32 v21, v23
	v_pk_add_f32 v[10:11], v[10:11], v[20:21]
	s_nop 0
	v_add_f32_e32 v10, v10, v11
	v_div_scale_f32 v11, s[2:3], v10, v10, 1.0
	v_rcp_f32_e32 v20, v11
	s_mov_b64 s[2:3], 0x58000
	v_fma_f32 v21, -v11, v20, 1.0
	v_fmac_f32_e32 v20, v21, v20
	v_div_scale_f32 v21, vcc, 1.0, v10, 1.0
	v_mul_f32_e32 v22, v21, v20
	v_fma_f32 v23, -v11, v22, v21
	v_fmac_f32_e32 v22, v23, v20
	v_fma_f32 v11, -v11, v22, v21
	v_div_fmas_f32 v11, v11, v20, v22
	v_div_fixup_f32 v20, v11, v10, 1.0
	v_pk_mul_f32 v[12:13], v[12:13], v[20:21] op_sel_hi:[1,0]
	v_pk_mul_f32 v[14:15], v[14:15], v[20:21] op_sel_hi:[1,0]
	v_pk_mul_f32 v[10:11], v[16:17], v[20:21] op_sel_hi:[1,0]
	v_pk_mul_f32 v[16:17], v[18:19], v[20:21] op_sel_hi:[1,0]
	v_bfe_u32 v18, v15, 16, 1
	v_bfe_u32 v19, v14, 16, 1
	v_bfe_u32 v21, v13, 16, 1
	v_cvt_pk_bf16_f32 v10, v10, v12
	v_add3_u32 v21, v13, v21, s96
	v_add3_u32 v12, v14, v19, s96
	v_add3_u32 v13, v15, v18, s96
	v_bfe_u32 v15, v11, 16, 1
	v_bfe_u32 v18, v16, 16, 1
	v_bfe_u32 v19, v17, 16, 1
	v_lshl_add_u64 v[22:23], v[2:3], 0, s[2:3]
	v_add3_u32 v17, v17, v19, s96
	v_add3_u32 v16, v16, v18, s96
	v_add3_u32 v11, v11, v15, s96
	s_mov_b32 s2, 0x58000
	v_lshrrev_b32_e32 v11, 16, v11
	v_lshrrev_b32_e32 v14, 16, v16
	v_lshrrev_b32_e32 v15, 16, v17
	v_add_co_u32_e32 v2, vcc, s2, v2
	v_and_or_b32 v13, v13, s97, v15
	v_and_or_b32 v12, v12, s97, v14
	v_and_or_b32 v11, v21, s97, v11
	v_addc_co_u32_e32 v3, vcc, 0, v3, vcc
	v_pk_mul_f32 v[4:5], v[4:5], v[20:21] op_sel_hi:[1,0]
	v_pk_mul_f32 v[0:1], v[0:1], v[20:21] op_sel_hi:[1,0]
	global_store_dwordx4 v[2:3], v[10:13], off
	v_pk_mul_f32 v[2:3], v[8:9], v[20:21] op_sel_hi:[1,0]
	v_pk_mul_f32 v[6:7], v[6:7], v[20:21] op_sel_hi:[1,0]
	v_bfe_u32 v10, v5, 16, 1
	v_bfe_u32 v11, v4, 16, 1
	v_add3_u32 v4, v4, v11, s96
	v_add3_u32 v5, v5, v10, s96
	v_bfe_u32 v8, v2, 16, 1
	v_bfe_u32 v9, v3, 16, 1
	v_add3_u32 v3, v3, v9, s96
	v_add3_u32 v2, v2, v8, s96
	v_lshrrev_b32_e32 v8, 16, v2
	v_lshrrev_b32_e32 v9, 16, v3
	v_cvt_pk_bf16_f32 v3, v7, v1
	v_cvt_pk_bf16_f32 v2, v6, v0
	v_and_or_b32 v1, v5, s97, v9
	v_and_or_b32 v0, v4, s97, v8
	global_store_dwordx4 v[22:23], v[0:3], off offset:256
	s_and_b64 vcc, exec, s[38:39]
	s_mov_b64 s[2:3], -1
	s_cbranch_vccnz .LBB0_304
	s_andn2_b64 vcc, exec, s[40:41]
	s_cbranch_vccnz .LBB0_303
	s_barrier
	s_branch .LBB0_303

.LBB0_381:
	s_lshl_b32 s1, s2, 8
	s_lshl_b32 s0, s0, 8
	v_mov_b32_e32 v72, v210
	v_mov_b32_e32 v160, v179
	s_add_i32 s1, s1, s72
	s_or_b32 s0, s0, s73
	s_nop 0
	v_lshl_add_u32 v196, v72, 3, s0
	v_add_u32_e32 v200, s1, v160
	v_ashrrev_i32_e32 v197, 31, v196
	v_ashrrev_i32_e32 v201, 31, v200
	v_lshlrev_b64 v[72:73], 2, v[196:197]
	v_lshlrev_b64 v[160:161], 5, v[200:201]
	v_lshl_add_u64 v[74:75], s[52:53], 0, v[72:73]
	v_lshl_add_u64 v[84:85], s[56:57], 0, v[72:73]
	v_lshl_add_u64 v[164:165], s[54:55], 0, v[160:161]
	global_load_dwordx4 v[100:103], v[74:75], off offset:16
	global_load_dwordx4 v[108:111], v[74:75], off
	global_load_dwordx4 v[96:99], v[84:85], off offset:16
	global_load_dwordx4 v[104:107], v[84:85], off
	global_load_dwordx4 v[76:79], v[74:75], off offset:528
	global_load_dwordx4 v[88:91], v[74:75], off offset:512
	s_nop 0
	global_load_dwordx4 v[72:75], v[84:85], off offset:528
	s_nop 0
	global_load_dwordx4 v[84:87], v[84:85], off offset:512
	s_nop 0
	global_load_dwordx4 v[160:163], v[164:165], off offset:16
	s_nop 0
	global_load_dwordx4 v[164:167], v[164:165], off
	s_mov_b32 s0, 0x3a800000
	v_add_u32_e32 v202, 16, v200
	v_ashrrev_i32_e32 v203, 31, v202
	v_lshlrev_b64 v[198:199], 11, v[200:201]
	v_lshl_add_u64 v[198:199], s[24:25], 0, v[198:199]
	v_lshl_add_u64 v[208:209], v[196:197], 1, v[198:199]
	s_waitcnt vmcnt(0)
	v_xor_b32_e32 v103, 0x80000000, v103
	v_xor_b32_e32 v199, 0x80000000, v111
	v_pk_add_f32 v[160:161], v[160:161], v[162:163]
	v_pk_add_f32 v[164:165], v[164:165], v[166:167]
	v_xor_b32_e32 v198, 0x80000000, v110
	v_pk_add_f32 v[160:161], v[164:165], v[160:161]
	v_xor_b32_e32 v102, 0x80000000, v102
	v_pk_mul_f32 v[204:205], v[160:161], s[0:1] op_sel_hi:[1,0]
	s_nop 0
	v_fma_f32 v160, -v204, v204, v205
	v_max_f32_e32 v160, 0, v160
	v_add_f32_e32 v160, 0x3727c5ac, v160
	v_cmp_gt_f32_e32 vcc, s51, v160
	v_mul_f32_e32 v161, 0x4b800000, v160
	v_mov_b32_e32 v205, v204
	v_cndmask_b32_e32 v160, v160, v161, vcc
	v_rsq_f32_e32 v160, v160
	s_nop 0
	v_mul_f32_e32 v161, 0x45800000, v160
	v_cndmask_b32_e32 v206, v160, v161, vcc
	v_lshlrev_b64 v[160:161], 5, v[202:203]
	v_lshl_add_u64 v[164:165], s[54:55], 0, v[160:161]
	global_load_dwordx4 v[160:163], v[164:165], off offset:16
	s_nop 0
	global_load_dwordx4 v[164:167], v[164:165], off
	v_mov_b32_e32 v207, v206
	v_cmp_gt_i32_e32 vcc, 2.0, v196
	s_and_saveexec_b64 s[0:1], vcc
	s_cbranch_execz .LBB0_383
	v_pk_fma_f32 v[156:157], v[108:109], v[204:205], v[156:157] neg_lo:[1,0,0] neg_hi:[1,0,0]
	s_mov_b32 s2, 0x3d800000
	v_pk_fma_f32 v[156:157], v[156:157], v[206:207], v[104:105]
	v_pk_mul_f32 v[156:157], v[156:157], s[2:3] op_sel_hi:[1,0]
	v_pk_fma_f32 v[158:159], v[198:199], v[204:205], v[158:159]
	v_pk_fma_f32 v[152:153], v[100:101], v[204:205], v[152:153] neg_lo:[1,0,0] neg_hi:[1,0,0]
	v_pk_fma_f32 v[158:159], v[158:159], v[206:207], v[106:107]
	v_pk_fma_f32 v[152:153], v[152:153], v[206:207], v[96:97]
	v_pk_mul_f32 v[158:159], v[158:159], s[2:3] op_sel_hi:[1,0]
	v_pk_mul_f32 v[152:153], v[152:153], s[2:3] op_sel_hi:[1,0]
	v_cvt_pk_bf16_f32 v156, v156, v157
	v_pk_fma_f32 v[110:111], v[102:103], v[204:205], v[154:155]
	v_pk_fma_f32 v[110:111], v[110:111], v[206:207], v[98:99]
	v_pk_mul_f32 v[110:111], v[110:111], s[2:3] op_sel_hi:[1,0]
	v_cvt_pk_bf16_f32 v157, v158, v159
	v_cvt_pk_bf16_f32 v158, v152, v153
	v_cvt_pk_bf16_f32 v159, v110, v111
	global_store_dwordx4 v[208:209], v[156:159], off
.LBB0_383:
	s_or_b64 exec, exec, s[0:1]
	v_cmp_gt_i32_e64 s[40:41], s78, v196
	v_xor_b32_e32 v91, 0x80000000, v91
	v_xor_b32_e32 v90, 0x80000000, v90
	v_xor_b32_e32 v79, 0x80000000, v79
	v_xor_b32_e32 v78, 0x80000000, v78
	s_and_saveexec_b64 s[0:1], s[40:41]
	s_cbranch_execz .LBB0_385
	v_pk_fma_f32 v[148:149], v[88:89], v[204:205], v[148:149] neg_lo:[1,0,0] neg_hi:[1,0,0]
	s_mov_b32 s2, 0x3d800000
	v_pk_fma_f32 v[148:149], v[148:149], v[206:207], v[84:85]
	v_pk_mul_f32 v[148:149], v[148:149], s[2:3] op_sel_hi:[1,0]
	v_pk_fma_f32 v[150:151], v[90:91], v[204:205], v[150:151]
	v_pk_fma_f32 v[144:145], v[76:77], v[204:205], v[144:145] neg_lo:[1,0,0] neg_hi:[1,0,0]
	v_pk_fma_f32 v[150:151], v[150:151], v[206:207], v[86:87]
	v_pk_fma_f32 v[144:145], v[144:145], v[206:207], v[72:73]
	v_pk_mul_f32 v[150:151], v[150:151], s[2:3] op_sel_hi:[1,0]
	v_pk_mul_f32 v[144:145], v[144:145], s[2:3] op_sel_hi:[1,0]
	v_cvt_pk_bf16_f32 v148, v148, v149
	v_pk_fma_f32 v[110:111], v[78:79], v[204:205], v[146:147]
	v_pk_fma_f32 v[110:111], v[110:111], v[206:207], v[74:75]
	v_pk_mul_f32 v[110:111], v[110:111], s[2:3] op_sel_hi:[1,0]
	v_cvt_pk_bf16_f32 v149, v150, v151
	v_cvt_pk_bf16_f32 v150, v144, v145
	v_cvt_pk_bf16_f32 v151, v110, v111
	global_store_dwordx4 v[208:209], v[148:151], off offset:256
.LBB0_385:
	s_or_b64 exec, exec, s[0:1]
	s_waitcnt vmcnt(0)
	v_pk_add_f32 v[110:111], v[164:165], v[166:167]
	v_pk_add_f32 v[144:145], v[160:161], v[162:163]
	s_mov_b32 s0, 0x3a800000
	v_pk_add_f32 v[110:111], v[110:111], v[144:145]
	v_lshlrev_b64 v[156:157], 11, v[202:203]
	v_pk_mul_f32 v[152:153], v[110:111], s[0:1] op_sel_hi:[1,0]
	v_lshl_add_u64 v[156:157], s[24:25], 0, v[156:157]
	v_fma_f32 v110, -v152, v152, v153
	v_max_f32_e32 v110, 0, v110
	v_add_f32_e32 v110, 0x3727c5ac, v110
	v_cmp_gt_f32_e64 s[0:1], s51, v110
	v_mul_f32_e32 v111, 0x4b800000, v110
	v_lshl_add_u64 v[156:157], v[196:197], 1, v[156:157]
	v_cndmask_b32_e64 v110, v110, v111, s[0:1]
	v_rsq_f32_e32 v110, v110
	v_mov_b32_e32 v153, v152
	v_mul_f32_e32 v111, 0x45800000, v110
	v_cndmask_b32_e64 v154, v110, v111, s[0:1]
	v_add_u32_e32 v110, 32, v200
	v_ashrrev_i32_e32 v111, 31, v110
	v_lshlrev_b64 v[144:145], 5, v[110:111]
	v_lshl_add_u64 v[148:149], s[54:55], 0, v[144:145]
	global_load_dwordx4 v[144:147], v[148:149], off offset:16
	s_nop 0
	global_load_dwordx4 v[148:151], v[148:149], off
	v_mov_b32_e32 v155, v154
	s_and_saveexec_b64 s[0:1], vcc
	s_cbranch_execz .LBB0_387
	v_pk_fma_f32 v[140:141], v[108:109], v[152:153], v[140:141] neg_lo:[1,0,0] neg_hi:[1,0,0]
	s_mov_b32 s2, 0x3d800000
	v_pk_fma_f32 v[140:141], v[140:141], v[154:155], v[104:105]
	v_pk_mul_f32 v[140:141], v[140:141], s[2:3] op_sel_hi:[1,0]
	v_pk_fma_f32 v[142:143], v[198:199], v[152:153], v[142:143]
	v_pk_fma_f32 v[142:143], v[142:143], v[154:155], v[106:107]
	v_pk_mul_f32 v[142:143], v[142:143], s[2:3] op_sel_hi:[1,0]
	v_cvt_pk_bf16_f32 v140, v140, v141
	v_pk_fma_f32 v[136:137], v[100:101], v[152:153], v[136:137] neg_lo:[1,0,0] neg_hi:[1,0,0]
	v_pk_fma_f32 v[136:137], v[136:137], v[154:155], v[96:97]
	v_pk_mul_f32 v[136:137], v[136:137], s[2:3] op_sel_hi:[1,0]
	v_cvt_pk_bf16_f32 v141, v142, v143
	v_pk_fma_f32 v[138:139], v[102:103], v[152:153], v[138:139]
	v_pk_fma_f32 v[138:139], v[138:139], v[154:155], v[98:99]
	v_pk_mul_f32 v[138:139], v[138:139], s[2:3] op_sel_hi:[1,0]
	v_cvt_pk_bf16_f32 v142, v136, v137
	v_cvt_pk_bf16_f32 v143, v138, v139
	global_store_dwordx4 v[156:157], v[140:143], off
.LBB0_387:
	s_or_b64 exec, exec, s[0:1]
	s_and_saveexec_b64 s[0:1], s[40:41]
	s_cbranch_execz .LBB0_389
	v_pk_fma_f32 v[132:133], v[88:89], v[152:153], v[132:133] neg_lo:[1,0,0] neg_hi:[1,0,0]
	s_mov_b32 s2, 0x3d800000
	v_pk_fma_f32 v[132:133], v[132:133], v[154:155], v[84:85]
	v_pk_mul_f32 v[132:133], v[132:133], s[2:3] op_sel_hi:[1,0]
	v_pk_fma_f32 v[134:135], v[90:91], v[152:153], v[134:135]
	v_pk_fma_f32 v[134:135], v[134:135], v[154:155], v[86:87]
	v_pk_mul_f32 v[134:135], v[134:135], s[2:3] op_sel_hi:[1,0]
	v_cvt_pk_bf16_f32 v132, v132, v133
	v_pk_fma_f32 v[128:129], v[76:77], v[152:153], v[128:129] neg_lo:[1,0,0] neg_hi:[1,0,0]
	v_pk_fma_f32 v[128:129], v[128:129], v[154:155], v[72:73]
	v_pk_mul_f32 v[128:129], v[128:129], s[2:3] op_sel_hi:[1,0]
	v_cvt_pk_bf16_f32 v133, v134, v135
	v_pk_fma_f32 v[130:131], v[78:79], v[152:153], v[130:131]
	v_pk_fma_f32 v[130:131], v[130:131], v[154:155], v[74:75]
	v_pk_mul_f32 v[130:131], v[130:131], s[2:3] op_sel_hi:[1,0]
	v_cvt_pk_bf16_f32 v134, v128, v129
	v_cvt_pk_bf16_f32 v135, v130, v131
	global_store_dwordx4 v[156:157], v[132:135], off offset:256
.LBB0_389:
	s_or_b64 exec, exec, s[0:1]
	s_waitcnt vmcnt(0)
	v_pk_add_f32 v[128:129], v[148:149], v[150:151]
	v_pk_add_f32 v[130:131], v[144:145], v[146:147]
	s_mov_b32 s0, 0x3a800000
	v_pk_add_f32 v[128:129], v[128:129], v[130:131]
	v_add_u32_e32 v136, 48, v200
	v_pk_mul_f32 v[138:139], v[128:129], s[0:1] op_sel_hi:[1,0]
	v_ashrrev_i32_e32 v137, 31, v136
	v_fma_f32 v128, -v138, v138, v139
	v_max_f32_e32 v128, 0, v128
	v_add_f32_e32 v128, 0x3727c5ac, v128
	v_cmp_gt_f32_e64 s[0:1], s51, v128
	v_mul_f32_e32 v129, 0x4b800000, v128
	v_lshlrev_b64 v[110:111], 11, v[110:111]
	v_cndmask_b32_e64 v128, v128, v129, s[0:1]
	v_rsq_f32_e32 v128, v128
	v_lshl_add_u64 v[110:111], s[24:25], 0, v[110:111]
	v_lshl_add_u64 v[110:111], v[196:197], 1, v[110:111]
	v_mov_b32_e32 v139, v138
	v_mul_f32_e32 v129, 0x45800000, v128
	v_cndmask_b32_e64 v140, v128, v129, s[0:1]
	v_lshlrev_b64 v[128:129], 5, v[136:137]
	v_lshl_add_u64 v[132:133], s[54:55], 0, v[128:129]
	global_load_dwordx4 v[128:131], v[132:133], off offset:16
	s_nop 0
	global_load_dwordx4 v[132:135], v[132:133], off
	v_mov_b32_e32 v141, v140
	s_and_saveexec_b64 s[0:1], vcc
	s_cbranch_execz .LBB0_391
	v_pk_fma_f32 v[124:125], v[108:109], v[138:139], v[124:125] neg_lo:[1,0,0] neg_hi:[1,0,0]
	s_mov_b32 s2, 0x3d800000
	v_pk_fma_f32 v[124:125], v[124:125], v[140:141], v[104:105]
	v_pk_mul_f32 v[124:125], v[124:125], s[2:3] op_sel_hi:[1,0]
	v_pk_fma_f32 v[126:127], v[198:199], v[138:139], v[126:127]
	v_pk_fma_f32 v[126:127], v[126:127], v[140:141], v[106:107]
	v_pk_mul_f32 v[126:127], v[126:127], s[2:3] op_sel_hi:[1,0]
	v_cvt_pk_bf16_f32 v124, v124, v125
	v_pk_fma_f32 v[120:121], v[100:101], v[138:139], v[120:121] neg_lo:[1,0,0] neg_hi:[1,0,0]
	v_pk_fma_f32 v[120:121], v[120:121], v[140:141], v[96:97]
	v_pk_mul_f32 v[120:121], v[120:121], s[2:3] op_sel_hi:[1,0]
	v_cvt_pk_bf16_f32 v125, v126, v127
	v_pk_fma_f32 v[122:123], v[102:103], v[138:139], v[122:123]
	v_pk_fma_f32 v[122:123], v[122:123], v[140:141], v[98:99]
	v_pk_mul_f32 v[122:123], v[122:123], s[2:3] op_sel_hi:[1,0]
	v_cvt_pk_bf16_f32 v126, v120, v121
	v_cvt_pk_bf16_f32 v127, v122, v123
	global_store_dwordx4 v[110:111], v[124:127], off
.LBB0_391:
	s_or_b64 exec, exec, s[0:1]
	s_and_saveexec_b64 s[0:1], s[40:41]
	s_cbranch_execz .LBB0_393
	v_pk_fma_f32 v[116:117], v[88:89], v[138:139], v[116:117] neg_lo:[1,0,0] neg_hi:[1,0,0]
	s_mov_b32 s2, 0x3d800000
	v_pk_fma_f32 v[116:117], v[116:117], v[140:141], v[84:85]
	v_pk_mul_f32 v[116:117], v[116:117], s[2:3] op_sel_hi:[1,0]
	v_pk_fma_f32 v[118:119], v[90:91], v[138:139], v[118:119]
	v_pk_fma_f32 v[118:119], v[118:119], v[140:141], v[86:87]
	v_pk_mul_f32 v[118:119], v[118:119], s[2:3] op_sel_hi:[1,0]
	v_cvt_pk_bf16_f32 v116, v116, v117
	v_pk_fma_f32 v[112:113], v[76:77], v[138:139], v[112:113] neg_lo:[1,0,0] neg_hi:[1,0,0]
	v_pk_fma_f32 v[112:113], v[112:113], v[140:141], v[72:73]
	v_pk_mul_f32 v[112:113], v[112:113], s[2:3] op_sel_hi:[1,0]
	v_cvt_pk_bf16_f32 v117, v118, v119
	v_pk_fma_f32 v[114:115], v[78:79], v[138:139], v[114:115]
	v_pk_fma_f32 v[114:115], v[114:115], v[140:141], v[74:75]
	v_pk_mul_f32 v[114:115], v[114:115], s[2:3] op_sel_hi:[1,0]
	v_cvt_pk_bf16_f32 v118, v112, v113
	v_cvt_pk_bf16_f32 v119, v114, v115
	global_store_dwordx4 v[110:111], v[116:119], off offset:256
.LBB0_393:
	s_or_b64 exec, exec, s[0:1]
	s_waitcnt vmcnt(0)
	v_pk_add_f32 v[110:111], v[132:133], v[134:135]
	v_pk_add_f32 v[112:113], v[128:129], v[130:131]
	s_mov_b32 s0, 0x3a800000
	v_pk_add_f32 v[110:111], v[110:111], v[112:113]
	v_add_u32_e32 v118, 0x80, v200
	v_pk_mul_f32 v[120:121], v[110:111], s[0:1] op_sel_hi:[1,0]
	v_ashrrev_i32_e32 v119, 31, v118
	v_fma_f32 v110, -v120, v120, v121
	v_max_f32_e32 v110, 0, v110
	v_add_f32_e32 v110, 0x3727c5ac, v110
	v_cmp_gt_f32_e64 s[0:1], s51, v110
	v_mul_f32_e32 v111, 0x4b800000, v110
	v_lshlrev_b64 v[124:125], 11, v[136:137]
	v_cndmask_b32_e64 v110, v110, v111, s[0:1]
	v_rsq_f32_e32 v110, v110
	v_lshl_add_u64 v[124:125], s[24:25], 0, v[124:125]
	v_lshl_add_u64 v[124:125], v[196:197], 1, v[124:125]
	v_mov_b32_e32 v121, v120
	v_mul_f32_e32 v111, 0x45800000, v110
	v_cndmask_b32_e64 v122, v110, v111, s[0:1]
	v_lshlrev_b64 v[110:111], 5, v[118:119]
	v_lshl_add_u64 v[114:115], s[54:55], 0, v[110:111]
	global_load_dwordx4 v[110:113], v[114:115], off offset:16
	s_nop 0
	global_load_dwordx4 v[114:117], v[114:115], off
	v_mov_b32_e32 v123, v122
	s_and_saveexec_b64 s[0:1], vcc
	s_cbranch_execz .LBB0_395
	v_pk_fma_f32 v[92:93], v[108:109], v[120:121], v[92:93] neg_lo:[1,0,0] neg_hi:[1,0,0]
	s_mov_b32 s2, 0x3d800000
	v_pk_fma_f32 v[92:93], v[92:93], v[122:123], v[104:105]
	v_pk_mul_f32 v[92:93], v[92:93], s[2:3] op_sel_hi:[1,0]
	v_pk_fma_f32 v[94:95], v[198:199], v[120:121], v[94:95]
	v_pk_fma_f32 v[94:95], v[94:95], v[122:123], v[106:107]
	v_pk_mul_f32 v[94:95], v[94:95], s[2:3] op_sel_hi:[1,0]
	v_cvt_pk_bf16_f32 v92, v92, v93
	v_pk_fma_f32 v[80:81], v[100:101], v[120:121], v[80:81] neg_lo:[1,0,0] neg_hi:[1,0,0]
	v_pk_fma_f32 v[80:81], v[80:81], v[122:123], v[96:97]
	v_pk_mul_f32 v[80:81], v[80:81], s[2:3] op_sel_hi:[1,0]
	v_cvt_pk_bf16_f32 v93, v94, v95
	v_pk_fma_f32 v[82:83], v[102:103], v[120:121], v[82:83]
	v_pk_fma_f32 v[82:83], v[82:83], v[122:123], v[98:99]
	v_pk_mul_f32 v[82:83], v[82:83], s[2:3] op_sel_hi:[1,0]
	v_cvt_pk_bf16_f32 v94, v80, v81
	v_cvt_pk_bf16_f32 v95, v82, v83
	global_store_dwordx4 v[124:125], v[92:95], off
.LBB0_395:
	s_or_b64 exec, exec, s[0:1]
	s_and_saveexec_b64 s[0:1], s[40:41]
	s_cbranch_execz .LBB0_397
	v_pk_fma_f32 v[68:69], v[88:89], v[120:121], v[68:69] neg_lo:[1,0,0] neg_hi:[1,0,0]
	s_mov_b32 s2, 0x3d800000
	v_pk_fma_f32 v[68:69], v[68:69], v[122:123], v[84:85]
	v_pk_mul_f32 v[68:69], v[68:69], s[2:3] op_sel_hi:[1,0]
	v_pk_fma_f32 v[70:71], v[90:91], v[120:121], v[70:71]
	v_pk_fma_f32 v[70:71], v[70:71], v[122:123], v[86:87]
	v_pk_mul_f32 v[70:71], v[70:71], s[2:3] op_sel_hi:[1,0]
	v_cvt_pk_bf16_f32 v68, v68, v69
	v_pk_fma_f32 v[64:65], v[76:77], v[120:121], v[64:65] neg_lo:[1,0,0] neg_hi:[1,0,0]
	v_pk_fma_f32 v[64:65], v[64:65], v[122:123], v[72:73]
	v_pk_mul_f32 v[64:65], v[64:65], s[2:3] op_sel_hi:[1,0]
	v_cvt_pk_bf16_f32 v69, v70, v71
	v_pk_fma_f32 v[66:67], v[78:79], v[120:121], v[66:67]
	v_pk_fma_f32 v[66:67], v[66:67], v[122:123], v[74:75]
	v_pk_mul_f32 v[66:67], v[66:67], s[2:3] op_sel_hi:[1,0]
	v_cvt_pk_bf16_f32 v70, v64, v65
	v_cvt_pk_bf16_f32 v71, v66, v67
	global_store_dwordx4 v[124:125], v[68:71], off offset:256
.LBB0_397:
	s_or_b64 exec, exec, s[0:1]
	s_waitcnt vmcnt(0)
	v_pk_add_f32 v[64:65], v[114:115], v[116:117]
	v_pk_add_f32 v[66:67], v[110:111], v[112:113]
	s_mov_b32 s0, 0x3a800000
	v_pk_add_f32 v[64:65], v[64:65], v[66:67]
	v_add_u32_e32 v80, 0x90, v200
	v_pk_mul_f32 v[82:83], v[64:65], s[0:1] op_sel_hi:[1,0]
	v_ashrrev_i32_e32 v81, 31, v80
	v_fma_f32 v64, -v82, v82, v83
	v_max_f32_e32 v64, 0, v64
	v_add_f32_e32 v64, 0x3727c5ac, v64
	v_cmp_gt_f32_e64 s[0:1], s51, v64
	v_mul_f32_e32 v65, 0x4b800000, v64
	v_lshlrev_b64 v[94:95], 11, v[118:119]
	v_cndmask_b32_e64 v64, v64, v65, s[0:1]
	v_rsq_f32_e32 v64, v64
	v_lshl_add_u64 v[94:95], s[24:25], 0, v[94:95]
	v_lshl_add_u64 v[94:95], v[196:197], 1, v[94:95]
	v_mov_b32_e32 v83, v82
	v_mul_f32_e32 v65, 0x45800000, v64
	v_cndmask_b32_e64 v92, v64, v65, s[0:1]
	v_lshlrev_b64 v[64:65], 5, v[80:81]
	v_lshl_add_u64 v[68:69], s[54:55], 0, v[64:65]
	global_load_dwordx4 v[64:67], v[68:69], off offset:16
	s_nop 0
	global_load_dwordx4 v[68:71], v[68:69], off
	v_mov_b32_e32 v93, v92
	s_and_saveexec_b64 s[0:1], vcc
	s_cbranch_execz .LBB0_399
	v_pk_fma_f32 v[60:61], v[108:109], v[82:83], v[60:61] neg_lo:[1,0,0] neg_hi:[1,0,0]
	s_mov_b32 s2, 0x3d800000
	v_pk_fma_f32 v[60:61], v[60:61], v[92:93], v[104:105]
	v_pk_mul_f32 v[60:61], v[60:61], s[2:3] op_sel_hi:[1,0]
	v_pk_fma_f32 v[62:63], v[198:199], v[82:83], v[62:63]
	v_pk_fma_f32 v[62:63], v[62:63], v[92:93], v[106:107]
	v_pk_mul_f32 v[62:63], v[62:63], s[2:3] op_sel_hi:[1,0]
	v_cvt_pk_bf16_f32 v60, v60, v61
	v_pk_fma_f32 v[56:57], v[100:101], v[82:83], v[56:57] neg_lo:[1,0,0] neg_hi:[1,0,0]
	v_pk_fma_f32 v[56:57], v[56:57], v[92:93], v[96:97]
	v_pk_mul_f32 v[56:57], v[56:57], s[2:3] op_sel_hi:[1,0]
	v_cvt_pk_bf16_f32 v61, v62, v63
	v_pk_fma_f32 v[58:59], v[102:103], v[82:83], v[58:59]
	v_pk_fma_f32 v[58:59], v[58:59], v[92:93], v[98:99]
	v_pk_mul_f32 v[58:59], v[58:59], s[2:3] op_sel_hi:[1,0]
	v_cvt_pk_bf16_f32 v62, v56, v57
	v_cvt_pk_bf16_f32 v63, v58, v59
	global_store_dwordx4 v[94:95], v[60:63], off
.LBB0_399:
	s_or_b64 exec, exec, s[0:1]
	s_and_saveexec_b64 s[0:1], s[40:41]
	s_cbranch_execz .LBB0_401
	v_pk_fma_f32 v[52:53], v[88:89], v[82:83], v[52:53] neg_lo:[1,0,0] neg_hi:[1,0,0]
	s_mov_b32 s2, 0x3d800000
	v_pk_fma_f32 v[52:53], v[52:53], v[92:93], v[84:85]
	v_pk_mul_f32 v[52:53], v[52:53], s[2:3] op_sel_hi:[1,0]
	v_pk_fma_f32 v[54:55], v[90:91], v[82:83], v[54:55]
	v_pk_fma_f32 v[54:55], v[54:55], v[92:93], v[86:87]
	v_pk_mul_f32 v[54:55], v[54:55], s[2:3] op_sel_hi:[1,0]
	v_cvt_pk_bf16_f32 v52, v52, v53
	v_pk_fma_f32 v[48:49], v[76:77], v[82:83], v[48:49] neg_lo:[1,0,0] neg_hi:[1,0,0]
	v_pk_fma_f32 v[48:49], v[48:49], v[92:93], v[72:73]
	v_pk_mul_f32 v[48:49], v[48:49], s[2:3] op_sel_hi:[1,0]
	v_cvt_pk_bf16_f32 v53, v54, v55
	v_pk_fma_f32 v[50:51], v[78:79], v[82:83], v[50:51]
	v_pk_fma_f32 v[50:51], v[50:51], v[92:93], v[74:75]
	v_pk_mul_f32 v[50:51], v[50:51], s[2:3] op_sel_hi:[1,0]
	v_cvt_pk_bf16_f32 v54, v48, v49
	v_cvt_pk_bf16_f32 v55, v50, v51
	global_store_dwordx4 v[94:95], v[52:55], off offset:256
.LBB0_401:
	s_or_b64 exec, exec, s[0:1]
	s_waitcnt vmcnt(0)
	v_pk_add_f32 v[48:49], v[68:69], v[70:71]
	v_pk_add_f32 v[50:51], v[64:65], v[66:67]
	s_mov_b32 s0, 0x3a800000
	v_pk_add_f32 v[48:49], v[48:49], v[50:51]
	v_add_u32_e32 v56, 0xa0, v200
	v_pk_mul_f32 v[58:59], v[48:49], s[0:1] op_sel_hi:[1,0]
	v_ashrrev_i32_e32 v57, 31, v56
	v_fma_f32 v48, -v58, v58, v59
	v_max_f32_e32 v48, 0, v48
	v_add_f32_e32 v48, 0x3727c5ac, v48
	v_cmp_gt_f32_e64 s[0:1], s51, v48
	v_mul_f32_e32 v49, 0x4b800000, v48
	v_lshlrev_b64 v[62:63], 11, v[80:81]
	v_cndmask_b32_e64 v48, v48, v49, s[0:1]
	v_rsq_f32_e32 v48, v48
	v_lshl_add_u64 v[62:63], s[24:25], 0, v[62:63]
	v_lshl_add_u64 v[62:63], v[196:197], 1, v[62:63]
	v_mov_b32_e32 v59, v58
	v_mul_f32_e32 v49, 0x45800000, v48
	v_cndmask_b32_e64 v60, v48, v49, s[0:1]
	v_lshlrev_b64 v[48:49], 5, v[56:57]
	v_lshl_add_u64 v[52:53], s[54:55], 0, v[48:49]
	global_load_dwordx4 v[48:51], v[52:53], off offset:16
	s_nop 0
	global_load_dwordx4 v[52:55], v[52:53], off
	v_mov_b32_e32 v61, v60
	s_and_saveexec_b64 s[0:1], vcc
	s_cbranch_execz .LBB0_403
	v_pk_fma_f32 v[44:45], v[108:109], v[58:59], v[44:45] neg_lo:[1,0,0] neg_hi:[1,0,0]
	s_mov_b32 s2, 0x3d800000
	v_pk_fma_f32 v[44:45], v[44:45], v[60:61], v[104:105]
	v_pk_mul_f32 v[44:45], v[44:45], s[2:3] op_sel_hi:[1,0]
	v_pk_fma_f32 v[46:47], v[198:199], v[58:59], v[46:47]
	v_pk_fma_f32 v[46:47], v[46:47], v[60:61], v[106:107]
	v_pk_mul_f32 v[46:47], v[46:47], s[2:3] op_sel_hi:[1,0]
	v_cvt_pk_bf16_f32 v44, v44, v45
	v_pk_fma_f32 v[40:41], v[100:101], v[58:59], v[40:41] neg_lo:[1,0,0] neg_hi:[1,0,0]
	v_pk_fma_f32 v[40:41], v[40:41], v[60:61], v[96:97]
	v_pk_mul_f32 v[40:41], v[40:41], s[2:3] op_sel_hi:[1,0]
	v_cvt_pk_bf16_f32 v45, v46, v47
	v_pk_fma_f32 v[42:43], v[102:103], v[58:59], v[42:43]
	v_pk_fma_f32 v[42:43], v[42:43], v[60:61], v[98:99]
	v_pk_mul_f32 v[42:43], v[42:43], s[2:3] op_sel_hi:[1,0]
	v_cvt_pk_bf16_f32 v46, v40, v41
	v_cvt_pk_bf16_f32 v47, v42, v43
	global_store_dwordx4 v[62:63], v[44:47], off
.LBB0_403:
	s_or_b64 exec, exec, s[0:1]
	s_and_saveexec_b64 s[0:1], s[40:41]
	s_cbranch_execz .LBB0_405
	v_pk_fma_f32 v[36:37], v[88:89], v[58:59], v[36:37] neg_lo:[1,0,0] neg_hi:[1,0,0]
	s_mov_b32 s2, 0x3d800000
	v_pk_fma_f32 v[36:37], v[36:37], v[60:61], v[84:85]
	v_pk_mul_f32 v[36:37], v[36:37], s[2:3] op_sel_hi:[1,0]
	v_pk_fma_f32 v[38:39], v[90:91], v[58:59], v[38:39]
	v_pk_fma_f32 v[38:39], v[38:39], v[60:61], v[86:87]
	v_pk_mul_f32 v[38:39], v[38:39], s[2:3] op_sel_hi:[1,0]
	v_cvt_pk_bf16_f32 v36, v36, v37
	v_pk_fma_f32 v[32:33], v[76:77], v[58:59], v[32:33] neg_lo:[1,0,0] neg_hi:[1,0,0]
	v_pk_fma_f32 v[32:33], v[32:33], v[60:61], v[72:73]
	v_pk_mul_f32 v[32:33], v[32:33], s[2:3] op_sel_hi:[1,0]
	v_cvt_pk_bf16_f32 v37, v38, v39
	v_pk_fma_f32 v[34:35], v[78:79], v[58:59], v[34:35]
	v_pk_fma_f32 v[34:35], v[34:35], v[60:61], v[74:75]
	v_pk_mul_f32 v[34:35], v[34:35], s[2:3] op_sel_hi:[1,0]
	v_cvt_pk_bf16_f32 v38, v32, v33
	v_cvt_pk_bf16_f32 v39, v34, v35
	global_store_dwordx4 v[62:63], v[36:39], off offset:256
.LBB0_405:
	s_or_b64 exec, exec, s[0:1]
	s_waitcnt vmcnt(0)
	v_pk_add_f32 v[32:33], v[52:53], v[54:55]
	v_pk_add_f32 v[34:35], v[48:49], v[50:51]
	s_mov_b32 s0, 0x3a800000
	v_pk_add_f32 v[32:33], v[32:33], v[34:35]
	v_add_u32_e32 v44, 0xb0, v200
	v_pk_mul_f32 v[40:41], v[32:33], s[0:1] op_sel_hi:[1,0]
	v_ashrrev_i32_e32 v45, 31, v44
	v_fma_f32 v32, -v40, v40, v41
	v_max_f32_e32 v32, 0, v32
	v_add_f32_e32 v32, 0x3727c5ac, v32
	v_cmp_gt_f32_e64 s[0:1], s51, v32
	v_mul_f32_e32 v33, 0x4b800000, v32
	v_lshlrev_b64 v[46:47], 11, v[56:57]
	v_cndmask_b32_e64 v32, v32, v33, s[0:1]
	v_rsq_f32_e32 v32, v32
	v_lshl_add_u64 v[46:47], s[24:25], 0, v[46:47]
	v_lshl_add_u64 v[46:47], v[196:197], 1, v[46:47]
	v_mov_b32_e32 v41, v40
	v_mul_f32_e32 v33, 0x45800000, v32
	v_cndmask_b32_e64 v42, v32, v33, s[0:1]
	v_lshlrev_b64 v[32:33], 5, v[44:45]
	v_lshl_add_u64 v[32:33], s[54:55], 0, v[32:33]
	global_load_dwordx4 v[36:39], v[32:33], off offset:16
	s_nop 0
	global_load_dwordx4 v[32:35], v[32:33], off
	v_mov_b32_e32 v43, v42
	s_and_saveexec_b64 s[0:1], vcc
	s_cbranch_execz .LBB0_407
	v_pk_fma_f32 v[28:29], v[108:109], v[40:41], v[28:29] neg_lo:[1,0,0] neg_hi:[1,0,0]
	s_mov_b32 s2, 0x3d800000
	v_pk_fma_f32 v[28:29], v[28:29], v[42:43], v[104:105]
	v_mov_b32_e32 v48, v40
	v_pk_mul_f32 v[28:29], v[28:29], s[2:3] op_sel_hi:[1,0]
	v_mov_b32_e32 v49, v40
	v_pk_fma_f32 v[30:31], v[198:199], v[40:41], v[30:31]
	v_mov_b32_e32 v50, v42
	v_mov_b32_e32 v51, v42
	v_pk_fma_f32 v[30:31], v[30:31], v[42:43], v[106:107]
	v_pk_mul_f32 v[30:31], v[30:31], s[2:3] op_sel_hi:[1,0]
	v_cvt_pk_bf16_f32 v28, v28, v29
	v_pk_fma_f32 v[24:25], v[100:101], v[40:41], v[24:25] neg_lo:[1,0,0] neg_hi:[1,0,0]
	v_pk_fma_f32 v[24:25], v[24:25], v[42:43], v[96:97]
	v_pk_mul_f32 v[24:25], v[24:25], s[2:3] op_sel_hi:[1,0]
	v_cvt_pk_bf16_f32 v29, v30, v31
	v_pk_fma_f32 v[26:27], v[102:103], v[40:41], v[26:27]
	v_pk_fma_f32 v[26:27], v[26:27], v[42:43], v[98:99]
	v_pk_mul_f32 v[26:27], v[26:27], s[2:3] op_sel_hi:[1,0]
	v_cvt_pk_bf16_f32 v30, v24, v25
	v_cvt_pk_bf16_f32 v31, v26, v27
	global_store_dwordx4 v[46:47], v[28:31], off
.LBB0_407:
	s_or_b64 exec, exec, s[0:1]
	s_and_saveexec_b64 s[0:1], s[40:41]
	s_cbranch_execz .LBB0_409
	v_pk_fma_f32 v[20:21], v[88:89], v[40:41], v[20:21] neg_lo:[1,0,0] neg_hi:[1,0,0]
	s_mov_b32 s2, 0x3d800000
	v_pk_fma_f32 v[20:21], v[20:21], v[42:43], v[84:85]
	v_pk_mul_f32 v[20:21], v[20:21], s[2:3] op_sel_hi:[1,0]
	v_pk_fma_f32 v[22:23], v[90:91], v[40:41], v[22:23]
	v_pk_fma_f32 v[22:23], v[22:23], v[42:43], v[86:87]
	v_pk_mul_f32 v[22:23], v[22:23], s[2:3] op_sel_hi:[1,0]
	v_cvt_pk_bf16_f32 v20, v20, v21
	v_pk_fma_f32 v[16:17], v[76:77], v[40:41], v[16:17] neg_lo:[1,0,0] neg_hi:[1,0,0]
	v_pk_fma_f32 v[16:17], v[16:17], v[42:43], v[72:73]
	v_pk_mul_f32 v[16:17], v[16:17], s[2:3] op_sel_hi:[1,0]
	v_cvt_pk_bf16_f32 v21, v22, v23
	v_pk_fma_f32 v[18:19], v[78:79], v[40:41], v[18:19]
	v_pk_fma_f32 v[18:19], v[18:19], v[42:43], v[74:75]
	v_pk_mul_f32 v[18:19], v[18:19], s[2:3] op_sel_hi:[1,0]
	v_cvt_pk_bf16_f32 v22, v16, v17
	v_cvt_pk_bf16_f32 v23, v18, v19
	global_store_dwordx4 v[46:47], v[20:23], off offset:256
.LBB0_409:
	s_or_b64 exec, exec, s[0:1]
	s_waitcnt vmcnt(0)
	v_pk_add_f32 v[16:17], v[36:37], v[38:39]
	v_pk_add_f32 v[18:19], v[32:33], v[34:35]
	s_mov_b32 s0, 0x3a800000
	v_pk_add_f32 v[16:17], v[18:19], v[16:17]
	s_nop 0
	v_pk_mul_f32 v[18:19], v[16:17], s[0:1] op_sel_hi:[1,0]
	s_nop 0
	v_fma_f32 v16, -v18, v18, v19
	v_max_f32_e32 v16, 0, v16
	v_add_f32_e32 v16, 0x3727c5ac, v16
	v_mul_f32_e32 v17, 0x4b800000, v16
	v_cmp_gt_f32_e64 s[0:1], s51, v16
	v_mov_b32_e32 v19, v18
	s_nop 0
	v_cndmask_b32_e64 v16, v16, v17, s[0:1]
	v_rsq_f32_e32 v16, v16
	s_nop 0
	v_mul_f32_e32 v17, 0x45800000, v16
	v_cndmask_b32_e64 v20, v16, v17, s[0:1]
	v_lshlrev_b64 v[16:17], 11, v[44:45]
	v_lshl_add_u64 v[16:17], s[24:25], 0, v[16:17]
	v_lshl_add_u64 v[16:17], v[196:197], 1, v[16:17]
	v_mov_b32_e32 v21, v20
	s_and_saveexec_b64 s[0:1], vcc
	s_cbranch_execz .LBB0_411
	v_pk_fma_f32 v[12:13], v[108:109], v[18:19], v[12:13] neg_lo:[1,0,0] neg_hi:[1,0,0]
	s_mov_b32 s2, 0x3d800000
	v_pk_fma_f32 v[12:13], v[12:13], v[20:21], v[104:105]
	v_pk_mul_f32 v[12:13], v[12:13], s[2:3] op_sel_hi:[1,0]
	v_pk_fma_f32 v[14:15], v[198:199], v[18:19], v[14:15]
	v_pk_fma_f32 v[14:15], v[14:15], v[20:21], v[106:107]
	v_pk_mul_f32 v[14:15], v[14:15], s[2:3] op_sel_hi:[1,0]
	v_cvt_pk_bf16_f32 v12, v12, v13
	v_pk_fma_f32 v[8:9], v[100:101], v[18:19], v[8:9] neg_lo:[1,0,0] neg_hi:[1,0,0]
	v_pk_fma_f32 v[8:9], v[8:9], v[20:21], v[96:97]
	v_pk_mul_f32 v[8:9], v[8:9], s[2:3] op_sel_hi:[1,0]
	v_cvt_pk_bf16_f32 v13, v14, v15
	v_pk_fma_f32 v[10:11], v[102:103], v[18:19], v[10:11]
	v_pk_fma_f32 v[10:11], v[10:11], v[20:21], v[98:99]
	v_pk_mul_f32 v[10:11], v[10:11], s[2:3] op_sel_hi:[1,0]
	v_cvt_pk_bf16_f32 v14, v8, v9
	v_cvt_pk_bf16_f32 v15, v10, v11
	global_store_dwordx4 v[16:17], v[12:15], off
.LBB0_411:
	s_or_b64 exec, exec, s[0:1]
	s_and_saveexec_b64 s[0:1], s[40:41]
	s_cbranch_execz .LBB0_413
	v_pk_fma_f32 v[4:5], v[88:89], v[18:19], v[4:5] neg_lo:[1,0,0] neg_hi:[1,0,0]
	s_mov_b32 s2, 0x3d800000
	v_pk_fma_f32 v[4:5], v[4:5], v[20:21], v[84:85]
	v_pk_mul_f32 v[4:5], v[4:5], s[2:3] op_sel_hi:[1,0]
	v_pk_fma_f32 v[6:7], v[90:91], v[18:19], v[6:7]
	v_pk_fma_f32 v[6:7], v[6:7], v[20:21], v[86:87]
	v_pk_mul_f32 v[6:7], v[6:7], s[2:3] op_sel_hi:[1,0]
	v_cvt_pk_bf16_f32 v4, v4, v5
	v_pk_fma_f32 v[0:1], v[76:77], v[18:19], v[0:1] neg_lo:[1,0,0] neg_hi:[1,0,0]
	v_pk_fma_f32 v[0:1], v[0:1], v[20:21], v[72:73]
	v_pk_mul_f32 v[0:1], v[0:1], s[2:3] op_sel_hi:[1,0]
	v_cvt_pk_bf16_f32 v5, v6, v7
	v_pk_fma_f32 v[2:3], v[78:79], v[18:19], v[2:3]
	v_pk_fma_f32 v[2:3], v[2:3], v[20:21], v[74:75]
	v_pk_mul_f32 v[2:3], v[2:3], s[2:3] op_sel_hi:[1,0]
	v_cvt_pk_bf16_f32 v6, v0, v1
	v_cvt_pk_bf16_f32 v7, v2, v3
	global_store_dwordx4 v[16:17], v[4:7], off offset:256

.LBB0_541:
	v_mov_b32_e32 v154, v142
	v_mov_b32_e32 v138, v143
	s_lshl_b32 s2, s2, 8
	v_lshl_add_u32 v140, v138, 3, s61
	v_ashrrev_i32_e32 v141, 31, v140
	v_lshl_add_u64 v[138:139], v[140:141], 2, s[40:41]
	global_load_dwordx4 v[146:149], v[138:139], off
	global_load_dwordx4 v[150:153], v[138:139], off offset:16
	s_add_i32 s2, s2, s60
	v_add_u32_e32 v154, s2, v154
	v_ashrrev_i32_e32 v155, 31, v154
	v_readlane_b32 s2, v254, 57
	v_lshlrev_b64 v[154:155], 11, v[154:155]
	v_readlane_b32 s3, v254, 58
	s_andn2_b64 vcc, exec, s[38:39]
	s_waitcnt vmcnt(0)
	v_pk_add_f32 v[126:127], v[126:127], v[148:149]
	v_lshl_add_u64 v[154:155], s[2:3], 0, v[154:155]
	v_lshl_add_u64 v[140:141], v[140:141], 1, v[154:155]
	global_load_dwordx4 v[154:157], v[140:141], off offset:1536
	v_pk_add_f32 v[124:125], v[124:125], v[146:147]
	v_pk_add_f32 v[122:123], v[122:123], v[152:153]
	v_pk_add_f32 v[120:121], v[120:121], v[150:151]
	v_mul_f32_e32 v124, 0xbfb8aa3b, v124
	v_mul_f32_e32 v125, 0xbfb8aa3b, v125
	v_mul_f32_e32 v126, 0xbfb8aa3b, v126
	v_mul_f32_e32 v120, 0xbfb8aa3b, v120
	v_mul_f32_e32 v121, 0xbfb8aa3b, v121
	v_mul_f32_e32 v122, 0xbfb8aa3b, v122
	v_mul_f32_e32 v127, 0xbfb8aa3b, v127
	v_mul_f32_e32 v123, 0xbfb8aa3b, v123
	v_exp_f32_e32 v146, v124
	v_exp_f32_e32 v147, v125
	v_exp_f32_e32 v148, v126
	v_exp_f32_e32 v150, v120
	v_exp_f32_e32 v151, v121
	v_exp_f32_e32 v152, v122
	v_exp_f32_e32 v149, v127
	v_exp_f32_e32 v153, v123
	v_add_f32_e32 v146, 1.0, v146
	v_add_f32_e32 v147, 1.0, v147
	v_add_f32_e32 v150, 1.0, v150
	v_add_f32_e32 v151, 1.0, v151
	v_add_f32_e32 v149, 1.0, v149
	v_add_f32_e32 v153, 1.0, v153
	v_rcp_f32_e32 v146, v146
	v_rcp_f32_e32 v150, v150
	v_rcp_f32_e32 v149, v149
	v_rcp_f32_e32 v153, v153
	s_mov_b64 s[2:3], 0x8000
	s_waitcnt vmcnt(0)
	v_lshlrev_b32_e32 v121, 16, v155
	v_lshlrev_b32_e32 v120, 16, v154
	v_and_b32_e32 v123, 0xffff0000, v155
	v_and_b32_e32 v122, 0xffff0000, v154
	v_add_f32_e32 v154, 1.0, v148
	v_add_f32_e32 v155, 1.0, v152
	v_rcp_f32_e32 v148, v147
	v_rcp_f32_e32 v147, v154
	v_rcp_f32_e32 v152, v151
	v_rcp_f32_e32 v151, v155
	v_lshlrev_b32_e32 v125, 16, v157
	v_lshlrev_b32_e32 v124, 16, v156
	v_and_b32_e32 v127, 0xffff0000, v157
	v_and_b32_e32 v126, 0xffff0000, v156
	v_pk_mul_f32 v[120:121], v[146:147], v[120:121]
	v_pk_mul_f32 v[124:125], v[150:151], v[124:125]
	v_pk_mul_f32 v[122:123], v[148:149], v[122:123]
	v_pk_mul_f32 v[126:127], v[152:153], v[126:127]
	v_cvt_pk_bf16_f32 v120, v120, v122
	v_cvt_pk_bf16_f32 v121, v121, v123
	v_cvt_pk_bf16_f32 v123, v125, v127
	v_cvt_pk_bf16_f32 v122, v124, v126
	global_store_dwordx4 v[140:141], v[120:123], off offset:1536
	global_load_dwordx4 v[120:123], v[138:139], off offset:512
	global_load_dwordx4 v[124:127], v[138:139], off offset:528
	global_load_dwordx4 v[146:149], v[140:141], off offset:1792
	s_waitcnt vmcnt(0)
	v_pk_add_f32 v[118:119], v[118:119], v[122:123]
	v_pk_add_f32 v[116:117], v[116:117], v[120:121]
	v_pk_add_f32 v[114:115], v[114:115], v[126:127]
	v_pk_add_f32 v[112:113], v[112:113], v[124:125]
	v_mul_f32_e32 v116, 0xbfb8aa3b, v116
	v_mul_f32_e32 v117, 0xbfb8aa3b, v117
	v_mul_f32_e32 v118, 0xbfb8aa3b, v118
	v_mul_f32_e32 v112, 0xbfb8aa3b, v112
	v_mul_f32_e32 v114, 0xbfb8aa3b, v114
	v_mul_f32_e32 v119, 0xbfb8aa3b, v119
	v_mul_f32_e32 v113, 0xbfb8aa3b, v113
	v_mul_f32_e32 v115, 0xbfb8aa3b, v115
	v_exp_f32_e32 v116, v116
	v_exp_f32_e32 v117, v117
	v_exp_f32_e32 v118, v118
	v_exp_f32_e32 v112, v112
	v_exp_f32_e32 v114, v114
	v_exp_f32_e32 v119, v119
	v_exp_f32_e32 v113, v113
	v_exp_f32_e32 v115, v115
	v_lshlrev_b32_e32 v120, 16, v146
	v_and_b32_e32 v122, 0xffff0000, v146
	v_lshlrev_b32_e32 v124, 16, v148
	v_and_b32_e32 v126, 0xffff0000, v148
	v_add_f32_e32 v116, 1.0, v116
	v_add_f32_e32 v117, 1.0, v117
	v_add_f32_e32 v118, 1.0, v118
	v_add_f32_e32 v146, 1.0, v112
	v_add_f32_e32 v148, 1.0, v114
	v_lshlrev_b32_e32 v121, 16, v147
	v_and_b32_e32 v123, 0xffff0000, v147
	v_lshlrev_b32_e32 v125, 16, v149
	v_and_b32_e32 v127, 0xffff0000, v149
	v_add_f32_e32 v119, 1.0, v119
	v_add_f32_e32 v147, 1.0, v113
	v_add_f32_e32 v149, 1.0, v115
	v_rcp_f32_e32 v112, v116
	v_rcp_f32_e32 v114, v117
	v_rcp_f32_e32 v113, v118
	v_rcp_f32_e32 v116, v146
	v_rcp_f32_e32 v117, v148
	v_rcp_f32_e32 v115, v119
	v_rcp_f32_e32 v118, v147
	v_rcp_f32_e32 v119, v149
	v_pk_mul_f32 v[112:113], v[112:113], v[120:121]
	v_pk_mul_f32 v[116:117], v[116:117], v[124:125]
	v_pk_mul_f32 v[114:115], v[114:115], v[122:123]
	v_pk_mul_f32 v[118:119], v[118:119], v[126:127]
	v_cvt_pk_bf16_f32 v112, v112, v114
	v_cvt_pk_bf16_f32 v113, v113, v115
	v_cvt_pk_bf16_f32 v115, v117, v119
	v_cvt_pk_bf16_f32 v114, v116, v118
	global_store_dwordx4 v[140:141], v[112:115], off offset:1792
	global_load_dwordx4 v[114:117], v[138:139], off
	global_load_dwordx4 v[118:121], v[138:139], off offset:16
	v_lshl_add_u64 v[112:113], v[140:141], 0, s[2:3]
	global_load_dwordx4 v[122:125], v[112:113], off offset:1536
	s_mov_b64 s[2:3], 0x10000
	s_waitcnt vmcnt(0)
	v_pk_add_f32 v[110:111], v[110:111], v[116:117]
	v_pk_add_f32 v[108:109], v[108:109], v[114:115]
	v_pk_add_f32 v[106:107], v[106:107], v[120:121]
	v_pk_add_f32 v[104:105], v[104:105], v[118:119]
	v_mul_f32_e32 v108, 0xbfb8aa3b, v108
	v_mul_f32_e32 v109, 0xbfb8aa3b, v109
	v_mul_f32_e32 v110, 0xbfb8aa3b, v110
	v_mul_f32_e32 v104, 0xbfb8aa3b, v104
	v_mul_f32_e32 v106, 0xbfb8aa3b, v106
	v_mul_f32_e32 v111, 0xbfb8aa3b, v111
	v_mul_f32_e32 v105, 0xbfb8aa3b, v105
	v_mul_f32_e32 v107, 0xbfb8aa3b, v107
	v_exp_f32_e32 v108, v108
	v_exp_f32_e32 v109, v109
	v_exp_f32_e32 v110, v110
	v_exp_f32_e32 v104, v104
	v_exp_f32_e32 v106, v106
	v_exp_f32_e32 v111, v111
	v_exp_f32_e32 v105, v105
	v_exp_f32_e32 v107, v107
	v_lshlrev_b32_e32 v114, 16, v122
	v_and_b32_e32 v116, 0xffff0000, v122
	v_lshlrev_b32_e32 v118, 16, v124
	v_and_b32_e32 v120, 0xffff0000, v124
	v_add_f32_e32 v108, 1.0, v108
	v_add_f32_e32 v109, 1.0, v109
	v_add_f32_e32 v110, 1.0, v110
	v_add_f32_e32 v122, 1.0, v104
	v_add_f32_e32 v124, 1.0, v106
	v_lshlrev_b32_e32 v115, 16, v123
	v_and_b32_e32 v117, 0xffff0000, v123
	v_lshlrev_b32_e32 v119, 16, v125
	v_and_b32_e32 v121, 0xffff0000, v125
	v_add_f32_e32 v111, 1.0, v111
	v_add_f32_e32 v123, 1.0, v105
	v_add_f32_e32 v125, 1.0, v107
	v_rcp_f32_e32 v104, v108
	v_rcp_f32_e32 v106, v109
	v_rcp_f32_e32 v105, v110
	v_rcp_f32_e32 v108, v122
	v_rcp_f32_e32 v109, v124
	v_rcp_f32_e32 v107, v111
	v_rcp_f32_e32 v110, v123
	v_rcp_f32_e32 v111, v125
	v_pk_mul_f32 v[104:105], v[104:105], v[114:115]
	v_pk_mul_f32 v[108:109], v[108:109], v[118:119]
	v_pk_mul_f32 v[106:107], v[106:107], v[116:117]
	v_pk_mul_f32 v[110:111], v[110:111], v[120:121]
	v_cvt_pk_bf16_f32 v104, v104, v106
	v_cvt_pk_bf16_f32 v105, v105, v107
	v_cvt_pk_bf16_f32 v107, v109, v111
	v_cvt_pk_bf16_f32 v106, v108, v110
	global_store_dwordx4 v[112:113], v[104:107], off offset:1536
	global_load_dwordx4 v[104:107], v[138:139], off offset:512
	global_load_dwordx4 v[108:111], v[138:139], off offset:528
	global_load_dwordx4 v[114:117], v[112:113], off offset:1792
	s_waitcnt vmcnt(0)
	v_pk_add_f32 v[102:103], v[102:103], v[106:107]
	v_pk_add_f32 v[100:101], v[100:101], v[104:105]
	v_pk_add_f32 v[98:99], v[98:99], v[110:111]
	v_pk_add_f32 v[96:97], v[96:97], v[108:109]
	v_mul_f32_e32 v100, 0xbfb8aa3b, v100
	v_mul_f32_e32 v101, 0xbfb8aa3b, v101
	v_mul_f32_e32 v102, 0xbfb8aa3b, v102
	v_mul_f32_e32 v96, 0xbfb8aa3b, v96
	v_mul_f32_e32 v98, 0xbfb8aa3b, v98
	v_mul_f32_e32 v103, 0xbfb8aa3b, v103
	v_mul_f32_e32 v97, 0xbfb8aa3b, v97
	v_mul_f32_e32 v99, 0xbfb8aa3b, v99
	v_exp_f32_e32 v100, v100
	v_exp_f32_e32 v101, v101
	v_exp_f32_e32 v102, v102
	v_exp_f32_e32 v96, v96
	v_exp_f32_e32 v98, v98
	v_exp_f32_e32 v103, v103
	v_exp_f32_e32 v97, v97
	v_exp_f32_e32 v99, v99
	v_lshlrev_b32_e32 v104, 16, v114
	v_and_b32_e32 v106, 0xffff0000, v114
	v_lshlrev_b32_e32 v108, 16, v116
	v_and_b32_e32 v110, 0xffff0000, v116
	v_add_f32_e32 v100, 1.0, v100
	v_add_f32_e32 v101, 1.0, v101
	v_add_f32_e32 v102, 1.0, v102
	v_add_f32_e32 v114, 1.0, v96
	v_add_f32_e32 v116, 1.0, v98
	v_lshlrev_b32_e32 v105, 16, v115
	v_and_b32_e32 v107, 0xffff0000, v115
	v_lshlrev_b32_e32 v109, 16, v117
	v_and_b32_e32 v111, 0xffff0000, v117
	v_add_f32_e32 v103, 1.0, v103
	v_add_f32_e32 v115, 1.0, v97
	v_add_f32_e32 v117, 1.0, v99
	v_rcp_f32_e32 v96, v100
	v_rcp_f32_e32 v98, v101
	v_rcp_f32_e32 v97, v102
	v_rcp_f32_e32 v100, v114
	v_rcp_f32_e32 v101, v116
	v_rcp_f32_e32 v99, v103
	v_rcp_f32_e32 v102, v115
	v_rcp_f32_e32 v103, v117
	v_pk_mul_f32 v[96:97], v[96:97], v[104:105]
	v_pk_mul_f32 v[100:101], v[100:101], v[108:109]
	v_pk_mul_f32 v[98:99], v[98:99], v[106:107]
	v_pk_mul_f32 v[102:103], v[102:103], v[110:111]
	v_cvt_pk_bf16_f32 v96, v96, v98
	v_cvt_pk_bf16_f32 v97, v97, v99
	v_cvt_pk_bf16_f32 v99, v101, v103
	v_cvt_pk_bf16_f32 v98, v100, v102
	global_store_dwordx4 v[112:113], v[96:99], off offset:1792
	global_load_dwordx4 v[98:101], v[138:139], off
	global_load_dwordx4 v[102:105], v[138:139], off offset:16
	v_lshl_add_u64 v[96:97], v[140:141], 0, s[2:3]
	global_load_dwordx4 v[106:109], v[96:97], off offset:1536
	s_mov_b64 s[2:3], 0x18000
	s_waitcnt vmcnt(0)
	v_pk_add_f32 v[94:95], v[94:95], v[100:101]
	v_pk_add_f32 v[92:93], v[92:93], v[98:99]
	v_pk_add_f32 v[90:91], v[90:91], v[104:105]
	v_pk_add_f32 v[88:89], v[88:89], v[102:103]
	v_mul_f32_e32 v92, 0xbfb8aa3b, v92
	v_mul_f32_e32 v93, 0xbfb8aa3b, v93
	v_mul_f32_e32 v94, 0xbfb8aa3b, v94
	v_mul_f32_e32 v88, 0xbfb8aa3b, v88
	v_mul_f32_e32 v90, 0xbfb8aa3b, v90
	v_mul_f32_e32 v95, 0xbfb8aa3b, v95
	v_mul_f32_e32 v89, 0xbfb8aa3b, v89
	v_mul_f32_e32 v91, 0xbfb8aa3b, v91
	v_exp_f32_e32 v92, v92
	v_exp_f32_e32 v93, v93
	v_exp_f32_e32 v94, v94
	v_exp_f32_e32 v88, v88
	v_exp_f32_e32 v90, v90
	v_exp_f32_e32 v95, v95
	v_exp_f32_e32 v89, v89
	v_exp_f32_e32 v91, v91
	v_lshlrev_b32_e32 v98, 16, v106
	v_and_b32_e32 v100, 0xffff0000, v106
	v_lshlrev_b32_e32 v102, 16, v108
	v_and_b32_e32 v104, 0xffff0000, v108
	v_add_f32_e32 v92, 1.0, v92
	v_add_f32_e32 v93, 1.0, v93
	v_add_f32_e32 v94, 1.0, v94
	v_add_f32_e32 v106, 1.0, v88
	v_add_f32_e32 v108, 1.0, v90
	v_lshlrev_b32_e32 v99, 16, v107
	v_and_b32_e32 v101, 0xffff0000, v107
	v_lshlrev_b32_e32 v103, 16, v109
	v_and_b32_e32 v105, 0xffff0000, v109
	v_add_f32_e32 v95, 1.0, v95
	v_add_f32_e32 v107, 1.0, v89
	v_add_f32_e32 v109, 1.0, v91
	v_rcp_f32_e32 v88, v92
	v_rcp_f32_e32 v90, v93
	v_rcp_f32_e32 v89, v94
	v_rcp_f32_e32 v92, v106
	v_rcp_f32_e32 v93, v108
	v_rcp_f32_e32 v91, v95
	v_rcp_f32_e32 v94, v107
	v_rcp_f32_e32 v95, v109
	v_pk_mul_f32 v[88:89], v[88:89], v[98:99]
	v_pk_mul_f32 v[92:93], v[92:93], v[102:103]
	v_pk_mul_f32 v[90:91], v[90:91], v[100:101]
	v_pk_mul_f32 v[94:95], v[94:95], v[104:105]
	v_cvt_pk_bf16_f32 v88, v88, v90
	v_cvt_pk_bf16_f32 v89, v89, v91
	v_cvt_pk_bf16_f32 v91, v93, v95
	v_cvt_pk_bf16_f32 v90, v92, v94
	global_store_dwordx4 v[96:97], v[88:91], off offset:1536
	global_load_dwordx4 v[88:91], v[138:139], off offset:512
	global_load_dwordx4 v[92:95], v[138:139], off offset:528
	global_load_dwordx4 v[98:101], v[96:97], off offset:1792
	s_waitcnt vmcnt(0)
	v_pk_add_f32 v[86:87], v[86:87], v[90:91]
	v_pk_add_f32 v[84:85], v[84:85], v[88:89]
	v_pk_add_f32 v[82:83], v[82:83], v[94:95]
	v_pk_add_f32 v[80:81], v[80:81], v[92:93]
	v_mul_f32_e32 v84, 0xbfb8aa3b, v84
	v_mul_f32_e32 v85, 0xbfb8aa3b, v85
	v_mul_f32_e32 v86, 0xbfb8aa3b, v86
	v_mul_f32_e32 v80, 0xbfb8aa3b, v80
	v_mul_f32_e32 v82, 0xbfb8aa3b, v82
	v_mul_f32_e32 v87, 0xbfb8aa3b, v87
	v_mul_f32_e32 v81, 0xbfb8aa3b, v81
	v_mul_f32_e32 v83, 0xbfb8aa3b, v83
	v_exp_f32_e32 v84, v84
	v_exp_f32_e32 v85, v85
	v_exp_f32_e32 v86, v86
	v_exp_f32_e32 v80, v80
	v_exp_f32_e32 v82, v82
	v_exp_f32_e32 v87, v87
	v_exp_f32_e32 v81, v81
	v_exp_f32_e32 v83, v83
	v_lshlrev_b32_e32 v88, 16, v98
	v_and_b32_e32 v90, 0xffff0000, v98
	v_lshlrev_b32_e32 v92, 16, v100
	v_and_b32_e32 v94, 0xffff0000, v100
	v_add_f32_e32 v84, 1.0, v84
	v_add_f32_e32 v85, 1.0, v85
	v_add_f32_e32 v86, 1.0, v86
	v_add_f32_e32 v98, 1.0, v80
	v_add_f32_e32 v100, 1.0, v82
	v_lshlrev_b32_e32 v89, 16, v99
	v_and_b32_e32 v91, 0xffff0000, v99
	v_lshlrev_b32_e32 v93, 16, v101
	v_and_b32_e32 v95, 0xffff0000, v101
	v_add_f32_e32 v87, 1.0, v87
	v_add_f32_e32 v99, 1.0, v81
	v_add_f32_e32 v101, 1.0, v83
	v_rcp_f32_e32 v80, v84
	v_rcp_f32_e32 v82, v85
	v_rcp_f32_e32 v81, v86
	v_rcp_f32_e32 v84, v98
	v_rcp_f32_e32 v85, v100
	v_rcp_f32_e32 v83, v87
	v_rcp_f32_e32 v86, v99
	v_rcp_f32_e32 v87, v101
	v_pk_mul_f32 v[80:81], v[80:81], v[88:89]
	v_pk_mul_f32 v[84:85], v[84:85], v[92:93]
	v_pk_mul_f32 v[82:83], v[82:83], v[90:91]
	v_pk_mul_f32 v[86:87], v[86:87], v[94:95]
	v_cvt_pk_bf16_f32 v80, v80, v82
	v_cvt_pk_bf16_f32 v81, v81, v83
	v_cvt_pk_bf16_f32 v83, v85, v87
	v_cvt_pk_bf16_f32 v82, v84, v86
	global_store_dwordx4 v[96:97], v[80:83], off offset:1792
	global_load_dwordx4 v[82:85], v[138:139], off
	global_load_dwordx4 v[86:89], v[138:139], off offset:16
	v_lshl_add_u64 v[80:81], v[140:141], 0, s[2:3]
	global_load_dwordx4 v[90:93], v[80:81], off offset:1536
	s_mov_b64 s[2:3], 0x40000
	s_waitcnt vmcnt(0)
	v_pk_add_f32 v[78:79], v[78:79], v[84:85]
	v_pk_add_f32 v[76:77], v[76:77], v[82:83]
	v_pk_add_f32 v[74:75], v[74:75], v[88:89]
	v_pk_add_f32 v[72:73], v[72:73], v[86:87]
	v_mul_f32_e32 v76, 0xbfb8aa3b, v76
	v_mul_f32_e32 v77, 0xbfb8aa3b, v77
	v_mul_f32_e32 v78, 0xbfb8aa3b, v78
	v_mul_f32_e32 v72, 0xbfb8aa3b, v72
	v_mul_f32_e32 v74, 0xbfb8aa3b, v74
	v_mul_f32_e32 v79, 0xbfb8aa3b, v79
	v_mul_f32_e32 v73, 0xbfb8aa3b, v73
	v_mul_f32_e32 v75, 0xbfb8aa3b, v75
	v_exp_f32_e32 v76, v76
	v_exp_f32_e32 v77, v77
	v_exp_f32_e32 v78, v78
	v_exp_f32_e32 v72, v72
	v_exp_f32_e32 v74, v74
	v_exp_f32_e32 v79, v79
	v_exp_f32_e32 v73, v73
	v_exp_f32_e32 v75, v75
	v_lshlrev_b32_e32 v82, 16, v90
	v_and_b32_e32 v84, 0xffff0000, v90
	v_lshlrev_b32_e32 v86, 16, v92
	v_and_b32_e32 v88, 0xffff0000, v92
	v_add_f32_e32 v76, 1.0, v76
	v_add_f32_e32 v77, 1.0, v77
	v_add_f32_e32 v78, 1.0, v78
	v_add_f32_e32 v90, 1.0, v72
	v_add_f32_e32 v92, 1.0, v74
	v_lshlrev_b32_e32 v83, 16, v91
	v_and_b32_e32 v85, 0xffff0000, v91
	v_lshlrev_b32_e32 v87, 16, v93
	v_and_b32_e32 v89, 0xffff0000, v93
	v_add_f32_e32 v79, 1.0, v79
	v_add_f32_e32 v91, 1.0, v73
	v_add_f32_e32 v93, 1.0, v75
	v_rcp_f32_e32 v72, v76
	v_rcp_f32_e32 v74, v77
	v_rcp_f32_e32 v73, v78
	v_rcp_f32_e32 v76, v90
	v_rcp_f32_e32 v77, v92
	v_rcp_f32_e32 v75, v79
	v_rcp_f32_e32 v78, v91
	v_rcp_f32_e32 v79, v93
	v_pk_mul_f32 v[72:73], v[72:73], v[82:83]
	v_pk_mul_f32 v[76:77], v[76:77], v[86:87]
	v_pk_mul_f32 v[74:75], v[74:75], v[84:85]
	v_pk_mul_f32 v[78:79], v[78:79], v[88:89]
	v_cvt_pk_bf16_f32 v72, v72, v74
	v_cvt_pk_bf16_f32 v73, v73, v75
	v_cvt_pk_bf16_f32 v75, v77, v79
	v_cvt_pk_bf16_f32 v74, v76, v78
	global_store_dwordx4 v[80:81], v[72:75], off offset:1536
	global_load_dwordx4 v[72:75], v[138:139], off offset:512
	global_load_dwordx4 v[76:79], v[138:139], off offset:528
	global_load_dwordx4 v[82:85], v[80:81], off offset:1792
	s_waitcnt vmcnt(0)
	v_pk_add_f32 v[70:71], v[70:71], v[74:75]
	v_pk_add_f32 v[68:69], v[68:69], v[72:73]
	v_pk_add_f32 v[66:67], v[66:67], v[78:79]
	v_pk_add_f32 v[64:65], v[64:65], v[76:77]
	v_mul_f32_e32 v68, 0xbfb8aa3b, v68
	v_mul_f32_e32 v69, 0xbfb8aa3b, v69
	v_mul_f32_e32 v70, 0xbfb8aa3b, v70
	v_mul_f32_e32 v64, 0xbfb8aa3b, v64
	v_mul_f32_e32 v66, 0xbfb8aa3b, v66
	v_mul_f32_e32 v71, 0xbfb8aa3b, v71
	v_mul_f32_e32 v65, 0xbfb8aa3b, v65
	v_mul_f32_e32 v67, 0xbfb8aa3b, v67
	v_exp_f32_e32 v68, v68
	v_exp_f32_e32 v69, v69
	v_exp_f32_e32 v70, v70
	v_exp_f32_e32 v64, v64
	v_exp_f32_e32 v66, v66
	v_exp_f32_e32 v71, v71
	v_exp_f32_e32 v65, v65
	v_exp_f32_e32 v67, v67
	v_lshlrev_b32_e32 v72, 16, v82
	v_and_b32_e32 v74, 0xffff0000, v82
	v_lshlrev_b32_e32 v76, 16, v84
	v_and_b32_e32 v78, 0xffff0000, v84
	v_add_f32_e32 v68, 1.0, v68
	v_add_f32_e32 v69, 1.0, v69
	v_add_f32_e32 v70, 1.0, v70
	v_add_f32_e32 v82, 1.0, v64
	v_add_f32_e32 v84, 1.0, v66
	v_lshlrev_b32_e32 v73, 16, v83
	v_and_b32_e32 v75, 0xffff0000, v83
	v_lshlrev_b32_e32 v77, 16, v85
	v_and_b32_e32 v79, 0xffff0000, v85
	v_add_f32_e32 v71, 1.0, v71
	v_add_f32_e32 v83, 1.0, v65
	v_add_f32_e32 v85, 1.0, v67
	v_rcp_f32_e32 v64, v68
	v_rcp_f32_e32 v66, v69
	v_rcp_f32_e32 v65, v70
	v_rcp_f32_e32 v68, v82
	v_rcp_f32_e32 v69, v84
	v_rcp_f32_e32 v67, v71
	v_rcp_f32_e32 v70, v83
	v_rcp_f32_e32 v71, v85
	v_pk_mul_f32 v[64:65], v[64:65], v[72:73]
	v_pk_mul_f32 v[68:69], v[68:69], v[76:77]
	v_pk_mul_f32 v[66:67], v[66:67], v[74:75]
	v_pk_mul_f32 v[70:71], v[70:71], v[78:79]
	v_cvt_pk_bf16_f32 v64, v64, v66
	v_cvt_pk_bf16_f32 v65, v65, v67
	v_cvt_pk_bf16_f32 v67, v69, v71
	v_cvt_pk_bf16_f32 v66, v68, v70
	global_store_dwordx4 v[80:81], v[64:67], off offset:1792
	global_load_dwordx4 v[66:69], v[138:139], off
	global_load_dwordx4 v[70:73], v[138:139], off offset:16
	v_lshl_add_u64 v[64:65], v[140:141], 0, s[2:3]
	global_load_dwordx4 v[74:77], v[64:65], off offset:1536
	s_mov_b64 s[2:3], 0x48000
	s_waitcnt vmcnt(0)
	v_pk_add_f32 v[62:63], v[62:63], v[68:69]
	v_pk_add_f32 v[60:61], v[60:61], v[66:67]
	v_pk_add_f32 v[58:59], v[58:59], v[72:73]
	v_pk_add_f32 v[56:57], v[56:57], v[70:71]
	v_mul_f32_e32 v60, 0xbfb8aa3b, v60
	v_mul_f32_e32 v61, 0xbfb8aa3b, v61
	v_mul_f32_e32 v62, 0xbfb8aa3b, v62
	v_mul_f32_e32 v56, 0xbfb8aa3b, v56
	v_mul_f32_e32 v58, 0xbfb8aa3b, v58
	v_mul_f32_e32 v63, 0xbfb8aa3b, v63
	v_mul_f32_e32 v57, 0xbfb8aa3b, v57
	v_mul_f32_e32 v59, 0xbfb8aa3b, v59
	v_exp_f32_e32 v60, v60
	v_exp_f32_e32 v61, v61
	v_exp_f32_e32 v62, v62
	v_exp_f32_e32 v56, v56
	v_exp_f32_e32 v58, v58
	v_exp_f32_e32 v63, v63
	v_exp_f32_e32 v57, v57
	v_exp_f32_e32 v59, v59
	v_lshlrev_b32_e32 v66, 16, v74
	v_and_b32_e32 v68, 0xffff0000, v74
	v_lshlrev_b32_e32 v70, 16, v76
	v_and_b32_e32 v72, 0xffff0000, v76
	v_add_f32_e32 v60, 1.0, v60
	v_add_f32_e32 v61, 1.0, v61
	v_add_f32_e32 v62, 1.0, v62
	v_add_f32_e32 v74, 1.0, v56
	v_add_f32_e32 v76, 1.0, v58
	v_lshlrev_b32_e32 v67, 16, v75
	v_and_b32_e32 v69, 0xffff0000, v75
	v_lshlrev_b32_e32 v71, 16, v77
	v_and_b32_e32 v73, 0xffff0000, v77
	v_add_f32_e32 v63, 1.0, v63
	v_add_f32_e32 v75, 1.0, v57
	v_add_f32_e32 v77, 1.0, v59
	v_rcp_f32_e32 v56, v60
	v_rcp_f32_e32 v58, v61
	v_rcp_f32_e32 v57, v62
	v_rcp_f32_e32 v60, v74
	v_rcp_f32_e32 v61, v76
	v_rcp_f32_e32 v59, v63
	v_rcp_f32_e32 v62, v75
	v_rcp_f32_e32 v63, v77
	v_pk_mul_f32 v[56:57], v[56:57], v[66:67]
	v_pk_mul_f32 v[60:61], v[60:61], v[70:71]
	v_pk_mul_f32 v[58:59], v[58:59], v[68:69]
	v_pk_mul_f32 v[62:63], v[62:63], v[72:73]
	v_cvt_pk_bf16_f32 v56, v56, v58
	v_cvt_pk_bf16_f32 v57, v57, v59
	v_cvt_pk_bf16_f32 v59, v61, v63
	v_cvt_pk_bf16_f32 v58, v60, v62
	global_store_dwordx4 v[64:65], v[56:59], off offset:1536
	global_load_dwordx4 v[56:59], v[138:139], off offset:512
	global_load_dwordx4 v[60:63], v[138:139], off offset:528
	global_load_dwordx4 v[66:69], v[64:65], off offset:1792
	s_waitcnt vmcnt(0)
	v_pk_add_f32 v[54:55], v[54:55], v[58:59]
	v_pk_add_f32 v[52:53], v[52:53], v[56:57]
	v_pk_add_f32 v[50:51], v[50:51], v[62:63]
	v_pk_add_f32 v[48:49], v[48:49], v[60:61]
	v_mul_f32_e32 v52, 0xbfb8aa3b, v52
	v_mul_f32_e32 v53, 0xbfb8aa3b, v53
	v_mul_f32_e32 v54, 0xbfb8aa3b, v54
	v_mul_f32_e32 v48, 0xbfb8aa3b, v48
	v_mul_f32_e32 v50, 0xbfb8aa3b, v50
	v_mul_f32_e32 v55, 0xbfb8aa3b, v55
	v_mul_f32_e32 v49, 0xbfb8aa3b, v49
	v_mul_f32_e32 v51, 0xbfb8aa3b, v51
	v_exp_f32_e32 v52, v52
	v_exp_f32_e32 v53, v53
	v_exp_f32_e32 v54, v54
	v_exp_f32_e32 v48, v48
	v_exp_f32_e32 v50, v50
	v_exp_f32_e32 v55, v55
	v_exp_f32_e32 v49, v49
	v_exp_f32_e32 v51, v51
	v_lshlrev_b32_e32 v56, 16, v66
	v_and_b32_e32 v58, 0xffff0000, v66
	v_lshlrev_b32_e32 v60, 16, v68
	v_and_b32_e32 v62, 0xffff0000, v68
	v_add_f32_e32 v52, 1.0, v52
	v_add_f32_e32 v53, 1.0, v53
	v_add_f32_e32 v54, 1.0, v54
	v_add_f32_e32 v66, 1.0, v48
	v_add_f32_e32 v68, 1.0, v50
	v_lshlrev_b32_e32 v57, 16, v67
	v_and_b32_e32 v59, 0xffff0000, v67
	v_lshlrev_b32_e32 v61, 16, v69
	v_and_b32_e32 v63, 0xffff0000, v69
	v_add_f32_e32 v55, 1.0, v55
	v_add_f32_e32 v67, 1.0, v49
	v_add_f32_e32 v69, 1.0, v51
	v_rcp_f32_e32 v48, v52
	v_rcp_f32_e32 v50, v53
	v_rcp_f32_e32 v49, v54
	v_rcp_f32_e32 v52, v66
	v_rcp_f32_e32 v53, v68
	v_rcp_f32_e32 v51, v55
	v_rcp_f32_e32 v54, v67
	v_rcp_f32_e32 v55, v69
	v_pk_mul_f32 v[48:49], v[48:49], v[56:57]
	v_pk_mul_f32 v[52:53], v[52:53], v[60:61]
	v_pk_mul_f32 v[50:51], v[50:51], v[58:59]
	v_pk_mul_f32 v[54:55], v[54:55], v[62:63]
	v_cvt_pk_bf16_f32 v48, v48, v50
	v_cvt_pk_bf16_f32 v49, v49, v51
	v_cvt_pk_bf16_f32 v51, v53, v55
	v_cvt_pk_bf16_f32 v50, v52, v54
	global_store_dwordx4 v[64:65], v[48:51], off offset:1792
	global_load_dwordx4 v[50:53], v[138:139], off
	global_load_dwordx4 v[54:57], v[138:139], off offset:16
	v_lshl_add_u64 v[48:49], v[140:141], 0, s[2:3]
	global_load_dwordx4 v[58:61], v[48:49], off offset:1536
	s_mov_b64 s[2:3], 0x50000
	s_waitcnt vmcnt(0)
	v_pk_add_f32 v[46:47], v[46:47], v[52:53]
	v_pk_add_f32 v[44:45], v[44:45], v[50:51]
	v_pk_add_f32 v[42:43], v[42:43], v[56:57]
	v_pk_add_f32 v[40:41], v[40:41], v[54:55]
	v_mul_f32_e32 v44, 0xbfb8aa3b, v44
	v_mul_f32_e32 v45, 0xbfb8aa3b, v45
	v_mul_f32_e32 v46, 0xbfb8aa3b, v46
	v_mul_f32_e32 v40, 0xbfb8aa3b, v40
	v_mul_f32_e32 v42, 0xbfb8aa3b, v42
	v_mul_f32_e32 v47, 0xbfb8aa3b, v47
	v_mul_f32_e32 v41, 0xbfb8aa3b, v41
	v_mul_f32_e32 v43, 0xbfb8aa3b, v43
	v_exp_f32_e32 v44, v44
	v_exp_f32_e32 v45, v45
	v_exp_f32_e32 v46, v46
	v_exp_f32_e32 v40, v40
	v_exp_f32_e32 v42, v42
	v_exp_f32_e32 v47, v47
	v_exp_f32_e32 v41, v41
	v_exp_f32_e32 v43, v43
	v_lshlrev_b32_e32 v50, 16, v58
	v_and_b32_e32 v52, 0xffff0000, v58
	v_lshlrev_b32_e32 v54, 16, v60
	v_and_b32_e32 v56, 0xffff0000, v60
	v_add_f32_e32 v44, 1.0, v44
	v_add_f32_e32 v45, 1.0, v45
	v_add_f32_e32 v46, 1.0, v46
	v_add_f32_e32 v58, 1.0, v40
	v_add_f32_e32 v60, 1.0, v42
	v_lshlrev_b32_e32 v51, 16, v59
	v_and_b32_e32 v53, 0xffff0000, v59
	v_lshlrev_b32_e32 v55, 16, v61
	v_and_b32_e32 v57, 0xffff0000, v61
	v_add_f32_e32 v47, 1.0, v47
	v_add_f32_e32 v59, 1.0, v41
	v_add_f32_e32 v61, 1.0, v43
	v_rcp_f32_e32 v40, v44
	v_rcp_f32_e32 v42, v45
	v_rcp_f32_e32 v41, v46
	v_rcp_f32_e32 v44, v58
	v_rcp_f32_e32 v45, v60
	v_rcp_f32_e32 v43, v47
	v_rcp_f32_e32 v46, v59
	v_rcp_f32_e32 v47, v61
	v_pk_mul_f32 v[40:41], v[40:41], v[50:51]
	v_pk_mul_f32 v[44:45], v[44:45], v[54:55]
	v_pk_mul_f32 v[42:43], v[42:43], v[52:53]
	v_pk_mul_f32 v[46:47], v[46:47], v[56:57]
	v_cvt_pk_bf16_f32 v40, v40, v42
	v_cvt_pk_bf16_f32 v41, v41, v43
	v_cvt_pk_bf16_f32 v43, v45, v47
	v_cvt_pk_bf16_f32 v42, v44, v46
	global_store_dwordx4 v[48:49], v[40:43], off offset:1536
	global_load_dwordx4 v[40:43], v[138:139], off offset:512
	global_load_dwordx4 v[44:47], v[138:139], off offset:528
	global_load_dwordx4 v[50:53], v[48:49], off offset:1792
	s_waitcnt vmcnt(0)
	v_pk_add_f32 v[38:39], v[38:39], v[42:43]
	v_pk_add_f32 v[36:37], v[36:37], v[40:41]
	v_pk_add_f32 v[34:35], v[34:35], v[46:47]
	v_pk_add_f32 v[32:33], v[32:33], v[44:45]
	v_mul_f32_e32 v36, 0xbfb8aa3b, v36
	v_mul_f32_e32 v37, 0xbfb8aa3b, v37
	v_mul_f32_e32 v38, 0xbfb8aa3b, v38
	v_mul_f32_e32 v32, 0xbfb8aa3b, v32
	v_mul_f32_e32 v34, 0xbfb8aa3b, v34
	v_mul_f32_e32 v39, 0xbfb8aa3b, v39
	v_mul_f32_e32 v33, 0xbfb8aa3b, v33
	v_mul_f32_e32 v35, 0xbfb8aa3b, v35
	v_exp_f32_e32 v36, v36
	v_exp_f32_e32 v37, v37
	v_exp_f32_e32 v38, v38
	v_exp_f32_e32 v32, v32
	v_exp_f32_e32 v34, v34
	v_exp_f32_e32 v39, v39
	v_exp_f32_e32 v33, v33
	v_exp_f32_e32 v35, v35
	v_lshlrev_b32_e32 v40, 16, v50
	v_and_b32_e32 v42, 0xffff0000, v50
	v_lshlrev_b32_e32 v44, 16, v52
	v_and_b32_e32 v46, 0xffff0000, v52
	v_add_f32_e32 v36, 1.0, v36
	v_add_f32_e32 v37, 1.0, v37
	v_add_f32_e32 v38, 1.0, v38
	v_add_f32_e32 v50, 1.0, v32
	v_add_f32_e32 v52, 1.0, v34
	v_lshlrev_b32_e32 v41, 16, v51
	v_and_b32_e32 v43, 0xffff0000, v51
	v_lshlrev_b32_e32 v45, 16, v53
	v_and_b32_e32 v47, 0xffff0000, v53
	v_add_f32_e32 v39, 1.0, v39
	v_add_f32_e32 v51, 1.0, v33
	v_add_f32_e32 v53, 1.0, v35
	v_rcp_f32_e32 v32, v36
	v_rcp_f32_e32 v34, v37
	v_rcp_f32_e32 v33, v38
	v_rcp_f32_e32 v36, v50
	v_rcp_f32_e32 v37, v52
	v_rcp_f32_e32 v35, v39
	v_rcp_f32_e32 v38, v51
	v_rcp_f32_e32 v39, v53
	v_pk_mul_f32 v[32:33], v[32:33], v[40:41]
	v_pk_mul_f32 v[36:37], v[36:37], v[44:45]
	v_pk_mul_f32 v[34:35], v[34:35], v[42:43]
	v_pk_mul_f32 v[38:39], v[38:39], v[46:47]
	v_cvt_pk_bf16_f32 v32, v32, v34
	v_cvt_pk_bf16_f32 v33, v33, v35
	v_cvt_pk_bf16_f32 v35, v37, v39
	v_cvt_pk_bf16_f32 v34, v36, v38
	global_store_dwordx4 v[48:49], v[32:35], off offset:1792
	global_load_dwordx4 v[34:37], v[138:139], off
	global_load_dwordx4 v[38:41], v[138:139], off offset:16
	v_lshl_add_u64 v[32:33], v[140:141], 0, s[2:3]
	global_load_dwordx4 v[42:45], v[32:33], off offset:1536
	s_mov_b64 s[2:3], 0x58000
	s_waitcnt vmcnt(0)
	v_pk_add_f32 v[30:31], v[30:31], v[36:37]
	v_pk_add_f32 v[28:29], v[28:29], v[34:35]
	v_pk_add_f32 v[26:27], v[26:27], v[40:41]
	v_pk_add_f32 v[24:25], v[24:25], v[38:39]
	v_mul_f32_e32 v28, 0xbfb8aa3b, v28
	v_mul_f32_e32 v29, 0xbfb8aa3b, v29
	v_mul_f32_e32 v30, 0xbfb8aa3b, v30
	v_mul_f32_e32 v24, 0xbfb8aa3b, v24
	v_mul_f32_e32 v26, 0xbfb8aa3b, v26
	v_mul_f32_e32 v31, 0xbfb8aa3b, v31
	v_mul_f32_e32 v25, 0xbfb8aa3b, v25
	v_mul_f32_e32 v27, 0xbfb8aa3b, v27
	v_exp_f32_e32 v28, v28
	v_exp_f32_e32 v29, v29
	v_exp_f32_e32 v30, v30
	v_exp_f32_e32 v24, v24
	v_exp_f32_e32 v26, v26
	v_exp_f32_e32 v31, v31
	v_exp_f32_e32 v25, v25
	v_exp_f32_e32 v27, v27
	v_lshlrev_b32_e32 v34, 16, v42
	v_and_b32_e32 v36, 0xffff0000, v42
	v_lshlrev_b32_e32 v38, 16, v44
	v_and_b32_e32 v40, 0xffff0000, v44
	v_add_f32_e32 v28, 1.0, v28
	v_add_f32_e32 v29, 1.0, v29
	v_add_f32_e32 v30, 1.0, v30
	v_add_f32_e32 v42, 1.0, v24
	v_add_f32_e32 v44, 1.0, v26
	v_lshlrev_b32_e32 v35, 16, v43
	v_and_b32_e32 v37, 0xffff0000, v43
	v_lshlrev_b32_e32 v39, 16, v45
	v_and_b32_e32 v41, 0xffff0000, v45
	v_add_f32_e32 v31, 1.0, v31
	v_add_f32_e32 v43, 1.0, v25
	v_add_f32_e32 v45, 1.0, v27
	v_rcp_f32_e32 v24, v28
	v_rcp_f32_e32 v26, v29
	v_rcp_f32_e32 v25, v30
	v_rcp_f32_e32 v28, v42
	v_rcp_f32_e32 v29, v44
	v_rcp_f32_e32 v27, v31
	v_rcp_f32_e32 v30, v43
	v_rcp_f32_e32 v31, v45
	v_pk_mul_f32 v[24:25], v[24:25], v[34:35]
	v_pk_mul_f32 v[28:29], v[28:29], v[38:39]
	v_pk_mul_f32 v[26:27], v[26:27], v[36:37]
	v_pk_mul_f32 v[30:31], v[30:31], v[40:41]
	v_cvt_pk_bf16_f32 v24, v24, v26
	v_cvt_pk_bf16_f32 v25, v25, v27
	v_cvt_pk_bf16_f32 v27, v29, v31
	v_cvt_pk_bf16_f32 v26, v28, v30
	global_store_dwordx4 v[32:33], v[24:27], off offset:1536
	global_load_dwordx4 v[24:27], v[138:139], off offset:512
	global_load_dwordx4 v[28:31], v[138:139], off offset:528
	global_load_dwordx4 v[34:37], v[32:33], off offset:1792
	s_waitcnt vmcnt(0)
	v_pk_add_f32 v[22:23], v[22:23], v[26:27]
	v_pk_add_f32 v[20:21], v[20:21], v[24:25]
	v_pk_add_f32 v[18:19], v[18:19], v[30:31]
	v_pk_add_f32 v[16:17], v[16:17], v[28:29]
	v_mul_f32_e32 v20, 0xbfb8aa3b, v20
	v_mul_f32_e32 v21, 0xbfb8aa3b, v21
	v_mul_f32_e32 v22, 0xbfb8aa3b, v22
	v_mul_f32_e32 v16, 0xbfb8aa3b, v16
	v_mul_f32_e32 v18, 0xbfb8aa3b, v18
	v_mul_f32_e32 v23, 0xbfb8aa3b, v23
	v_mul_f32_e32 v17, 0xbfb8aa3b, v17
	v_mul_f32_e32 v19, 0xbfb8aa3b, v19
	v_exp_f32_e32 v20, v20
	v_exp_f32_e32 v21, v21
	v_exp_f32_e32 v22, v22
	v_exp_f32_e32 v16, v16
	v_exp_f32_e32 v18, v18
	v_exp_f32_e32 v23, v23
	v_exp_f32_e32 v17, v17
	v_exp_f32_e32 v19, v19
	v_lshlrev_b32_e32 v24, 16, v34
	v_and_b32_e32 v26, 0xffff0000, v34
	v_lshlrev_b32_e32 v28, 16, v36
	v_and_b32_e32 v30, 0xffff0000, v36
	v_add_f32_e32 v20, 1.0, v20
	v_add_f32_e32 v21, 1.0, v21
	v_add_f32_e32 v22, 1.0, v22
	v_add_f32_e32 v34, 1.0, v16
	v_add_f32_e32 v36, 1.0, v18
	v_lshlrev_b32_e32 v25, 16, v35
	v_and_b32_e32 v27, 0xffff0000, v35
	v_lshlrev_b32_e32 v29, 16, v37
	v_and_b32_e32 v31, 0xffff0000, v37
	v_add_f32_e32 v23, 1.0, v23
	v_add_f32_e32 v35, 1.0, v17
	v_add_f32_e32 v37, 1.0, v19
	v_rcp_f32_e32 v16, v20
	v_rcp_f32_e32 v18, v21
	v_rcp_f32_e32 v17, v22
	v_rcp_f32_e32 v20, v34
	v_rcp_f32_e32 v21, v36
	v_rcp_f32_e32 v19, v23
	v_rcp_f32_e32 v22, v35
	v_rcp_f32_e32 v23, v37
	v_pk_mul_f32 v[16:17], v[16:17], v[24:25]
	v_pk_mul_f32 v[20:21], v[20:21], v[28:29]
	v_pk_mul_f32 v[18:19], v[18:19], v[26:27]
	v_pk_mul_f32 v[22:23], v[22:23], v[30:31]
	v_cvt_pk_bf16_f32 v16, v16, v18
	v_cvt_pk_bf16_f32 v17, v17, v19
	v_cvt_pk_bf16_f32 v19, v21, v23
	v_cvt_pk_bf16_f32 v18, v20, v22
	global_store_dwordx4 v[32:33], v[16:19], off offset:1792
	global_load_dwordx4 v[18:21], v[138:139], off
	global_load_dwordx4 v[22:25], v[138:139], off offset:16
	v_lshl_add_u64 v[16:17], v[140:141], 0, s[2:3]
	global_load_dwordx4 v[26:29], v[16:17], off offset:1536
	s_mov_b64 s[2:3], -1
	s_waitcnt vmcnt(0)
	v_pk_add_f32 v[14:15], v[14:15], v[20:21]
	v_pk_add_f32 v[12:13], v[12:13], v[18:19]
	v_pk_add_f32 v[10:11], v[10:11], v[24:25]
	v_pk_add_f32 v[8:9], v[8:9], v[22:23]
	v_mul_f32_e32 v12, 0xbfb8aa3b, v12
	v_mul_f32_e32 v13, 0xbfb8aa3b, v13
	v_mul_f32_e32 v14, 0xbfb8aa3b, v14
	v_mul_f32_e32 v8, 0xbfb8aa3b, v8
	v_mul_f32_e32 v10, 0xbfb8aa3b, v10
	v_mul_f32_e32 v15, 0xbfb8aa3b, v15
	v_mul_f32_e32 v9, 0xbfb8aa3b, v9
	v_mul_f32_e32 v11, 0xbfb8aa3b, v11
	v_exp_f32_e32 v12, v12
	v_exp_f32_e32 v13, v13
	v_exp_f32_e32 v14, v14
	v_exp_f32_e32 v8, v8
	v_exp_f32_e32 v10, v10
	v_exp_f32_e32 v15, v15
	v_exp_f32_e32 v9, v9
	v_exp_f32_e32 v11, v11
	v_lshlrev_b32_e32 v18, 16, v26
	v_and_b32_e32 v20, 0xffff0000, v26
	v_lshlrev_b32_e32 v22, 16, v28
	v_and_b32_e32 v24, 0xffff0000, v28
	v_add_f32_e32 v12, 1.0, v12
	v_add_f32_e32 v13, 1.0, v13
	v_add_f32_e32 v14, 1.0, v14
	v_add_f32_e32 v26, 1.0, v8
	v_add_f32_e32 v28, 1.0, v10
	v_lshlrev_b32_e32 v19, 16, v27
	v_and_b32_e32 v21, 0xffff0000, v27
	v_lshlrev_b32_e32 v23, 16, v29
	v_and_b32_e32 v25, 0xffff0000, v29
	v_add_f32_e32 v15, 1.0, v15
	v_add_f32_e32 v27, 1.0, v9
	v_add_f32_e32 v29, 1.0, v11
	v_rcp_f32_e32 v8, v12
	v_rcp_f32_e32 v10, v13
	v_rcp_f32_e32 v9, v14
	v_rcp_f32_e32 v12, v26
	v_rcp_f32_e32 v13, v28
	v_rcp_f32_e32 v11, v15
	v_rcp_f32_e32 v14, v27
	v_rcp_f32_e32 v15, v29
	v_pk_mul_f32 v[8:9], v[8:9], v[18:19]
	v_pk_mul_f32 v[12:13], v[12:13], v[22:23]
	v_pk_mul_f32 v[10:11], v[10:11], v[20:21]
	v_pk_mul_f32 v[14:15], v[14:15], v[24:25]
	v_cvt_pk_bf16_f32 v8, v8, v10
	v_cvt_pk_bf16_f32 v9, v9, v11
	v_cvt_pk_bf16_f32 v11, v13, v15
	v_cvt_pk_bf16_f32 v10, v12, v14
	global_store_dwordx4 v[16:17], v[8:11], off offset:1536
	global_load_dwordx4 v[8:11], v[138:139], off offset:528
	global_load_dwordx4 v[12:15], v[138:139], off offset:512
	global_load_dwordx4 v[18:21], v[16:17], off offset:1792
	s_waitcnt vmcnt(0)
	v_pk_add_f32 v[6:7], v[6:7], v[10:11]
	v_pk_add_f32 v[4:5], v[4:5], v[8:9]
	v_pk_add_f32 v[2:3], v[2:3], v[14:15]
	v_pk_add_f32 v[0:1], v[0:1], v[12:13]
	v_mul_f32_e32 v2, 0xbfb8aa3b, v2
	v_mul_f32_e32 v0, 0xbfb8aa3b, v0
	v_mul_f32_e32 v4, 0xbfb8aa3b, v4
	v_mul_f32_e32 v6, 0xbfb8aa3b, v6
	v_mul_f32_e32 v5, 0xbfb8aa3b, v5
	v_mul_f32_e32 v1, 0xbfb8aa3b, v1
	v_mul_f32_e32 v3, 0xbfb8aa3b, v3
	v_mul_f32_e32 v7, 0xbfb8aa3b, v7
	v_exp_f32_e32 v0, v0
	v_exp_f32_e32 v2, v2
	v_exp_f32_e32 v4, v4
	v_exp_f32_e32 v6, v6
	v_exp_f32_e32 v5, v5
	v_exp_f32_e32 v1, v1
	v_exp_f32_e32 v3, v3
	v_exp_f32_e32 v7, v7
	v_lshlrev_b32_e32 v9, 16, v19
	v_lshlrev_b32_e32 v8, 16, v18
	v_and_b32_e32 v11, 0xffff0000, v19
	v_and_b32_e32 v10, 0xffff0000, v18
	v_lshlrev_b32_e32 v13, 16, v21
	v_and_b32_e32 v15, 0xffff0000, v21
	v_add_f32_e32 v18, 1.0, v0
	v_add_f32_e32 v19, 1.0, v2
	v_add_f32_e32 v21, 1.0, v4
	v_add_f32_e32 v22, 1.0, v6
	v_lshlrev_b32_e32 v12, 16, v20
	v_and_b32_e32 v14, 0xffff0000, v20
	v_add_f32_e32 v5, 1.0, v5
	v_add_f32_e32 v1, 1.0, v1
	v_add_f32_e32 v20, 1.0, v3
	v_add_f32_e32 v23, 1.0, v7
	v_rcp_f32_e32 v2, v18
	v_rcp_f32_e32 v3, v19
	v_rcp_f32_e32 v6, v21
	v_rcp_f32_e32 v7, v22
	v_rcp_f32_e32 v0, v5
	v_rcp_f32_e32 v4, v1
	v_rcp_f32_e32 v5, v20
	v_rcp_f32_e32 v1, v23
	v_pk_mul_f32 v[2:3], v[2:3], v[8:9]
	v_pk_mul_f32 v[6:7], v[6:7], v[12:13]
	v_pk_mul_f32 v[4:5], v[4:5], v[10:11]
	v_pk_mul_f32 v[0:1], v[0:1], v[14:15]
	v_bfe_u32 v12, v2, 16, 1
	v_bfe_u32 v13, v3, 16, 1
	v_bfe_u32 v10, v5, 16, 1
	v_bfe_u32 v11, v4, 16, 1
	v_add3_u32 v3, v3, v13, s96
	v_add3_u32 v2, v2, v12, s96
	v_add3_u32 v4, v4, v11, s96
	v_add3_u32 v5, v5, v10, s96
	v_lshrrev_b32_e32 v8, 16, v2
	v_lshrrev_b32_e32 v9, 16, v3
	v_cvt_pk_bf16_f32 v3, v7, v1
	v_cvt_pk_bf16_f32 v2, v6, v0
	v_and_or_b32 v1, v5, s97, v9
	v_and_or_b32 v0, v4, s97, v8
	global_store_dwordx4 v[16:17], v[0:3], off offset:1792
	s_cbranch_vccnz .LBB0_528
	s_andn2_b64 vcc, exec, s[24:25]
	s_cbranch_vccnz .LBB0_527
	s_barrier
	s_branch .LBB0_527

.LBB0_549:
	s_or_b64 exec, exec, s[0:1]
	s_mov_b64 s[0:1], 0
	v_mov_b32_e32 v2, v190
	s_waitcnt lgkmcnt(0)
	s_barrier
	v_readlane_b32 s21, v253, 55
	v_and_b32_e32 v82, 15, v2
	v_ashrrev_i32_e32 v2, 2, v2
	v_and_b32_e32 v72, -4, v2
	v_lshl_add_u64 v[0:1], v[200:201], 0, s[0:1]
	v_ashrrev_i32_e32 v73, 31, v72
	v_lshl_add_u64 v[68:69], v[72:73], 2, v[0:1]
	v_lshl_add_u32 v0, v82, 2, s21
	v_or_b32_e32 v70, s58, v82
	v_mov_b32_e32 v71, s59
	ds_read2st64_b32 v[78:79], v0 offset1:1
	ds_read2st64_b32 v[84:85], v0 offset0:2 offset1:3
	ds_read2st64_b32 v[86:87], v0 offset0:4 offset1:5
	ds_read2st64_b32 v[88:89], v0 offset0:6 offset1:7
	v_lshlrev_b64 v[0:1], 11, v[70:71]
	v_lshl_add_u64 v[0:1], s[54:55], 0, v[0:1]
	v_lshl_add_u64 v[74:75], v[0:1], 0, v[192:193]
	global_load_dwordx4 v[0:3], v[68:69], off
	global_load_dwordx4 v[100:103], v[68:69], off
	global_load_dwordx4 v[104:107], v[68:69], off offset:64
	global_load_dwordx4 v[108:111], v[68:69], off offset:128
	global_load_dwordx4 v[112:115], v[68:69], off offset:192
	v_or_b32_e32 v83, 16, v82
	v_lshl_add_u32 v70, v83, 2, s21
	s_waitcnt lgkmcnt(3)
	v_mov_b32_e32 v97, v78
	s_mov_b32 s0, 0x3727c5ac
	s_mov_b32 s34, 0x3b000000
	s_mov_b32 s20, 0x800000
	s_mov_b32 s22, 0x20600000
	s_mov_b64 s[26:27], 0x20600200
	s_add_i32 s2, s2, s3
	v_lshl_add_u64 v[206:207], v[206:207], 0, s[56:57]
	v_mov_b32_e32 v230, v170
	s_waitcnt vmcnt(0)
	v_mov_b32_e32 v80, v0
	v_mov_b32_e32 v81, v2
	v_mov_b32_e32 v2, v1
	v_lshlrev_b64 v[0:1], 1, v[72:73]
	ds_read2st64_b32 v[72:73], v70 offset1:1
	ds_read2st64_b32 v[90:91], v70 offset0:2 offset1:3
	ds_read2st64_b32 v[92:93], v70 offset0:4 offset1:5
	ds_read2st64_b32 v[94:95], v70 offset0:6 offset1:7
	v_lshl_add_u64 v[76:77], v[74:75], 0, v[0:1]
	s_waitcnt lgkmcnt(3)
	v_mov_b32_e32 v96, v72
	v_pk_add_f32 v[96:97], v[96:97], 0 op_sel_hi:[1,0]
	v_mov_b32_e32 v78, v73
	v_pk_add_f32 v[72:73], v[96:97], v[78:79]
	s_waitcnt lgkmcnt(2)
	v_mov_b32_e32 v78, v90
	v_mov_b32_e32 v79, v84
	v_pk_add_f32 v[72:73], v[72:73], v[78:79]
	v_mov_b32_e32 v84, v91
	v_pk_add_f32 v[72:73], v[72:73], v[84:85]
	s_waitcnt lgkmcnt(1)
	v_mov_b32_e32 v78, v92
	v_mov_b32_e32 v79, v86
	v_pk_add_f32 v[72:73], v[72:73], v[78:79]
	v_mov_b32_e32 v86, v93
	v_pk_add_f32 v[72:73], v[72:73], v[86:87]
	s_waitcnt lgkmcnt(0)
	v_mov_b32_e32 v78, v94
	v_mov_b32_e32 v79, v88
	v_pk_add_f32 v[72:73], v[72:73], v[78:79]
	v_mov_b32_e32 v88, v95
	v_pk_add_f32 v[78:79], v[72:73], v[88:89]
	v_mov_b64_e32 v[72:73], s[0:1]
	v_pk_fma_f32 v[78:79], v[78:79], s[34:35], v[72:73] op_sel_hi:[1,0,0]
	v_lshl_add_u64 v[74:75], v[76:77], 0, s[26:27]
	v_mul_f32_e32 v70, 0x4b800000, v79
	v_cmp_gt_f32_e64 s[0:1], s20, v79
	v_cmp_gt_f32_e32 vcc, s20, v78
	s_nop 0
	v_cndmask_b32_e64 v70, v79, v70, s[0:1]
	v_rsq_f32_e32 v70, v70
	s_nop 0
	v_mul_f32_e32 v79, 0x45800000, v70
	v_cndmask_b32_e64 v70, v70, v79, s[0:1]
	v_pk_mul_f32 v[54:55], v[54:55], v[70:71] op_sel_hi:[1,0]
	v_pk_mul_f32 v[58:59], v[58:59], v[70:71] op_sel_hi:[1,0]
	v_pk_mul_f32 v[54:55], v[80:81], v[54:55]
	v_pk_mul_f32 v[2:3], v[2:3], v[58:59]
	v_cvt_pk_bf16_f32 v2, v54, v2
	v_add_co_u32_e64 v54, s[0:1], s22, v76
	v_cvt_pk_bf16_f32 v3, v55, v3
	s_nop 0
	v_addc_co_u32_e64 v55, s[0:1], 0, v77, s[0:1]
	global_store_dwordx2 v[54:55], v[2:3], off offset:512
	v_mov_b32_e32 v84, v104
	v_mov_b32_e32 v85, v105
	v_mov_b32_e32 v86, v106
	v_mov_b32_e32 v87, v107
	v_pk_mul_f32 v[2:3], v[56:57], v[70:71] op_sel_hi:[1,0]
	v_pk_mul_f32 v[52:53], v[52:53], v[70:71] op_sel_hi:[1,0]
	v_pk_mul_f32 v[50:51], v[50:51], v[70:71] op_sel_hi:[1,0]
	v_mov_b32_e32 v54, v84
	v_mov_b32_e32 v55, v86
	v_pk_mul_f32 v[2:3], v[54:55], v[2:3]
	v_mov_b32_e32 v86, v85
	v_pk_mul_f32 v[52:53], v[86:87], v[52:53]
	v_cvt_pk_bf16_f32 v3, v3, v53
	v_cvt_pk_bf16_f32 v2, v2, v52
	global_store_dwordx2 v[74:75], v[2:3], off offset:32
	v_mov_b32_e32 v52, v108
	v_mov_b32_e32 v53, v109
	v_mov_b32_e32 v54, v110
	v_mov_b32_e32 v55, v111
	v_pk_mul_f32 v[2:3], v[64:65], v[70:71] op_sel_hi:[1,0]
	v_mov_b32_e32 v56, v52
	v_mov_b32_e32 v57, v54
	v_pk_mul_f32 v[2:3], v[56:57], v[2:3]
	v_pk_mul_f32 v[56:57], v[60:61], v[70:71] op_sel_hi:[1,0]
	v_mov_b32_e32 v54, v53
	v_pk_mul_f32 v[52:53], v[54:55], v[56:57]
	v_cvt_pk_bf16_f32 v3, v3, v53
	v_cvt_pk_bf16_f32 v2, v2, v52
	global_store_dwordx2 v[74:75], v[2:3], off offset:64
	v_mov_b32_e32 v52, v112
	v_mov_b32_e32 v53, v113
	v_mov_b32_e32 v54, v114
	v_mov_b32_e32 v55, v115
	v_pk_mul_f32 v[2:3], v[62:63], v[70:71] op_sel_hi:[1,0]
	v_or_b32_e32 v70, s58, v83
	v_mov_b32_e32 v56, v52
	v_mov_b32_e32 v57, v54
	v_pk_mul_f32 v[2:3], v[56:57], v[2:3]
	v_mov_b32_e32 v54, v53
	v_pk_mul_f32 v[50:51], v[54:55], v[50:51]
	v_cvt_pk_bf16_f32 v3, v3, v51
	v_cvt_pk_bf16_f32 v2, v2, v50
	v_lshlrev_b64 v[50:51], 11, v[70:71]
	global_store_dwordx2 v[74:75], v[2:3], off offset:96
	v_lshl_add_u64 v[50:51], s[54:55], 0, v[50:51]
	v_lshl_add_u64 v[54:55], v[50:51], 0, v[192:193]
	v_mov_b32_e32 v50, v100
	v_mov_b32_e32 v51, v101
	v_mov_b32_e32 v52, v102
	v_mov_b32_e32 v53, v103
	v_mul_f32_e32 v2, 0x4b800000, v78
	v_cndmask_b32_e32 v2, v78, v2, vcc
	v_rsq_f32_e32 v2, v2
	v_mov_b32_e32 v56, v50
	v_mul_f32_e32 v3, 0x45800000, v2
	v_cndmask_b32_e32 v2, v2, v3, vcc
	v_pk_mul_f32 v[48:49], v[48:49], v[2:3] op_sel_hi:[1,0]
	v_mov_b32_e32 v57, v52
	v_pk_mul_f32 v[48:49], v[56:57], v[48:49]
	v_pk_mul_f32 v[46:47], v[46:47], v[2:3] op_sel_hi:[1,0]
	v_mov_b32_e32 v52, v51
	v_pk_mul_f32 v[46:47], v[52:53], v[46:47]
	v_and_b32_sdwa v3, v49, v228 dst_sel:DWORD dst_unused:UNUSED_PAD src0_sel:WORD_1 src1_sel:DWORD
	s_nop 0
	v_add3_u32 v3, v49, v3, s96
	v_and_b32_sdwa v49, v47, v228 dst_sel:DWORD dst_unused:UNUSED_PAD src0_sel:WORD_1 src1_sel:DWORD
	s_nop 0
	v_add3_u32 v47, v47, v49, s96
	v_and_b32_e32 v47, 0xffff0000, v47
	v_lshl_add_u64 v[50:51], v[54:55], 0, v[0:1]
	v_or_b32_sdwa v49, v47, v3 dst_sel:DWORD dst_unused:UNUSED_PAD src0_sel:DWORD src1_sel:WORD_1
	v_cvt_pk_bf16_f32 v48, v48, v46
	v_lshl_add_u64 v[46:47], v[50:51], 0, s[26:27]
	v_add_co_u32_e32 v50, vcc, s22, v50
	v_pk_mul_f32 v[44:45], v[44:45], v[2:3] op_sel_hi:[1,0]
	s_nop 0
	v_addc_co_u32_e32 v51, vcc, 0, v51, vcc
	global_store_dwordx2 v[50:51], v[48:49], off offset:512
	v_mov_b32_e32 v48, v104
	v_mov_b32_e32 v49, v105
	v_mov_b32_e32 v50, v106
	v_mov_b32_e32 v51, v107
	v_pk_mul_f32 v[40:41], v[40:41], v[2:3] op_sel_hi:[1,0]
	v_mov_b32_e32 v52, v48
	v_mov_b32_e32 v53, v50
	v_pk_mul_f32 v[44:45], v[52:53], v[44:45]
	v_mov_b32_e32 v50, v49
	v_pk_mul_f32 v[40:41], v[50:51], v[40:41]
	v_and_b32_sdwa v3, v45, v228 dst_sel:DWORD dst_unused:UNUSED_PAD src0_sel:WORD_1 src1_sel:DWORD
	s_nop 0
	v_add3_u32 v3, v45, v3, s96
	v_and_b32_sdwa v45, v41, v228 dst_sel:DWORD dst_unused:UNUSED_PAD src0_sel:WORD_1 src1_sel:DWORD
	s_nop 0
	v_add3_u32 v41, v41, v45, s96
	v_and_b32_e32 v41, 0xffff0000, v41
	v_or_b32_sdwa v41, v41, v3 dst_sel:DWORD dst_unused:UNUSED_PAD src0_sel:DWORD src1_sel:WORD_1
	v_cvt_pk_bf16_f32 v40, v44, v40
	global_store_dwordx2 v[46:47], v[40:41], off offset:32
	v_mov_b32_e32 v48, v108
	v_mov_b32_e32 v49, v109
	v_mov_b32_e32 v50, v110
	v_mov_b32_e32 v51, v111
	v_pk_mul_f32 v[40:41], v[42:43], v[2:3] op_sel_hi:[1,0]
	v_pk_mul_f32 v[36:37], v[36:37], v[2:3] op_sel_hi:[1,0]
	v_mov_b32_e32 v42, v48
	v_mov_b32_e32 v43, v50
	v_pk_mul_f32 v[40:41], v[42:43], v[40:41]
	v_mov_b32_e32 v50, v49
	v_pk_mul_f32 v[36:37], v[50:51], v[36:37]
	v_and_b32_sdwa v3, v41, v228 dst_sel:DWORD dst_unused:UNUSED_PAD src0_sel:WORD_1 src1_sel:DWORD
	s_nop 0
	v_add3_u32 v3, v41, v3, s96
	v_and_b32_sdwa v41, v37, v228 dst_sel:DWORD dst_unused:UNUSED_PAD src0_sel:WORD_1 src1_sel:DWORD
	s_nop 0
	v_add3_u32 v37, v37, v41, s96
	v_and_b32_e32 v37, 0xffff0000, v37
	v_or_b32_sdwa v37, v37, v3 dst_sel:DWORD dst_unused:UNUSED_PAD src0_sel:DWORD src1_sel:WORD_1
	v_cvt_pk_bf16_f32 v36, v40, v36
	global_store_dwordx2 v[46:47], v[36:37], off offset:64
	v_mov_b32_e32 v40, v112
	v_mov_b32_e32 v41, v113
	v_mov_b32_e32 v42, v114
	v_mov_b32_e32 v43, v115
	v_pk_mul_f32 v[36:37], v[38:39], v[2:3] op_sel_hi:[1,0]
	v_pk_mul_f32 v[2:3], v[34:35], v[2:3] op_sel_hi:[1,0]
	v_mov_b32_e32 v38, v40
	v_mov_b32_e32 v39, v42
	v_pk_mul_f32 v[36:37], v[38:39], v[36:37]
	v_mov_b32_e32 v42, v41
	v_pk_mul_f32 v[2:3], v[42:43], v[2:3]
	v_cvt_pk_bf16_f32 v3, v37, v3
	v_cvt_pk_bf16_f32 v2, v36, v2
	global_store_dwordx2 v[46:47], v[2:3], off offset:96
	v_or_b32_e32 v2, 32, v82
	v_lshl_add_u32 v3, v2, 2, s21
	ds_read2st64_b32 v[34:35], v3 offset1:1
	ds_read2st64_b32 v[42:43], v3 offset0:2 offset1:3
	ds_read2st64_b32 v[44:45], v3 offset0:4 offset1:5
	ds_read2st64_b32 v[46:47], v3 offset0:6 offset1:7
	v_mov_b32_e32 v38, v100
	v_mov_b32_e32 v39, v101
	v_mov_b32_e32 v40, v102
	v_mov_b32_e32 v41, v103
	v_or_b32_e32 v37, 48, v82
	v_lshl_add_u32 v36, v37, 2, s21
	ds_read2st64_b32 v[50:51], v36 offset1:1
	ds_read2st64_b32 v[52:53], v36 offset0:2 offset1:3
	ds_read2st64_b32 v[54:55], v36 offset0:4 offset1:5
	ds_read2st64_b32 v[56:57], v36 offset0:6 offset1:7
	s_waitcnt lgkmcnt(7)
	v_mov_b32_e32 v59, v34
	s_waitcnt lgkmcnt(3)
	v_mov_b32_e32 v58, v50
	v_pk_add_f32 v[58:59], v[58:59], 0 op_sel_hi:[1,0]
	v_mov_b32_e32 v34, v51
	v_pk_add_f32 v[34:35], v[58:59], v[34:35]
	s_waitcnt lgkmcnt(2)
	v_mov_b32_e32 v50, v52
	v_mov_b32_e32 v51, v42
	v_pk_add_f32 v[34:35], v[34:35], v[50:51]
	v_mov_b32_e32 v42, v53
	v_pk_add_f32 v[34:35], v[34:35], v[42:43]
	s_waitcnt lgkmcnt(1)
	v_mov_b32_e32 v42, v54
	v_mov_b32_e32 v43, v44
	v_pk_add_f32 v[34:35], v[34:35], v[42:43]
	v_mov_b32_e32 v44, v55
	v_pk_add_f32 v[34:35], v[34:35], v[44:45]
	s_waitcnt lgkmcnt(0)
	v_mov_b32_e32 v42, v56
	v_mov_b32_e32 v43, v46
	v_pk_add_f32 v[34:35], v[34:35], v[42:43]
	v_mov_b32_e32 v46, v57
	v_pk_add_f32 v[34:35], v[34:35], v[46:47]
	v_or_b32_e32 v70, s58, v2
	v_pk_fma_f32 v[34:35], v[34:35], s[34:35], v[72:73] op_sel_hi:[1,0,0]
	v_lshlrev_b64 v[2:3], 11, v[70:71]
	v_mul_f32_e32 v36, 0x4b800000, v35
	v_cmp_gt_f32_e64 s[0:1], s20, v35
	v_lshl_add_u64 v[2:3], s[54:55], 0, v[2:3]
	v_lshl_add_u64 v[2:3], v[2:3], 0, v[192:193]
	v_cndmask_b32_e64 v35, v35, v36, s[0:1]
	v_rsq_f32_e32 v35, v35
	v_or_b32_e32 v70, s58, v37
	v_cmp_gt_f32_e32 vcc, s20, v34
	v_mul_f32_e32 v36, 0x45800000, v35
	v_cndmask_b32_e64 v36, v35, v36, s[0:1]
	v_pk_mul_f32 v[32:33], v[32:33], v[36:37] op_sel_hi:[1,0]
	v_pk_mul_f32 v[30:31], v[30:31], v[36:37] op_sel_hi:[1,0]
	v_pk_mul_f32 v[28:29], v[28:29], v[36:37] op_sel_hi:[1,0]
	v_pk_mul_f32 v[24:25], v[24:25], v[36:37] op_sel_hi:[1,0]
	v_pk_mul_f32 v[20:21], v[20:21], v[36:37] op_sel_hi:[1,0]
	v_pk_mul_f32 v[18:19], v[18:19], v[36:37] op_sel_hi:[1,0]
	v_mov_b32_e32 v48, v38
	v_mov_b32_e32 v49, v40
	v_mov_b32_e32 v40, v39
	v_pk_mul_f32 v[32:33], v[48:49], v[32:33]
	v_pk_mul_f32 v[30:31], v[40:41], v[30:31]
	v_lshl_add_u64 v[38:39], v[2:3], 0, v[0:1]
	v_cvt_pk_bf16_f32 v30, v32, v30
	v_add_co_u32_e64 v32, s[0:1], s22, v38
	v_cvt_pk_bf16_f32 v31, v33, v31
	s_nop 0
	v_addc_co_u32_e64 v33, s[0:1], 0, v39, s[0:1]
	global_store_dwordx2 v[32:33], v[30:31], off offset:512
	v_mov_b32_e32 v30, v104
	v_mov_b32_e32 v31, v105
	v_mov_b32_e32 v32, v106
	v_mov_b32_e32 v33, v107
	v_lshl_add_u64 v[2:3], v[38:39], 0, s[26:27]
	v_readlane_b32 s0, v254, 19
	s_add_i32 s24, s24, s0
	s_cmpk_lt_i32 s24, 0x400
	v_readlane_b32 s1, v254, 20
	v_mov_b32_e32 v38, v30
	v_mov_b32_e32 v39, v32
	v_pk_mul_f32 v[28:29], v[38:39], v[28:29]
	v_mov_b32_e32 v32, v31
	v_pk_mul_f32 v[24:25], v[32:33], v[24:25]
	v_cvt_pk_bf16_f32 v25, v29, v25
	v_cvt_pk_bf16_f32 v24, v28, v24
	global_store_dwordx2 v[2:3], v[24:25], off offset:32
	v_mov_b32_e32 v28, v108
	v_mov_b32_e32 v29, v109
	v_mov_b32_e32 v30, v110
	v_mov_b32_e32 v31, v111
	v_pk_mul_f32 v[24:25], v[26:27], v[36:37] op_sel_hi:[1,0]
	v_mov_b32_e32 v26, v28
	v_mov_b32_e32 v27, v30
	v_pk_mul_f32 v[24:25], v[26:27], v[24:25]
	v_mov_b32_e32 v30, v29
	v_pk_mul_f32 v[20:21], v[30:31], v[20:21]
	v_cvt_pk_bf16_f32 v21, v25, v21
	v_cvt_pk_bf16_f32 v20, v24, v20
	global_store_dwordx2 v[2:3], v[20:21], off offset:64
	v_mov_b32_e32 v24, v112
	v_mov_b32_e32 v25, v113
	v_mov_b32_e32 v26, v114
	v_mov_b32_e32 v27, v115
	v_pk_mul_f32 v[20:21], v[22:23], v[36:37] op_sel_hi:[1,0]
	v_mov_b32_e32 v22, v24
	v_mov_b32_e32 v23, v26
	v_pk_mul_f32 v[20:21], v[22:23], v[20:21]
	v_mov_b32_e32 v26, v25
	v_pk_mul_f32 v[18:19], v[26:27], v[18:19]
	v_cvt_pk_bf16_f32 v19, v21, v19
	v_cvt_pk_bf16_f32 v18, v20, v18
	global_store_dwordx2 v[2:3], v[18:19], off offset:96
	v_lshlrev_b64 v[18:19], 11, v[70:71]
	v_lshl_add_u64 v[18:19], s[54:55], 0, v[18:19]
	v_lshl_add_u64 v[22:23], v[18:19], 0, v[192:193]
	v_mov_b32_e32 v18, v100
	v_mov_b32_e32 v19, v101
	v_mov_b32_e32 v20, v102
	v_mov_b32_e32 v21, v103
	v_mul_f32_e32 v2, 0x4b800000, v34
	v_cndmask_b32_e32 v2, v34, v2, vcc
	v_rsq_f32_e32 v2, v2
	v_mov_b32_e32 v24, v18
	v_mul_f32_e32 v3, 0x45800000, v2
	v_cndmask_b32_e32 v2, v2, v3, vcc
	v_pk_mul_f32 v[16:17], v[16:17], v[2:3] op_sel_hi:[1,0]
	v_mov_b32_e32 v25, v20
	v_pk_mul_f32 v[16:17], v[24:25], v[16:17]
	v_pk_mul_f32 v[14:15], v[14:15], v[2:3] op_sel_hi:[1,0]
	v_mov_b32_e32 v20, v19
	v_pk_mul_f32 v[14:15], v[20:21], v[14:15]
	v_and_b32_sdwa v3, v17, v228 dst_sel:DWORD dst_unused:UNUSED_PAD src0_sel:WORD_1 src1_sel:DWORD
	s_nop 0
	v_add3_u32 v3, v17, v3, s96
	v_and_b32_sdwa v17, v15, v228 dst_sel:DWORD dst_unused:UNUSED_PAD src0_sel:WORD_1 src1_sel:DWORD
	s_nop 0
	v_add3_u32 v15, v15, v17, s96
	v_cvt_pk_bf16_f32 v14, v16, v14
	v_lshl_add_u64 v[16:17], v[22:23], 0, v[0:1]
	v_and_b32_e32 v15, 0xffff0000, v15
	v_lshl_add_u64 v[0:1], v[16:17], 0, s[26:27]
	v_add_co_u32_e32 v16, vcc, s22, v16
	v_or_b32_sdwa v15, v15, v3 dst_sel:DWORD dst_unused:UNUSED_PAD src0_sel:DWORD src1_sel:WORD_1
	s_nop 0
	v_addc_co_u32_e32 v17, vcc, 0, v17, vcc
	global_store_dwordx2 v[16:17], v[14:15], off offset:512
	v_mov_b32_e32 v14, v104
	v_mov_b32_e32 v15, v105
	v_mov_b32_e32 v16, v106
	v_mov_b32_e32 v17, v107
	v_pk_mul_f32 v[12:13], v[12:13], v[2:3] op_sel_hi:[1,0]
	v_pk_mul_f32 v[8:9], v[8:9], v[2:3] op_sel_hi:[1,0]
	v_mov_b32_e32 v18, v14
	v_mov_b32_e32 v19, v16
	v_pk_mul_f32 v[12:13], v[18:19], v[12:13]
	v_mov_b32_e32 v16, v15
	v_pk_mul_f32 v[8:9], v[16:17], v[8:9]
	v_and_b32_sdwa v3, v13, v228 dst_sel:DWORD dst_unused:UNUSED_PAD src0_sel:WORD_1 src1_sel:DWORD
	s_nop 0
	v_add3_u32 v3, v13, v3, s96
	v_and_b32_sdwa v13, v9, v228 dst_sel:DWORD dst_unused:UNUSED_PAD src0_sel:WORD_1 src1_sel:DWORD
	s_nop 0
	v_add3_u32 v9, v9, v13, s96
	v_and_b32_e32 v9, 0xffff0000, v9
	v_or_b32_sdwa v9, v9, v3 dst_sel:DWORD dst_unused:UNUSED_PAD src0_sel:DWORD src1_sel:WORD_1
	v_cvt_pk_bf16_f32 v8, v12, v8
	global_store_dwordx2 v[0:1], v[8:9], off offset:32
	v_mov_b32_e32 v12, v108
	v_mov_b32_e32 v13, v109
	v_mov_b32_e32 v14, v110
	v_mov_b32_e32 v15, v111
	v_pk_mul_f32 v[8:9], v[10:11], v[2:3] op_sel_hi:[1,0]
	v_pk_mul_f32 v[4:5], v[4:5], v[2:3] op_sel_hi:[1,0]
	v_mov_b32_e32 v10, v12
	v_mov_b32_e32 v11, v14
	v_pk_mul_f32 v[8:9], v[10:11], v[8:9]
	v_mov_b32_e32 v14, v13
	v_pk_mul_f32 v[4:5], v[14:15], v[4:5]
	v_and_b32_sdwa v3, v9, v228 dst_sel:DWORD dst_unused:UNUSED_PAD src0_sel:WORD_1 src1_sel:DWORD
	s_nop 0
	v_add3_u32 v3, v9, v3, s96
	v_and_b32_sdwa v9, v5, v228 dst_sel:DWORD dst_unused:UNUSED_PAD src0_sel:WORD_1 src1_sel:DWORD
	s_nop 0
	v_add3_u32 v5, v5, v9, s96
	v_and_b32_e32 v5, 0xffff0000, v5
	v_or_b32_sdwa v5, v5, v3 dst_sel:DWORD dst_unused:UNUSED_PAD src0_sel:DWORD src1_sel:WORD_1
	v_cvt_pk_bf16_f32 v4, v8, v4
	global_store_dwordx2 v[0:1], v[4:5], off offset:64
	v_mov_b32_e32 v8, v112
	v_mov_b32_e32 v9, v113
	v_mov_b32_e32 v10, v114
	v_mov_b32_e32 v11, v115
	v_pk_mul_f32 v[4:5], v[6:7], v[2:3] op_sel_hi:[1,0]
	v_pk_mul_f32 v[2:3], v[66:67], v[2:3] op_sel_hi:[1,0]
	v_mov_b32_e32 v6, v8
	v_mov_b32_e32 v7, v10
	v_pk_mul_f32 v[4:5], v[6:7], v[4:5]
	v_mov_b32_e32 v10, v9
	v_pk_mul_f32 v[2:3], v[10:11], v[2:3]
	v_cvt_pk_bf16_f32 v3, v5, v3
	v_cvt_pk_bf16_f32 v2, v4, v2
	global_store_dwordx2 v[0:1], v[2:3], off offset:96
	s_barrier
	s_cbranch_scc0 .LBB0_556

.LBB0_554:
	s_or_b64 exec, exec, s[0:1]
	s_mov_b64 s[0:1], 0
	s_movk_i32 s20, 0x84
	v_lshl_add_u64 v[96:97], v[198:199], 0, s[0:1]
	v_mov_b32_e32 v96, v213
	v_mov_b32_e32 v170, v230
	v_mov_b32_e32 v232, 0x1b00
	s_movk_i32 s23, 0x420
	s_mov_b32 s25, 0x5040100
	s_waitcnt vmcnt(0)
	v_mul_f32_e32 v97, 0x3fb8aa3b, v96
	v_fma_f32 v99, v96, s22, -v97
	v_rndne_f32_e32 v148, v97
	v_fmac_f32_e32 v99, 0x32a5705f, v96
	v_sub_f32_e32 v97, v97, v148
	v_add_f32_e32 v97, v97, v99
	v_exp_f32_e32 v97, v97
	v_cvt_i32_f32_e32 v99, v148
	v_cmp_ngt_f32_e32 vcc, s37, v96
	s_movk_i32 s22, 0x600
	v_ldexp_f32 v97, v97, v99
	v_cndmask_b32_e32 v97, 0, v97, vcc
	v_cmp_nlt_f32_e32 vcc, s30, v96
	s_nop 1
	v_cndmask_b32_e32 v96, v231, v97, vcc
	v_mul_f32_e64 v97, v93, -v96
	ds_bpermute_b32 v83, v83, v97
	s_waitcnt lgkmcnt(0)
	v_fma_f32 v83, v93, -v96, v83
	v_cndmask_b32_e64 v83, v83, v97, s[38:39]
	ds_bpermute_b32 v85, v85, v83
	s_waitcnt lgkmcnt(0)
	v_add_f32_e32 v85, v83, v85
	v_cndmask_b32_e64 v83, v85, v83, s[40:41]
	ds_bpermute_b32 v85, v87, v83
	s_waitcnt lgkmcnt(0)
	v_add_f32_e32 v85, v83, v85
	v_cndmask_b32_e64 v83, v85, v83, s[42:43]
	ds_bpermute_b32 v85, v89, v83
	s_waitcnt lgkmcnt(0)
	v_add_f32_e32 v85, v83, v85
	v_cndmask_b32_e64 v83, v85, v83, s[44:45]
	ds_bpermute_b32 v85, v91, v83
	s_waitcnt lgkmcnt(0)
	v_add_f32_e32 v85, v83, v85
	v_cndmask_b32_e64 v83, v85, v83, s[46:47]
	ds_bpermute_b32 v85, v95, v83
	s_waitcnt lgkmcnt(0)
	v_add_f32_e32 v85, v83, v85
	v_cndmask_b32_e64 v83, v85, v83, s[48:49]
	ds_bpermute_b32 v85, v230, v83
	v_mov_b32_e32 v230, 0x1200
	s_waitcnt lgkmcnt(0)
	v_sub_f32_e32 v83, v85, v83
	v_fma_f32 v83, v93, -v96, v83
	v_lshl_add_u32 v96, v98, 1, v191
	v_mad_u64_u32 v[98:99], s[0:1], v80, s20, v[96:97]
	ds_write2st64_b32 v241, v93, v83 offset0:71 offset1:72
	ds_write2_b32 v98, v32, v33 offset1:1
	ds_write2_b32 v98, v34, v35 offset0:2 offset1:3
	v_mad_u64_u32 v[32:33], s[0:1], v82, s20, v[96:97]
	ds_write2_b32 v32, v40, v41 offset1:1
	ds_write2_b32 v32, v42, v43 offset0:2 offset1:3
	v_mad_u64_u32 v[32:33], s[0:1], v84, s20, v[96:97]
	ds_write2_b32 v32, v48, v49 offset1:1
	ds_write2_b32 v32, v50, v51 offset0:2 offset1:3
	v_mad_u64_u32 v[32:33], s[0:1], v86, s20, v[96:97]
	ds_write2_b32 v32, v52, v53 offset1:1
	ds_write2_b32 v32, v54, v55 offset0:2 offset1:3
	v_mad_u64_u32 v[32:33], s[0:1], v88, s20, v[96:97]
	ds_write2_b32 v32, v64, v65 offset1:1
	ds_write2_b32 v32, v66, v67 offset0:2 offset1:3
	v_mad_u64_u32 v[32:33], s[0:1], v90, s20, v[96:97]
	ds_write2_b32 v32, v68, v69 offset1:1
	ds_write2_b32 v32, v70, v71 offset0:2 offset1:3
	v_mad_u64_u32 v[32:33], s[0:1], v92, s20, v[96:97]
	ds_write2_b32 v32, v72, v73 offset1:1
	ds_write2_b32 v32, v74, v75 offset0:2 offset1:3
	v_mad_u64_u32 v[32:33], s[0:1], v94, s20, v[96:97]
	ds_write2_b32 v32, v76, v77 offset1:1
	ds_write2_b32 v32, v78, v79 offset0:2 offset1:3
	v_lshl_add_u32 v32, v81, 2, v191
	s_waitcnt lgkmcnt(0)
	v_add_u32_e32 v80, 0x4400, v32
	v_add_u32_e32 v81, 0x4800, v32
	ds_read2_b32 v[64:65], v80 offset0:128 offset1:144
	ds_read2_b32 v[66:67], v81 offset1:16
	v_mfma_f32_16x16x32_bf16 v[40:43], v[36:39], v[4:7], 0
	ds_read2_b32 v[148:149], v80 offset0:160 offset1:176
	ds_read2_b32 v[150:151], v81 offset0:32 offset1:48
	s_waitcnt lgkmcnt(3)
	v_mul_f32_e32 v33, 0x3fb8aa3b, v64
	s_waitcnt lgkmcnt(2)
	v_mul_f32_e32 v32, 0x3fb8aa3b, v66
	v_exp_f32_e32 v52, v33
	v_exp_f32_e32 v54, v32
	v_mfma_f32_16x16x32_bf16 v[32:35], v[24:27], v[4:7], 0
	v_mul_f32_e32 v64, 0x3fb8aa3b, v65
	v_exp_f32_e32 v86, v64
	v_mul_f32_e32 v64, 0x3fb8aa3b, v67
	v_mfma_f32_16x16x32_bf16 v[40:43], v[44:47], v[0:3], v[40:43]
	v_exp_f32_e32 v88, v64
	s_waitcnt lgkmcnt(1)
	v_mul_f32_e32 v80, 0x3fb8aa3b, v148
	v_exp_f32_e32 v148, v80
	v_mfma_f32_16x16x32_bf16 v[32:35], v[28:31], v[0:3], v[32:35]
	s_waitcnt lgkmcnt(0)
	v_mul_f32_e32 v80, 0x3fb8aa3b, v150
	s_nop 0
	v_pk_mul_f32 v[40:41], v[54:55], v[40:41] op_sel_hi:[0,1]
	v_pk_mul_f32 v[42:43], v[54:55], v[42:43] op_sel_hi:[0,1]
	v_mfma_f32_16x16x32_bf16 v[48:51], v[100:103], v[4:7], 0
	v_exp_f32_e32 v150, v80
	s_nop 0
	v_pk_fma_f32 v[34:35], v[34:35], v[52:53], v[42:43] op_sel_hi:[1,0,1]
	v_pk_fma_f32 v[32:33], v[32:33], v[52:53], v[40:41] op_sel_hi:[1,0,1]
	v_mfma_f32_16x16x32_bf16 v[40:43], v[56:59], v[4:7], 0
	v_add_f32_e64 v34, v34, 0
	v_add_f32_e64 v35, v35, 0
	v_pk_add_f32 v[32:33], v[32:33], 0 op_sel_hi:[1,0]
	v_mfma_f32_16x16x32_bf16 v[48:51], v[104:107], v[0:3], v[48:51]
	v_mfma_f32_16x16x32_bf16 v[40:43], v[60:63], v[0:3], v[40:43]
	v_mfma_f32_16x16x32_bf16 v[68:71], v[116:119], v[4:7], 0
	s_nop 5
	v_mul_f32_e64 v48, v54, v48
	v_mul_f32_e64 v49, v54, v49
	v_pk_mul_f32 v[50:51], v[54:55], v[50:51] op_sel_hi:[0,1]
	v_pk_fma_f32 v[42:43], v[52:53], v[42:43], v[50:51] op_sel_hi:[0,1,1]
	v_pk_fma_f32 v[40:41], v[52:53], v[40:41], v[48:49] op_sel_hi:[0,1,1]
	v_mfma_f32_16x16x32_bf16 v[48:51], v[108:111], v[4:7], 0
	v_add_f32_e64 v42, v42, 0
	v_add_f32_e64 v43, v43, 0
	v_pk_add_f32 v[40:41], v[40:41], 0 op_sel_hi:[1,0]
	v_mfma_f32_16x16x32_bf16 v[68:71], v[120:123], v[0:3], v[68:71]
	v_mfma_f32_16x16x32_bf16 v[48:51], v[112:115], v[0:3], v[48:51]
	v_mfma_f32_16x16x32_bf16 v[72:75], v[140:143], v[4:7], 0
	s_nop 5
	v_mul_f32_e64 v68, v54, v68
	v_mul_f32_e64 v69, v54, v69
	v_pk_mul_f32 v[70:71], v[54:55], v[70:71] op_sel_hi:[0,1]
	v_pk_fma_f32 v[50:51], v[52:53], v[50:51], v[70:71] op_sel_hi:[0,1,1]
	v_pk_fma_f32 v[48:49], v[52:53], v[48:49], v[68:69] op_sel_hi:[0,1,1]
	v_mfma_f32_16x16x32_bf16 v[68:71], v[124:127], v[4:7], 0
	v_add_f32_e64 v50, v50, 0
	v_add_f32_e64 v51, v51, 0
	v_pk_add_f32 v[48:49], v[48:49], 0 op_sel_hi:[1,0]
	v_mfma_f32_16x16x32_bf16 v[72:75], v[144:147], v[0:3], v[72:75]
	v_mfma_f32_16x16x32_bf16 v[68:71], v[136:139], v[0:3], v[68:71]
	v_mfma_f32_16x16x32_bf16 v[64:67], v[24:27], v[8:11], 0
	s_nop 5
	v_mul_f32_e64 v72, v54, v72
	v_mul_f32_e64 v73, v54, v73
	v_pk_mul_f32 v[54:55], v[54:55], v[74:75] op_sel_hi:[0,1]
	v_pk_fma_f32 v[54:55], v[52:53], v[70:71], v[54:55] op_sel_hi:[0,1,1]
	v_pk_fma_f32 v[52:53], v[52:53], v[68:69], v[72:73] op_sel_hi:[0,1,1]
	v_mfma_f32_16x16x32_bf16 v[68:71], v[36:39], v[8:11], 0
	v_add_f32_e64 v54, v54, 0
	v_add_f32_e64 v55, v55, 0
	v_pk_add_f32 v[52:53], v[52:53], 0 op_sel_hi:[1,0]
	v_mfma_f32_16x16x32_bf16 v[68:71], v[44:47], v[16:19], v[68:71]
	v_mfma_f32_16x16x32_bf16 v[64:67], v[28:31], v[16:19], v[64:67]
	v_mfma_f32_16x16x32_bf16 v[72:75], v[100:103], v[8:11], 0
	s_nop 5
	v_mul_f32_e64 v68, v88, v68
	v_mul_f32_e64 v69, v88, v69
	v_pk_mul_f32 v[70:71], v[88:89], v[70:71] op_sel_hi:[0,1]
	v_pk_fma_f32 v[66:67], v[66:67], v[86:87], v[70:71] op_sel_hi:[1,0,1]
	v_pk_fma_f32 v[64:65], v[64:65], v[86:87], v[68:69] op_sel_hi:[1,0,1]
	v_mfma_f32_16x16x32_bf16 v[68:71], v[56:59], v[8:11], 0
	v_add_f32_e64 v66, v66, 0
	v_add_f32_e64 v67, v67, 0
	v_pk_add_f32 v[64:65], v[64:65], 0 op_sel_hi:[1,0]
	v_mfma_f32_16x16x32_bf16 v[72:75], v[104:107], v[16:19], v[72:75]
	v_mfma_f32_16x16x32_bf16 v[68:71], v[60:63], v[16:19], v[68:71]
	v_mfma_f32_16x16x32_bf16 v[76:79], v[116:119], v[8:11], 0
	s_nop 5
	v_mul_f32_e64 v72, v88, v72
	v_mul_f32_e64 v73, v88, v73
	v_pk_mul_f32 v[74:75], v[88:89], v[74:75] op_sel_hi:[0,1]
	v_pk_fma_f32 v[70:71], v[86:87], v[70:71], v[74:75] op_sel_hi:[0,1,1]
	v_pk_fma_f32 v[68:69], v[86:87], v[68:69], v[72:73] op_sel_hi:[0,1,1]
	v_mfma_f32_16x16x32_bf16 v[72:75], v[108:111], v[8:11], 0
	v_add_f32_e64 v70, v70, 0
	v_add_f32_e64 v71, v71, 0
	v_pk_add_f32 v[68:69], v[68:69], 0 op_sel_hi:[1,0]
	v_mfma_f32_16x16x32_bf16 v[76:79], v[120:123], v[16:19], v[76:79]
	v_mfma_f32_16x16x32_bf16 v[72:75], v[112:115], v[16:19], v[72:75]
	v_mfma_f32_16x16x32_bf16 v[82:85], v[140:143], v[8:11], 0
	s_nop 5
	v_mul_f32_e64 v76, v88, v76
	v_mul_f32_e64 v77, v88, v77
	v_pk_mul_f32 v[78:79], v[88:89], v[78:79] op_sel_hi:[0,1]
	v_pk_fma_f32 v[74:75], v[86:87], v[74:75], v[78:79] op_sel_hi:[0,1,1]
	v_pk_fma_f32 v[72:73], v[86:87], v[72:73], v[76:77] op_sel_hi:[0,1,1]
	v_mfma_f32_16x16x32_bf16 v[76:79], v[124:127], v[8:11], 0
	v_add_f32_e64 v74, v74, 0
	v_add_f32_e64 v75, v75, 0
	v_pk_add_f32 v[72:73], v[72:73], 0 op_sel_hi:[1,0]
	v_mfma_f32_16x16x32_bf16 v[82:85], v[144:147], v[16:19], v[82:85]
	v_mfma_f32_16x16x32_bf16 v[76:79], v[136:139], v[16:19], v[76:79]
	v_mfma_f32_16x16x32_bf16 v[92:95], v[116:119], v[12:15], 0
	s_nop 5
	v_mul_f32_e64 v82, v88, v82
	v_mul_f32_e64 v83, v88, v83
	v_pk_mul_f32 v[84:85], v[88:89], v[84:85] op_sel_hi:[0,1]
	v_pk_fma_f32 v[78:79], v[86:87], v[78:79], v[84:85] op_sel_hi:[0,1,1]
	v_pk_fma_f32 v[76:77], v[86:87], v[76:77], v[82:83] op_sel_hi:[0,1,1]
	v_mfma_f32_16x16x32_bf16 v[84:87], v[36:39], v[12:15], 0
	v_add_f32_e64 v78, v78, 0
	v_add_f32_e64 v79, v79, 0
	v_pk_add_f32 v[76:77], v[76:77], 0 op_sel_hi:[1,0]
	v_mfma_f32_16x16x32_bf16 v[80:83], v[24:27], v[12:15], 0
	v_mfma_f32_16x16x32_bf16 v[84:87], v[44:47], v[128:131], v[84:87]
	v_mfma_f32_16x16x32_bf16 v[80:83], v[28:31], v[128:131], v[80:83]
	v_mfma_f32_16x16x32_bf16 v[88:91], v[100:103], v[12:15], 0
	s_nop 5
	v_mul_f32_e64 v84, v150, v84
	v_mul_f32_e64 v85, v150, v85
	v_pk_mul_f32 v[86:87], v[150:151], v[86:87] op_sel_hi:[0,1]
	v_pk_fma_f32 v[82:83], v[82:83], v[148:149], v[86:87] op_sel_hi:[1,0,1]
	v_pk_fma_f32 v[80:81], v[80:81], v[148:149], v[84:85] op_sel_hi:[1,0,1]
	v_mfma_f32_16x16x32_bf16 v[84:87], v[56:59], v[12:15], 0
	v_add_f32_e64 v82, v82, 0
	v_add_f32_e64 v83, v83, 0
	v_pk_add_f32 v[80:81], v[80:81], 0 op_sel_hi:[1,0]
	v_mfma_f32_16x16x32_bf16 v[88:91], v[104:107], v[128:131], v[88:91]
	v_mfma_f32_16x16x32_bf16 v[84:87], v[60:63], v[128:131], v[84:87]
	v_mfma_f32_16x16x32_bf16 v[92:95], v[120:123], v[128:131], v[92:95]
	s_nop 5
	v_mul_f32_e64 v88, v150, v88
	v_mul_f32_e64 v89, v150, v89
	v_pk_mul_f32 v[90:91], v[150:151], v[90:91] op_sel_hi:[0,1]
	v_pk_fma_f32 v[86:87], v[148:149], v[86:87], v[90:91] op_sel_hi:[0,1,1]
	v_pk_fma_f32 v[84:85], v[148:149], v[84:85], v[88:89] op_sel_hi:[0,1,1]
	v_mfma_f32_16x16x32_bf16 v[88:91], v[108:111], v[12:15], 0
	v_mul_f32_e64 v92, v150, v92
	v_mul_f32_e64 v93, v150, v93
	v_pk_mul_f32 v[94:95], v[150:151], v[94:95] op_sel_hi:[0,1]
	v_pk_add_f32 v[86:87], v[86:87], 0 op_sel_hi:[1,0]
	v_mfma_f32_16x16x32_bf16 v[88:91], v[112:115], v[128:131], v[88:91]
	v_add_f32_e64 v84, v84, 0
	v_add_f32_e64 v85, v85, 0
	v_mfma_f32_16x16x32_bf16 v[96:99], v[140:143], v[12:15], 0
	v_mfma_f32_16x16x32_bf16 v[24:27], v[24:27], v[20:23], 0
	s_nop 3
	v_fma_f32 v90, v148, v90, v94
	v_fma_f32 v91, v148, v91, v95
	v_pk_fma_f32 v[88:89], v[148:149], v[88:89], v[92:93] op_sel_hi:[0,1,1]
	v_pk_add_f32 v[90:91], v[90:91], 0 op_sel_hi:[1,0]
	v_mfma_f32_16x16x32_bf16 v[92:95], v[124:127], v[12:15], 0
	v_add_f32_e64 v88, v88, 0
	v_add_f32_e64 v89, v89, 0
	v_mfma_f32_16x16x32_bf16 v[96:99], v[144:147], v[128:131], v[96:99]
	v_mfma_f32_16x16x32_bf16 v[92:95], v[136:139], v[128:131], v[92:95]
	v_mfma_f32_16x16x32_bf16 v[24:27], v[28:31], v[132:135], v[24:27]
	s_nop 5
	v_mul_f32_e64 v96, v150, v96
	v_mul_f32_e64 v97, v150, v97
	v_pk_mul_f32 v[98:99], v[150:151], v[98:99] op_sel_hi:[0,1]
	v_pk_fma_f32 v[92:93], v[148:149], v[92:93], v[96:97] op_sel_hi:[0,1,1]
	v_mfma_f32_16x16x32_bf16 v[28:31], v[36:39], v[20:23], 0
	v_mul_f32_e32 v96, 0x3fb8aa3b, v149
	v_pk_fma_f32 v[94:95], v[148:149], v[94:95], v[98:99] op_sel_hi:[0,1,1]
	v_exp_f32_e32 v148, v96
	v_mul_f32_e32 v96, 0x3fb8aa3b, v151
	v_exp_f32_e32 v150, v96
	v_mfma_f32_16x16x32_bf16 v[28:31], v[44:47], v[132:135], v[28:31]
	v_add_f32_e64 v94, v94, 0
	v_add_f32_e64 v95, v95, 0
	v_pk_add_f32 v[92:93], v[92:93], 0 op_sel_hi:[1,0]
	s_nop 4
	v_pk_mul_f32 v[28:29], v[150:151], v[28:29] op_sel_hi:[0,1]
	v_pk_mul_f32 v[30:31], v[150:151], v[30:31] op_sel_hi:[0,1]
	v_pk_fma_f32 v[26:27], v[26:27], v[148:149], v[30:31] op_sel_hi:[1,0,1]
	v_pk_fma_f32 v[24:25], v[24:25], v[148:149], v[28:29] op_sel_hi:[1,0,1]
	v_mfma_f32_16x16x32_bf16 v[28:31], v[100:103], v[20:23], 0
	v_add_f32_e64 v98, v26, 0
	v_add_f32_e64 v99, v27, 0
	v_pk_add_f32 v[96:97], v[24:25], 0 op_sel_hi:[1,0]
	v_mfma_f32_16x16x32_bf16 v[24:27], v[56:59], v[20:23], 0
	v_mfma_f32_16x16x32_bf16 v[28:31], v[104:107], v[132:135], v[28:31]
	v_mfma_f32_16x16x32_bf16 v[24:27], v[60:63], v[132:135], v[24:27]
	s_nop 6
	v_mul_f32_e64 v28, v150, v28
	v_mul_f32_e64 v29, v150, v29
	v_pk_mul_f32 v[30:31], v[150:151], v[30:31] op_sel_hi:[0,1]
	v_pk_fma_f32 v[26:27], v[148:149], v[26:27], v[30:31] op_sel_hi:[0,1,1]
	v_pk_fma_f32 v[24:25], v[148:149], v[24:25], v[28:29] op_sel_hi:[0,1,1]
	v_mfma_f32_16x16x32_bf16 v[28:31], v[116:119], v[20:23], 0
	v_add_f32_e64 v102, v26, 0
	v_add_f32_e64 v103, v27, 0
	v_pk_add_f32 v[100:101], v[24:25], 0 op_sel_hi:[1,0]
	v_mfma_f32_16x16x32_bf16 v[24:27], v[108:111], v[20:23], 0
	v_mfma_f32_16x16x32_bf16 v[28:31], v[120:123], v[132:135], v[28:31]
	v_mfma_f32_16x16x32_bf16 v[24:27], v[112:115], v[132:135], v[24:27]
	s_nop 6
	v_mul_f32_e64 v28, v150, v28
	v_mul_f32_e64 v29, v150, v29
	v_pk_mul_f32 v[30:31], v[150:151], v[30:31] op_sel_hi:[0,1]
	v_pk_fma_f32 v[26:27], v[148:149], v[26:27], v[30:31] op_sel_hi:[0,1,1]
	v_pk_fma_f32 v[24:25], v[148:149], v[24:25], v[28:29] op_sel_hi:[0,1,1]
	v_mfma_f32_16x16x32_bf16 v[28:31], v[140:143], v[20:23], 0
	v_add_f32_e64 v106, v26, 0
	v_add_f32_e64 v107, v27, 0
	v_pk_add_f32 v[104:105], v[24:25], 0 op_sel_hi:[1,0]
	v_mfma_f32_16x16x32_bf16 v[24:27], v[124:127], v[20:23], 0
	v_mfma_f32_16x16x32_bf16 v[28:31], v[144:147], v[132:135], v[28:31]
	v_mfma_f32_16x16x32_bf16 v[24:27], v[136:139], v[132:135], v[24:27]
	s_nop 6
	v_mul_f32_e64 v28, v150, v28
	v_mul_f32_e64 v29, v150, v29
	v_pk_fma_f32 v[24:25], v[148:149], v[24:25], v[28:29] op_sel_hi:[0,1,1]
	v_pk_mul_f32 v[30:31], v[150:151], v[30:31] op_sel_hi:[0,1]
	v_pk_add_f32 v[108:109], v[24:25], 0 op_sel_hi:[1,0]
	v_mov_b32_e32 v24, v190
	v_pk_fma_f32 v[26:27], v[148:149], v[26:27], v[30:31] op_sel_hi:[0,1,1]
	v_pk_add_f32 v[110:111], v[26:27], 0 op_sel_hi:[1,0]
	v_ashrrev_i32_e32 v25, 1, v24
	v_and_or_b32 v28, v24, 15, s58
	v_and_b32_e32 v26, -8, v25
	v_mad_u64_u32 v[24:25], s[0:1], v28, s22, v[202:203]
	v_or_b32_e32 v29, 16, v28
	v_ashrrev_i32_e32 v27, 31, v26
	s_mul_i32 s0, s59, 0x600
	v_mad_u64_u32 v[44:45], s[20:21], v29, s22, v[202:203]
	v_add_u32_e32 v25, s0, v25
	v_lshlrev_b64 v[30:31], 1, v[26:27]
	v_add_u32_e32 v45, s0, v45
	v_lshl_add_u64 v[36:37], v[24:25], 0, v[30:31]
	v_lshl_add_u64 v[56:57], v[44:45], 0, v[30:31]
	v_or_b32_e32 v29, 32, v28
	global_load_dwordx4 v[24:27], v[36:37], off offset:1024
	s_nop 0
	global_load_dwordx4 v[36:39], v[36:37], off offset:1088
	s_nop 0
	global_load_dwordx4 v[44:47], v[56:57], off offset:1024
	global_load_dwordx4 v[112:115], v[56:57], off offset:1088
	v_mad_u64_u32 v[56:57], s[20:21], v29, s22, v[202:203]
	v_or_b32_e32 v28, 48, v28
	v_add_u32_e32 v57, s0, v57
	v_mad_u64_u32 v[28:29], s[20:21], v28, s22, v[202:203]
	v_lshl_add_u64 v[60:61], v[56:57], 0, v[30:31]
	v_add_u32_e32 v29, s0, v29
	global_load_dwordx4 v[56:59], v[60:61], off offset:1024
	global_load_dwordx4 v[136:139], v[60:61], off offset:1088
	v_lshl_add_u64 v[60:61], v[28:29], 0, v[30:31]
	global_load_dwordx4 v[28:31], v[60:61], off offset:1024
	global_load_dwordx4 v[140:143], v[60:61], off offset:1088
	s_waitcnt vmcnt(7)
	v_mfma_f32_16x16x32_bf16 v[60:63], v[24:27], v[4:7], 0
	s_movk_i32 s21, 0x90
	s_movk_i32 s22, 0x1220
	s_mul_i32 s20, s59, 0x1220
	v_mfma_f32_16x16x32_bf16 v[116:119], v[24:27], v[8:11], 0
	v_mfma_f32_16x16x32_bf16 v[120:123], v[24:27], v[12:15], 0
	v_mfma_f32_16x16x32_bf16 v[24:27], v[24:27], v[20:23], 0
	s_waitcnt vmcnt(5)
	v_mfma_f32_16x16x32_bf16 v[144:147], v[44:47], v[4:7], 0
	v_mfma_f32_16x16x32_bf16 v[148:151], v[44:47], v[8:11], 0
	v_mfma_f32_16x16x32_bf16 v[152:155], v[44:47], v[12:15], 0
	v_mfma_f32_16x16x32_bf16 v[44:47], v[44:47], v[20:23], 0
	s_waitcnt vmcnt(3)
	v_mfma_f32_16x16x32_bf16 v[160:163], v[56:59], v[8:11], 0
	v_mfma_f32_16x16x32_bf16 v[164:167], v[56:59], v[12:15], 0
	s_waitcnt vmcnt(1)
	v_mfma_f32_16x16x32_bf16 v[216:219], v[28:31], v[8:11], 0
	v_mfma_f32_16x16x32_bf16 v[220:223], v[28:31], v[12:15], 0
	v_mfma_f32_16x16x32_bf16 v[156:159], v[56:59], v[4:7], 0
	v_mfma_f32_16x16x32_bf16 v[208:211], v[56:59], v[20:23], 0
	v_mfma_f32_16x16x32_bf16 v[212:215], v[28:31], v[4:7], 0
	v_mfma_f32_16x16x32_bf16 v[244:247], v[28:31], v[20:23], 0
	v_mfma_f32_16x16x32_bf16 v[124:127], v[36:39], v[0:3], v[60:63]
	v_mfma_f32_16x16x32_bf16 v[60:63], v[36:39], v[16:19], v[116:119]
	v_mfma_f32_16x16x32_bf16 v[28:31], v[36:39], v[128:131], v[120:123]
	v_mfma_f32_16x16x32_bf16 v[12:15], v[36:39], v[132:135], v[24:27]
	v_mfma_f32_16x16x32_bf16 v[56:59], v[112:115], v[16:19], v[148:151]
	v_mfma_f32_16x16x32_bf16 v[24:27], v[112:115], v[128:131], v[152:155]
	v_mfma_f32_16x16x32_bf16 v[8:11], v[112:115], v[132:135], v[44:47]
	v_mfma_f32_16x16x32_bf16 v[44:47], v[136:139], v[16:19], v[160:163]
	v_mfma_f32_16x16x32_bf16 v[20:23], v[136:139], v[128:131], v[164:167]
	s_waitcnt vmcnt(0)
	v_mfma_f32_16x16x32_bf16 v[36:39], v[140:143], v[16:19], v[216:219]
	v_mfma_f32_16x16x32_bf16 v[16:19], v[140:143], v[128:131], v[220:223]
	v_mov_b32_e32 v129, v190
	s_nop 0
	v_mov_b32_e32 v216, v60
	v_ashrrev_i32_e32 v130, 4, v129
	v_and_b32_e32 v128, 15, v129
	v_and_b32_e32 v129, -16, v129
	v_lshlrev_b32_e32 v131, 3, v130
	v_add_u32_e32 v129, v191, v129
	v_mfma_f32_16x16x32_bf16 v[116:119], v[136:139], v[0:3], v[156:159]
	v_mov_b32_e32 v217, v62
	v_mov_b32_e32 v218, v56
	v_mov_b32_e32 v219, v58
	v_mfma_f32_16x16x32_bf16 v[4:7], v[136:139], v[132:135], v[208:211]
	v_sub_u32_e32 v139, v129, v131
	v_lshl_add_u32 v131, v128, 2, v191
	v_mov_b32_e32 v58, v57
	v_mfma_f32_16x16x32_bf16 v[120:123], v[112:115], v[0:3], v[144:147]
	v_mov_b32_e32 v210, v116
	v_mov_b32_e32 v211, v118
	v_mov_b32_e32 v118, v117
	v_mfma_f32_16x16x32_bf16 v[112:115], v[140:143], v[0:3], v[212:215]
	v_mov_b32_e32 v220, v24
	v_mov_b32_e32 v221, v26
	v_mov_b32_e32 v26, v25
	v_mfma_f32_16x16x32_bf16 v[0:3], v[140:143], v[132:135], v[244:247]
	ds_read_b32 v142, v131 offset:17920
	ds_read_b128 v[134:137], v129 offset:17920
	ds_read_b128 v[144:147], v129 offset:17664
	v_lshlrev_b32_e32 v132, 2, v130
	v_mov_b32_e32 v214, v124
	v_mov_b32_e32 v215, v126
	s_waitcnt lgkmcnt(1)
	v_sub_f32_e32 v133, v142, v134
	v_mul_f32_e32 v133, 0x3fb8aa3b, v133
	v_exp_f32_e32 v148, v133
	v_sub_f32_e32 v133, v142, v135
	v_mul_f32_e32 v133, 0x3fb8aa3b, v133
	v_exp_f32_e32 v133, v133
	v_or_b32_e32 v134, 2, v132
	v_cmp_le_i32_e32 vcc, v132, v128
	v_cmp_le_i32_e64 s[0:1], v134, v128
	v_mul_f32_e32 v133, v125, v133
	s_waitcnt lgkmcnt(0)
	v_mul_f32_e32 v143, v145, v133
	v_sub_f32_e32 v133, v142, v136
	v_mul_f32_e32 v133, 0x3fb8aa3b, v133
	v_exp_f32_e32 v149, v133
	v_sub_f32_e32 v133, v142, v137
	v_mul_f32_e32 v133, 0x3fb8aa3b, v133
	v_exp_f32_e32 v133, v133
	v_pk_mul_f32 v[148:149], v[214:215], v[148:149]
	v_mov_b32_e32 v145, v146
	v_pk_mul_f32 v[144:145], v[144:145], v[148:149]
	v_mul_f32_e32 v133, v127, v133
	v_mov_b32_e32 v209, v114
	v_mov_b32_e32 v114, v113
	v_or_b32_e32 v113, 3, v132
	v_cndmask_b32_e32 v124, 0, v144, vcc
	v_cndmask_b32_e64 v126, 0, v145, s[0:1]
	v_mul_f32_e32 v144, v147, v133
	v_cmp_lt_i32_e64 s[0:1], v132, v128
	v_cmp_ge_i32_e64 s[50:51], v128, v113
	s_nop 0
	v_cndmask_b32_e64 v143, 0, v143, s[0:1]
	v_cndmask_b32_e64 v144, 0, v144, s[50:51]
	v_mad_u32_u24 v141, v128, s21, v139
	v_cvt_pk_bf16_f32 v145, v126, v144
	v_cvt_pk_bf16_f32 v144, v124, v143
	ds_write_b64 v141, v[144:145] offset:8448
	ds_read_b128 v[144:147], v129 offset:17984
	ds_read_b128 v[148:151], v129 offset:17728
	v_mov_b32_e32 v212, v120
	v_mov_b32_e32 v213, v122
	v_add_u32_e32 v138, 16, v132
	s_waitcnt lgkmcnt(1)
	v_sub_f32_e32 v143, v142, v144
	v_mul_f32_e32 v143, 0x3fb8aa3b, v143
	v_exp_f32_e32 v144, v143
	v_sub_f32_e32 v143, v142, v145
	v_mul_f32_e32 v143, 0x3fb8aa3b, v143
	v_exp_f32_e32 v152, v143
	v_sub_f32_e32 v143, v142, v146
	v_mul_f32_e32 v143, 0x3fb8aa3b, v143
	v_exp_f32_e32 v145, v143
	v_sub_f32_e32 v143, v142, v147
	v_mul_f32_e32 v143, 0x3fb8aa3b, v143
	v_exp_f32_e32 v153, v143
	v_pk_mul_f32 v[144:145], v[212:213], v[144:145]
	s_waitcnt lgkmcnt(0)
	v_mov_b32_e32 v146, v148
	v_mov_b32_e32 v147, v150
	v_add_u32_e32 v137, 18, v132
	v_pk_mul_f32 v[144:145], v[146:147], v[144:145]
	v_cmp_le_i32_e64 s[0:1], v138, v128
	v_mov_b32_e32 v122, v121
	v_add_u32_e32 v136, 17, v132
	v_cndmask_b32_e64 v143, 0, v144, s[0:1]
	v_cmp_le_i32_e64 s[0:1], v137, v128
	v_mov_b32_e32 v150, v149
	v_add_u32_e32 v135, 19, v132
	v_cndmask_b32_e64 v146, 0, v145, s[0:1]
	v_pk_mul_f32 v[144:145], v[122:123], v[152:153]
	v_cmp_le_i32_e64 s[0:1], v136, v128
	v_pk_mul_f32 v[144:145], v[150:151], v[144:145]
	s_nop 0
	v_cndmask_b32_e64 v144, 0, v144, s[0:1]
	v_cmp_le_i32_e64 s[0:1], v135, v128
	s_nop 1
	v_cndmask_b32_e64 v145, 0, v145, s[0:1]
	v_cvt_pk_bf16_f32 v145, v146, v145
	v_cvt_pk_bf16_f32 v144, v143, v144
	ds_write_b64 v141, v[144:145] offset:8480
	ds_read_b128 v[144:147], v129 offset:18048
	ds_read_b128 v[148:151], v129 offset:17792
	v_add_u32_e32 v133, 32, v132
	v_add_u32_e32 v126, 34, v132
	v_cmp_le_i32_e64 s[0:1], v133, v128
	s_waitcnt lgkmcnt(1)
	v_sub_f32_e32 v143, v142, v144
	v_mul_f32_e32 v143, 0x3fb8aa3b, v143
	v_exp_f32_e32 v144, v143
	v_sub_f32_e32 v143, v142, v145
	v_mul_f32_e32 v143, 0x3fb8aa3b, v143
	v_exp_f32_e32 v152, v143
	v_sub_f32_e32 v143, v142, v146
	v_mul_f32_e32 v143, 0x3fb8aa3b, v143
	v_exp_f32_e32 v145, v143
	v_sub_f32_e32 v143, v142, v147
	v_mul_f32_e32 v143, 0x3fb8aa3b, v143
	v_exp_f32_e32 v153, v143
	v_pk_mul_f32 v[144:145], v[210:211], v[144:145]
	s_waitcnt lgkmcnt(0)
	v_mov_b32_e32 v146, v148
	v_mov_b32_e32 v147, v150
	v_pk_mul_f32 v[144:145], v[146:147], v[144:145]
	v_add_u32_e32 v124, 33, v132
	v_cndmask_b32_e64 v143, 0, v144, s[0:1]
	v_cmp_le_i32_e64 s[0:1], v126, v128
	v_mov_b32_e32 v150, v149
	v_add_u32_e32 v121, 35, v132
	v_cndmask_b32_e64 v146, 0, v145, s[0:1]
	v_pk_mul_f32 v[144:145], v[118:119], v[152:153]
	v_cmp_le_i32_e64 s[0:1], v124, v128
	v_pk_mul_f32 v[144:145], v[150:151], v[144:145]
	s_nop 0
	v_cndmask_b32_e64 v144, 0, v144, s[0:1]
	v_cmp_le_i32_e64 s[0:1], v121, v128
	s_nop 1
	v_cndmask_b32_e64 v145, 0, v145, s[0:1]
	v_cvt_pk_bf16_f32 v145, v146, v145
	v_cvt_pk_bf16_f32 v144, v143, v144
	ds_write_b64 v141, v[144:145] offset:8512
	ds_read_b128 v[144:147], v129 offset:18112
	ds_read_b128 v[148:151], v129 offset:17856
	v_mov_b32_e32 v208, v112
	v_add_u32_e32 v140, 48, v132
	v_add_u32_e32 v120, 50, v132
	s_waitcnt lgkmcnt(1)
	v_sub_f32_e32 v143, v142, v144
	v_mul_f32_e32 v143, 0x3fb8aa3b, v143
	v_exp_f32_e32 v144, v143
	v_sub_f32_e32 v143, v142, v145
	v_mul_f32_e32 v143, 0x3fb8aa3b, v143
	v_exp_f32_e32 v152, v143
	v_sub_f32_e32 v143, v142, v146
	v_mul_f32_e32 v143, 0x3fb8aa3b, v143
	v_exp_f32_e32 v145, v143
	v_sub_f32_e32 v142, v142, v147
	v_mul_f32_e32 v142, 0x3fb8aa3b, v142
	v_exp_f32_e32 v153, v142
	v_pk_mul_f32 v[142:143], v[208:209], v[144:145]
	s_waitcnt lgkmcnt(0)
	v_mov_b32_e32 v144, v148
	v_mov_b32_e32 v145, v150
	v_pk_mul_f32 v[142:143], v[144:145], v[142:143]
	v_cmp_le_i32_e64 s[0:1], v140, v128
	v_add_u32_e32 v117, 49, v132
	v_mov_b32_e32 v150, v149
	v_cndmask_b32_e64 v144, 0, v142, s[0:1]
	v_cmp_le_i32_e64 s[0:1], v120, v128
	v_add_u32_e32 v116, 51, v132
	s_nop 0
	v_cndmask_b32_e64 v145, 0, v143, s[0:1]
	v_pk_mul_f32 v[142:143], v[114:115], v[152:153]
	v_cmp_le_i32_e64 s[0:1], v117, v128
	v_pk_mul_f32 v[142:143], v[150:151], v[142:143]
	s_nop 0
	v_cndmask_b32_e64 v142, 0, v142, s[0:1]
	v_cmp_le_i32_e64 s[0:1], v116, v128
	s_nop 1
	v_cndmask_b32_e64 v143, 0, v143, s[0:1]
	v_or_b32_e32 v112, 16, v128
	v_cvt_pk_bf16_f32 v143, v145, v143
	v_cvt_pk_bf16_f32 v142, v144, v142
	ds_write_b64 v141, v[142:143] offset:8544
	v_lshl_add_u32 v141, v112, 2, v191
	ds_read_b32 v142, v141 offset:17920
	ds_read_b128 v[144:147], v129 offset:17920
	ds_read_b128 v[148:151], v129 offset:17664
	v_cmp_le_i32_e64 s[0:1], v132, v112
	v_cmp_ge_i32_e64 s[50:51], v112, v113
	v_mad_u32_u24 v141, v112, s21, v139
	s_waitcnt lgkmcnt(1)
	v_sub_f32_e32 v143, v142, v144
	v_mul_f32_e32 v143, 0x3fb8aa3b, v143
	v_exp_f32_e32 v144, v143
	v_sub_f32_e32 v143, v142, v145
	v_mul_f32_e32 v143, 0x3fb8aa3b, v143
	v_sub_f32_e32 v145, v142, v146
	v_exp_f32_e32 v143, v143
	v_mul_f32_e32 v145, 0x3fb8aa3b, v145
	v_exp_f32_e32 v145, v145
	v_mov_b32_e32 v222, v12
	v_mul_f32_e32 v143, v61, v143
	s_waitcnt lgkmcnt(0)
	v_mul_f32_e32 v143, v149, v143
	v_pk_mul_f32 v[144:145], v[216:217], v[144:145]
	v_mov_b32_e32 v149, v150
	v_pk_mul_f32 v[144:145], v[148:149], v[144:145]
	v_mov_b32_e32 v223, v14
	v_cndmask_b32_e64 v60, 0, v144, s[0:1]
	v_sub_f32_e32 v144, v142, v147
	v_mul_f32_e32 v144, 0x3fb8aa3b, v144
	v_exp_f32_e32 v144, v144
	v_cmp_le_i32_e64 s[0:1], v134, v112
	v_mul_f32_e32 v144, v63, v144
	s_nop 0
	v_cndmask_b32_e64 v62, 0, v145, s[0:1]
	v_cmp_lt_i32_e64 s[0:1], v132, v112
	v_mul_f32_e32 v144, v151, v144
	v_cndmask_b32_e64 v144, 0, v144, s[50:51]
	v_cndmask_b32_e64 v143, 0, v143, s[0:1]
	v_cvt_pk_bf16_f32 v145, v62, v144
	v_cvt_pk_bf16_f32 v144, v60, v143
	ds_write_b64 v141, v[144:145] offset:8448
	ds_read_b128 v[144:147], v129 offset:17984
	ds_read_b128 v[148:151], v129 offset:17728
	v_cmp_le_i32_e64 s[0:1], v137, v112
	v_mad_u32_u24 v174, v128, s21, v129
	v_mad_u32_u24 v175, v112, s21, v129
	s_waitcnt lgkmcnt(1)
	v_sub_f32_e32 v60, v142, v144
	v_mul_f32_e32 v60, 0x3fb8aa3b, v60
	v_exp_f32_e32 v144, v60
	v_sub_f32_e32 v60, v142, v145
	v_mul_f32_e32 v60, 0x3fb8aa3b, v60
	v_exp_f32_e32 v152, v60
	v_sub_f32_e32 v60, v142, v146
	v_mul_f32_e32 v60, 0x3fb8aa3b, v60
	v_exp_f32_e32 v145, v60
	v_sub_f32_e32 v60, v142, v147
	v_mul_f32_e32 v60, 0x3fb8aa3b, v60
	v_exp_f32_e32 v153, v60
	v_pk_mul_f32 v[144:145], v[218:219], v[144:145]
	s_waitcnt lgkmcnt(0)
	v_mov_b32_e32 v146, v148
	v_mov_b32_e32 v147, v150
	v_pk_mul_f32 v[144:145], v[146:147], v[144:145]
	v_pk_mul_f32 v[56:57], v[58:59], v[152:153]
	v_mov_b32_e32 v150, v149
	v_cndmask_b32_e64 v62, 0, v145, s[0:1]
	v_pk_mul_f32 v[56:57], v[150:151], v[56:57]
	v_cmp_le_i32_e64 s[0:1], v136, v112
	v_cndmask_b32_e32 v60, 0, v144, vcc
	s_nop 0
	v_cndmask_b32_e64 v56, 0, v56, s[0:1]
	v_cmp_le_i32_e64 s[0:1], v135, v112
	s_nop 1
	v_cndmask_b32_e64 v57, 0, v57, s[0:1]
	v_cvt_pk_bf16_f32 v57, v62, v57
	v_cvt_pk_bf16_f32 v56, v60, v56
	ds_write_b64 v141, v[56:57] offset:8480
	ds_read_b128 v[144:147], v129 offset:18048
	ds_read_b128 v[148:151], v129 offset:17792
	v_mov_b32_e32 v57, v46
	v_cmp_le_i32_e64 s[0:1], v133, v112
	v_mov_b32_e32 v46, v45
	s_waitcnt lgkmcnt(1)
	v_sub_f32_e32 v56, v142, v144
	v_mul_f32_e32 v56, 0x3fb8aa3b, v56
	v_exp_f32_e32 v144, v56
	v_sub_f32_e32 v56, v142, v145
	v_mul_f32_e32 v56, 0x3fb8aa3b, v56
	v_exp_f32_e32 v152, v56
	v_sub_f32_e32 v56, v142, v146
	v_mul_f32_e32 v56, 0x3fb8aa3b, v56
	v_exp_f32_e32 v145, v56
	v_sub_f32_e32 v56, v142, v147
	v_mul_f32_e32 v56, 0x3fb8aa3b, v56
	v_exp_f32_e32 v153, v56
	v_mov_b32_e32 v56, v44
	v_pk_mul_f32 v[144:145], v[56:57], v[144:145]
	s_waitcnt lgkmcnt(0)
	v_mov_b32_e32 v146, v148
	v_mov_b32_e32 v147, v150
	v_pk_mul_f32 v[144:145], v[146:147], v[144:145]
	v_pk_mul_f32 v[44:45], v[46:47], v[152:153]
	v_cndmask_b32_e64 v60, 0, v144, s[0:1]
	v_cmp_le_i32_e64 s[0:1], v126, v112
	v_mov_b32_e32 v150, v149
	v_pk_mul_f32 v[44:45], v[150:151], v[44:45]
	v_cndmask_b32_e64 v62, 0, v145, s[0:1]
	v_cmp_le_i32_e64 s[0:1], v124, v112
	s_nop 1
	v_cndmask_b32_e64 v44, 0, v44, s[0:1]
	v_cmp_le_i32_e64 s[0:1], v121, v112
	s_nop 1
	v_cndmask_b32_e64 v45, 0, v45, s[0:1]
	v_cvt_pk_bf16_f32 v45, v62, v45
	v_cvt_pk_bf16_f32 v44, v60, v44
	ds_write_b64 v141, v[44:45] offset:8512
	ds_read_b128 v[144:147], v129 offset:18112
	ds_read_b128 v[148:151], v129 offset:17856
	v_mov_b32_e32 v45, v38
	v_cmp_le_i32_e64 s[0:1], v140, v112
	v_mov_b32_e32 v38, v37
	s_waitcnt lgkmcnt(1)
	v_sub_f32_e32 v44, v142, v144
	v_mul_f32_e32 v44, 0x3fb8aa3b, v44
	v_exp_f32_e32 v144, v44
	v_sub_f32_e32 v44, v142, v145
	v_mul_f32_e32 v44, 0x3fb8aa3b, v44
	v_exp_f32_e32 v152, v44
	v_sub_f32_e32 v44, v142, v146
	v_mul_f32_e32 v44, 0x3fb8aa3b, v44
	v_exp_f32_e32 v145, v44
	v_sub_f32_e32 v44, v142, v147
	v_mul_f32_e32 v44, 0x3fb8aa3b, v44
	v_exp_f32_e32 v153, v44
	v_mov_b32_e32 v44, v36
	v_pk_mul_f32 v[142:143], v[44:45], v[144:145]
	s_waitcnt lgkmcnt(0)
	v_mov_b32_e32 v144, v148
	v_mov_b32_e32 v145, v150
	v_pk_mul_f32 v[142:143], v[144:145], v[142:143]
	v_pk_mul_f32 v[36:37], v[38:39], v[152:153]
	v_cndmask_b32_e64 v60, 0, v142, s[0:1]
	v_cmp_le_i32_e64 s[0:1], v120, v112
	v_mov_b32_e32 v150, v149
	v_pk_mul_f32 v[36:37], v[150:151], v[36:37]
	v_cndmask_b32_e64 v62, 0, v143, s[0:1]
	v_cmp_le_i32_e64 s[0:1], v117, v112
	s_nop 1
	v_cndmask_b32_e64 v36, 0, v36, s[0:1]
	v_cmp_le_i32_e64 s[0:1], v116, v112
	s_nop 1
	v_cndmask_b32_e64 v37, 0, v37, s[0:1]
	v_cvt_pk_bf16_f32 v37, v62, v37
	v_cvt_pk_bf16_f32 v36, v60, v36
	ds_write_b64 v141, v[36:37] offset:8544
	ds_read_b32 v142, v131 offset:18048
	ds_read_b128 v[144:147], v129 offset:17920
	ds_read_b128 v[148:151], v129 offset:17664
	v_mov_b32_e32 v37, v30
	v_or_b32_e32 v141, 32, v128
	v_cmp_le_i32_e64 s[0:1], v132, v141
	s_waitcnt lgkmcnt(1)
	v_sub_f32_e32 v36, v142, v144
	v_mul_f32_e32 v36, 0x3fb8aa3b, v36
	v_exp_f32_e32 v144, v36
	v_sub_f32_e32 v36, v142, v145
	v_mul_f32_e32 v36, 0x3fb8aa3b, v36
	v_exp_f32_e32 v36, v36
	v_cmp_ge_i32_e64 s[50:51], v141, v113
	v_mad_u32_u24 v60, v128, s21, v230
	v_add_u32_e32 v62, v139, v60
	v_mul_f32_e32 v36, v29, v36
	s_waitcnt lgkmcnt(0)
	v_mul_f32_e32 v143, v149, v36
	v_sub_f32_e32 v36, v142, v146
	v_mul_f32_e32 v36, 0x3fb8aa3b, v36
	v_exp_f32_e32 v145, v36
	v_sub_f32_e32 v36, v142, v147
	v_mul_f32_e32 v36, 0x3fb8aa3b, v36
	v_exp_f32_e32 v36, v36
	v_mov_b32_e32 v149, v150
	v_add_u32_e32 v176, v129, v60
	v_mul_f32_e32 v36, v31, v36
	v_mul_f32_e32 v146, v151, v36
	v_mov_b32_e32 v36, v28
	v_pk_mul_f32 v[144:145], v[36:37], v[144:145]
	s_nop 0
	v_pk_mul_f32 v[144:145], v[148:149], v[144:145]
	s_nop 0
	v_cndmask_b32_e64 v28, 0, v144, s[0:1]
	v_cmp_le_i32_e64 s[0:1], v134, v141
	v_cndmask_b32_e64 v144, 0, v146, s[50:51]
	s_nop 0
	v_cndmask_b32_e64 v30, 0, v145, s[0:1]
	v_cmp_lt_i32_e64 s[0:1], v132, v141
	s_nop 1
	v_cndmask_b32_e64 v143, 0, v143, s[0:1]
	v_cvt_pk_bf16_f32 v145, v30, v144
	v_cvt_pk_bf16_f32 v144, v28, v143
	ds_write_b64 v62, v[144:145] offset:8448
	ds_read_b128 v[144:147], v129 offset:17984
	ds_read_b128 v[148:151], v129 offset:17728
	v_cmp_le_i32_e64 s[0:1], v138, v141
	s_waitcnt lgkmcnt(1)
	v_sub_f32_e32 v28, v142, v144
	v_mul_f32_e32 v28, 0x3fb8aa3b, v28
	v_exp_f32_e32 v144, v28
	v_sub_f32_e32 v28, v142, v145
	v_mul_f32_e32 v28, 0x3fb8aa3b, v28
	v_exp_f32_e32 v152, v28
	v_sub_f32_e32 v28, v142, v146
	v_mul_f32_e32 v28, 0x3fb8aa3b, v28
	v_exp_f32_e32 v145, v28
	v_sub_f32_e32 v28, v142, v147
	v_mul_f32_e32 v28, 0x3fb8aa3b, v28
	v_exp_f32_e32 v153, v28
	v_pk_mul_f32 v[144:145], v[220:221], v[144:145]
	s_waitcnt lgkmcnt(0)
	v_mov_b32_e32 v146, v148
	v_mov_b32_e32 v147, v150
	v_pk_mul_f32 v[144:145], v[146:147], v[144:145]
	v_pk_mul_f32 v[24:25], v[26:27], v[152:153]
	v_cndmask_b32_e64 v28, 0, v144, s[0:1]
	v_cmp_le_i32_e64 s[0:1], v137, v141
	v_mov_b32_e32 v150, v149
	v_pk_mul_f32 v[24:25], v[150:151], v[24:25]
	v_cndmask_b32_e64 v30, 0, v145, s[0:1]
	v_cmp_le_i32_e64 s[0:1], v136, v141
	s_nop 1
	v_cndmask_b32_e64 v24, 0, v24, s[0:1]
	v_cmp_le_i32_e64 s[0:1], v135, v141
	s_nop 1
	v_cndmask_b32_e64 v25, 0, v25, s[0:1]
	v_cvt_pk_bf16_f32 v25, v30, v25
	v_cvt_pk_bf16_f32 v24, v28, v24
	ds_write_b64 v62, v[24:25] offset:8480
	ds_read_b128 v[144:147], v129 offset:18048
	ds_read_b128 v[148:151], v129 offset:17792
	v_mov_b32_e32 v25, v22
	v_mov_b32_e32 v22, v21
	v_cmp_le_i32_e64 s[0:1], v126, v141
	s_waitcnt lgkmcnt(1)
	v_sub_f32_e32 v24, v142, v144
	v_mul_f32_e32 v24, 0x3fb8aa3b, v24
	v_exp_f32_e32 v144, v24
	v_sub_f32_e32 v24, v142, v145
	v_mul_f32_e32 v24, 0x3fb8aa3b, v24
	v_exp_f32_e32 v152, v24
	v_sub_f32_e32 v24, v142, v146
	v_mul_f32_e32 v24, 0x3fb8aa3b, v24
	v_exp_f32_e32 v145, v24
	v_sub_f32_e32 v24, v142, v147
	v_mul_f32_e32 v24, 0x3fb8aa3b, v24
	v_exp_f32_e32 v153, v24
	v_mov_b32_e32 v24, v20
	v_pk_mul_f32 v[144:145], v[24:25], v[144:145]
	s_waitcnt lgkmcnt(0)
	v_mov_b32_e32 v146, v148
	v_mov_b32_e32 v147, v150
	v_pk_mul_f32 v[144:145], v[146:147], v[144:145]
	v_pk_mul_f32 v[20:21], v[22:23], v[152:153]
	v_mov_b32_e32 v150, v149
	v_cndmask_b32_e64 v30, 0, v145, s[0:1]
	v_pk_mul_f32 v[20:21], v[150:151], v[20:21]
	v_cmp_le_i32_e64 s[0:1], v124, v141
	v_cndmask_b32_e32 v28, 0, v144, vcc
	s_nop 0
	v_cndmask_b32_e64 v20, 0, v20, s[0:1]
	v_cmp_le_i32_e64 s[0:1], v121, v141
	s_nop 1
	v_cndmask_b32_e64 v21, 0, v21, s[0:1]
	v_cvt_pk_bf16_f32 v21, v30, v21
	v_cvt_pk_bf16_f32 v20, v28, v20
	ds_write_b64 v62, v[20:21] offset:8512
	ds_read_b128 v[144:147], v129 offset:18112
	ds_read_b128 v[148:151], v129 offset:17856
	v_mov_b32_e32 v21, v18
	v_cmp_le_i32_e64 s[0:1], v140, v141
	v_mov_b32_e32 v18, v17
	s_waitcnt lgkmcnt(1)
	v_sub_f32_e32 v20, v142, v144
	v_mul_f32_e32 v20, 0x3fb8aa3b, v20
	v_exp_f32_e32 v144, v20
	v_sub_f32_e32 v20, v142, v145
	v_mul_f32_e32 v20, 0x3fb8aa3b, v20
	v_exp_f32_e32 v152, v20
	v_sub_f32_e32 v20, v142, v146
	v_mul_f32_e32 v20, 0x3fb8aa3b, v20
	v_exp_f32_e32 v145, v20
	v_sub_f32_e32 v20, v142, v147
	v_mul_f32_e32 v20, 0x3fb8aa3b, v20
	v_exp_f32_e32 v153, v20
	v_mov_b32_e32 v20, v16
	v_pk_mul_f32 v[142:143], v[20:21], v[144:145]
	s_waitcnt lgkmcnt(0)
	v_mov_b32_e32 v144, v148
	v_mov_b32_e32 v145, v150
	v_pk_mul_f32 v[142:143], v[144:145], v[142:143]
	v_pk_mul_f32 v[16:17], v[18:19], v[152:153]
	v_cndmask_b32_e64 v28, 0, v142, s[0:1]
	v_cmp_le_i32_e64 s[0:1], v120, v141
	v_mov_b32_e32 v150, v149
	v_pk_mul_f32 v[16:17], v[150:151], v[16:17]
	v_cndmask_b32_e64 v30, 0, v143, s[0:1]
	v_cmp_le_i32_e64 s[0:1], v117, v141
	s_nop 1
	v_cndmask_b32_e64 v16, 0, v16, s[0:1]
	v_cmp_le_i32_e64 s[0:1], v116, v141
	s_nop 1
	v_cndmask_b32_e64 v17, 0, v17, s[0:1]
	v_cvt_pk_bf16_f32 v17, v30, v17
	v_cvt_pk_bf16_f32 v16, v28, v16
	ds_write_b64 v62, v[16:17] offset:8544
	ds_read_b32 v62, v131 offset:18112
	ds_read_b128 v[140:143], v129 offset:17920
	ds_read_b128 v[144:147], v129 offset:17664
	v_mad_u32_u24 v28, v128, s21, v232
	v_add_u32_e32 v150, v139, v28
	v_or_b32_e32 v30, 48, v128
	s_waitcnt lgkmcnt(1)
	v_sub_f32_e32 v17, v62, v141
	v_mul_f32_e32 v17, 0x3fb8aa3b, v17
	v_exp_f32_e32 v17, v17
	v_sub_f32_e32 v16, v62, v140
	v_mul_f32_e32 v16, 0x3fb8aa3b, v16
	v_exp_f32_e32 v16, v16
	v_mul_f32_e32 v17, v13, v17
	s_waitcnt lgkmcnt(0)
	v_mul_f32_e32 v139, v145, v17
	v_sub_f32_e32 v17, v62, v142
	v_mul_f32_e32 v17, 0x3fb8aa3b, v17
	v_exp_f32_e32 v17, v17
	v_sub_f32_e32 v140, v62, v143
	v_mul_f32_e32 v140, 0x3fb8aa3b, v140
	v_exp_f32_e32 v140, v140
	v_pk_mul_f32 v[16:17], v[222:223], v[16:17]
	v_mov_b32_e32 v145, v146
	v_pk_mul_f32 v[16:17], v[144:145], v[16:17]
	v_cmp_le_i32_e64 s[0:1], v132, v30
	v_mul_f32_e32 v140, v15, v140
	v_mul_f32_e32 v140, v147, v140
	v_cndmask_b32_e64 v12, 0, v16, s[0:1]
	v_cmp_le_i32_e64 s[0:1], v134, v30
	v_cmp_ge_i32_e64 s[50:51], v30, v113
	v_add_u32_e32 v177, v129, v28
	v_cndmask_b32_e64 v14, 0, v17, s[0:1]
	v_cmp_lt_i32_e64 s[0:1], v132, v30
	v_cndmask_b32_e64 v16, 0, v140, s[50:51]
	s_nop 0
	v_cndmask_b32_e64 v17, 0, v139, s[0:1]
	v_and_b32_sdwa v132, v12, v228 dst_sel:DWORD dst_unused:UNUSED_PAD src0_sel:WORD_1 src1_sel:DWORD
	v_add3_u32 v12, v12, v132, s96
	v_and_b32_sdwa v132, v17, v228 dst_sel:DWORD dst_unused:UNUSED_PAD src0_sel:WORD_1 src1_sel:DWORD
	s_nop 0
	v_add3_u32 v17, v17, v132, s96
	v_and_b32_e32 v113, 0xffff0000, v17
	v_cvt_pk_bf16_f32 v17, v14, v16
	v_or_b32_sdwa v16, v113, v12 dst_sel:DWORD dst_unused:UNUSED_PAD src0_sel:DWORD src1_sel:WORD_1
	ds_write_b64 v150, v[16:17] offset:8448
	ds_read_b128 v[140:143], v129 offset:17984
	ds_read_b128 v[144:147], v129 offset:17728
	v_mov_b32_e32 v16, v8
	v_mov_b32_e32 v17, v10
	v_cmp_le_i32_e64 s[0:1], v138, v30
	s_waitcnt lgkmcnt(1)
	v_sub_f32_e32 v12, v62, v140
	v_mul_f32_e32 v12, 0x3fb8aa3b, v12
	v_exp_f32_e32 v140, v12
	v_sub_f32_e32 v12, v62, v141
	v_mul_f32_e32 v12, 0x3fb8aa3b, v12
	v_exp_f32_e32 v148, v12
	v_sub_f32_e32 v12, v62, v142
	v_mul_f32_e32 v12, 0x3fb8aa3b, v12
	v_exp_f32_e32 v141, v12
	v_sub_f32_e32 v12, v62, v143
	v_mul_f32_e32 v12, 0x3fb8aa3b, v12
	v_exp_f32_e32 v149, v12
	v_pk_mul_f32 v[140:141], v[16:17], v[140:141]
	s_waitcnt lgkmcnt(0)
	v_mov_b32_e32 v142, v144
	v_mov_b32_e32 v143, v146
	v_pk_mul_f32 v[140:141], v[142:143], v[140:141]
	v_mov_b32_e32 v10, v9
	v_cndmask_b32_e64 v12, 0, v140, s[0:1]
	v_cmp_le_i32_e64 s[0:1], v137, v30
	v_pk_mul_f32 v[8:9], v[10:11], v[148:149]
	v_mov_b32_e32 v146, v145
	v_cndmask_b32_e64 v14, 0, v141, s[0:1]
	v_pk_mul_f32 v[8:9], v[146:147], v[8:9]
	v_cmp_le_i32_e64 s[0:1], v136, v30
	s_nop 1
	v_cndmask_b32_e64 v8, 0, v8, s[0:1]
	v_cmp_le_i32_e64 s[0:1], v135, v30
	s_nop 1
	v_cndmask_b32_e64 v9, 0, v9, s[0:1]
	v_cvt_pk_bf16_f32 v9, v14, v9
	v_cvt_pk_bf16_f32 v8, v12, v8
	ds_write_b64 v150, v[8:9] offset:8480
	ds_read_b128 v[134:137], v129 offset:18048
	ds_read_b128 v[138:141], v129 offset:17792
	v_mov_b32_e32 v9, v6
	v_cmp_le_i32_e64 s[0:1], v133, v30
	v_mov_b32_e32 v6, v5
	s_waitcnt lgkmcnt(1)
	v_sub_f32_e32 v8, v62, v134
	v_mul_f32_e32 v8, 0x3fb8aa3b, v8
	v_exp_f32_e32 v134, v8
	v_sub_f32_e32 v8, v62, v135
	v_mul_f32_e32 v8, 0x3fb8aa3b, v8
	v_exp_f32_e32 v142, v8
	v_sub_f32_e32 v8, v62, v136
	v_mul_f32_e32 v8, 0x3fb8aa3b, v8
	v_exp_f32_e32 v135, v8
	v_sub_f32_e32 v8, v62, v137
	v_mul_f32_e32 v8, 0x3fb8aa3b, v8
	v_exp_f32_e32 v143, v8
	v_mov_b32_e32 v8, v4
	v_pk_mul_f32 v[134:135], v[8:9], v[134:135]
	s_waitcnt lgkmcnt(0)
	v_mov_b32_e32 v136, v138
	v_mov_b32_e32 v137, v140
	v_pk_mul_f32 v[134:135], v[136:137], v[134:135]
	v_pk_mul_f32 v[4:5], v[6:7], v[142:143]
	v_cndmask_b32_e64 v12, 0, v134, s[0:1]
	v_cmp_le_i32_e64 s[0:1], v126, v30
	v_mov_b32_e32 v140, v139
	v_pk_mul_f32 v[4:5], v[140:141], v[4:5]
	v_cndmask_b32_e64 v14, 0, v135, s[0:1]
	v_cmp_le_i32_e64 s[0:1], v124, v30
	s_nop 1
	v_cndmask_b32_e64 v4, 0, v4, s[0:1]
	v_cmp_le_i32_e64 s[0:1], v121, v30
	s_nop 1
	v_cndmask_b32_e64 v5, 0, v5, s[0:1]
	v_cvt_pk_bf16_f32 v5, v14, v5
	v_cvt_pk_bf16_f32 v4, v12, v4
	ds_write_b64 v150, v[4:5] offset:8512
	ds_read_b128 v[132:135], v129 offset:18112
	ds_read_b128 v[136:139], v129 offset:17856
	v_mov_b32_e32 v5, v2
	v_mov_b32_e32 v2, v1
	s_waitcnt lgkmcnt(1)
	v_sub_f32_e32 v4, v62, v132
	v_mul_f32_e32 v4, 0x3fb8aa3b, v4
	v_exp_f32_e32 v132, v4
	v_sub_f32_e32 v4, v62, v133
	v_mul_f32_e32 v4, 0x3fb8aa3b, v4
	v_exp_f32_e32 v140, v4
	v_sub_f32_e32 v4, v62, v134
	v_mul_f32_e32 v4, 0x3fb8aa3b, v4
	v_exp_f32_e32 v133, v4
	v_sub_f32_e32 v4, v62, v135
	v_mul_f32_e32 v4, 0x3fb8aa3b, v4
	v_exp_f32_e32 v141, v4
	v_mov_b32_e32 v4, v0
	v_pk_mul_f32 v[132:133], v[4:5], v[132:133]
	s_waitcnt lgkmcnt(0)
	v_mov_b32_e32 v134, v136
	v_mov_b32_e32 v135, v138
	v_pk_mul_f32 v[132:133], v[134:135], v[132:133]
	v_pk_mul_f32 v[0:1], v[2:3], v[140:141]
	v_cndmask_b32_e32 v12, 0, v132, vcc
	v_cmp_le_i32_e32 vcc, v120, v30
	v_mov_b32_e32 v138, v137
	v_pk_mul_f32 v[0:1], v[138:139], v[0:1]
	v_cndmask_b32_e32 v14, 0, v133, vcc
	v_cmp_le_i32_e32 vcc, v117, v30
	s_nop 1
	v_cndmask_b32_e32 v0, 0, v0, vcc
	v_cmp_le_i32_e32 vcc, v116, v30
	s_nop 1
	v_cndmask_b32_e32 v1, 0, v1, vcc
	v_cvt_pk_bf16_f32 v1, v14, v1
	v_cvt_pk_bf16_f32 v0, v12, v0
	ds_write_b64 v150, v[0:1] offset:8544
	v_lshlrev_b32_e32 v0, 1, v128
	v_sub_u32_e32 v0, v131, v0
	v_mad_u64_u32 v[0:1], s[0:1], v130, s23, v[0:1]
	s_waitcnt lgkmcnt(0)
	ds_read_u16 v1, v0 offset:132
	ds_read_u16 v12, v0 offset:264
	ds_read_u16 v14, v0 offset:396
	ds_read_u16 v30, v0 offset:528
	ds_read_u16 v62, v0 offset:660
	ds_read_u16 v113, v0 offset:792
	ds_read_u16 v116, v0 offset:924
	ds_read_u16 v117, v0
	ds_read_u16 v120, v0 offset:32
	ds_read_u16 v121, v0 offset:164
	ds_read_u16 v124, v0 offset:296
	ds_read_u16 v126, v0 offset:428
	ds_read_u16 v132, v0 offset:560
	ds_read_u16 v133, v0 offset:692
	ds_read_u16 v134, v0 offset:824
	ds_read_u16 v135, v0 offset:956
	ds_read_u16 v179, v0 offset:64
	ds_read_u16 v225, v0 offset:196
	ds_read_u16 v233, v0 offset:328
	ds_read_u16 v234, v0 offset:460
	ds_read_u16 v235, v0 offset:592
	ds_read_u16 v236, v0 offset:724
	ds_read_u16 v237, v0 offset:856
	ds_read_u16 v243, v0 offset:988
	ds_read_u16 v244, v0 offset:96
	ds_read_u16 v245, v0 offset:228
	ds_read_u16 v246, v0 offset:360
	ds_read_u16 v247, v0 offset:492
	ds_read_u16 v248, v0 offset:624
	ds_read_u16 v249, v0 offset:756
	ds_read_u16 v250, v0 offset:888
	ds_read_u16 v251, v0 offset:1020
	ds_read_b128 v[160:163], v176 offset:8448
	ds_read_b128 v[164:167], v177 offset:8448
	s_waitcnt lgkmcnt(14)
	v_perm_b32 v131, v116, v113, s25
	v_perm_b32 v130, v62, v30, s25
	v_perm_b32 v129, v14, v12, s25
	v_perm_b32 v128, v1, v117, s25
	ds_read_b128 v[152:155], v174 offset:8448
	ds_read_b128 v[156:159], v175 offset:8448
	s_waitcnt lgkmcnt(3)
	v_mfma_f32_16x16x32_bf16 v[144:147], v[128:131], v[160:163], v[80:83]
	s_nop 2
	v_perm_b32 v83, v135, v134, s25
	v_perm_b32 v82, v133, v132, s25
	v_perm_b32 v81, v126, v124, s25
	v_perm_b32 v80, v121, v120, s25
	s_waitcnt lgkmcnt(0)
	v_mfma_f32_16x16x32_bf16 v[148:151], v[128:131], v[156:159], v[64:67]
	v_mov_b32_e32 v126, v125
	v_mfma_f32_16x16x32_bf16 v[64:67], v[80:83], v[152:155], v[40:43]
	s_nop 2
	v_perm_b32 v43, v243, v237, s25
	v_perm_b32 v42, v236, v235, s25
	v_perm_b32 v41, v234, v233, s25
	v_perm_b32 v40, v225, v179, s25
	v_mfma_f32_16x16x32_bf16 v[32:35], v[128:131], v[152:155], v[32:35]
	v_mfma_f32_16x16x32_bf16 v[140:143], v[128:131], v[164:167], v[96:99]
	v_mfma_f32_16x16x32_bf16 v[68:71], v[80:83], v[156:159], v[68:71]
	v_mfma_f32_16x16x32_bf16 v[136:139], v[80:83], v[160:163], v[84:87]
	v_mfma_f32_16x16x32_bf16 v[132:135], v[80:83], v[164:167], v[100:103]
	v_mfma_f32_16x16x32_bf16 v[80:83], v[40:43], v[152:155], v[48:51]
	v_mfma_f32_16x16x32_bf16 v[84:87], v[40:43], v[156:159], v[72:75]
	v_mfma_f32_16x16x32_bf16 v[88:91], v[40:43], v[160:163], v[88:91]
	v_mfma_f32_16x16x32_bf16 v[128:131], v[40:43], v[164:167], v[104:107]
	v_perm_b32 v43, v251, v250, s25
	v_perm_b32 v42, v249, v248, s25
	v_perm_b32 v41, v247, v246, s25
	v_perm_b32 v40, v245, v244, s25
	s_nop 1
	v_mfma_f32_16x16x32_bf16 v[96:99], v[40:43], v[152:155], v[52:55]
	v_mfma_f32_16x16x32_bf16 v[100:103], v[40:43], v[156:159], v[76:79]
	v_mfma_f32_16x16x32_bf16 v[104:107], v[40:43], v[160:163], v[92:95]
	v_mfma_f32_16x16x32_bf16 v[108:111], v[40:43], v[164:167], v[108:111]
	ds_read_u16 v40, v0 offset:4224
	ds_read_u16 v41, v0 offset:4356
	ds_read_u16 v42, v0 offset:4488
	ds_read_u16 v43, v0 offset:4620
	ds_read_u16 v48, v0 offset:4752
	ds_read_u16 v49, v0 offset:4884
	ds_read_u16 v50, v0 offset:5016
	ds_read_u16 v51, v0 offset:5148
	ds_read_u16 v72, v0 offset:4256
	ds_read_u16 v73, v0 offset:4388
	ds_read_u16 v74, v0 offset:4520
	ds_read_u16 v75, v0 offset:4652
	ds_read_u16 v76, v0 offset:4784
	ds_read_u16 v77, v0 offset:4916
	ds_read_u16 v78, v0 offset:5048
	ds_read_u16 v79, v0 offset:5180
	ds_read_u16 v92, v0 offset:4288
	ds_read_u16 v93, v0 offset:4420
	ds_read_u16 v94, v0 offset:4552
	ds_read_u16 v95, v0 offset:4684
	ds_read_u16 v112, v0 offset:4816
	ds_read_u16 v113, v0 offset:4948
	ds_read_u16 v116, v0 offset:5080
	ds_read_u16 v117, v0 offset:5212
	ds_read_u16 v1, v0 offset:4320
	ds_read_u16 v12, v0 offset:4452
	ds_read_u16 v14, v0 offset:4584
	ds_read_u16 v28, v0 offset:4716
	ds_read_u16 v30, v0 offset:4848
	ds_read_u16 v60, v0 offset:4980
	ds_read_u16 v62, v0 offset:5112
	ds_read_u16 v0, v0 offset:5244
	ds_read_b128 v[152:155], v174 offset:8512
	ds_read_b128 v[156:159], v175 offset:8512
	ds_read_b128 v[160:163], v176 offset:8512
	ds_read_b128 v[164:167], v177 offset:8512
	s_waitcnt lgkmcnt(14)
	v_perm_b32 v79, v79, v78, s25
	v_perm_b32 v78, v77, v76, s25
	v_perm_b32 v77, v75, v74, s25
	v_perm_b32 v76, v73, v72, s25
	v_perm_b32 v55, v51, v50, s25
	v_perm_b32 v54, v49, v48, s25
	s_waitcnt lgkmcnt(3)
	v_mfma_f32_16x16x32_bf16 v[64:67], v[76:79], v[152:155], v[64:67]
	v_perm_b32 v53, v43, v42, s25
	v_perm_b32 v52, v41, v40, s25
	s_waitcnt lgkmcnt(0)
	s_waitcnt lgkmcnt(2)
	v_mfma_f32_16x16x32_bf16 v[68:71], v[76:79], v[156:159], v[68:71]
	s_waitcnt lgkmcnt(1)
	v_mfma_f32_16x16x32_bf16 v[72:75], v[76:79], v[160:163], v[136:139]
	s_waitcnt lgkmcnt(0)
	v_mfma_f32_16x16x32_bf16 v[76:79], v[76:79], v[164:167], v[132:135]
	s_nop 2
	v_perm_b32 v135, v117, v116, s25
	v_perm_b32 v134, v113, v112, s25
	v_perm_b32 v133, v95, v94, s25
	v_perm_b32 v132, v93, v92, s25
	v_mov_b32_e32 v116, v190
	v_mfma_f32_16x16x32_bf16 v[32:35], v[52:55], v[152:155], v[32:35]
	v_mfma_f32_16x16x32_bf16 v[92:95], v[132:135], v[164:167], v[128:131]
	s_nop 2
	v_perm_b32 v131, v0, v62, s25
	v_perm_b32 v130, v60, v30, s25
	v_perm_b32 v129, v28, v14, s25
	v_perm_b32 v128, v12, v1, s25
	v_and_b32_e32 v12, 15, v116
	v_mfma_f32_16x16x32_bf16 v[40:43], v[52:55], v[156:159], v[148:151]
	v_or_b32_e32 v0, s58, v12
	v_mad_u64_u32 v[112:113], s[0:1], v0, s22, v[204:205]
	v_mfma_f32_16x16x32_bf16 v[48:51], v[52:55], v[160:163], v[144:147]
	v_or_b32_e32 v14, 32, v12
	v_add_u32_e32 v113, s20, v113
	v_mov_b32_e32 v30, v29
	v_mfma_f32_16x16x32_bf16 v[52:55], v[52:55], v[164:167], v[140:143]
	v_mov_b32_e32 v62, v61
	v_mfma_f32_16x16x32_bf16 v[108:111], v[128:131], v[164:167], v[108:111]
	v_or_b32_e32 v167, 16, v12
	v_or_b32_e32 v0, s58, v167
	v_mfma_f32_16x16x32_bf16 v[84:87], v[132:135], v[156:159], v[84:87]
	v_mfma_f32_16x16x32_bf16 v[96:99], v[128:131], v[152:155], v[96:99]
	v_mfma_f32_16x16x32_bf16 v[100:103], v[128:131], v[156:159], v[100:103]
	v_or_b32_e32 v156, 48, v12
	v_lshl_add_u32 v157, v12, 2, v191
	ds_read_b32 v165, v157 offset:18432
	v_mfma_f32_16x16x32_bf16 v[104:107], v[128:131], v[160:163], v[104:107]
	v_mad_u64_u32 v[130:131], s[0:1], v0, s22, v[204:205]
	v_or_b32_e32 v0, s58, v14
	v_mad_u64_u32 v[148:149], s[0:1], v0, s22, v[204:205]
	v_or_b32_e32 v0, s58, v156
	v_mfma_f32_16x16x32_bf16 v[80:83], v[132:135], v[152:155], v[80:83]
	v_ashrrev_i32_e32 v155, 4, v116
	v_mad_u64_u32 v[150:151], s[0:1], v0, s22, v[204:205]
	v_mov_b32_e32 v0, 0x900
	v_mad_u32_u24 v152, v12, s21, v0
	v_lshlrev_b32_e32 v0, 2, v155
	v_ashrrev_i32_e32 v1, 31, v0
	v_lshlrev_b64 v[28:29], 1, v[0:1]
	v_add_u32_e32 v131, s20, v131
	v_lshl_add_u64 v[60:61], v[112:113], 0, v[28:29]
	v_add_u32_e32 v149, s20, v149
	v_add_u32_e32 v151, s20, v151
	global_load_dwordx2 v[142:143], v[60:61], off offset:1536
	v_lshl_add_u64 v[60:61], v[130:131], 0, v[28:29]
	v_and_b32_e32 v1, -16, v116
	v_mfma_f32_16x16x32_bf16 v[88:91], v[132:135], v[160:163], v[88:91]
	global_load_dwordx2 v[134:135], v[60:61], off offset:1536
	v_lshl_add_u64 v[60:61], v[148:149], 0, v[28:29]
	v_lshl_add_u64 v[28:29], v[150:151], 0, v[28:29]
	v_add_u32_e32 v1, v191, v1
	global_load_dwordx2 v[128:129], v[60:61], off offset:1536
	global_load_dwordx2 v[120:121], v[28:29], off offset:1536
	ds_read_b128 v[136:139], v1 offset:18432
	ds_read_b128 v[144:147], v1 offset:18176
	v_lshlrev_b32_e32 v28, 3, v155
	v_sub_u32_e32 v162, v1, v28
	v_cmp_lt_i32_e32 vcc, v0, v12
	s_waitcnt lgkmcnt(1)
	v_sub_f32_e32 v29, v165, v137
	v_mul_f32_e32 v29, 0x3fb8aa3b, v29
	v_sub_f32_e32 v28, v165, v136
	v_exp_f32_e32 v60, v29
	v_sub_f32_e32 v29, v165, v138
	v_mul_f32_e32 v28, 0x3fb8aa3b, v28
	v_mul_f32_e32 v29, 0x3fb8aa3b, v29
	v_exp_f32_e32 v28, v28
	v_exp_f32_e32 v29, v29
	s_waitcnt lgkmcnt(0)
	v_mov_b32_e32 v116, v144
	v_mov_b32_e32 v117, v146
	v_or_b32_e32 v158, 2, v0
	v_pk_mul_f32 v[28:29], v[214:215], v[28:29]
	v_cmp_ge_i32_e64 s[0:1], v158, v12
	v_pk_mul_f32 v[28:29], v[116:117], v[28:29]
	v_or_b32_e32 v160, 1, v0
	v_cndmask_b32_e64 v116, v28, 0, vcc
	v_sub_f32_e32 v28, v165, v139
	v_mul_f32_e32 v28, 0x3fb8aa3b, v28
	v_exp_f32_e32 v61, v28
	v_cndmask_b32_e64 v117, 0, v29, s[0:1]
	v_mov_b32_e32 v146, v145
	v_or_b32_e32 v159, 3, v0
	v_pk_mul_f32 v[28:29], v[126:127], v[60:61]
	v_cmp_ge_i32_e64 s[0:1], v160, v12
	v_pk_mul_f32 v[28:29], v[146:147], v[28:29]
	v_and_b32_sdwa v60, v117, v228 dst_sel:DWORD dst_unused:UNUSED_PAD src0_sel:WORD_1 src1_sel:DWORD
	v_cndmask_b32_e64 v28, 0, v28, s[0:1]
	v_cmp_ge_i32_e64 s[0:1], v159, v12
	v_cvt_pk_bf16_f32 v28, v116, v28
	s_nop 0
	v_cndmask_b32_e64 v29, 0, v29, s[0:1]
	v_add3_u32 v60, v117, v60, s96
	v_and_b32_sdwa v116, v29, v228 dst_sel:DWORD dst_unused:UNUSED_PAD src0_sel:WORD_1 src1_sel:DWORD
	s_nop 0
	v_add3_u32 v29, v29, v116, s96
	v_and_b32_e32 v29, 0xffff0000, v29
	v_mad_u32_u24 v174, v12, s21, v162
	v_or_b32_sdwa v29, v29, v60 dst_sel:DWORD dst_unused:UNUSED_PAD src0_sel:DWORD src1_sel:WORD_1
	ds_write_b64 v174, v[28:29] offset:8448
	ds_read_b128 v[124:127], v1 offset:18496
	ds_read_b128 v[138:141], v1 offset:18240
	v_add_u32_e32 v161, 18, v0
	v_add_u32_e32 v164, 17, v0
	v_add_u32_e32 v163, 34, v0
	s_waitcnt lgkmcnt(1)
	v_sub_f32_e32 v28, v165, v124
	v_mul_f32_e32 v28, 0x3fb8aa3b, v28
	v_exp_f32_e32 v60, v28
	v_sub_f32_e32 v28, v165, v125
	v_mul_f32_e32 v28, 0x3fb8aa3b, v28
	v_exp_f32_e32 v116, v28
	v_sub_f32_e32 v28, v165, v126
	v_mul_f32_e32 v28, 0x3fb8aa3b, v28
	v_exp_f32_e32 v61, v28
	v_sub_f32_e32 v28, v165, v127
	v_mul_f32_e32 v28, 0x3fb8aa3b, v28
	v_exp_f32_e32 v117, v28
	v_add_u32_e32 v28, 16, v0
	v_pk_mul_f32 v[60:61], v[212:213], v[60:61]
	s_waitcnt lgkmcnt(0)
	v_mov_b32_e32 v132, v138
	v_mov_b32_e32 v133, v140
	v_pk_mul_f32 v[60:61], v[132:133], v[60:61]
	v_cmp_ge_i32_e64 s[0:1], v28, v12
	v_ashrrev_i32_e32 v29, 31, v28
	v_mov_b32_e32 v140, v139
	v_cndmask_b32_e64 v132, 0, v60, s[0:1]
	v_cmp_ge_i32_e64 s[0:1], v161, v12
	v_lshlrev_b64 v[124:125], 1, v[28:29]
	v_add_u32_e32 v29, 19, v0
	v_cndmask_b32_e64 v133, 0, v61, s[0:1]
	v_pk_mul_f32 v[60:61], v[122:123], v[116:117]
	v_cmp_ge_i32_e64 s[0:1], v164, v12
	v_pk_mul_f32 v[60:61], v[140:141], v[60:61]
	s_nop 0
	v_cndmask_b32_e64 v60, 0, v60, s[0:1]
	v_cmp_ge_i32_e64 s[0:1], v29, v12
	s_nop 1
	v_cndmask_b32_e64 v61, 0, v61, s[0:1]
	v_lshl_add_u64 v[126:127], v[112:113], 0, v[124:125]
	global_load_dwordx2 v[144:145], v[126:127], off offset:1536
	v_lshl_add_u64 v[126:127], v[130:131], 0, v[124:125]
	v_cvt_pk_bf16_f32 v61, v133, v61
	v_cvt_pk_bf16_f32 v60, v132, v60
	global_load_dwordx2 v[136:137], v[126:127], off offset:1536
	v_lshl_add_u64 v[126:127], v[148:149], 0, v[124:125]
	v_lshl_add_u64 v[124:125], v[150:151], 0, v[124:125]
	ds_write_b64 v174, v[60:61] offset:8480
	global_load_dwordx2 v[126:127], v[126:127], off offset:1536
	v_add_u32_e32 v166, 33, v0
	global_load_dwordx2 v[124:125], v[124:125], off offset:1536
	ds_read_b128 v[138:141], v1 offset:18560
	ds_read_b128 v[212:215], v1 offset:18304
	v_mad_u32_u24 v153, v12, s21, v230
	v_mad_u32_u24 v154, v12, s21, v232
	s_waitcnt lgkmcnt(1)
	v_sub_f32_e32 v60, v165, v138
	v_mul_f32_e32 v60, 0x3fb8aa3b, v60
	v_exp_f32_e32 v138, v60
	v_sub_f32_e32 v60, v165, v139
	v_mul_f32_e32 v60, 0x3fb8aa3b, v60
	v_exp_f32_e32 v146, v60
	v_sub_f32_e32 v60, v165, v140
	v_mul_f32_e32 v60, 0x3fb8aa3b, v60
	v_exp_f32_e32 v139, v60
	v_sub_f32_e32 v60, v165, v141
	v_mul_f32_e32 v60, 0x3fb8aa3b, v60
	v_exp_f32_e32 v147, v60
	v_add_u32_e32 v60, 32, v0
	v_pk_mul_f32 v[138:139], v[210:211], v[138:139]
	s_waitcnt lgkmcnt(0)
	v_mov_b32_e32 v210, v212
	v_mov_b32_e32 v211, v214
	v_pk_mul_f32 v[138:139], v[210:211], v[138:139]
	v_cmp_ge_i32_e64 s[0:1], v60, v12
	v_ashrrev_i32_e32 v61, 31, v60
	v_pk_mul_f32 v[118:119], v[118:119], v[146:147]
	v_cndmask_b32_e64 v138, 0, v138, s[0:1]
	v_cmp_ge_i32_e64 s[0:1], v163, v12
	v_mov_b32_e32 v214, v213
	v_lshlrev_b64 v[116:117], 1, v[60:61]
	v_cndmask_b32_e64 v139, 0, v139, s[0:1]
	v_add_u32_e32 v61, 35, v0
	v_pk_mul_f32 v[118:119], v[214:215], v[118:119]
	v_cmp_ge_i32_e64 s[0:1], v166, v12
	s_nop 1
	v_cndmask_b32_e64 v118, 0, v118, s[0:1]
	v_cmp_ge_i32_e64 s[0:1], v61, v12
	s_nop 1
	v_cndmask_b32_e64 v119, 0, v119, s[0:1]
	v_lshl_add_u64 v[122:123], v[112:113], 0, v[116:117]
	global_load_dwordx2 v[140:141], v[122:123], off offset:1536
	v_lshl_add_u64 v[122:123], v[130:131], 0, v[116:117]
	v_cvt_pk_bf16_f32 v119, v139, v119
	v_cvt_pk_bf16_f32 v118, v138, v118
	global_load_dwordx2 v[132:133], v[122:123], off offset:1536
	v_lshl_add_u64 v[122:123], v[148:149], 0, v[116:117]
	v_lshl_add_u64 v[116:117], v[150:151], 0, v[116:117]
	ds_write_b64 v174, v[118:119] offset:8512
	global_load_dwordx2 v[122:123], v[122:123], off offset:1536
	v_add_u32_e32 v146, 48, v0
	global_load_dwordx2 v[116:117], v[116:117], off offset:1536
	ds_read_b128 v[210:213], v1 offset:18624
	ds_read_b128 v[244:247], v1 offset:18368
	v_ashrrev_i32_e32 v147, 31, v146
	v_cmp_ge_i32_e64 s[0:1], v146, v12
	s_waitcnt lgkmcnt(1)
	v_sub_f32_e32 v118, v165, v210
	v_mul_f32_e32 v118, 0x3fb8aa3b, v118
	v_exp_f32_e32 v210, v118
	v_sub_f32_e32 v118, v165, v211
	v_mul_f32_e32 v118, 0x3fb8aa3b, v118
	v_exp_f32_e32 v214, v118
	v_sub_f32_e32 v118, v165, v212
	v_mul_f32_e32 v118, 0x3fb8aa3b, v118
	v_exp_f32_e32 v211, v118
	v_sub_f32_e32 v118, v165, v213
	v_lshlrev_b64 v[212:213], 1, v[146:147]
	v_mul_f32_e32 v118, 0x3fb8aa3b, v118
	v_lshl_add_u64 v[112:113], v[112:113], 0, v[212:213]
	v_exp_f32_e32 v215, v118
	global_load_dwordx2 v[138:139], v[112:113], off offset:1536
	v_lshl_add_u64 v[112:113], v[130:131], 0, v[212:213]
	global_load_dwordx2 v[130:131], v[112:113], off offset:1536
	v_lshl_add_u64 v[112:113], v[148:149], 0, v[212:213]
	global_load_dwordx2 v[118:119], v[112:113], off offset:1536
	v_lshl_add_u64 v[112:113], v[150:151], 0, v[212:213]
	v_pk_mul_f32 v[148:149], v[208:209], v[210:211]
	s_waitcnt lgkmcnt(0)
	v_mov_b32_e32 v150, v244
	v_mov_b32_e32 v151, v246
	v_add_u32_e32 v165, 50, v0
	v_pk_mul_f32 v[148:149], v[150:151], v[148:149]
	v_pk_mul_f32 v[114:115], v[114:115], v[214:215]
	v_cndmask_b32_e64 v150, 0, v148, s[0:1]
	v_cmp_ge_i32_e64 s[0:1], v165, v12
	v_add_u32_e32 v148, 49, v0
	v_mov_b32_e32 v246, v245
	v_cndmask_b32_e64 v149, 0, v149, s[0:1]
	v_add_u32_e32 v147, 51, v0
	v_pk_mul_f32 v[114:115], v[246:247], v[114:115]
	v_cmp_ge_i32_e64 s[0:1], v148, v12
	s_nop 1
	v_cndmask_b32_e64 v114, 0, v114, s[0:1]
	v_cmp_ge_i32_e64 s[0:1], v147, v12
	s_nop 1
	v_cndmask_b32_e64 v115, 0, v115, s[0:1]
	v_cvt_pk_bf16_f32 v115, v149, v115
	v_cvt_pk_bf16_f32 v114, v150, v114
	ds_write_b64 v174, v[114:115] offset:8544
	ds_read_b32 v149, v157 offset:18496
	global_load_dwordx2 v[112:113], v[112:113], off offset:1536
	ds_read_b128 v[208:211], v1 offset:18432
	ds_read_b128 v[212:215], v1 offset:18176
	v_cmp_ge_i32_e64 s[0:1], v0, v167
	v_add_u32_e32 v174, v162, v152
	s_waitcnt lgkmcnt(1)
	v_sub_f32_e32 v115, v149, v209
	v_mul_f32_e32 v115, 0x3fb8aa3b, v115
	v_sub_f32_e32 v114, v149, v208
	v_exp_f32_e32 v150, v115
	v_sub_f32_e32 v115, v149, v210
	v_mul_f32_e32 v114, 0x3fb8aa3b, v114
	v_mul_f32_e32 v115, 0x3fb8aa3b, v115
	v_exp_f32_e32 v114, v114
	v_exp_f32_e32 v115, v115
	v_sub_f32_e32 v151, v149, v211
	v_mul_f32_e32 v151, 0x3fb8aa3b, v151
	v_exp_f32_e32 v151, v151
	v_pk_mul_f32 v[114:115], v[216:217], v[114:115]
	s_waitcnt lgkmcnt(0)
	v_mov_b32_e32 v208, v212
	v_mov_b32_e32 v209, v214
	v_pk_mul_f32 v[114:115], v[208:209], v[114:115]
	v_pk_mul_f32 v[62:63], v[62:63], v[150:151]
	v_cndmask_b32_e64 v114, 0, v114, s[0:1]
	v_cmp_ge_i32_e64 s[0:1], v158, v167
	v_mov_b32_e32 v214, v213
	v_pk_mul_f32 v[62:63], v[214:215], v[62:63]
	v_cndmask_b32_e64 v115, 0, v115, s[0:1]
	v_cmp_ge_i32_e64 s[0:1], v160, v167
	s_nop 1
	v_cndmask_b32_e64 v62, 0, v62, s[0:1]
	v_cmp_ge_i32_e64 s[0:1], v159, v167
	s_nop 1
	v_cndmask_b32_e64 v63, 0, v63, s[0:1]
	v_cvt_pk_bf16_f32 v63, v115, v63
	v_cvt_pk_bf16_f32 v62, v114, v62
	ds_write_b64 v174, v[62:63] offset:8448
	ds_read_b128 v[208:211], v1 offset:18496
	ds_read_b128 v[212:215], v1 offset:18240
	v_cmp_ge_i32_e64 s[0:1], v161, v167
	s_waitcnt lgkmcnt(1)
	v_sub_f32_e32 v63, v149, v209
	v_mul_f32_e32 v63, 0x3fb8aa3b, v63
	v_sub_f32_e32 v62, v149, v208
	v_exp_f32_e32 v114, v63
	v_sub_f32_e32 v63, v149, v210
	v_mul_f32_e32 v62, 0x3fb8aa3b, v62
	v_mul_f32_e32 v63, 0x3fb8aa3b, v63
	v_sub_f32_e32 v115, v149, v211
	v_exp_f32_e32 v62, v62
	v_exp_f32_e32 v63, v63
	v_mul_f32_e32 v115, 0x3fb8aa3b, v115
	v_exp_f32_e32 v115, v115
	s_waitcnt lgkmcnt(0)
	v_mov_b32_e32 v150, v212
	v_pk_mul_f32 v[62:63], v[218:219], v[62:63]
	v_mov_b32_e32 v151, v214
	v_pk_mul_f32 v[62:63], v[150:151], v[62:63]
	v_pk_mul_f32 v[58:59], v[58:59], v[114:115]
	v_mov_b32_e32 v214, v213
	v_cndmask_b32_e64 v63, 0, v63, s[0:1]
	v_pk_mul_f32 v[58:59], v[214:215], v[58:59]
	v_cmp_ge_i32_e64 s[0:1], v164, v167
	v_cndmask_b32_e64 v62, v62, 0, vcc
	s_nop 0
	v_cndmask_b32_e64 v58, 0, v58, s[0:1]
	v_cmp_ge_i32_e64 s[0:1], v29, v167
	s_nop 1
	v_cndmask_b32_e64 v59, 0, v59, s[0:1]
	v_cvt_pk_bf16_f32 v59, v63, v59
	v_cvt_pk_bf16_f32 v58, v62, v58
	ds_write_b64 v174, v[58:59] offset:8480
	ds_read_b128 v[208:211], v1 offset:18560
	ds_read_b128 v[212:215], v1 offset:18304
	v_cmp_ge_i32_e64 s[0:1], v60, v167
	s_waitcnt lgkmcnt(1)
	v_sub_f32_e32 v59, v149, v209
	v_mul_f32_e32 v59, 0x3fb8aa3b, v59
	v_sub_f32_e32 v58, v149, v208
	v_exp_f32_e32 v62, v59
	v_sub_f32_e32 v59, v149, v210
	v_mul_f32_e32 v58, 0x3fb8aa3b, v58
	v_mul_f32_e32 v59, 0x3fb8aa3b, v59
	v_exp_f32_e32 v58, v58
	v_exp_f32_e32 v59, v59
	v_sub_f32_e32 v63, v149, v211
	v_mul_f32_e32 v63, 0x3fb8aa3b, v63
	v_exp_f32_e32 v63, v63
	v_pk_mul_f32 v[56:57], v[56:57], v[58:59]
	s_waitcnt lgkmcnt(0)
	v_mov_b32_e32 v58, v212
	v_mov_b32_e32 v59, v214
	v_pk_mul_f32 v[56:57], v[58:59], v[56:57]
	v_pk_mul_f32 v[46:47], v[46:47], v[62:63]
	v_cndmask_b32_e64 v56, 0, v56, s[0:1]
	v_cmp_ge_i32_e64 s[0:1], v163, v167
	v_mov_b32_e32 v214, v213
	v_pk_mul_f32 v[46:47], v[214:215], v[46:47]
	v_cndmask_b32_e64 v57, 0, v57, s[0:1]
	v_cmp_ge_i32_e64 s[0:1], v166, v167
	s_nop 1
	v_cndmask_b32_e64 v46, 0, v46, s[0:1]
	v_cmp_ge_i32_e64 s[0:1], v61, v167
	s_nop 1
	v_cndmask_b32_e64 v47, 0, v47, s[0:1]
	v_cvt_pk_bf16_f32 v47, v57, v47
	v_cvt_pk_bf16_f32 v46, v56, v46
	ds_write_b64 v174, v[46:47] offset:8512
	ds_read_b128 v[56:59], v1 offset:18624
	ds_read_b128 v[208:211], v1 offset:18368
	v_cmp_ge_i32_e64 s[0:1], v146, v167
	v_add_u32_e32 v63, v162, v153
	s_waitcnt lgkmcnt(1)
	v_sub_f32_e32 v47, v149, v57
	v_mul_f32_e32 v47, 0x3fb8aa3b, v47
	v_sub_f32_e32 v46, v149, v56
	v_exp_f32_e32 v56, v47
	v_sub_f32_e32 v47, v149, v58
	v_mul_f32_e32 v46, 0x3fb8aa3b, v46
	v_mul_f32_e32 v47, 0x3fb8aa3b, v47
	v_exp_f32_e32 v46, v46
	v_exp_f32_e32 v47, v47
	v_sub_f32_e32 v57, v149, v59
	v_mul_f32_e32 v57, 0x3fb8aa3b, v57
	v_exp_f32_e32 v57, v57
	v_pk_mul_f32 v[44:45], v[44:45], v[46:47]
	s_waitcnt lgkmcnt(0)
	v_mov_b32_e32 v46, v208
	v_mov_b32_e32 v47, v210
	v_pk_mul_f32 v[44:45], v[46:47], v[44:45]
	v_pk_mul_f32 v[38:39], v[38:39], v[56:57]
	v_cndmask_b32_e64 v44, 0, v44, s[0:1]
	v_cmp_ge_i32_e64 s[0:1], v165, v167
	v_mov_b32_e32 v210, v209
	v_pk_mul_f32 v[38:39], v[210:211], v[38:39]
	v_cndmask_b32_e64 v45, 0, v45, s[0:1]
	v_cmp_ge_i32_e64 s[0:1], v148, v167
	s_nop 1
	v_cndmask_b32_e64 v38, 0, v38, s[0:1]
	v_cmp_ge_i32_e64 s[0:1], v147, v167
	s_nop 1
	v_cndmask_b32_e64 v39, 0, v39, s[0:1]
	v_cvt_pk_bf16_f32 v39, v45, v39
	v_cvt_pk_bf16_f32 v38, v44, v38
	ds_write_b64 v174, v[38:39] offset:8544
	ds_read_b32 v62, v157 offset:18560
	ds_read_b128 v[44:47], v1 offset:18432
	ds_read_b128 v[56:59], v1 offset:18176
	v_cmp_ge_i32_e64 s[0:1], v0, v14
	v_add_u32_e32 v167, v1, v152
	v_add_u32_e32 v174, v1, v153
	s_waitcnt lgkmcnt(1)
	v_sub_f32_e32 v39, v62, v45
	v_mul_f32_e32 v39, 0x3fb8aa3b, v39
	v_sub_f32_e32 v38, v62, v44
	v_exp_f32_e32 v44, v39
	v_sub_f32_e32 v39, v62, v46
	v_mul_f32_e32 v38, 0x3fb8aa3b, v38
	v_mul_f32_e32 v39, 0x3fb8aa3b, v39
	v_exp_f32_e32 v38, v38
	v_exp_f32_e32 v39, v39
	s_nop 0
	v_pk_mul_f32 v[36:37], v[36:37], v[38:39]
	s_waitcnt lgkmcnt(0)
	v_mov_b32_e32 v38, v56
	v_mov_b32_e32 v39, v58
	v_pk_mul_f32 v[36:37], v[38:39], v[36:37]
	v_sub_f32_e32 v38, v62, v47
	v_mul_f32_e32 v38, 0x3fb8aa3b, v38
	v_exp_f32_e32 v45, v38
	v_cndmask_b32_e64 v36, 0, v36, s[0:1]
	v_cmp_ge_i32_e64 s[0:1], v158, v14
	v_mov_b32_e32 v58, v57
	v_pk_mul_f32 v[30:31], v[30:31], v[44:45]
	v_cndmask_b32_e64 v37, 0, v37, s[0:1]
	v_pk_mul_f32 v[30:31], v[58:59], v[30:31]
	v_cmp_ge_i32_e64 s[0:1], v160, v14
	s_nop 1
	v_cndmask_b32_e64 v30, 0, v30, s[0:1]
	v_cmp_ge_i32_e64 s[0:1], v159, v14
	s_nop 1
	v_cndmask_b32_e64 v31, 0, v31, s[0:1]
	v_cvt_pk_bf16_f32 v31, v37, v31
	v_cvt_pk_bf16_f32 v30, v36, v30
	ds_write_b64 v63, v[30:31] offset:8448
	ds_read_b128 v[36:39], v1 offset:18496
	ds_read_b128 v[44:47], v1 offset:18240
	v_cmp_ge_i32_e64 s[0:1], v28, v14
	s_waitcnt lgkmcnt(1)
	v_sub_f32_e32 v31, v62, v37
	v_mul_f32_e32 v31, 0x3fb8aa3b, v31
	v_sub_f32_e32 v30, v62, v36
	v_exp_f32_e32 v36, v31
	v_sub_f32_e32 v31, v62, v38
	v_mul_f32_e32 v30, 0x3fb8aa3b, v30
	v_mul_f32_e32 v31, 0x3fb8aa3b, v31
	v_exp_f32_e32 v30, v30
	v_exp_f32_e32 v31, v31
	v_sub_f32_e32 v37, v62, v39
	v_mul_f32_e32 v37, 0x3fb8aa3b, v37
	v_exp_f32_e32 v37, v37
	v_pk_mul_f32 v[30:31], v[220:221], v[30:31]
	s_waitcnt lgkmcnt(0)
	v_mov_b32_e32 v38, v44
	v_mov_b32_e32 v39, v46
	v_pk_mul_f32 v[30:31], v[38:39], v[30:31]
	v_pk_mul_f32 v[26:27], v[26:27], v[36:37]
	v_cndmask_b32_e64 v30, 0, v30, s[0:1]
	v_cmp_ge_i32_e64 s[0:1], v161, v14
	v_mov_b32_e32 v46, v45
	v_pk_mul_f32 v[26:27], v[46:47], v[26:27]
	v_cndmask_b32_e64 v31, 0, v31, s[0:1]
	v_cmp_ge_i32_e64 s[0:1], v164, v14
	s_nop 1
	v_cndmask_b32_e64 v26, 0, v26, s[0:1]
	v_cmp_ge_i32_e64 s[0:1], v29, v14
	s_nop 1
	v_cndmask_b32_e64 v27, 0, v27, s[0:1]
	v_cvt_pk_bf16_f32 v27, v31, v27
	v_cvt_pk_bf16_f32 v26, v30, v26
	ds_write_b64 v63, v[26:27] offset:8480
	ds_read_b128 v[36:39], v1 offset:18560
	ds_read_b128 v[44:47], v1 offset:18304
	v_cmp_ge_i32_e64 s[0:1], v163, v14
	s_waitcnt lgkmcnt(1)
	v_sub_f32_e32 v27, v62, v37
	v_mul_f32_e32 v27, 0x3fb8aa3b, v27
	v_sub_f32_e32 v26, v62, v36
	v_exp_f32_e32 v30, v27
	v_sub_f32_e32 v27, v62, v38
	v_mul_f32_e32 v26, 0x3fb8aa3b, v26
	v_mul_f32_e32 v27, 0x3fb8aa3b, v27
	v_sub_f32_e32 v31, v62, v39
	v_exp_f32_e32 v26, v26
	v_exp_f32_e32 v27, v27
	v_mul_f32_e32 v31, 0x3fb8aa3b, v31
	v_exp_f32_e32 v31, v31
	v_pk_mul_f32 v[24:25], v[24:25], v[26:27]
	s_waitcnt lgkmcnt(0)
	v_mov_b32_e32 v26, v44
	v_mov_b32_e32 v27, v46
	v_pk_mul_f32 v[24:25], v[26:27], v[24:25]
	v_pk_mul_f32 v[22:23], v[22:23], v[30:31]
	v_mov_b32_e32 v46, v45
	v_cndmask_b32_e64 v25, 0, v25, s[0:1]
	v_pk_mul_f32 v[22:23], v[46:47], v[22:23]
	v_cmp_ge_i32_e64 s[0:1], v166, v14
	v_cndmask_b32_e64 v24, v24, 0, vcc
	s_nop 0
	v_cndmask_b32_e64 v22, 0, v22, s[0:1]
	v_cmp_ge_i32_e64 s[0:1], v61, v14
	s_nop 1
	v_cndmask_b32_e64 v23, 0, v23, s[0:1]
	v_cvt_pk_bf16_f32 v23, v25, v23
	v_cvt_pk_bf16_f32 v22, v24, v22
	ds_write_b64 v63, v[22:23] offset:8512
	ds_read_b128 v[22:25], v1 offset:18624
	ds_read_b128 v[36:39], v1 offset:18368
	v_cmp_ge_i32_e64 s[0:1], v146, v14
	s_waitcnt lgkmcnt(1)
	v_sub_f32_e32 v23, v62, v23
	v_mul_f32_e32 v23, 0x3fb8aa3b, v23
	v_sub_f32_e32 v22, v62, v22
	v_exp_f32_e32 v26, v23
	v_sub_f32_e32 v23, v62, v24
	v_mul_f32_e32 v22, 0x3fb8aa3b, v22
	v_mul_f32_e32 v23, 0x3fb8aa3b, v23
	v_exp_f32_e32 v22, v22
	v_exp_f32_e32 v23, v23
	v_sub_f32_e32 v24, v62, v25
	v_mul_f32_e32 v24, 0x3fb8aa3b, v24
	v_exp_f32_e32 v27, v24
	v_pk_mul_f32 v[20:21], v[20:21], v[22:23]
	s_waitcnt lgkmcnt(0)
	v_mov_b32_e32 v22, v36
	v_mov_b32_e32 v23, v38
	v_pk_mul_f32 v[20:21], v[22:23], v[20:21]
	v_pk_mul_f32 v[18:19], v[18:19], v[26:27]
	v_cndmask_b32_e64 v20, 0, v20, s[0:1]
	v_cmp_ge_i32_e64 s[0:1], v165, v14
	v_mov_b32_e32 v38, v37
	v_pk_mul_f32 v[18:19], v[38:39], v[18:19]
	v_cndmask_b32_e64 v21, 0, v21, s[0:1]
	v_cmp_ge_i32_e64 s[0:1], v148, v14
	s_nop 1
	v_cndmask_b32_e64 v18, 0, v18, s[0:1]
	v_cmp_ge_i32_e64 s[0:1], v147, v14
	s_nop 1
	v_cndmask_b32_e64 v14, 0, v19, s[0:1]
	v_cvt_pk_bf16_f32 v19, v21, v14
	v_cvt_pk_bf16_f32 v18, v20, v18
	ds_write_b64 v63, v[18:19] offset:8544
	ds_read_b32 v36, v157 offset:18624
	ds_read_b128 v[18:21], v1 offset:18432
	ds_read_b128 v[22:25], v1 offset:18176
	v_cmp_ge_i32_e64 s[0:1], v0, v156
	v_add_u32_e32 v37, v162, v154
	v_add_u32_e32 v154, v1, v154
	s_waitcnt lgkmcnt(1)
	v_sub_f32_e32 v14, v36, v18
	v_mul_f32_e32 v14, 0x3fb8aa3b, v14
	v_exp_f32_e32 v18, v14
	v_sub_f32_e32 v14, v36, v19
	v_mul_f32_e32 v14, 0x3fb8aa3b, v14
	v_exp_f32_e32 v26, v14
	v_sub_f32_e32 v14, v36, v20
	v_mul_f32_e32 v14, 0x3fb8aa3b, v14
	v_exp_f32_e32 v19, v14
	v_sub_f32_e32 v14, v36, v21
	v_mul_f32_e32 v14, 0x3fb8aa3b, v14
	v_exp_f32_e32 v27, v14
	v_pk_mul_f32 v[18:19], v[222:223], v[18:19]
	s_waitcnt lgkmcnt(0)
	v_mov_b32_e32 v30, v22
	v_mov_b32_e32 v31, v24
	v_pk_mul_f32 v[18:19], v[30:31], v[18:19]
	v_mov_b32_e32 v14, v13
	v_cndmask_b32_e64 v0, 0, v18, s[0:1]
	v_cmp_ge_i32_e64 s[0:1], v158, v156
	v_pk_mul_f32 v[14:15], v[14:15], v[26:27]
	v_mov_b32_e32 v24, v23
	v_cndmask_b32_e64 v18, 0, v19, s[0:1]
	v_pk_mul_f32 v[14:15], v[24:25], v[14:15]
	v_cmp_ge_i32_e64 s[0:1], v160, v156
	s_nop 1
	v_cndmask_b32_e64 v13, 0, v14, s[0:1]
	v_cmp_ge_i32_e64 s[0:1], v159, v156
	s_nop 1
	v_cndmask_b32_e64 v14, 0, v15, s[0:1]
	v_cvt_pk_bf16_f32 v15, v18, v14
	v_cvt_pk_bf16_f32 v14, v0, v13
	ds_write_b64 v37, v[14:15] offset:8448
	ds_read_b128 v[18:21], v1 offset:18496
	ds_read_b128 v[22:25], v1 offset:18240
	v_cmp_ge_i32_e64 s[0:1], v28, v156
	s_waitcnt lgkmcnt(1)
	v_sub_f32_e32 v0, v36, v18
	v_mul_f32_e32 v0, 0x3fb8aa3b, v0
	v_exp_f32_e32 v14, v0
	v_sub_f32_e32 v0, v36, v19
	v_mul_f32_e32 v0, 0x3fb8aa3b, v0
	v_exp_f32_e32 v18, v0
	v_sub_f32_e32 v0, v36, v20
	v_mul_f32_e32 v0, 0x3fb8aa3b, v0
	v_exp_f32_e32 v15, v0
	v_sub_f32_e32 v0, v36, v21
	v_mul_f32_e32 v0, 0x3fb8aa3b, v0
	v_exp_f32_e32 v19, v0
	v_pk_mul_f32 v[14:15], v[16:17], v[14:15]
	s_waitcnt lgkmcnt(0)
	v_mov_b32_e32 v16, v22
	v_mov_b32_e32 v17, v24
	v_pk_mul_f32 v[14:15], v[16:17], v[14:15]
	v_pk_mul_f32 v[10:11], v[10:11], v[18:19]
	v_cndmask_b32_e64 v0, 0, v14, s[0:1]
	v_cmp_ge_i32_e64 s[0:1], v161, v156
	v_mov_b32_e32 v24, v23
	v_pk_mul_f32 v[10:11], v[24:25], v[10:11]
	v_cndmask_b32_e64 v13, 0, v15, s[0:1]
	v_cmp_ge_i32_e64 s[0:1], v164, v156
	s_nop 1
	v_cndmask_b32_e64 v10, 0, v10, s[0:1]
	v_cmp_ge_i32_e64 s[0:1], v29, v156
	s_nop 1
	v_cndmask_b32_e64 v11, 0, v11, s[0:1]
	v_cvt_pk_bf16_f32 v11, v13, v11
	v_cvt_pk_bf16_f32 v10, v0, v10
	ds_write_b64 v37, v[10:11] offset:8480
	ds_read_b128 v[14:17], v1 offset:18560
	ds_read_b128 v[18:21], v1 offset:18304
	v_cmp_ge_i32_e64 s[0:1], v60, v156
	s_waitcnt lgkmcnt(1)
	v_sub_f32_e32 v0, v36, v14
	v_mul_f32_e32 v0, 0x3fb8aa3b, v0
	v_exp_f32_e32 v10, v0
	v_sub_f32_e32 v0, v36, v15
	v_mul_f32_e32 v0, 0x3fb8aa3b, v0
	v_exp_f32_e32 v14, v0
	v_sub_f32_e32 v0, v36, v16
	v_mul_f32_e32 v0, 0x3fb8aa3b, v0
	v_exp_f32_e32 v11, v0
	v_sub_f32_e32 v0, v36, v17
	v_mul_f32_e32 v0, 0x3fb8aa3b, v0
	v_exp_f32_e32 v15, v0
	v_pk_mul_f32 v[8:9], v[8:9], v[10:11]
	s_waitcnt lgkmcnt(0)
	v_mov_b32_e32 v10, v18
	v_mov_b32_e32 v11, v20
	v_pk_mul_f32 v[8:9], v[10:11], v[8:9]
	v_pk_mul_f32 v[6:7], v[6:7], v[14:15]
	v_cndmask_b32_e64 v0, 0, v8, s[0:1]
	v_cmp_ge_i32_e64 s[0:1], v163, v156
	v_mov_b32_e32 v20, v19
	v_pk_mul_f32 v[6:7], v[20:21], v[6:7]
	v_cndmask_b32_e64 v8, 0, v9, s[0:1]
	v_cmp_ge_i32_e64 s[0:1], v166, v156
	s_nop 1
	v_cndmask_b32_e64 v6, 0, v6, s[0:1]
	v_cmp_ge_i32_e64 s[0:1], v61, v156
	s_nop 1
	v_cndmask_b32_e64 v7, 0, v7, s[0:1]
	v_cvt_pk_bf16_f32 v7, v8, v7
	v_cvt_pk_bf16_f32 v6, v0, v6
	ds_write_b64 v37, v[6:7] offset:8512
	ds_read_b128 v[6:9], v1 offset:18624
	ds_read_b128 v[14:17], v1 offset:18368
	v_mad_u32_u24 v166, v12, s21, v1
	s_waitcnt lgkmcnt(1)
	v_sub_f32_e32 v0, v36, v6
	v_mul_f32_e32 v0, 0x3fb8aa3b, v0
	v_exp_f32_e32 v6, v0
	v_sub_f32_e32 v0, v36, v7
	v_mul_f32_e32 v0, 0x3fb8aa3b, v0
	v_exp_f32_e32 v10, v0
	v_sub_f32_e32 v0, v36, v8
	v_mul_f32_e32 v0, 0x3fb8aa3b, v0
	v_exp_f32_e32 v7, v0
	v_sub_f32_e32 v0, v36, v9
	v_mul_f32_e32 v0, 0x3fb8aa3b, v0
	v_exp_f32_e32 v11, v0
	v_pk_mul_f32 v[4:5], v[4:5], v[6:7]
	s_waitcnt lgkmcnt(0)
	v_mov_b32_e32 v6, v14
	v_mov_b32_e32 v7, v16
	v_pk_mul_f32 v[4:5], v[6:7], v[4:5]
	v_pk_mul_f32 v[2:3], v[2:3], v[10:11]
	v_cndmask_b32_e64 v0, v4, 0, vcc
	v_cmp_ge_i32_e32 vcc, v165, v156
	v_mov_b32_e32 v16, v15
	v_pk_mul_f32 v[2:3], v[16:17], v[2:3]
	v_cndmask_b32_e32 v4, 0, v5, vcc
	v_cmp_ge_i32_e32 vcc, v148, v156
	s_nop 1
	v_cndmask_b32_e32 v2, 0, v2, vcc
	v_cmp_ge_i32_e32 vcc, v147, v156
	s_nop 1
	v_cndmask_b32_e32 v3, 0, v3, vcc
	v_cvt_pk_bf16_f32 v3, v4, v3
	v_cvt_pk_bf16_f32 v2, v0, v2
	ds_write_b64 v37, v[2:3] offset:8544
	v_lshlrev_b32_e32 v0, 1, v12
	v_mul_lo_u32 v2, v155, s23
	v_add3_u32 v114, v191, v0, v2
	s_waitcnt lgkmcnt(0)
	ds_read_u16 v0, v114 offset:132
	ds_read_u16 v4, v114 offset:264
	ds_read_u16 v5, v114 offset:396
	ds_read_u16 v2, v114 offset:528
	ds_read_u16 v6, v114 offset:660
	ds_read_u16 v3, v114 offset:792
	ds_read_u16 v7, v114 offset:924
	ds_read_u16 v8, v114
	ds_read_u16 v9, v114 offset:32
	ds_read_u16 v10, v114 offset:164
	ds_read_u16 v11, v114 offset:296
	ds_read_u16 v20, v114 offset:428
	ds_read_u16 v21, v114 offset:560
	ds_read_u16 v22, v114 offset:692
	ds_read_u16 v23, v114 offset:824
	ds_read_u16 v24, v114 offset:956
	ds_read_u16 v36, v114 offset:64
	ds_read_u16 v37, v114 offset:196
	ds_read_u16 v38, v114 offset:328
	ds_read_u16 v39, v114 offset:460
	ds_read_u16 v115, v114 offset:592
	ds_read_u16 v155, v114 offset:724
	ds_read_u16 v156, v114 offset:856
	ds_read_u16 v157, v114 offset:988
	ds_read_u16 v158, v114 offset:96
	ds_read_u16 v159, v114 offset:228
	ds_read_u16 v160, v114 offset:360
	ds_read_u16 v161, v114 offset:492
	ds_read_u16 v162, v114 offset:624
	ds_read_u16 v163, v114 offset:756
	ds_read_u16 v164, v114 offset:888
	ds_read_u16 v165, v114 offset:1020
	ds_read_b128 v[16:19], v166 offset:8448
	ds_read_b128 v[150:153], v154 offset:8448
	ds_read_b128 v[56:59], v167 offset:8448
	ds_read_b128 v[146:149], v174 offset:8448
	s_waitcnt lgkmcnt(14)
	v_perm_b32 v3, v7, v3, s25
	v_perm_b32 v2, v6, v2, s25
	v_perm_b32 v1, v5, v4, s25
	v_perm_b32 v0, v0, v8, s25
	s_waitcnt lgkmcnt(3)
	s_nop 0
	v_mfma_f32_16x16x32_bf16 v[60:63], v[0:3], v[16:19], v[32:35]
	s_waitcnt lgkmcnt(1)
	v_mfma_f32_16x16x32_bf16 v[44:47], v[0:3], v[56:59], v[40:43]
	s_waitcnt lgkmcnt(0)
	v_mfma_f32_16x16x32_bf16 v[28:31], v[0:3], v[146:149], v[48:51]
	v_mfma_f32_16x16x32_bf16 v[12:15], v[0:3], v[150:153], v[52:55]
	v_perm_b32 v3, v24, v23, s25
	v_perm_b32 v2, v22, v21, s25
	v_perm_b32 v1, v20, v11, s25
	v_perm_b32 v0, v10, v9, s25
	s_nop 1
	v_mfma_f32_16x16x32_bf16 v[48:51], v[0:3], v[16:19], v[64:67]
	s_nop 2
	v_perm_b32 v67, v165, v164, s25
	v_perm_b32 v66, v163, v162, s25
	v_mfma_f32_16x16x32_bf16 v[40:43], v[0:3], v[56:59], v[68:71]
	v_perm_b32 v65, v161, v160, s25
	v_perm_b32 v64, v159, v158, s25
	v_mfma_f32_16x16x32_bf16 v[24:27], v[0:3], v[146:149], v[72:75]
	v_mfma_f32_16x16x32_bf16 v[8:11], v[0:3], v[150:153], v[76:79]
	v_perm_b32 v3, v157, v156, s25
	v_perm_b32 v2, v155, v115, s25
	v_perm_b32 v1, v39, v38, s25
	v_perm_b32 v0, v37, v36, s25
	v_mfma_f32_16x16x32_bf16 v[52:55], v[64:67], v[146:149], v[104:107]
	s_nop 0
	v_mfma_f32_16x16x32_bf16 v[36:39], v[0:3], v[16:19], v[80:83]
	v_mfma_f32_16x16x32_bf16 v[32:35], v[0:3], v[56:59], v[84:87]
	v_mfma_f32_16x16x32_bf16 v[20:23], v[0:3], v[146:149], v[88:91]
	v_mfma_f32_16x16x32_bf16 v[4:7], v[0:3], v[150:153], v[92:95]
	v_mfma_f32_16x16x32_bf16 v[0:3], v[64:67], v[16:19], v[96:99]
	v_mfma_f32_16x16x32_bf16 v[16:19], v[64:67], v[56:59], v[100:103]
	v_mfma_f32_16x16x32_bf16 v[56:59], v[64:67], v[150:153], v[108:111]
	s_nop 1
	ds_read_u16 v100, v114 offset:4224
	ds_read_u16 v104, v114 offset:4356
	ds_read_u16 v101, v114 offset:4488
	ds_read_u16 v105, v114 offset:4620
	ds_read_u16 v102, v114 offset:4752
	ds_read_u16 v106, v114 offset:4884
	ds_read_u16 v103, v114 offset:5016
	ds_read_u16 v107, v114 offset:5148
	ds_read_u16 v64, v114 offset:4256
	ds_read_u16 v65, v114 offset:4388
	ds_read_u16 v66, v114 offset:4520
	ds_read_u16 v67, v114 offset:4652
	ds_read_u16 v108, v114 offset:4784
	ds_read_u16 v109, v114 offset:4916
	ds_read_u16 v110, v114 offset:5048
	ds_read_u16 v111, v114 offset:5180
	ds_read_u16 v92, v114 offset:4288
	ds_read_u16 v93, v114 offset:4420
	ds_read_u16 v94, v114 offset:4552
	ds_read_u16 v95, v114 offset:4684
	ds_read_u16 v96, v114 offset:4816
	ds_read_u16 v97, v114 offset:4948
	ds_read_u16 v98, v114 offset:5080
	ds_read_u16 v99, v114 offset:5212
	ds_read_u16 v84, v114 offset:4320
	ds_read_u16 v85, v114 offset:4452
	ds_read_u16 v86, v114 offset:4584
	ds_read_u16 v87, v114 offset:4716
	ds_read_u16 v88, v114 offset:4848
	ds_read_u16 v89, v114 offset:4980
	ds_read_u16 v90, v114 offset:5112
	ds_read_u16 v91, v114 offset:5244
	ds_read_b128 v[68:71], v166 offset:8512
	ds_read_b128 v[72:75], v167 offset:8512
	ds_read_b128 v[76:79], v174 offset:8512
	ds_read_b128 v[80:83], v154 offset:8512
	s_waitcnt lgkmcnt(14)
	v_perm_b32 v103, v107, v103, s25
	v_perm_b32 v102, v106, v102, s25
	v_perm_b32 v101, v105, v101, s25
	v_perm_b32 v100, v104, v100, s25
	s_waitcnt lgkmcnt(4)
	v_perm_b32 v91, v91, v90, s25
	v_perm_b32 v90, v89, v88, s25
	s_waitcnt lgkmcnt(3)
	v_mfma_f32_16x16x32_bf16 v[104:107], v[100:103], v[68:71], v[60:63]
	v_perm_b32 v89, v87, v86, s25
	s_nop 1
	v_perm_b32 v63, v111, v110, s25
	v_perm_b32 v62, v109, v108, s25
	v_perm_b32 v61, v67, v66, s25
	v_perm_b32 v60, v65, v64, s25
	v_perm_b32 v88, v85, v84, s25
	s_waitcnt lgkmcnt(2)
	v_mfma_f32_16x16x32_bf16 v[44:47], v[100:103], v[72:75], v[44:47]
	s_waitcnt lgkmcnt(0)
	v_mfma_f32_16x16x32_bf16 v[64:67], v[60:63], v[68:71], v[48:51]
	s_nop 2
	v_perm_b32 v51, v99, v98, s25
	v_perm_b32 v50, v97, v96, s25
	v_perm_b32 v49, v95, v94, s25
	v_perm_b32 v48, v93, v92, s25
	v_mfma_f32_16x16x32_bf16 v[40:43], v[60:63], v[72:75], v[40:43]
	s_waitcnt lgkmcnt(1)
	v_mfma_f32_16x16x32_bf16 v[24:27], v[60:63], v[76:79], v[24:27]
	s_waitcnt lgkmcnt(0)
	v_mfma_f32_16x16x32_bf16 v[8:11], v[60:63], v[80:83], v[8:11]
	v_mfma_f32_16x16x32_bf16 v[60:63], v[48:51], v[68:71], v[36:39]
	v_mfma_f32_16x16x32_bf16 v[36:39], v[48:51], v[72:75], v[32:35]
	v_mfma_f32_16x16x32_bf16 v[20:23], v[48:51], v[76:79], v[20:23]
	s_nop 5
	v_mov_b32_e32 v84, v60
	v_mov_b32_e32 v85, v62
	v_mov_b32_e32 v62, v61
	v_mfma_f32_16x16x32_bf16 v[4:7], v[48:51], v[80:83], v[4:7]
	v_mfma_f32_16x16x32_bf16 v[48:51], v[88:91], v[68:71], v[0:3]
	s_waitcnt vmcnt(15)
	v_and_b32_e32 v68, 0xffff0000, v142
	v_and_b32_e32 v69, 0xffff0000, v143
	v_mfma_f32_16x16x32_bf16 v[0:3], v[88:91], v[80:83], v[56:59]
	s_nop 2
	v_mul_f32_e32 v59, 0xbfb8aa3b, v68
	v_exp_f32_e32 v59, v59
	v_mfma_f32_16x16x32_bf16 v[32:35], v[88:91], v[72:75], v[16:19]
	v_mov_b32_e32 v74, v190
	v_lshlrev_b32_e32 v57, 16, v143
	v_lshlrev_b32_e32 v56, 16, v142
	v_add_f32_e32 v59, 1.0, v59
	v_mfma_f32_16x16x32_bf16 v[16:19], v[88:91], v[76:79], v[52:55]
	v_mul_f32_e32 v58, 0xbfb8aa3b, v56
	v_rcp_f32_e32 v70, v59
	v_mul_f32_e32 v59, 0xbfb8aa3b, v57
	v_ashrrev_i32_e32 v53, 2, v74
	v_and_b32_e32 v52, 15, v74
	v_lshlrev_b32_e32 v53, 1, v53
	v_exp_f32_e32 v58, v58
	v_exp_f32_e32 v59, v59
	v_and_b32_e32 v53, -8, v53
	v_mul_u32_u24_e32 v52, 0x84, v52
	v_mfma_f32_16x16x32_bf16 v[28:31], v[100:103], v[76:79], v[28:31]
	v_xor_b32_e32 v54, 16, v224
	v_add_u32_e32 v55, 64, v168
	v_add3_u32 v77, v191, v53, v52
	v_cmp_lt_i32_e32 vcc, v54, v55
	ds_read2_b32 v[52:53], v77 offset1:1
	v_add_f32_e32 v58, 1.0, v58
	v_cndmask_b32_e32 v54, v224, v54, vcc
	v_add_f32_e32 v59, 1.0, v59
	v_lshlrev_b32_e32 v76, 2, v54
	v_xor_b32_e32 v54, 32, v224
	v_rcp_f32_e32 v58, v58
	v_rcp_f32_e32 v59, v59
	v_cmp_lt_i32_e32 vcc, v54, v55
	s_waitcnt lgkmcnt(0)
	v_lshlrev_b32_e32 v55, 16, v53
	v_mov_b32_e32 v72, v104
	v_cndmask_b32_e32 v54, v224, v54, vcc
	v_lshlrev_b32_e32 v75, 2, v54
	v_lshlrev_b32_e32 v54, 16, v52
	v_mov_b32_e32 v73, v106
	v_pk_fma_f32 v[54:55], v[188:189], v[54:55], v[72:73]
	v_pk_mul_f32 v[56:57], v[58:59], v[56:57]
	s_waitcnt vmcnt(11)
	v_and_b32_e32 v78, 0xffff0000, v144
	v_pk_mul_f32 v[54:55], v[56:57], v[54:55]
	v_mul_f32_e32 v56, 0xbfb8aa3b, v69
	v_exp_f32_e32 v56, v56
	v_mfma_f32_16x16x32_bf16 v[12:15], v[100:103], v[80:83], v[12:15]
	v_mul_f32_e32 v73, 0xbfb8aa3b, v78
	v_mov_b32_e32 v82, v64
	v_add_f32_e32 v56, 1.0, v56
	v_rcp_f32_e32 v71, v56
	v_exp_f32_e32 v73, v73
	v_and_b32_e32 v79, 0xffff0000, v145
	v_and_b32_e32 v53, 0xffff0000, v53
	v_pk_mul_f32 v[56:57], v[70:71], v[68:69]
	v_lshlrev_b32_e32 v71, 16, v145
	v_mul_f32_e32 v64, 0xbfb8aa3b, v71
	v_exp_f32_e32 v64, v64
	v_add_f32_e32 v73, 1.0, v73
	v_and_b32_e32 v52, 0xffff0000, v52
	v_mov_b32_e32 v106, v105
	v_add_f32_e32 v64, 1.0, v64
	v_lshlrev_b32_e32 v70, 16, v144
	v_rcp_f32_e32 v80, v73
	v_rcp_f32_e32 v73, v64
	v_mul_f32_e32 v64, 0xbfb8aa3b, v79
	v_pk_fma_f32 v[52:53], v[188:189], v[52:53], v[106:107]
	v_mul_f32_e32 v72, 0xbfb8aa3b, v70
	v_exp_f32_e32 v64, v64
	v_pk_mul_f32 v[58:59], v[56:57], v[52:53]
	v_exp_f32_e32 v72, v72
	v_pk_mul_f32 v[52:53], v[58:59], v[58:59]
	v_add_f32_e32 v64, 1.0, v64
	v_pk_fma_f32 v[68:69], v[54:55], v[54:55], v[52:53]
	ds_read2_b32 v[52:53], v77 offset0:8 offset1:9
	v_add_f32_e32 v72, 1.0, v72
	v_rcp_f32_e32 v81, v64
	v_rcp_f32_e32 v72, v72
	v_mov_b32_e32 v83, v66
	s_waitcnt lgkmcnt(0)
	v_lshlrev_b32_e32 v56, 16, v52
	v_lshlrev_b32_e32 v57, 16, v53
	v_and_b32_e32 v53, 0xffff0000, v53
	v_and_b32_e32 v52, 0xffff0000, v52
	v_mov_b32_e32 v66, v65
	v_pk_fma_f32 v[52:53], v[188:189], v[52:53], v[66:67]
	v_pk_mul_f32 v[64:65], v[80:81], v[78:79]
	v_pk_fma_f32 v[56:57], v[188:189], v[56:57], v[82:83]
	v_pk_mul_f32 v[70:71], v[72:73], v[70:71]
	v_pk_mul_f32 v[52:53], v[64:65], v[52:53]
	v_pk_mul_f32 v[56:57], v[70:71], v[56:57]
	v_pk_mul_f32 v[64:65], v[52:53], v[52:53]
	s_waitcnt vmcnt(7)
	v_and_b32_e32 v80, 0xffff0000, v140
	v_pk_fma_f32 v[66:67], v[56:57], v[56:57], v[64:65]
	ds_read2_b32 v[64:65], v77 offset0:16 offset1:17
	v_mul_f32_e32 v79, 0xbfb8aa3b, v80
	v_exp_f32_e32 v79, v79
	v_and_b32_e32 v81, 0xffff0000, v141
	v_mov_b32_e32 v86, v48
	s_waitcnt lgkmcnt(0)
	v_lshlrev_b32_e32 v71, 16, v65
	v_and_b32_e32 v73, 0xffff0000, v65
	v_lshlrev_b32_e32 v65, 16, v141
	v_mul_f32_e32 v60, 0xbfb8aa3b, v65
	v_exp_f32_e32 v60, v60
	v_and_b32_e32 v72, 0xffff0000, v64
	v_add_f32_e32 v79, 1.0, v79
	v_lshlrev_b32_e32 v70, 16, v64
	v_add_f32_e32 v60, 1.0, v60
	v_lshlrev_b32_e32 v64, 16, v140
	v_rcp_f32_e32 v82, v79
	v_rcp_f32_e32 v79, v60
	v_pk_fma_f32 v[60:61], v[188:189], v[72:73], v[62:63]
	v_mul_f32_e32 v62, 0xbfb8aa3b, v81
	v_mul_f32_e32 v78, 0xbfb8aa3b, v64
	v_exp_f32_e32 v62, v62
	v_exp_f32_e32 v78, v78
	v_pk_fma_f32 v[70:71], v[188:189], v[70:71], v[84:85]
	v_mov_b32_e32 v87, v50
	v_add_f32_e32 v62, 1.0, v62
	v_add_f32_e32 v78, 1.0, v78
	v_rcp_f32_e32 v83, v62
	v_rcp_f32_e32 v78, v78
	v_mov_b32_e32 v50, v49
	v_add_f32_e32 v66, v66, v67
	v_pk_mul_f32 v[62:63], v[82:83], v[80:81]
	v_pk_mul_f32 v[64:65], v[78:79], v[64:65]
	v_pk_mul_f32 v[60:61], v[62:63], v[60:61]
	v_pk_mul_f32 v[64:65], v[64:65], v[70:71]
	v_pk_mul_f32 v[62:63], v[60:61], v[60:61]
	s_waitcnt vmcnt(3)
	v_and_b32_e32 v82, 0xffff0000, v138
	v_pk_fma_f32 v[70:71], v[64:65], v[64:65], v[62:63]
	ds_read2_b32 v[62:63], v77 offset0:24 offset1:25
	v_mul_f32_e32 v81, 0xbfb8aa3b, v82
	v_exp_f32_e32 v81, v81
	v_and_b32_e32 v83, 0xffff0000, v139
	v_add_f32_e32 v67, v68, v69
	s_waitcnt lgkmcnt(0)
	v_lshlrev_b32_e32 v73, 16, v63
	v_and_b32_e32 v79, 0xffff0000, v63
	v_lshlrev_b32_e32 v63, 16, v139
	v_mul_f32_e32 v48, 0xbfb8aa3b, v63
	v_exp_f32_e32 v48, v48
	v_and_b32_e32 v78, 0xffff0000, v62
	v_add_f32_e32 v81, 1.0, v81
	v_lshlrev_b32_e32 v72, 16, v62
	v_add_f32_e32 v48, 1.0, v48
	v_lshlrev_b32_e32 v62, 16, v138
	v_rcp_f32_e32 v84, v81
	v_rcp_f32_e32 v81, v48
	v_pk_fma_f32 v[48:49], v[188:189], v[78:79], v[50:51]
	v_mul_f32_e32 v50, 0xbfb8aa3b, v83
	v_mul_f32_e32 v80, 0xbfb8aa3b, v62
	v_exp_f32_e32 v50, v50
	v_exp_f32_e32 v80, v80
	v_pk_fma_f32 v[72:73], v[188:189], v[72:73], v[86:87]
	v_add_f32_e32 v66, v67, v66
	v_add_f32_e32 v50, 1.0, v50
	v_add_f32_e32 v80, 1.0, v80
	v_rcp_f32_e32 v85, v50
	v_rcp_f32_e32 v80, v80
	v_add_f32_e32 v67, v70, v71
	v_add_f32_e32 v66, v66, v67
	v_pk_mul_f32 v[50:51], v[84:85], v[82:83]
	v_pk_mul_f32 v[62:63], v[80:81], v[62:63]
	v_pk_mul_f32 v[50:51], v[50:51], v[48:49]
	v_pk_mul_f32 v[62:63], v[62:63], v[72:73]
	v_pk_mul_f32 v[48:49], v[50:51], v[50:51]
	v_and_b32_e32 v72, 0xffff0000, v134
	v_pk_fma_f32 v[48:49], v[62:63], v[62:63], v[48:49]
	v_mul_f32_e32 v71, 0xbfb8aa3b, v72
	v_add_f32_e32 v48, v48, v49
	v_add_f32_e32 v48, v66, v48
	ds_bpermute_b32 v49, v76, v48
	v_mov_b32_e32 v82, v44
	v_exp_f32_e32 v71, v71
	v_and_b32_e32 v73, 0xffff0000, v135
	v_mov_b32_e32 v83, v46
	s_waitcnt lgkmcnt(0)
	v_add_f32_e32 v78, v48, v49
	v_add_u32_e32 v48, 0x840, v77
	ds_read2_b32 v[48:49], v48 offset1:1
	v_add_f32_e32 v71, 1.0, v71
	v_mov_b32_e32 v46, v45
	v_rcp_f32_e32 v80, v71
	v_mov_b32_e32 v84, v40
	s_waitcnt lgkmcnt(0)
	v_lshlrev_b32_e32 v67, 16, v49
	v_and_b32_e32 v69, 0xffff0000, v49
	v_lshlrev_b32_e32 v49, 16, v135
	v_mul_f32_e32 v44, 0xbfb8aa3b, v49
	v_exp_f32_e32 v44, v44
	v_and_b32_e32 v68, 0xffff0000, v48
	v_lshlrev_b32_e32 v66, 16, v48
	v_lshlrev_b32_e32 v48, 16, v134
	v_add_f32_e32 v44, 1.0, v44
	v_rcp_f32_e32 v71, v44
	v_pk_fma_f32 v[44:45], v[188:189], v[68:69], v[46:47]
	v_mul_f32_e32 v46, 0xbfb8aa3b, v73
	v_mul_f32_e32 v70, 0xbfb8aa3b, v48
	v_exp_f32_e32 v46, v46
	v_exp_f32_e32 v70, v70
	v_pk_fma_f32 v[66:67], v[188:189], v[66:67], v[82:83]
	v_mov_b32_e32 v85, v42
	v_add_f32_e32 v46, 1.0, v46
	v_add_f32_e32 v70, 1.0, v70
	v_rcp_f32_e32 v81, v46
	v_rcp_f32_e32 v70, v70
	v_mov_b32_e32 v42, v41
	v_mov_b32_e32 v86, v36
	v_pk_mul_f32 v[46:47], v[80:81], v[72:73]
	v_pk_mul_f32 v[48:49], v[70:71], v[48:49]
	v_pk_mul_f32 v[46:47], v[46:47], v[44:45]
	v_pk_mul_f32 v[48:49], v[48:49], v[66:67]
	v_pk_mul_f32 v[44:45], v[46:47], v[46:47]
	v_and_b32_e32 v80, 0xffff0000, v136
	v_pk_fma_f32 v[66:67], v[48:49], v[48:49], v[44:45]
	v_add_u32_e32 v44, 0x860, v77
	ds_read2_b32 v[44:45], v44 offset1:1
	v_mul_f32_e32 v73, 0xbfb8aa3b, v80
	v_exp_f32_e32 v73, v73
	v_and_b32_e32 v81, 0xffff0000, v137
	v_mov_b32_e32 v87, v38
	s_waitcnt lgkmcnt(0)
	v_lshlrev_b32_e32 v69, 16, v45
	v_and_b32_e32 v71, 0xffff0000, v45
	v_lshlrev_b32_e32 v45, 16, v137
	v_mul_f32_e32 v40, 0xbfb8aa3b, v45
	v_exp_f32_e32 v40, v40
	v_and_b32_e32 v70, 0xffff0000, v44
	v_add_f32_e32 v73, 1.0, v73
	v_lshlrev_b32_e32 v68, 16, v44
	v_add_f32_e32 v40, 1.0, v40
	v_lshlrev_b32_e32 v44, 16, v136
	v_rcp_f32_e32 v82, v73
	v_rcp_f32_e32 v73, v40
	v_pk_fma_f32 v[40:41], v[188:189], v[70:71], v[42:43]
	v_mul_f32_e32 v42, 0xbfb8aa3b, v81
	v_mul_f32_e32 v72, 0xbfb8aa3b, v44
	v_exp_f32_e32 v42, v42
	v_exp_f32_e32 v72, v72
	v_pk_fma_f32 v[68:69], v[188:189], v[68:69], v[84:85]
	v_mov_b32_e32 v38, v37
	v_add_f32_e32 v42, 1.0, v42
	v_add_f32_e32 v72, 1.0, v72
	v_rcp_f32_e32 v83, v42
	v_rcp_f32_e32 v72, v72
	v_mov_b32_e32 v88, v32
	v_mov_b32_e32 v89, v34
	v_pk_mul_f32 v[42:43], v[82:83], v[80:81]
	v_pk_mul_f32 v[44:45], v[72:73], v[44:45]
	v_pk_mul_f32 v[40:41], v[42:43], v[40:41]
	v_pk_mul_f32 v[44:45], v[44:45], v[68:69]
	v_pk_mul_f32 v[42:43], v[40:41], v[40:41]
	v_and_b32_e32 v82, 0xffff0000, v132
	v_pk_fma_f32 v[68:69], v[44:45], v[44:45], v[42:43]
	v_add_u32_e32 v42, 0x880, v77
	ds_read2_b32 v[42:43], v42 offset1:1
	v_mul_f32_e32 v81, 0xbfb8aa3b, v82
	v_exp_f32_e32 v81, v81
	v_and_b32_e32 v83, 0xffff0000, v133
	v_mov_b32_e32 v34, v33
	s_waitcnt lgkmcnt(0)
	v_lshlrev_b32_e32 v71, 16, v43
	v_and_b32_e32 v73, 0xffff0000, v43
	v_lshlrev_b32_e32 v43, 16, v133
	v_mul_f32_e32 v36, 0xbfb8aa3b, v43
	v_exp_f32_e32 v36, v36
	v_and_b32_e32 v72, 0xffff0000, v42
	v_add_f32_e32 v81, 1.0, v81
	v_lshlrev_b32_e32 v70, 16, v42
	v_add_f32_e32 v36, 1.0, v36
	v_lshlrev_b32_e32 v42, 16, v132
	v_rcp_f32_e32 v84, v81
	v_rcp_f32_e32 v81, v36
	v_pk_fma_f32 v[36:37], v[188:189], v[72:73], v[38:39]
	v_mul_f32_e32 v38, 0xbfb8aa3b, v83
	v_mul_f32_e32 v80, 0xbfb8aa3b, v42
	v_exp_f32_e32 v38, v38
	v_exp_f32_e32 v80, v80
	v_pk_fma_f32 v[70:71], v[188:189], v[70:71], v[86:87]
	v_add_f32_e32 v68, v68, v69
	v_add_f32_e32 v38, 1.0, v38
	v_add_f32_e32 v80, 1.0, v80
	v_rcp_f32_e32 v85, v38
	v_rcp_f32_e32 v80, v80
	v_add_f32_e32 v66, v66, v67
	v_add_f32_e32 v66, v66, v68
	v_pk_mul_f32 v[38:39], v[84:85], v[82:83]
	v_pk_mul_f32 v[42:43], v[80:81], v[42:43]
	v_pk_mul_f32 v[36:37], v[38:39], v[36:37]
	v_pk_mul_f32 v[42:43], v[42:43], v[70:71]
	v_pk_mul_f32 v[38:39], v[36:37], v[36:37]
	s_waitcnt vmcnt(2)
	v_and_b32_e32 v84, 0xffff0000, v130
	v_pk_fma_f32 v[70:71], v[42:43], v[42:43], v[38:39]
	v_add_u32_e32 v38, 0x8a0, v77
	ds_read2_b32 v[38:39], v38 offset1:1
	v_mul_f32_e32 v83, 0xbfb8aa3b, v84
	v_exp_f32_e32 v83, v83
	v_and_b32_e32 v85, 0xffff0000, v131
	v_add_f32_e32 v67, v70, v71
	s_waitcnt lgkmcnt(0)
	v_lshlrev_b32_e32 v73, 16, v39
	v_and_b32_e32 v81, 0xffff0000, v39
	v_lshlrev_b32_e32 v39, 16, v131
	v_mul_f32_e32 v32, 0xbfb8aa3b, v39
	v_exp_f32_e32 v32, v32
	v_and_b32_e32 v80, 0xffff0000, v38
	v_add_f32_e32 v83, 1.0, v83
	v_lshlrev_b32_e32 v72, 16, v38
	v_add_f32_e32 v32, 1.0, v32
	v_lshlrev_b32_e32 v38, 16, v130
	v_rcp_f32_e32 v86, v83
	v_rcp_f32_e32 v83, v32
	v_pk_fma_f32 v[32:33], v[188:189], v[80:81], v[34:35]
	v_mul_f32_e32 v34, 0xbfb8aa3b, v85
	v_mul_f32_e32 v82, 0xbfb8aa3b, v38
	v_exp_f32_e32 v34, v34
	v_exp_f32_e32 v82, v82
	v_pk_fma_f32 v[72:73], v[188:189], v[72:73], v[88:89]
	v_add_f32_e32 v66, v66, v67
	v_add_f32_e32 v34, 1.0, v34
	v_add_f32_e32 v82, 1.0, v82
	v_rcp_f32_e32 v87, v34
	v_rcp_f32_e32 v82, v82
	v_mov_b32_e32 v88, v20
	v_mov_b32_e32 v89, v22
	v_pk_mul_f32 v[34:35], v[86:87], v[84:85]
	v_pk_mul_f32 v[38:39], v[82:83], v[38:39]
	v_pk_mul_f32 v[34:35], v[34:35], v[32:33]
	v_pk_mul_f32 v[38:39], v[38:39], v[72:73]
	v_pk_mul_f32 v[32:33], v[34:35], v[34:35]
	v_and_b32_e32 v72, 0xffff0000, v128
	v_pk_fma_f32 v[32:33], v[38:39], v[38:39], v[32:33]
	v_mul_f32_e32 v71, 0xbfb8aa3b, v72
	v_add_f32_e32 v32, v32, v33
	v_add_f32_e32 v32, v66, v32
	ds_bpermute_b32 v33, v76, v32
	v_mov_b32_e32 v84, v28
	v_exp_f32_e32 v71, v71
	v_and_b32_e32 v73, 0xffff0000, v129
	v_mov_b32_e32 v85, v30
	s_waitcnt lgkmcnt(0)
	v_add_f32_e32 v80, v32, v33
	v_add_u32_e32 v32, 0x1080, v77
	ds_read2_b32 v[32:33], v32 offset1:1
	v_add_f32_e32 v71, 1.0, v71
	v_mov_b32_e32 v30, v29
	v_rcp_f32_e32 v82, v71
	v_mov_b32_e32 v86, v24
	s_waitcnt lgkmcnt(0)
	v_lshlrev_b32_e32 v67, 16, v33
	v_and_b32_e32 v69, 0xffff0000, v33
	v_lshlrev_b32_e32 v33, 16, v129
	v_mul_f32_e32 v28, 0xbfb8aa3b, v33
	v_exp_f32_e32 v28, v28
	v_and_b32_e32 v68, 0xffff0000, v32
	v_lshlrev_b32_e32 v66, 16, v32
	v_lshlrev_b32_e32 v32, 16, v128
	v_add_f32_e32 v28, 1.0, v28
	v_rcp_f32_e32 v71, v28
	v_pk_fma_f32 v[28:29], v[188:189], v[68:69], v[30:31]
	v_mul_f32_e32 v30, 0xbfb8aa3b, v73
	v_mul_f32_e32 v70, 0xbfb8aa3b, v32
	v_exp_f32_e32 v30, v30
	v_exp_f32_e32 v70, v70
	v_pk_fma_f32 v[66:67], v[188:189], v[66:67], v[84:85]
	v_mov_b32_e32 v87, v26
	v_add_f32_e32 v30, 1.0, v30
	v_add_f32_e32 v70, 1.0, v70
	v_rcp_f32_e32 v83, v30
	v_rcp_f32_e32 v70, v70
	v_mov_b32_e32 v26, v25
	v_mov_b32_e32 v22, v21
	v_pk_mul_f32 v[30:31], v[82:83], v[72:73]
	v_pk_mul_f32 v[32:33], v[70:71], v[32:33]
	v_pk_mul_f32 v[30:31], v[30:31], v[28:29]
	v_pk_mul_f32 v[32:33], v[32:33], v[66:67]
	v_pk_mul_f32 v[28:29], v[30:31], v[30:31]
	v_and_b32_e32 v82, 0xffff0000, v126
	v_pk_fma_f32 v[66:67], v[32:33], v[32:33], v[28:29]
	v_add_u32_e32 v28, 0x10a0, v77
	ds_read2_b32 v[28:29], v28 offset1:1
	v_mul_f32_e32 v73, 0xbfb8aa3b, v82
	v_exp_f32_e32 v73, v73
	v_and_b32_e32 v83, 0xffff0000, v127
	v_mov_b32_e32 v90, v16
	s_waitcnt lgkmcnt(0)
	v_lshlrev_b32_e32 v69, 16, v29
	v_and_b32_e32 v71, 0xffff0000, v29
	v_lshlrev_b32_e32 v29, 16, v127
	v_mul_f32_e32 v24, 0xbfb8aa3b, v29
	v_exp_f32_e32 v24, v24
	v_and_b32_e32 v70, 0xffff0000, v28
	v_add_f32_e32 v73, 1.0, v73
	v_lshlrev_b32_e32 v68, 16, v28
	v_add_f32_e32 v24, 1.0, v24
	v_lshlrev_b32_e32 v28, 16, v126
	v_rcp_f32_e32 v84, v73
	v_rcp_f32_e32 v73, v24
	v_pk_fma_f32 v[24:25], v[188:189], v[70:71], v[26:27]
	v_mul_f32_e32 v26, 0xbfb8aa3b, v83
	v_mul_f32_e32 v72, 0xbfb8aa3b, v28
	v_exp_f32_e32 v26, v26
	v_exp_f32_e32 v72, v72
	v_pk_fma_f32 v[68:69], v[188:189], v[68:69], v[86:87]
	v_mov_b32_e32 v91, v18
	v_add_f32_e32 v26, 1.0, v26
	v_add_f32_e32 v72, 1.0, v72
	v_rcp_f32_e32 v85, v26
	v_rcp_f32_e32 v72, v72
	v_mov_b32_e32 v18, v17
	v_add_f32_e32 v66, v66, v67
	v_pk_mul_f32 v[26:27], v[84:85], v[82:83]
	v_pk_mul_f32 v[28:29], v[72:73], v[28:29]
	v_pk_mul_f32 v[24:25], v[26:27], v[24:25]
	v_pk_mul_f32 v[28:29], v[28:29], v[68:69]
	v_pk_mul_f32 v[26:27], v[24:25], v[24:25]
	v_and_b32_e32 v84, 0xffff0000, v122
	v_pk_fma_f32 v[68:69], v[28:29], v[28:29], v[26:27]
	v_add_u32_e32 v26, 0x10c0, v77
	ds_read2_b32 v[26:27], v26 offset1:1
	v_mul_f32_e32 v83, 0xbfb8aa3b, v84
	v_exp_f32_e32 v83, v83
	v_and_b32_e32 v85, 0xffff0000, v123
	v_add_f32_e32 v68, v68, v69
	s_waitcnt lgkmcnt(0)
	v_lshlrev_b32_e32 v71, 16, v27
	v_and_b32_e32 v73, 0xffff0000, v27
	v_lshlrev_b32_e32 v27, 16, v123
	v_mul_f32_e32 v20, 0xbfb8aa3b, v27
	v_exp_f32_e32 v20, v20
	v_and_b32_e32 v72, 0xffff0000, v26
	v_add_f32_e32 v83, 1.0, v83
	v_lshlrev_b32_e32 v70, 16, v26
	v_add_f32_e32 v20, 1.0, v20
	v_lshlrev_b32_e32 v26, 16, v122
	v_rcp_f32_e32 v86, v83
	v_rcp_f32_e32 v83, v20
	v_pk_fma_f32 v[20:21], v[188:189], v[72:73], v[22:23]
	v_mul_f32_e32 v22, 0xbfb8aa3b, v85
	v_mul_f32_e32 v82, 0xbfb8aa3b, v26
	v_exp_f32_e32 v22, v22
	v_exp_f32_e32 v82, v82
	v_pk_fma_f32 v[70:71], v[188:189], v[70:71], v[88:89]
	v_add_f32_e32 v66, v66, v68
	v_add_f32_e32 v22, 1.0, v22
	v_add_f32_e32 v82, 1.0, v82
	v_rcp_f32_e32 v87, v22
	v_rcp_f32_e32 v82, v82
	v_mov_b32_e32 v92, v0
	v_mov_b32_e32 v93, v2
	v_pk_mul_f32 v[22:23], v[86:87], v[84:85]
	v_pk_mul_f32 v[26:27], v[82:83], v[26:27]
	v_pk_mul_f32 v[20:21], v[22:23], v[20:21]
	v_pk_mul_f32 v[26:27], v[26:27], v[70:71]
	v_pk_mul_f32 v[22:23], v[20:21], v[20:21]
	s_waitcnt vmcnt(1)
	v_and_b32_e32 v86, 0xffff0000, v118
	v_pk_fma_f32 v[70:71], v[26:27], v[26:27], v[22:23]
	v_add_u32_e32 v22, 0x10e0, v77
	ds_read2_b32 v[22:23], v22 offset1:1
	v_mul_f32_e32 v85, 0xbfb8aa3b, v86
	v_exp_f32_e32 v85, v85
	v_and_b32_e32 v87, 0xffff0000, v119
	v_add_f32_e32 v67, v70, v71
	s_waitcnt lgkmcnt(0)
	v_lshlrev_b32_e32 v73, 16, v23
	v_and_b32_e32 v83, 0xffff0000, v23
	v_lshlrev_b32_e32 v23, 16, v119
	v_mul_f32_e32 v16, 0xbfb8aa3b, v23
	v_exp_f32_e32 v16, v16
	v_and_b32_e32 v82, 0xffff0000, v22
	v_add_f32_e32 v85, 1.0, v85
	v_lshlrev_b32_e32 v72, 16, v22
	v_add_f32_e32 v16, 1.0, v16
	v_lshlrev_b32_e32 v22, 16, v118
	v_rcp_f32_e32 v88, v85
	v_rcp_f32_e32 v85, v16
	v_pk_fma_f32 v[16:17], v[188:189], v[82:83], v[18:19]
	v_mul_f32_e32 v18, 0xbfb8aa3b, v87
	v_mul_f32_e32 v84, 0xbfb8aa3b, v22
	v_exp_f32_e32 v18, v18
	v_exp_f32_e32 v84, v84
	v_pk_fma_f32 v[72:73], v[188:189], v[72:73], v[90:91]
	v_add_f32_e32 v66, v66, v67
	v_add_f32_e32 v18, 1.0, v18
	v_add_f32_e32 v84, 1.0, v84
	v_rcp_f32_e32 v89, v18
	v_rcp_f32_e32 v84, v84
	v_mov_b32_e32 v90, v4
	v_mov_b32_e32 v91, v6
	v_pk_mul_f32 v[18:19], v[88:89], v[86:87]
	v_pk_mul_f32 v[22:23], v[84:85], v[22:23]
	v_pk_mul_f32 v[18:19], v[18:19], v[16:17]
	v_pk_mul_f32 v[22:23], v[22:23], v[72:73]
	v_pk_mul_f32 v[16:17], v[18:19], v[18:19]
	v_and_b32_e32 v72, 0xffff0000, v120
	v_pk_fma_f32 v[16:17], v[22:23], v[22:23], v[16:17]
	v_mul_f32_e32 v71, 0xbfb8aa3b, v72
	v_add_f32_e32 v16, v16, v17
	v_add_f32_e32 v16, v66, v16
	ds_bpermute_b32 v17, v76, v16
	v_mov_b32_e32 v86, v12
	v_exp_f32_e32 v71, v71
	v_and_b32_e32 v73, 0xffff0000, v121
	v_mov_b32_e32 v87, v14
	s_waitcnt lgkmcnt(0)
	v_add_f32_e32 v82, v16, v17
	v_add_u32_e32 v16, 0x18c0, v77
	ds_read2_b32 v[16:17], v16 offset1:1
	v_add_f32_e32 v71, 1.0, v71
	v_mov_b32_e32 v14, v13
	v_rcp_f32_e32 v84, v71
	v_mov_b32_e32 v88, v8
	s_waitcnt lgkmcnt(0)
	v_lshlrev_b32_e32 v67, 16, v17
	v_and_b32_e32 v69, 0xffff0000, v17
	v_lshlrev_b32_e32 v17, 16, v121
	v_mul_f32_e32 v12, 0xbfb8aa3b, v17
	v_exp_f32_e32 v12, v12
	v_and_b32_e32 v68, 0xffff0000, v16
	v_lshlrev_b32_e32 v66, 16, v16
	v_lshlrev_b32_e32 v16, 16, v120
	v_add_f32_e32 v12, 1.0, v12
	v_rcp_f32_e32 v71, v12
	v_pk_fma_f32 v[12:13], v[188:189], v[68:69], v[14:15]
	v_mul_f32_e32 v14, 0xbfb8aa3b, v73
	v_mul_f32_e32 v70, 0xbfb8aa3b, v16
	v_exp_f32_e32 v14, v14
	v_exp_f32_e32 v70, v70
	v_pk_fma_f32 v[66:67], v[188:189], v[66:67], v[86:87]
	v_mov_b32_e32 v89, v10
	v_add_f32_e32 v14, 1.0, v14
	v_add_f32_e32 v70, 1.0, v70
	v_rcp_f32_e32 v85, v14
	v_rcp_f32_e32 v70, v70
	v_mov_b32_e32 v10, v9
	v_mov_b32_e32 v6, v5
	v_pk_mul_f32 v[14:15], v[84:85], v[72:73]
	v_pk_mul_f32 v[16:17], v[70:71], v[16:17]
	v_pk_mul_f32 v[14:15], v[14:15], v[12:13]
	v_pk_mul_f32 v[16:17], v[16:17], v[66:67]
	v_pk_mul_f32 v[12:13], v[14:15], v[14:15]
	v_and_b32_e32 v84, 0xffff0000, v124
	v_pk_fma_f32 v[68:69], v[16:17], v[16:17], v[12:13]
	v_add_u32_e32 v12, 0x18e0, v77
	ds_read2_b32 v[12:13], v12 offset1:1
	v_mul_f32_e32 v73, 0xbfb8aa3b, v84
	v_exp_f32_e32 v73, v73
	v_and_b32_e32 v85, 0xffff0000, v125
	v_mov_b32_e32 v2, v1
	s_waitcnt lgkmcnt(0)
	v_lshlrev_b32_e32 v67, 16, v13
	v_and_b32_e32 v71, 0xffff0000, v13
	v_lshlrev_b32_e32 v13, 16, v125
	v_mul_f32_e32 v8, 0xbfb8aa3b, v13
	v_exp_f32_e32 v8, v8
	v_and_b32_e32 v70, 0xffff0000, v12
	v_add_f32_e32 v73, 1.0, v73
	v_lshlrev_b32_e32 v66, 16, v12
	v_add_f32_e32 v8, 1.0, v8
	v_lshlrev_b32_e32 v12, 16, v124
	v_rcp_f32_e32 v86, v73
	v_rcp_f32_e32 v73, v8
	v_pk_fma_f32 v[8:9], v[188:189], v[70:71], v[10:11]
	v_mul_f32_e32 v10, 0xbfb8aa3b, v85
	v_mul_f32_e32 v72, 0xbfb8aa3b, v12
	v_exp_f32_e32 v10, v10
	v_exp_f32_e32 v72, v72
	v_pk_fma_f32 v[66:67], v[188:189], v[66:67], v[88:89]
	ds_bpermute_b32 v79, v75, v78
	v_add_f32_e32 v10, 1.0, v10
	v_add_f32_e32 v72, 1.0, v72
	v_rcp_f32_e32 v87, v10
	v_rcp_f32_e32 v72, v72
	ds_bpermute_b32 v81, v75, v80
	ds_bpermute_b32 v83, v75, v82
	v_pk_mul_f32 v[10:11], v[86:87], v[84:85]
	v_pk_mul_f32 v[12:13], v[72:73], v[12:13]
	v_pk_mul_f32 v[8:9], v[10:11], v[8:9]
	v_pk_mul_f32 v[12:13], v[12:13], v[66:67]
	v_pk_mul_f32 v[10:11], v[8:9], v[8:9]
	v_and_b32_e32 v86, 0xffff0000, v116
	v_pk_fma_f32 v[70:71], v[12:13], v[12:13], v[10:11]
	v_add_u32_e32 v10, 0x1900, v77
	ds_read2_b32 v[10:11], v10 offset1:1
	v_mul_f32_e32 v85, 0xbfb8aa3b, v86
	v_exp_f32_e32 v85, v85
	v_and_b32_e32 v87, 0xffff0000, v117
	v_cmp_gt_u32_e32 vcc, 16, v74
	s_waitcnt lgkmcnt(0)
	v_lshlrev_b32_e32 v67, 16, v11
	v_and_b32_e32 v73, 0xffff0000, v11
	v_lshlrev_b32_e32 v11, 16, v117
	v_mul_f32_e32 v4, 0xbfb8aa3b, v11
	v_exp_f32_e32 v4, v4
	v_and_b32_e32 v72, 0xffff0000, v10
	v_add_f32_e32 v85, 1.0, v85
	v_lshlrev_b32_e32 v66, 16, v10
	v_add_f32_e32 v4, 1.0, v4
	v_lshlrev_b32_e32 v10, 16, v116
	v_rcp_f32_e32 v88, v85
	v_rcp_f32_e32 v85, v4
	v_pk_fma_f32 v[4:5], v[188:189], v[72:73], v[6:7]
	v_mul_f32_e32 v6, 0xbfb8aa3b, v87
	v_mul_f32_e32 v84, 0xbfb8aa3b, v10
	v_exp_f32_e32 v6, v6
	v_exp_f32_e32 v84, v84
	v_pk_fma_f32 v[66:67], v[188:189], v[66:67], v[90:91]
	v_add_f32_e32 v6, 1.0, v6
	v_add_f32_e32 v84, 1.0, v84
	v_rcp_f32_e32 v89, v6
	v_rcp_f32_e32 v84, v84
	v_pk_mul_f32 v[6:7], v[88:89], v[86:87]
	v_pk_mul_f32 v[10:11], v[84:85], v[10:11]
	v_pk_mul_f32 v[4:5], v[6:7], v[4:5]
	v_pk_mul_f32 v[10:11], v[10:11], v[66:67]
	v_pk_mul_f32 v[6:7], v[4:5], v[4:5]
	s_waitcnt vmcnt(0)
	v_and_b32_e32 v89, 0xffff0000, v113
	v_pk_fma_f32 v[72:73], v[10:11], v[10:11], v[6:7]
	v_add_u32_e32 v6, 0x1920, v77
	ds_read2_b32 v[6:7], v6 offset1:1
	v_and_b32_e32 v88, 0xffff0000, v112
	s_waitcnt lgkmcnt(0)
	v_lshlrev_b32_e32 v66, 16, v6
	v_lshlrev_b32_e32 v67, 16, v7
	v_and_b32_e32 v85, 0xffff0000, v7
	v_and_b32_e32 v84, 0xffff0000, v6
	v_lshlrev_b32_e32 v7, 16, v113
	v_lshlrev_b32_e32 v6, 16, v112
	v_mul_f32_e32 v77, 0xbfb8aa3b, v6
	v_mul_f32_e32 v0, 0xbfb8aa3b, v7
	v_exp_f32_e32 v77, v77
	v_exp_f32_e32 v0, v0
	v_pk_fma_f32 v[66:67], v[188:189], v[66:67], v[92:93]
	v_add_f32_e32 v77, 1.0, v77
	v_add_f32_e32 v0, 1.0, v0
	v_rcp_f32_e32 v86, v77
	v_mul_f32_e32 v77, 0xbfb8aa3b, v88
	v_rcp_f32_e32 v87, v0
	v_pk_fma_f32 v[0:1], v[188:189], v[84:85], v[2:3]
	v_mul_f32_e32 v2, 0xbfb8aa3b, v89
	v_exp_f32_e32 v77, v77
	v_exp_f32_e32 v2, v2
	v_pk_mul_f32 v[6:7], v[86:87], v[6:7]
	v_add_f32_e32 v77, 1.0, v77
	v_add_f32_e32 v2, 1.0, v2
	v_rcp_f32_e32 v90, v77
	v_rcp_f32_e32 v91, v2
	v_pk_mul_f32 v[6:7], v[6:7], v[66:67]
	v_pk_mul_f32 v[2:3], v[90:91], v[88:89]
	s_nop 0
	v_pk_mul_f32 v[66:67], v[2:3], v[0:1]
	v_add_f32_e32 v2, v70, v71
	v_pk_mul_f32 v[0:1], v[66:67], v[66:67]
	v_add_f32_e32 v3, v68, v69
	v_pk_fma_f32 v[0:1], v[6:7], v[6:7], v[0:1]
	v_add_f32_e32 v2, v3, v2
	v_add_f32_e32 v3, v72, v73
	v_add_f32_e32 v2, v2, v3
	v_add_f32_e32 v0, v0, v1
	v_add_f32_e32 v0, v2, v0
	ds_bpermute_b32 v1, v76, v0
	s_waitcnt lgkmcnt(0)
	v_add_f32_e32 v0, v0, v1
	ds_bpermute_b32 v1, v75, v0
	s_and_saveexec_b64 s[0:1], vcc
	s_cbranch_execz .LBB0_549
	v_add_f32_e32 v2, v80, v81
	v_add_f32_e32 v3, v78, v79
	v_lshl_add_u32 v68, v74, 2, v242
	s_waitcnt lgkmcnt(0)
	v_add_f32_e32 v0, v0, v1
	v_add_f32_e32 v1, v82, v83
	ds_write2_b32 v68, v3, v2 offset1:16
	ds_write2_b32 v68, v1, v0 offset0:32 offset1:48
	s_branch .LBB0_549

.LBB0_577:
	v_mul_f32_e32 v147, 0x3d372713, v124
	v_mul_f32_e32 v147, v124, v147
	v_mul_f32_e32 v148, 0x3d372713, v125
	v_fma_f32 v147, v124, v147, v124
	v_mul_f32_e32 v148, v125, v148
	v_mul_f32_e32 v150, 0x3d372713, v127
	v_mul_f32_e32 v147, 0x3f4c422a, v147
	v_fma_f32 v148, v125, v148, v125
	v_mul_f32_e32 v150, v127, v150
	v_add_f32_e32 v147, v147, v147
	v_mul_f32_e32 v148, 0x3f4c422a, v148
	v_fma_f32 v150, v127, v150, v127
	v_mul_f32_e32 v147, 0x3fb8aa3b, v147
	v_add_f32_e32 v148, v148, v148
	v_mul_f32_e32 v150, 0x3f4c422a, v150
	v_exp_f32_e32 v147, v147
	v_mul_f32_e32 v148, 0x3fb8aa3b, v148
	v_add_f32_e32 v150, v150, v150
	v_exp_f32_e32 v149, v148
	v_mul_f32_e32 v150, 0x3fb8aa3b, v150
	v_exp_f32_e32 v151, v150
	v_add_f32_e32 v147, 1.0, v147
	v_rcp_f32_e32 v148, v147
	v_add_f32_e32 v147, 1.0, v149
	v_rcp_f32_e32 v150, v147
	v_add_f32_e32 v147, 1.0, v151
	v_rcp_f32_e32 v151, v147
	v_mul_f32_e32 v149, 0x3d372713, v126
	v_mul_f32_e32 v149, v126, v149
	v_fma_f32 v149, v126, v149, v126
	v_mov_b32_e32 v153, v126
	v_pk_fma_f32 v[150:151], v[150:151], 2.0, 1.0 op_sel_hi:[1,0,0] neg_lo:[1,0,0] neg_hi:[1,0,0]
	v_mov_b32_e32 v126, v125
	v_mov_b32_e32 v152, v124
	v_pk_mul_f32 v[124:125], v[126:127], 0.5 op_sel_hi:[1,0]
	v_pk_add_f32 v[126:127], v[150:151], 1.0 op_sel_hi:[1,0]
	v_mul_f32_e32 v147, 0x3d372713, v120
	v_mul_f32_e32 v150, 0x3d372713, v121
	v_mul_f32_e32 v147, v120, v147
	v_mul_f32_e32 v150, v121, v150
	v_fma_f32 v147, v120, v147, v120
	v_fma_f32 v150, v121, v150, v121
	v_mul_f32_e32 v147, 0x3f4c422a, v147
	v_mul_f32_e32 v150, 0x3f4c422a, v150
	v_add_f32_e32 v147, v147, v147
	v_add_f32_e32 v150, v150, v150
	v_mul_f32_e32 v147, 0x3fb8aa3b, v147
	v_mul_f32_e32 v150, 0x3fb8aa3b, v150
	v_exp_f32_e32 v147, v147
	v_exp_f32_e32 v150, v150
	v_pk_mul_f32 v[124:125], v[124:125], v[126:127]
	v_mul_f32_e32 v149, 0x3f4c422a, v149
	v_add_f32_e32 v126, 1.0, v147
	v_add_f32_e32 v147, 1.0, v150
	v_mul_f32_e32 v150, 0x3d372713, v123
	v_mul_f32_e32 v127, 0x3d372713, v122
	v_mul_f32_e32 v150, v123, v150
	v_add_f32_e32 v149, v149, v149
	v_mul_f32_e32 v127, v122, v127
	v_fma_f32 v150, v123, v150, v123
	v_mul_f32_e32 v149, 0x3fb8aa3b, v149
	v_fma_f32 v127, v122, v127, v122
	v_mul_f32_e32 v150, 0x3f4c422a, v150
	v_exp_f32_e32 v149, v149
	v_mul_f32_e32 v127, 0x3f4c422a, v127
	v_add_f32_e32 v150, v150, v150
	v_add_f32_e32 v127, v127, v127
	v_mul_f32_e32 v150, 0x3fb8aa3b, v150
	v_mul_f32_e32 v127, 0x3fb8aa3b, v127
	v_exp_f32_e32 v151, v150
	v_exp_f32_e32 v127, v127
	v_add_f32_e32 v149, 1.0, v149
	v_rcp_f32_e32 v149, v149
	v_rcp_f32_e32 v150, v147
	v_add_f32_e32 v147, 1.0, v151
	v_add_f32_e32 v127, 1.0, v127
	v_rcp_f32_e32 v151, v147
	v_rcp_f32_e32 v126, v126
	v_rcp_f32_e32 v127, v127
	v_pk_fma_f32 v[148:149], v[148:149], 2.0, 1.0 op_sel_hi:[1,0,0] neg_lo:[1,0,0] neg_hi:[1,0,0]
	v_pk_mul_f32 v[152:153], v[152:153], 0.5 op_sel_hi:[1,0]
	v_pk_add_f32 v[148:149], v[148:149], 1.0 op_sel_hi:[1,0]
	v_pk_fma_f32 v[150:151], v[150:151], 2.0, 1.0 op_sel_hi:[1,0,0] neg_lo:[1,0,0] neg_hi:[1,0,0]
	v_pk_mul_f32 v[148:149], v[152:153], v[148:149]
	v_mov_b32_e32 v153, v122
	v_mov_b32_e32 v122, v121
	v_pk_fma_f32 v[126:127], v[126:127], 2.0, 1.0 op_sel_hi:[1,0,0] neg_lo:[1,0,0] neg_hi:[1,0,0]
	v_mov_b32_e32 v152, v120
	v_pk_mul_f32 v[120:121], v[122:123], 0.5 op_sel_hi:[1,0]
	v_pk_add_f32 v[122:123], v[150:151], 1.0 op_sel_hi:[1,0]
	v_mov_b32_e32 v144, v140
	v_mov_b32_e32 v154, v141
	s_lshl_b32 s3, s20, 8
	v_pk_mul_f32 v[152:153], v[152:153], 0.5 op_sel_hi:[1,0]
	v_pk_add_f32 v[126:127], v[126:127], 1.0 op_sel_hi:[1,0]
	v_pk_mul_f32 v[120:121], v[120:121], v[122:123]
	s_add_i32 s3, s3, s60
	v_pk_mul_f32 v[126:127], v[152:153], v[126:127]
	v_add_u32_e32 v144, s3, v144
	v_lshl_add_u32 v155, v154, 3, s61
	v_ashrrev_i32_e32 v146, 4, v155
	v_ashrrev_i32_e32 v145, 31, v144
	v_readlane_b32 s20, v254, 57
	s_lshl_b32 s2, s2, 4
	v_lshlrev_b64 v[144:145], 15, v[144:145]
	v_ashrrev_i32_e32 v147, 31, v146
	v_readlane_b32 s21, v254, 58
	s_ashr_i32 s3, s2, 31
	v_cvt_pk_bf16_f32 v127, v127, v121
	v_cvt_pk_bf16_f32 v126, v126, v120
	v_cvt_pk_bf16_f32 v125, v149, v125
	v_cvt_pk_bf16_f32 v124, v148, v124
	v_lshl_add_u64 v[120:121], s[20:21], 0, v[144:145]
	v_lshlrev_b64 v[122:123], 11, v[146:147]
	v_lshl_add_u64 v[144:145], v[120:121], 0, v[122:123]
	s_lshl_b64 s[20:21], s[2:3], 1
	v_lshlrev_b32_e32 v146, 4, v154
	v_lshl_add_u64 v[144:145], v[144:145], 0, s[20:21]
	v_and_b32_e32 v168, 16, v146
	v_lshl_add_u64 v[144:145], v[144:145], 0, v[168:169]
	global_store_dwordx4 v[144:145], v[124:127], off offset:1536
	v_mul_f32_e32 v144, 0x3d372713, v119
	v_mul_f32_e32 v144, v119, v144
	v_mul_f32_e32 v125, 0x3d372713, v116
	v_mul_f32_e32 v125, v116, v125
	v_mul_f32_e32 v126, 0x3d372713, v117
	v_fma_f32 v125, v116, v125, v116
	v_mul_f32_e32 v126, v117, v126
	v_mul_f32_e32 v125, 0x3f4c422a, v125
	v_fma_f32 v126, v117, v126, v117
	v_add_f32_e32 v125, v125, v125
	v_mul_f32_e32 v126, 0x3f4c422a, v126
	v_fma_f32 v144, v119, v144, v119
	v_mul_f32_e32 v125, 0x3fb8aa3b, v125
	v_add_f32_e32 v126, v126, v126
	v_mul_f32_e32 v144, 0x3f4c422a, v144
	v_exp_f32_e32 v125, v125
	v_mul_f32_e32 v126, 0x3fb8aa3b, v126
	v_add_f32_e32 v144, v144, v144
	v_exp_f32_e32 v127, v126
	v_mul_f32_e32 v144, 0x3fb8aa3b, v144
	v_exp_f32_e32 v145, v144
	v_add_f32_e32 v125, 1.0, v125
	v_rcp_f32_e32 v126, v125
	v_add_f32_e32 v125, 1.0, v127
	v_rcp_f32_e32 v144, v125
	v_add_f32_e32 v125, 1.0, v145
	v_rcp_f32_e32 v145, v125
	v_mul_f32_e32 v127, 0x3d372713, v118
	v_mul_f32_e32 v127, v118, v127
	v_fma_f32 v127, v118, v127, v118
	v_mov_b32_e32 v147, v118
	v_pk_fma_f32 v[144:145], v[144:145], 2.0, 1.0 op_sel_hi:[1,0,0] neg_lo:[1,0,0] neg_hi:[1,0,0]
	v_mov_b32_e32 v118, v117
	v_mov_b32_e32 v146, v116
	v_pk_mul_f32 v[116:117], v[118:119], 0.5 op_sel_hi:[1,0]
	v_pk_add_f32 v[118:119], v[144:145], 1.0 op_sel_hi:[1,0]
	v_mul_f32_e32 v125, 0x3d372713, v112
	v_mul_f32_e32 v144, 0x3d372713, v113
	v_mul_f32_e32 v125, v112, v125
	v_mul_f32_e32 v144, v113, v144
	v_fma_f32 v125, v112, v125, v112
	v_fma_f32 v144, v113, v144, v113
	v_mul_f32_e32 v125, 0x3f4c422a, v125
	v_mul_f32_e32 v144, 0x3f4c422a, v144
	v_add_f32_e32 v125, v125, v125
	v_add_f32_e32 v144, v144, v144
	v_mul_f32_e32 v125, 0x3fb8aa3b, v125
	v_mul_f32_e32 v144, 0x3fb8aa3b, v144
	v_exp_f32_e32 v125, v125
	v_exp_f32_e32 v144, v144
	v_pk_mul_f32 v[116:117], v[116:117], v[118:119]
	v_mul_f32_e32 v127, 0x3f4c422a, v127
	v_add_f32_e32 v118, 1.0, v125
	v_add_f32_e32 v125, 1.0, v144
	v_mul_f32_e32 v144, 0x3d372713, v115
	v_mul_f32_e32 v144, v115, v144
	v_add_f32_e32 v127, v127, v127
	v_mul_f32_e32 v119, 0x3d372713, v114
	v_fma_f32 v144, v115, v144, v115
	v_mul_f32_e32 v127, 0x3fb8aa3b, v127
	v_mul_f32_e32 v119, v114, v119
	v_mul_f32_e32 v144, 0x3f4c422a, v144
	v_exp_f32_e32 v127, v127
	v_fma_f32 v119, v114, v119, v114
	v_add_f32_e32 v144, v144, v144
	v_mul_f32_e32 v119, 0x3f4c422a, v119
	v_mul_f32_e32 v144, 0x3fb8aa3b, v144
	v_add_f32_e32 v119, v119, v119
	v_exp_f32_e32 v145, v144
	v_mul_f32_e32 v119, 0x3fb8aa3b, v119
	v_add_f32_e32 v127, 1.0, v127
	v_exp_f32_e32 v119, v119
	v_rcp_f32_e32 v127, v127
	v_rcp_f32_e32 v144, v125
	v_add_f32_e32 v125, 1.0, v145
	v_rcp_f32_e32 v145, v125
	v_add_f32_e32 v119, 1.0, v119
	v_pk_fma_f32 v[126:127], v[126:127], 2.0, 1.0 op_sel_hi:[1,0,0] neg_lo:[1,0,0] neg_hi:[1,0,0]
	v_rcp_f32_e32 v118, v118
	v_rcp_f32_e32 v119, v119
	v_pk_mul_f32 v[146:147], v[146:147], 0.5 op_sel_hi:[1,0]
	v_pk_add_f32 v[126:127], v[126:127], 1.0 op_sel_hi:[1,0]
	v_pk_fma_f32 v[144:145], v[144:145], 2.0, 1.0 op_sel_hi:[1,0,0] neg_lo:[1,0,0] neg_hi:[1,0,0]
	v_pk_mul_f32 v[126:127], v[146:147], v[126:127]
	v_mov_b32_e32 v147, v114
	v_mov_b32_e32 v114, v113
	v_mov_b32_e32 v146, v112
	v_pk_mul_f32 v[112:113], v[114:115], 0.5 op_sel_hi:[1,0]
	v_pk_add_f32 v[114:115], v[144:145], 1.0 op_sel_hi:[1,0]
	v_pk_fma_f32 v[118:119], v[118:119], 2.0, 1.0 op_sel_hi:[1,0,0] neg_lo:[1,0,0] neg_hi:[1,0,0]
	v_pk_mul_f32 v[112:113], v[112:113], v[114:115]
	v_pk_mul_f32 v[146:147], v[146:147], 0.5 op_sel_hi:[1,0]
	v_pk_add_f32 v[118:119], v[118:119], 1.0 op_sel_hi:[1,0]
	s_nop 0
	v_pk_mul_f32 v[118:119], v[146:147], v[118:119]
	v_cvt_pk_bf16_f32 v114, v126, v116
	v_add_u32_e32 v124, 0x80, v155
	v_ashrrev_i32_e32 v124, 4, v124
	v_cvt_pk_bf16_f32 v115, v127, v117
	v_ashrrev_i32_e32 v125, 31, v124
	v_cvt_pk_bf16_f32 v117, v119, v113
	v_cvt_pk_bf16_f32 v116, v118, v112
	v_lshlrev_b64 v[112:113], 11, v[124:125]
	v_lshl_add_u64 v[118:119], v[120:121], 0, v[112:113]
	v_lshl_add_u64 v[118:119], v[118:119], 0, s[20:21]
	v_lshl_add_u64 v[118:119], v[118:119], 0, v[168:169]
	global_store_dwordx4 v[118:119], v[114:117], off offset:1536
	v_mov_b32_e32 v119, v110
	v_mov_b32_e32 v118, v108
	v_mul_f32_e32 v115, 0x3d372713, v109
	v_mul_f32_e32 v117, 0x3d372713, v111
	v_mul_f32_e32 v115, v109, v115
	v_mul_f32_e32 v117, v111, v117
	v_fma_f32 v115, v109, v115, v109
	v_fma_f32 v117, v111, v117, v111
	v_mul_f32_e32 v115, 0x3f4c422a, v115
	v_mul_f32_e32 v117, 0x3f4c422a, v117
	v_add_f32_e32 v115, v115, v115
	v_add_f32_e32 v117, v117, v117
	v_mul_f32_e32 v115, 0x3fb8aa3b, v115
	v_mul_f32_e32 v117, 0x3fb8aa3b, v117
	v_exp_f32_e32 v115, v115
	v_exp_f32_e32 v117, v117
	v_mul_f32_e32 v114, 0x3d372713, v108
	v_mul_f32_e32 v114, v108, v114
	v_add_f32_e32 v116, 1.0, v115
	v_add_f32_e32 v117, 1.0, v117
	v_rcp_f32_e32 v116, v116
	v_rcp_f32_e32 v117, v117
	v_mul_f32_e32 v115, 0x3d372713, v110
	v_mul_f32_e32 v115, v110, v115
	v_fma_f32 v115, v110, v115, v110
	v_pk_fma_f32 v[116:117], v[116:117], 2.0, 1.0 op_sel_hi:[1,0,0] neg_lo:[1,0,0] neg_hi:[1,0,0]
	v_mov_b32_e32 v110, v109
	v_fma_f32 v114, v108, v114, v108
	v_pk_mul_f32 v[108:109], v[110:111], 0.5 op_sel_hi:[1,0]
	v_pk_add_f32 v[110:111], v[116:117], 1.0 op_sel_hi:[1,0]
	v_mul_f32_e32 v116, 0x3d372713, v104
	v_mul_f32_e32 v117, 0x3d372713, v105
	v_mul_f32_e32 v116, v104, v116
	v_mul_f32_e32 v117, v105, v117
	v_fma_f32 v116, v104, v116, v104
	v_fma_f32 v117, v105, v117, v105
	v_mul_f32_e32 v116, 0x3f4c422a, v116
	v_mul_f32_e32 v117, 0x3f4c422a, v117
	v_add_f32_e32 v116, v116, v116
	v_add_f32_e32 v117, v117, v117
	v_mul_f32_e32 v116, 0x3fb8aa3b, v116
	v_mul_f32_e32 v117, 0x3fb8aa3b, v117
	v_exp_f32_e32 v116, v116
	v_exp_f32_e32 v117, v117
	v_pk_mul_f32 v[108:109], v[108:109], v[110:111]
	v_mul_f32_e32 v114, 0x3f4c422a, v114
	v_add_f32_e32 v110, 1.0, v116
	v_add_f32_e32 v116, 1.0, v117
	v_mul_f32_e32 v117, 0x3d372713, v107
	v_mul_f32_e32 v115, 0x3f4c422a, v115
	v_mul_f32_e32 v111, 0x3d372713, v106
	v_mul_f32_e32 v117, v107, v117
	v_add_f32_e32 v114, v114, v114
	v_add_f32_e32 v115, v115, v115
	v_mul_f32_e32 v111, v106, v111
	v_fma_f32 v117, v107, v117, v107
	v_mul_f32_e32 v114, 0x3fb8aa3b, v114
	v_mul_f32_e32 v115, 0x3fb8aa3b, v115
	v_fma_f32 v111, v106, v111, v106
	v_mul_f32_e32 v117, 0x3f4c422a, v117
	v_exp_f32_e32 v114, v114
	v_exp_f32_e32 v115, v115
	v_mul_f32_e32 v111, 0x3f4c422a, v111
	v_add_f32_e32 v117, v117, v117
	v_add_f32_e32 v111, v111, v111
	v_mul_f32_e32 v117, 0x3fb8aa3b, v117
	v_mul_f32_e32 v111, 0x3fb8aa3b, v111
	v_exp_f32_e32 v117, v117
	v_exp_f32_e32 v111, v111
	v_add_f32_e32 v114, 1.0, v114
	v_add_f32_e32 v115, 1.0, v115
	v_rcp_f32_e32 v114, v114
	v_rcp_f32_e32 v115, v115
	v_add_f32_e32 v117, 1.0, v117
	v_add_f32_e32 v111, 1.0, v111
	v_rcp_f32_e32 v116, v116
	v_rcp_f32_e32 v117, v117
	v_rcp_f32_e32 v110, v110
	v_rcp_f32_e32 v111, v111
	v_pk_fma_f32 v[114:115], v[114:115], 2.0, 1.0 op_sel_hi:[1,0,0] neg_lo:[1,0,0] neg_hi:[1,0,0]
	v_pk_mul_f32 v[118:119], v[118:119], 0.5 op_sel_hi:[1,0]
	v_pk_add_f32 v[114:115], v[114:115], 1.0 op_sel_hi:[1,0]
	v_pk_fma_f32 v[116:117], v[116:117], 2.0, 1.0 op_sel_hi:[1,0,0] neg_lo:[1,0,0] neg_hi:[1,0,0]
	v_pk_mul_f32 v[114:115], v[118:119], v[114:115]
	v_mov_b32_e32 v119, v106
	v_mov_b32_e32 v106, v105
	v_pk_fma_f32 v[110:111], v[110:111], 2.0, 1.0 op_sel_hi:[1,0,0] neg_lo:[1,0,0] neg_hi:[1,0,0]
	v_mov_b32_e32 v118, v104
	v_pk_mul_f32 v[104:105], v[106:107], 0.5 op_sel_hi:[1,0]
	v_pk_add_f32 v[106:107], v[116:117], 1.0 op_sel_hi:[1,0]
	v_pk_mul_f32 v[118:119], v[118:119], 0.5 op_sel_hi:[1,0]
	v_pk_add_f32 v[110:111], v[110:111], 1.0 op_sel_hi:[1,0]
	v_pk_mul_f32 v[104:105], v[104:105], v[106:107]
	v_pk_mul_f32 v[110:111], v[118:119], v[110:111]
	s_mov_b64 s[2:3], 0x80000
	v_cvt_pk_bf16_f32 v107, v111, v105
	v_cvt_pk_bf16_f32 v106, v110, v104
	v_cvt_pk_bf16_f32 v105, v115, v109
	v_cvt_pk_bf16_f32 v104, v114, v108
	v_lshl_add_u64 v[108:109], v[120:121], 0, s[2:3]
	v_lshl_add_u64 v[110:111], v[108:109], 0, v[122:123]
	v_lshl_add_u64 v[110:111], v[110:111], 0, s[20:21]
	v_lshl_add_u64 v[110:111], v[110:111], 0, v[168:169]
	global_store_dwordx4 v[110:111], v[104:107], off offset:1536
	v_mov_b32_e32 v111, v102
	v_mov_b32_e32 v110, v100
	v_mul_f32_e32 v105, 0x3d372713, v101
	v_mul_f32_e32 v107, 0x3d372713, v103
	v_mul_f32_e32 v105, v101, v105
	v_mul_f32_e32 v107, v103, v107
	v_fma_f32 v105, v101, v105, v101
	v_fma_f32 v107, v103, v107, v103
	v_mul_f32_e32 v105, 0x3f4c422a, v105
	v_mul_f32_e32 v107, 0x3f4c422a, v107
	v_add_f32_e32 v105, v105, v105
	v_add_f32_e32 v107, v107, v107
	v_mul_f32_e32 v105, 0x3fb8aa3b, v105
	v_mul_f32_e32 v107, 0x3fb8aa3b, v107
	v_exp_f32_e32 v105, v105
	v_exp_f32_e32 v107, v107
	v_mul_f32_e32 v104, 0x3d372713, v100
	v_mul_f32_e32 v104, v100, v104
	v_add_f32_e32 v106, 1.0, v105
	v_add_f32_e32 v107, 1.0, v107
	v_rcp_f32_e32 v106, v106
	v_rcp_f32_e32 v107, v107
	v_mul_f32_e32 v105, 0x3d372713, v102
	v_mul_f32_e32 v105, v102, v105
	v_fma_f32 v105, v102, v105, v102
	v_pk_fma_f32 v[106:107], v[106:107], 2.0, 1.0 op_sel_hi:[1,0,0] neg_lo:[1,0,0] neg_hi:[1,0,0]
	v_mov_b32_e32 v102, v101
	v_fma_f32 v104, v100, v104, v100
	v_pk_mul_f32 v[100:101], v[102:103], 0.5 op_sel_hi:[1,0]
	v_pk_add_f32 v[102:103], v[106:107], 1.0 op_sel_hi:[1,0]
	v_mul_f32_e32 v106, 0x3d372713, v96
	v_mul_f32_e32 v107, 0x3d372713, v97
	v_mul_f32_e32 v106, v96, v106
	v_mul_f32_e32 v107, v97, v107
	v_fma_f32 v106, v96, v106, v96
	v_fma_f32 v107, v97, v107, v97
	v_mul_f32_e32 v106, 0x3f4c422a, v106
	v_mul_f32_e32 v107, 0x3f4c422a, v107
	v_add_f32_e32 v106, v106, v106
	v_add_f32_e32 v107, v107, v107
	v_mul_f32_e32 v106, 0x3fb8aa3b, v106
	v_mul_f32_e32 v107, 0x3fb8aa3b, v107
	v_exp_f32_e32 v106, v106
	v_exp_f32_e32 v107, v107
	v_pk_mul_f32 v[100:101], v[100:101], v[102:103]
	v_mul_f32_e32 v104, 0x3f4c422a, v104
	v_add_f32_e32 v102, 1.0, v106
	v_add_f32_e32 v106, 1.0, v107
	v_mul_f32_e32 v107, 0x3d372713, v99
	v_mul_f32_e32 v105, 0x3f4c422a, v105
	v_mul_f32_e32 v103, 0x3d372713, v98
	v_mul_f32_e32 v107, v99, v107
	v_add_f32_e32 v104, v104, v104
	v_add_f32_e32 v105, v105, v105
	v_mul_f32_e32 v103, v98, v103
	v_fma_f32 v107, v99, v107, v99
	v_mul_f32_e32 v104, 0x3fb8aa3b, v104
	v_mul_f32_e32 v105, 0x3fb8aa3b, v105
	v_fma_f32 v103, v98, v103, v98
	v_mul_f32_e32 v107, 0x3f4c422a, v107
	v_exp_f32_e32 v104, v104
	v_exp_f32_e32 v105, v105
	v_mul_f32_e32 v103, 0x3f4c422a, v103
	v_add_f32_e32 v107, v107, v107
	v_add_f32_e32 v103, v103, v103
	v_mul_f32_e32 v107, 0x3fb8aa3b, v107
	v_mul_f32_e32 v103, 0x3fb8aa3b, v103
	v_exp_f32_e32 v107, v107
	v_exp_f32_e32 v103, v103
	v_add_f32_e32 v104, 1.0, v104
	v_add_f32_e32 v105, 1.0, v105
	v_rcp_f32_e32 v104, v104
	v_rcp_f32_e32 v105, v105
	v_add_f32_e32 v107, 1.0, v107
	v_add_f32_e32 v103, 1.0, v103
	v_rcp_f32_e32 v106, v106
	v_rcp_f32_e32 v107, v107
	v_rcp_f32_e32 v102, v102
	v_rcp_f32_e32 v103, v103
	v_pk_fma_f32 v[104:105], v[104:105], 2.0, 1.0 op_sel_hi:[1,0,0] neg_lo:[1,0,0] neg_hi:[1,0,0]
	v_pk_mul_f32 v[110:111], v[110:111], 0.5 op_sel_hi:[1,0]
	v_pk_add_f32 v[104:105], v[104:105], 1.0 op_sel_hi:[1,0]
	v_pk_fma_f32 v[106:107], v[106:107], 2.0, 1.0 op_sel_hi:[1,0,0] neg_lo:[1,0,0] neg_hi:[1,0,0]
	v_pk_mul_f32 v[104:105], v[110:111], v[104:105]
	v_mov_b32_e32 v111, v98
	v_mov_b32_e32 v98, v97
	v_pk_fma_f32 v[102:103], v[102:103], 2.0, 1.0 op_sel_hi:[1,0,0] neg_lo:[1,0,0] neg_hi:[1,0,0]
	v_mov_b32_e32 v110, v96
	v_pk_mul_f32 v[96:97], v[98:99], 0.5 op_sel_hi:[1,0]
	v_pk_add_f32 v[98:99], v[106:107], 1.0 op_sel_hi:[1,0]
	v_pk_mul_f32 v[110:111], v[110:111], 0.5 op_sel_hi:[1,0]
	v_pk_add_f32 v[102:103], v[102:103], 1.0 op_sel_hi:[1,0]
	v_pk_mul_f32 v[96:97], v[96:97], v[98:99]
	v_pk_mul_f32 v[102:103], v[110:111], v[102:103]
	v_cvt_pk_bf16_f32 v99, v103, v97
	v_cvt_pk_bf16_f32 v98, v102, v96
	v_cvt_pk_bf16_f32 v97, v105, v101
	v_cvt_pk_bf16_f32 v96, v104, v100
	v_lshl_add_u64 v[100:101], v[108:109], 0, v[112:113]
	v_lshl_add_u64 v[100:101], v[100:101], 0, s[20:21]
	v_lshl_add_u64 v[100:101], v[100:101], 0, v[168:169]
	global_store_dwordx4 v[100:101], v[96:99], off offset:1536
	v_mov_b32_e32 v101, v94
	v_mov_b32_e32 v100, v92
	v_mul_f32_e32 v97, 0x3d372713, v93
	v_mul_f32_e32 v99, 0x3d372713, v95
	v_mul_f32_e32 v97, v93, v97
	v_mul_f32_e32 v99, v95, v99
	v_fma_f32 v97, v93, v97, v93
	v_fma_f32 v99, v95, v99, v95
	v_mul_f32_e32 v97, 0x3f4c422a, v97
	v_mul_f32_e32 v99, 0x3f4c422a, v99
	v_add_f32_e32 v97, v97, v97
	v_add_f32_e32 v99, v99, v99
	v_mul_f32_e32 v97, 0x3fb8aa3b, v97
	v_mul_f32_e32 v99, 0x3fb8aa3b, v99
	v_exp_f32_e32 v97, v97
	v_exp_f32_e32 v99, v99
	v_mul_f32_e32 v96, 0x3d372713, v92
	v_mul_f32_e32 v96, v92, v96
	v_add_f32_e32 v98, 1.0, v97
	v_add_f32_e32 v99, 1.0, v99
	v_rcp_f32_e32 v98, v98
	v_rcp_f32_e32 v99, v99
	v_mul_f32_e32 v97, 0x3d372713, v94
	v_mul_f32_e32 v97, v94, v97
	v_fma_f32 v97, v94, v97, v94
	v_pk_fma_f32 v[98:99], v[98:99], 2.0, 1.0 op_sel_hi:[1,0,0] neg_lo:[1,0,0] neg_hi:[1,0,0]
	v_mov_b32_e32 v94, v93
	v_fma_f32 v96, v92, v96, v92
	v_pk_mul_f32 v[92:93], v[94:95], 0.5 op_sel_hi:[1,0]
	v_pk_add_f32 v[94:95], v[98:99], 1.0 op_sel_hi:[1,0]
	v_mul_f32_e32 v98, 0x3d372713, v88
	v_mul_f32_e32 v99, 0x3d372713, v89
	v_mul_f32_e32 v98, v88, v98
	v_mul_f32_e32 v99, v89, v99
	v_fma_f32 v98, v88, v98, v88
	v_fma_f32 v99, v89, v99, v89
	v_mul_f32_e32 v98, 0x3f4c422a, v98
	v_mul_f32_e32 v99, 0x3f4c422a, v99
	v_add_f32_e32 v98, v98, v98
	v_add_f32_e32 v99, v99, v99
	v_mul_f32_e32 v98, 0x3fb8aa3b, v98
	v_mul_f32_e32 v99, 0x3fb8aa3b, v99
	v_exp_f32_e32 v98, v98
	v_exp_f32_e32 v99, v99
	v_pk_mul_f32 v[92:93], v[92:93], v[94:95]
	v_mul_f32_e32 v96, 0x3f4c422a, v96
	v_add_f32_e32 v94, 1.0, v98
	v_add_f32_e32 v98, 1.0, v99
	v_mul_f32_e32 v99, 0x3d372713, v91
	v_mul_f32_e32 v97, 0x3f4c422a, v97
	v_mul_f32_e32 v95, 0x3d372713, v90
	v_mul_f32_e32 v99, v91, v99
	v_add_f32_e32 v96, v96, v96
	v_add_f32_e32 v97, v97, v97
	v_mul_f32_e32 v95, v90, v95
	v_fma_f32 v99, v91, v99, v91
	v_mul_f32_e32 v96, 0x3fb8aa3b, v96
	v_mul_f32_e32 v97, 0x3fb8aa3b, v97
	v_fma_f32 v95, v90, v95, v90
	v_mul_f32_e32 v99, 0x3f4c422a, v99
	v_exp_f32_e32 v96, v96
	v_exp_f32_e32 v97, v97
	v_mul_f32_e32 v95, 0x3f4c422a, v95
	v_add_f32_e32 v99, v99, v99
	v_add_f32_e32 v95, v95, v95
	v_mul_f32_e32 v99, 0x3fb8aa3b, v99
	v_mul_f32_e32 v95, 0x3fb8aa3b, v95
	v_exp_f32_e32 v99, v99
	v_exp_f32_e32 v95, v95
	v_add_f32_e32 v96, 1.0, v96
	v_add_f32_e32 v97, 1.0, v97
	v_rcp_f32_e32 v96, v96
	v_rcp_f32_e32 v97, v97
	v_add_f32_e32 v99, 1.0, v99
	v_add_f32_e32 v95, 1.0, v95
	v_rcp_f32_e32 v98, v98
	v_rcp_f32_e32 v99, v99
	v_rcp_f32_e32 v94, v94
	v_rcp_f32_e32 v95, v95
	v_pk_fma_f32 v[96:97], v[96:97], 2.0, 1.0 op_sel_hi:[1,0,0] neg_lo:[1,0,0] neg_hi:[1,0,0]
	v_pk_mul_f32 v[100:101], v[100:101], 0.5 op_sel_hi:[1,0]
	v_pk_add_f32 v[96:97], v[96:97], 1.0 op_sel_hi:[1,0]
	v_pk_fma_f32 v[98:99], v[98:99], 2.0, 1.0 op_sel_hi:[1,0,0] neg_lo:[1,0,0] neg_hi:[1,0,0]
	v_pk_mul_f32 v[96:97], v[100:101], v[96:97]
	v_mov_b32_e32 v101, v90
	v_mov_b32_e32 v90, v89
	v_pk_fma_f32 v[94:95], v[94:95], 2.0, 1.0 op_sel_hi:[1,0,0] neg_lo:[1,0,0] neg_hi:[1,0,0]
	v_mov_b32_e32 v100, v88
	v_pk_mul_f32 v[88:89], v[90:91], 0.5 op_sel_hi:[1,0]
	v_pk_add_f32 v[90:91], v[98:99], 1.0 op_sel_hi:[1,0]
	v_pk_mul_f32 v[100:101], v[100:101], 0.5 op_sel_hi:[1,0]
	v_pk_add_f32 v[94:95], v[94:95], 1.0 op_sel_hi:[1,0]
	v_pk_mul_f32 v[88:89], v[88:89], v[90:91]
	v_pk_mul_f32 v[94:95], v[100:101], v[94:95]
	s_mov_b64 s[2:3], 0x100000
	v_cvt_pk_bf16_f32 v91, v95, v89
	v_cvt_pk_bf16_f32 v90, v94, v88
	v_cvt_pk_bf16_f32 v89, v97, v93
	v_cvt_pk_bf16_f32 v88, v96, v92
	v_lshl_add_u64 v[92:93], v[120:121], 0, s[2:3]
	v_lshl_add_u64 v[94:95], v[92:93], 0, v[122:123]
	v_lshl_add_u64 v[94:95], v[94:95], 0, s[20:21]
	v_lshl_add_u64 v[94:95], v[94:95], 0, v[168:169]
	global_store_dwordx4 v[94:95], v[88:91], off offset:1536
	v_mov_b32_e32 v95, v86
	v_mov_b32_e32 v94, v84
	v_mul_f32_e32 v89, 0x3d372713, v85
	v_mul_f32_e32 v91, 0x3d372713, v87
	v_mul_f32_e32 v89, v85, v89
	v_mul_f32_e32 v91, v87, v91
	v_fma_f32 v89, v85, v89, v85
	v_fma_f32 v91, v87, v91, v87
	v_mul_f32_e32 v89, 0x3f4c422a, v89
	v_mul_f32_e32 v91, 0x3f4c422a, v91
	v_add_f32_e32 v89, v89, v89
	v_add_f32_e32 v91, v91, v91
	v_mul_f32_e32 v89, 0x3fb8aa3b, v89
	v_mul_f32_e32 v91, 0x3fb8aa3b, v91
	v_exp_f32_e32 v89, v89
	v_exp_f32_e32 v91, v91
	v_mul_f32_e32 v88, 0x3d372713, v84
	v_mul_f32_e32 v88, v84, v88
	v_add_f32_e32 v90, 1.0, v89
	v_add_f32_e32 v91, 1.0, v91
	v_rcp_f32_e32 v90, v90
	v_rcp_f32_e32 v91, v91
	v_mul_f32_e32 v89, 0x3d372713, v86
	v_mul_f32_e32 v89, v86, v89
	v_fma_f32 v89, v86, v89, v86
	v_pk_fma_f32 v[90:91], v[90:91], 2.0, 1.0 op_sel_hi:[1,0,0] neg_lo:[1,0,0] neg_hi:[1,0,0]
	v_mov_b32_e32 v86, v85
	v_fma_f32 v88, v84, v88, v84
	v_pk_mul_f32 v[84:85], v[86:87], 0.5 op_sel_hi:[1,0]
	v_pk_add_f32 v[86:87], v[90:91], 1.0 op_sel_hi:[1,0]
	v_mul_f32_e32 v90, 0x3d372713, v80
	v_mul_f32_e32 v91, 0x3d372713, v81
	v_mul_f32_e32 v90, v80, v90
	v_mul_f32_e32 v91, v81, v91
	v_fma_f32 v90, v80, v90, v80
	v_fma_f32 v91, v81, v91, v81
	v_mul_f32_e32 v90, 0x3f4c422a, v90
	v_mul_f32_e32 v91, 0x3f4c422a, v91
	v_add_f32_e32 v90, v90, v90
	v_add_f32_e32 v91, v91, v91
	v_mul_f32_e32 v90, 0x3fb8aa3b, v90
	v_mul_f32_e32 v91, 0x3fb8aa3b, v91
	v_exp_f32_e32 v90, v90
	v_exp_f32_e32 v91, v91
	v_pk_mul_f32 v[84:85], v[84:85], v[86:87]
	v_mul_f32_e32 v88, 0x3f4c422a, v88
	v_add_f32_e32 v86, 1.0, v90
	v_add_f32_e32 v90, 1.0, v91
	v_mul_f32_e32 v91, 0x3d372713, v83
	v_mul_f32_e32 v89, 0x3f4c422a, v89
	v_mul_f32_e32 v87, 0x3d372713, v82
	v_mul_f32_e32 v91, v83, v91
	v_add_f32_e32 v88, v88, v88
	v_add_f32_e32 v89, v89, v89
	v_mul_f32_e32 v87, v82, v87
	v_fma_f32 v91, v83, v91, v83
	v_mul_f32_e32 v88, 0x3fb8aa3b, v88
	v_mul_f32_e32 v89, 0x3fb8aa3b, v89
	v_fma_f32 v87, v82, v87, v82
	v_mul_f32_e32 v91, 0x3f4c422a, v91
	v_exp_f32_e32 v88, v88
	v_exp_f32_e32 v89, v89
	v_mul_f32_e32 v87, 0x3f4c422a, v87
	v_add_f32_e32 v91, v91, v91
	v_add_f32_e32 v87, v87, v87
	v_mul_f32_e32 v91, 0x3fb8aa3b, v91
	v_mul_f32_e32 v87, 0x3fb8aa3b, v87
	v_exp_f32_e32 v91, v91
	v_exp_f32_e32 v87, v87
	v_add_f32_e32 v88, 1.0, v88
	v_add_f32_e32 v89, 1.0, v89
	v_rcp_f32_e32 v88, v88
	v_rcp_f32_e32 v89, v89
	v_add_f32_e32 v91, 1.0, v91
	v_add_f32_e32 v87, 1.0, v87
	v_rcp_f32_e32 v90, v90
	v_rcp_f32_e32 v91, v91
	v_rcp_f32_e32 v86, v86
	v_rcp_f32_e32 v87, v87
	v_pk_fma_f32 v[88:89], v[88:89], 2.0, 1.0 op_sel_hi:[1,0,0] neg_lo:[1,0,0] neg_hi:[1,0,0]
	v_pk_mul_f32 v[94:95], v[94:95], 0.5 op_sel_hi:[1,0]
	v_pk_add_f32 v[88:89], v[88:89], 1.0 op_sel_hi:[1,0]
	v_pk_fma_f32 v[90:91], v[90:91], 2.0, 1.0 op_sel_hi:[1,0,0] neg_lo:[1,0,0] neg_hi:[1,0,0]
	v_pk_mul_f32 v[88:89], v[94:95], v[88:89]
	v_mov_b32_e32 v95, v82
	v_mov_b32_e32 v82, v81
	v_pk_fma_f32 v[86:87], v[86:87], 2.0, 1.0 op_sel_hi:[1,0,0] neg_lo:[1,0,0] neg_hi:[1,0,0]
	v_mov_b32_e32 v94, v80
	v_pk_mul_f32 v[80:81], v[82:83], 0.5 op_sel_hi:[1,0]
	v_pk_add_f32 v[82:83], v[90:91], 1.0 op_sel_hi:[1,0]
	v_pk_mul_f32 v[94:95], v[94:95], 0.5 op_sel_hi:[1,0]
	v_pk_add_f32 v[86:87], v[86:87], 1.0 op_sel_hi:[1,0]
	v_pk_mul_f32 v[80:81], v[80:81], v[82:83]
	v_pk_mul_f32 v[86:87], v[94:95], v[86:87]
	v_cvt_pk_bf16_f32 v83, v87, v81
	v_cvt_pk_bf16_f32 v82, v86, v80
	v_cvt_pk_bf16_f32 v81, v89, v85
	v_cvt_pk_bf16_f32 v80, v88, v84
	v_lshl_add_u64 v[84:85], v[92:93], 0, v[112:113]
	v_lshl_add_u64 v[84:85], v[84:85], 0, s[20:21]
	v_lshl_add_u64 v[84:85], v[84:85], 0, v[168:169]
	global_store_dwordx4 v[84:85], v[80:83], off offset:1536
	v_mov_b32_e32 v85, v78
	v_mov_b32_e32 v84, v76
	v_mul_f32_e32 v81, 0x3d372713, v77
	v_mul_f32_e32 v83, 0x3d372713, v79
	v_mul_f32_e32 v81, v77, v81
	v_mul_f32_e32 v83, v79, v83
	v_fma_f32 v81, v77, v81, v77
	v_fma_f32 v83, v79, v83, v79
	v_mul_f32_e32 v81, 0x3f4c422a, v81
	v_mul_f32_e32 v83, 0x3f4c422a, v83
	v_add_f32_e32 v81, v81, v81
	v_add_f32_e32 v83, v83, v83
	v_mul_f32_e32 v81, 0x3fb8aa3b, v81
	v_mul_f32_e32 v83, 0x3fb8aa3b, v83
	v_exp_f32_e32 v81, v81
	v_exp_f32_e32 v83, v83
	v_mul_f32_e32 v80, 0x3d372713, v76
	v_mul_f32_e32 v80, v76, v80
	v_add_f32_e32 v82, 1.0, v81
	v_add_f32_e32 v83, 1.0, v83
	v_rcp_f32_e32 v82, v82
	v_rcp_f32_e32 v83, v83
	v_mul_f32_e32 v81, 0x3d372713, v78
	v_mul_f32_e32 v81, v78, v81
	v_fma_f32 v81, v78, v81, v78
	v_pk_fma_f32 v[82:83], v[82:83], 2.0, 1.0 op_sel_hi:[1,0,0] neg_lo:[1,0,0] neg_hi:[1,0,0]
	v_mov_b32_e32 v78, v77
	v_fma_f32 v80, v76, v80, v76
	v_pk_mul_f32 v[76:77], v[78:79], 0.5 op_sel_hi:[1,0]
	v_pk_add_f32 v[78:79], v[82:83], 1.0 op_sel_hi:[1,0]
	v_mul_f32_e32 v82, 0x3d372713, v72
	v_mul_f32_e32 v83, 0x3d372713, v73
	v_mul_f32_e32 v82, v72, v82
	v_mul_f32_e32 v83, v73, v83
	v_fma_f32 v82, v72, v82, v72
	v_fma_f32 v83, v73, v83, v73
	v_mul_f32_e32 v82, 0x3f4c422a, v82
	v_mul_f32_e32 v83, 0x3f4c422a, v83
	v_add_f32_e32 v82, v82, v82
	v_add_f32_e32 v83, v83, v83
	v_mul_f32_e32 v82, 0x3fb8aa3b, v82
	v_mul_f32_e32 v83, 0x3fb8aa3b, v83
	v_exp_f32_e32 v82, v82
	v_exp_f32_e32 v83, v83
	v_pk_mul_f32 v[76:77], v[76:77], v[78:79]
	v_mul_f32_e32 v80, 0x3f4c422a, v80
	v_add_f32_e32 v78, 1.0, v82
	v_add_f32_e32 v82, 1.0, v83
	v_mul_f32_e32 v83, 0x3d372713, v75
	v_mul_f32_e32 v81, 0x3f4c422a, v81
	v_mul_f32_e32 v79, 0x3d372713, v74
	v_mul_f32_e32 v83, v75, v83
	v_add_f32_e32 v80, v80, v80
	v_add_f32_e32 v81, v81, v81
	v_mul_f32_e32 v79, v74, v79
	v_fma_f32 v83, v75, v83, v75
	v_mul_f32_e32 v80, 0x3fb8aa3b, v80
	v_mul_f32_e32 v81, 0x3fb8aa3b, v81
	v_fma_f32 v79, v74, v79, v74
	v_mul_f32_e32 v83, 0x3f4c422a, v83
	v_exp_f32_e32 v80, v80
	v_exp_f32_e32 v81, v81
	v_mul_f32_e32 v79, 0x3f4c422a, v79
	v_add_f32_e32 v83, v83, v83
	v_add_f32_e32 v79, v79, v79
	v_mul_f32_e32 v83, 0x3fb8aa3b, v83
	v_mul_f32_e32 v79, 0x3fb8aa3b, v79
	v_exp_f32_e32 v83, v83
	v_exp_f32_e32 v79, v79
	v_add_f32_e32 v80, 1.0, v80
	v_add_f32_e32 v81, 1.0, v81
	v_rcp_f32_e32 v80, v80
	v_rcp_f32_e32 v81, v81
	v_add_f32_e32 v83, 1.0, v83
	v_add_f32_e32 v79, 1.0, v79
	v_rcp_f32_e32 v82, v82
	v_rcp_f32_e32 v83, v83
	v_rcp_f32_e32 v78, v78
	v_rcp_f32_e32 v79, v79
	v_pk_fma_f32 v[80:81], v[80:81], 2.0, 1.0 op_sel_hi:[1,0,0] neg_lo:[1,0,0] neg_hi:[1,0,0]
	v_pk_mul_f32 v[84:85], v[84:85], 0.5 op_sel_hi:[1,0]
	v_pk_add_f32 v[80:81], v[80:81], 1.0 op_sel_hi:[1,0]
	v_pk_fma_f32 v[82:83], v[82:83], 2.0, 1.0 op_sel_hi:[1,0,0] neg_lo:[1,0,0] neg_hi:[1,0,0]
	v_pk_mul_f32 v[80:81], v[84:85], v[80:81]
	v_mov_b32_e32 v85, v74
	v_mov_b32_e32 v74, v73
	v_pk_fma_f32 v[78:79], v[78:79], 2.0, 1.0 op_sel_hi:[1,0,0] neg_lo:[1,0,0] neg_hi:[1,0,0]
	v_mov_b32_e32 v84, v72
	v_pk_mul_f32 v[72:73], v[74:75], 0.5 op_sel_hi:[1,0]
	v_pk_add_f32 v[74:75], v[82:83], 1.0 op_sel_hi:[1,0]
	v_pk_mul_f32 v[84:85], v[84:85], 0.5 op_sel_hi:[1,0]
	v_pk_add_f32 v[78:79], v[78:79], 1.0 op_sel_hi:[1,0]
	v_pk_mul_f32 v[72:73], v[72:73], v[74:75]
	v_pk_mul_f32 v[78:79], v[84:85], v[78:79]
	s_mov_b64 s[2:3], 0x180000
	v_cvt_pk_bf16_f32 v75, v79, v73
	v_cvt_pk_bf16_f32 v74, v78, v72
	v_cvt_pk_bf16_f32 v73, v81, v77
	v_cvt_pk_bf16_f32 v72, v80, v76
	v_lshl_add_u64 v[76:77], v[120:121], 0, s[2:3]
	v_lshl_add_u64 v[78:79], v[76:77], 0, v[122:123]
	v_lshl_add_u64 v[78:79], v[78:79], 0, s[20:21]
	v_lshl_add_u64 v[78:79], v[78:79], 0, v[168:169]
	global_store_dwordx4 v[78:79], v[72:75], off offset:1536
	v_mov_b32_e32 v79, v70
	v_mov_b32_e32 v78, v68
	v_mul_f32_e32 v73, 0x3d372713, v69
	v_mul_f32_e32 v75, 0x3d372713, v71
	v_mul_f32_e32 v73, v69, v73
	v_mul_f32_e32 v75, v71, v75
	v_fma_f32 v73, v69, v73, v69
	v_fma_f32 v75, v71, v75, v71
	v_mul_f32_e32 v73, 0x3f4c422a, v73
	v_mul_f32_e32 v75, 0x3f4c422a, v75
	v_add_f32_e32 v73, v73, v73
	v_add_f32_e32 v75, v75, v75
	v_mul_f32_e32 v73, 0x3fb8aa3b, v73
	v_mul_f32_e32 v75, 0x3fb8aa3b, v75
	v_exp_f32_e32 v73, v73
	v_exp_f32_e32 v75, v75
	v_mul_f32_e32 v72, 0x3d372713, v68
	v_mul_f32_e32 v72, v68, v72
	v_add_f32_e32 v74, 1.0, v73
	v_add_f32_e32 v75, 1.0, v75
	v_rcp_f32_e32 v74, v74
	v_rcp_f32_e32 v75, v75
	v_mul_f32_e32 v73, 0x3d372713, v70
	v_mul_f32_e32 v73, v70, v73
	v_fma_f32 v73, v70, v73, v70
	v_pk_fma_f32 v[74:75], v[74:75], 2.0, 1.0 op_sel_hi:[1,0,0] neg_lo:[1,0,0] neg_hi:[1,0,0]
	v_mov_b32_e32 v70, v69
	v_fma_f32 v72, v68, v72, v68
	v_pk_mul_f32 v[68:69], v[70:71], 0.5 op_sel_hi:[1,0]
	v_pk_add_f32 v[70:71], v[74:75], 1.0 op_sel_hi:[1,0]
	v_mul_f32_e32 v74, 0x3d372713, v64
	v_mul_f32_e32 v75, 0x3d372713, v65
	v_mul_f32_e32 v74, v64, v74
	v_mul_f32_e32 v75, v65, v75
	v_fma_f32 v74, v64, v74, v64
	v_fma_f32 v75, v65, v75, v65
	v_mul_f32_e32 v74, 0x3f4c422a, v74
	v_mul_f32_e32 v75, 0x3f4c422a, v75
	v_add_f32_e32 v74, v74, v74
	v_add_f32_e32 v75, v75, v75
	v_mul_f32_e32 v74, 0x3fb8aa3b, v74
	v_mul_f32_e32 v75, 0x3fb8aa3b, v75
	v_exp_f32_e32 v74, v74
	v_exp_f32_e32 v75, v75
	v_pk_mul_f32 v[68:69], v[68:69], v[70:71]
	v_mul_f32_e32 v72, 0x3f4c422a, v72
	v_add_f32_e32 v70, 1.0, v74
	v_add_f32_e32 v74, 1.0, v75
	v_mul_f32_e32 v75, 0x3d372713, v67
	v_mul_f32_e32 v73, 0x3f4c422a, v73
	v_mul_f32_e32 v71, 0x3d372713, v66
	v_mul_f32_e32 v75, v67, v75
	v_add_f32_e32 v72, v72, v72
	v_add_f32_e32 v73, v73, v73
	v_mul_f32_e32 v71, v66, v71
	v_fma_f32 v75, v67, v75, v67
	v_mul_f32_e32 v72, 0x3fb8aa3b, v72
	v_mul_f32_e32 v73, 0x3fb8aa3b, v73
	v_fma_f32 v71, v66, v71, v66
	v_mul_f32_e32 v75, 0x3f4c422a, v75
	v_exp_f32_e32 v72, v72
	v_exp_f32_e32 v73, v73
	v_mul_f32_e32 v71, 0x3f4c422a, v71
	v_add_f32_e32 v75, v75, v75
	v_add_f32_e32 v71, v71, v71
	v_mul_f32_e32 v75, 0x3fb8aa3b, v75
	v_mul_f32_e32 v71, 0x3fb8aa3b, v71
	v_exp_f32_e32 v75, v75
	v_exp_f32_e32 v71, v71
	v_add_f32_e32 v72, 1.0, v72
	v_add_f32_e32 v73, 1.0, v73
	v_rcp_f32_e32 v72, v72
	v_rcp_f32_e32 v73, v73
	v_add_f32_e32 v75, 1.0, v75
	v_add_f32_e32 v71, 1.0, v71
	v_rcp_f32_e32 v74, v74
	v_rcp_f32_e32 v75, v75
	v_rcp_f32_e32 v70, v70
	v_rcp_f32_e32 v71, v71
	v_pk_fma_f32 v[72:73], v[72:73], 2.0, 1.0 op_sel_hi:[1,0,0] neg_lo:[1,0,0] neg_hi:[1,0,0]
	v_pk_mul_f32 v[78:79], v[78:79], 0.5 op_sel_hi:[1,0]
	v_pk_add_f32 v[72:73], v[72:73], 1.0 op_sel_hi:[1,0]
	v_pk_fma_f32 v[74:75], v[74:75], 2.0, 1.0 op_sel_hi:[1,0,0] neg_lo:[1,0,0] neg_hi:[1,0,0]
	v_pk_mul_f32 v[72:73], v[78:79], v[72:73]
	v_mov_b32_e32 v79, v66
	v_mov_b32_e32 v66, v65
	v_pk_fma_f32 v[70:71], v[70:71], 2.0, 1.0 op_sel_hi:[1,0,0] neg_lo:[1,0,0] neg_hi:[1,0,0]
	v_mov_b32_e32 v78, v64
	v_pk_mul_f32 v[64:65], v[66:67], 0.5 op_sel_hi:[1,0]
	v_pk_add_f32 v[66:67], v[74:75], 1.0 op_sel_hi:[1,0]
	v_pk_mul_f32 v[78:79], v[78:79], 0.5 op_sel_hi:[1,0]
	v_pk_add_f32 v[70:71], v[70:71], 1.0 op_sel_hi:[1,0]
	v_pk_mul_f32 v[64:65], v[64:65], v[66:67]
	v_pk_mul_f32 v[70:71], v[78:79], v[70:71]
	v_cvt_pk_bf16_f32 v67, v71, v65
	v_cvt_pk_bf16_f32 v66, v70, v64
	v_cvt_pk_bf16_f32 v65, v73, v69
	v_cvt_pk_bf16_f32 v64, v72, v68
	v_lshl_add_u64 v[68:69], v[76:77], 0, v[112:113]
	v_lshl_add_u64 v[68:69], v[68:69], 0, s[20:21]
	v_lshl_add_u64 v[68:69], v[68:69], 0, v[168:169]
	global_store_dwordx4 v[68:69], v[64:67], off offset:1536
	v_mov_b32_e32 v69, v62
	v_mov_b32_e32 v68, v60
	v_mul_f32_e32 v65, 0x3d372713, v61
	v_mul_f32_e32 v67, 0x3d372713, v63
	v_mul_f32_e32 v65, v61, v65
	v_mul_f32_e32 v67, v63, v67
	v_fma_f32 v65, v61, v65, v61
	v_fma_f32 v67, v63, v67, v63
	v_mul_f32_e32 v65, 0x3f4c422a, v65
	v_mul_f32_e32 v67, 0x3f4c422a, v67
	v_add_f32_e32 v65, v65, v65
	v_add_f32_e32 v67, v67, v67
	v_mul_f32_e32 v65, 0x3fb8aa3b, v65
	v_mul_f32_e32 v67, 0x3fb8aa3b, v67
	v_exp_f32_e32 v65, v65
	v_exp_f32_e32 v67, v67
	v_mul_f32_e32 v64, 0x3d372713, v60
	v_mul_f32_e32 v64, v60, v64
	v_add_f32_e32 v66, 1.0, v65
	v_add_f32_e32 v67, 1.0, v67
	v_rcp_f32_e32 v66, v66
	v_rcp_f32_e32 v67, v67
	v_mul_f32_e32 v65, 0x3d372713, v62
	v_mul_f32_e32 v65, v62, v65
	v_fma_f32 v65, v62, v65, v62
	v_pk_fma_f32 v[66:67], v[66:67], 2.0, 1.0 op_sel_hi:[1,0,0] neg_lo:[1,0,0] neg_hi:[1,0,0]
	v_mov_b32_e32 v62, v61
	v_fma_f32 v64, v60, v64, v60
	v_pk_mul_f32 v[60:61], v[62:63], 0.5 op_sel_hi:[1,0]
	v_pk_add_f32 v[62:63], v[66:67], 1.0 op_sel_hi:[1,0]
	v_mul_f32_e32 v66, 0x3d372713, v56
	v_mul_f32_e32 v67, 0x3d372713, v57
	v_mul_f32_e32 v66, v56, v66
	v_mul_f32_e32 v67, v57, v67
	v_fma_f32 v66, v56, v66, v56
	v_fma_f32 v67, v57, v67, v57
	v_mul_f32_e32 v66, 0x3f4c422a, v66
	v_mul_f32_e32 v67, 0x3f4c422a, v67
	v_add_f32_e32 v66, v66, v66
	v_add_f32_e32 v67, v67, v67
	v_mul_f32_e32 v66, 0x3fb8aa3b, v66
	v_mul_f32_e32 v67, 0x3fb8aa3b, v67
	v_exp_f32_e32 v66, v66
	v_exp_f32_e32 v67, v67
	v_pk_mul_f32 v[60:61], v[60:61], v[62:63]
	v_mul_f32_e32 v64, 0x3f4c422a, v64
	v_add_f32_e32 v62, 1.0, v66
	v_add_f32_e32 v66, 1.0, v67
	v_mul_f32_e32 v67, 0x3d372713, v59
	v_mul_f32_e32 v65, 0x3f4c422a, v65
	v_mul_f32_e32 v63, 0x3d372713, v58
	v_mul_f32_e32 v67, v59, v67
	v_add_f32_e32 v64, v64, v64
	v_add_f32_e32 v65, v65, v65
	v_mul_f32_e32 v63, v58, v63
	v_fma_f32 v67, v59, v67, v59
	v_mul_f32_e32 v64, 0x3fb8aa3b, v64
	v_mul_f32_e32 v65, 0x3fb8aa3b, v65
	v_fma_f32 v63, v58, v63, v58
	v_mul_f32_e32 v67, 0x3f4c422a, v67
	v_exp_f32_e32 v64, v64
	v_exp_f32_e32 v65, v65
	v_mul_f32_e32 v63, 0x3f4c422a, v63
	v_add_f32_e32 v67, v67, v67
	v_add_f32_e32 v63, v63, v63
	v_mul_f32_e32 v67, 0x3fb8aa3b, v67
	v_mul_f32_e32 v63, 0x3fb8aa3b, v63
	v_exp_f32_e32 v67, v67
	v_exp_f32_e32 v63, v63
	v_add_f32_e32 v64, 1.0, v64
	v_add_f32_e32 v65, 1.0, v65
	v_rcp_f32_e32 v64, v64
	v_rcp_f32_e32 v65, v65
	v_add_f32_e32 v67, 1.0, v67
	v_add_f32_e32 v63, 1.0, v63
	v_rcp_f32_e32 v66, v66
	v_rcp_f32_e32 v67, v67
	v_rcp_f32_e32 v62, v62
	v_rcp_f32_e32 v63, v63
	v_pk_fma_f32 v[64:65], v[64:65], 2.0, 1.0 op_sel_hi:[1,0,0] neg_lo:[1,0,0] neg_hi:[1,0,0]
	v_pk_mul_f32 v[68:69], v[68:69], 0.5 op_sel_hi:[1,0]
	v_pk_add_f32 v[64:65], v[64:65], 1.0 op_sel_hi:[1,0]
	v_pk_fma_f32 v[66:67], v[66:67], 2.0, 1.0 op_sel_hi:[1,0,0] neg_lo:[1,0,0] neg_hi:[1,0,0]
	v_pk_mul_f32 v[64:65], v[68:69], v[64:65]
	v_mov_b32_e32 v69, v58
	v_mov_b32_e32 v58, v57
	v_pk_fma_f32 v[62:63], v[62:63], 2.0, 1.0 op_sel_hi:[1,0,0] neg_lo:[1,0,0] neg_hi:[1,0,0]
	v_mov_b32_e32 v68, v56
	v_pk_mul_f32 v[56:57], v[58:59], 0.5 op_sel_hi:[1,0]
	v_pk_add_f32 v[58:59], v[66:67], 1.0 op_sel_hi:[1,0]
	v_pk_mul_f32 v[68:69], v[68:69], 0.5 op_sel_hi:[1,0]
	v_pk_add_f32 v[62:63], v[62:63], 1.0 op_sel_hi:[1,0]
	v_pk_mul_f32 v[56:57], v[56:57], v[58:59]
	v_pk_mul_f32 v[62:63], v[68:69], v[62:63]
	s_mov_b64 s[2:3], 0x400000
	v_cvt_pk_bf16_f32 v59, v63, v57
	v_cvt_pk_bf16_f32 v58, v62, v56
	v_cvt_pk_bf16_f32 v57, v65, v61
	v_cvt_pk_bf16_f32 v56, v64, v60
	v_lshl_add_u64 v[60:61], v[120:121], 0, s[2:3]
	v_lshl_add_u64 v[62:63], v[60:61], 0, v[122:123]
	v_lshl_add_u64 v[62:63], v[62:63], 0, s[20:21]
	v_lshl_add_u64 v[62:63], v[62:63], 0, v[168:169]
	global_store_dwordx4 v[62:63], v[56:59], off offset:1536
	v_mov_b32_e32 v63, v54
	v_mov_b32_e32 v62, v52
	v_mul_f32_e32 v57, 0x3d372713, v53
	v_mul_f32_e32 v59, 0x3d372713, v55
	v_mul_f32_e32 v57, v53, v57
	v_mul_f32_e32 v59, v55, v59
	v_fma_f32 v57, v53, v57, v53
	v_fma_f32 v59, v55, v59, v55
	v_mul_f32_e32 v57, 0x3f4c422a, v57
	v_mul_f32_e32 v59, 0x3f4c422a, v59
	v_add_f32_e32 v57, v57, v57
	v_add_f32_e32 v59, v59, v59
	v_mul_f32_e32 v57, 0x3fb8aa3b, v57
	v_mul_f32_e32 v59, 0x3fb8aa3b, v59
	v_exp_f32_e32 v57, v57
	v_exp_f32_e32 v59, v59
	v_mul_f32_e32 v56, 0x3d372713, v52
	v_mul_f32_e32 v56, v52, v56
	v_add_f32_e32 v58, 1.0, v57
	v_add_f32_e32 v59, 1.0, v59
	v_rcp_f32_e32 v58, v58
	v_rcp_f32_e32 v59, v59
	v_mul_f32_e32 v57, 0x3d372713, v54
	v_mul_f32_e32 v57, v54, v57
	v_fma_f32 v57, v54, v57, v54
	v_pk_fma_f32 v[58:59], v[58:59], 2.0, 1.0 op_sel_hi:[1,0,0] neg_lo:[1,0,0] neg_hi:[1,0,0]
	v_mov_b32_e32 v54, v53
	v_fma_f32 v56, v52, v56, v52
	v_pk_mul_f32 v[52:53], v[54:55], 0.5 op_sel_hi:[1,0]
	v_pk_add_f32 v[54:55], v[58:59], 1.0 op_sel_hi:[1,0]
	v_mul_f32_e32 v58, 0x3d372713, v48
	v_mul_f32_e32 v59, 0x3d372713, v49
	v_mul_f32_e32 v58, v48, v58
	v_mul_f32_e32 v59, v49, v59
	v_fma_f32 v58, v48, v58, v48
	v_fma_f32 v59, v49, v59, v49
	v_mul_f32_e32 v58, 0x3f4c422a, v58
	v_mul_f32_e32 v59, 0x3f4c422a, v59
	v_add_f32_e32 v58, v58, v58
	v_add_f32_e32 v59, v59, v59
	v_mul_f32_e32 v58, 0x3fb8aa3b, v58
	v_mul_f32_e32 v59, 0x3fb8aa3b, v59
	v_exp_f32_e32 v58, v58
	v_exp_f32_e32 v59, v59
	v_pk_mul_f32 v[52:53], v[52:53], v[54:55]
	v_mul_f32_e32 v56, 0x3f4c422a, v56
	v_add_f32_e32 v54, 1.0, v58
	v_add_f32_e32 v58, 1.0, v59
	v_mul_f32_e32 v59, 0x3d372713, v51
	v_mul_f32_e32 v57, 0x3f4c422a, v57
	v_mul_f32_e32 v55, 0x3d372713, v50
	v_mul_f32_e32 v59, v51, v59
	v_add_f32_e32 v56, v56, v56
	v_add_f32_e32 v57, v57, v57
	v_mul_f32_e32 v55, v50, v55
	v_fma_f32 v59, v51, v59, v51
	v_mul_f32_e32 v56, 0x3fb8aa3b, v56
	v_mul_f32_e32 v57, 0x3fb8aa3b, v57
	v_fma_f32 v55, v50, v55, v50
	v_mul_f32_e32 v59, 0x3f4c422a, v59
	v_exp_f32_e32 v56, v56
	v_exp_f32_e32 v57, v57
	v_mul_f32_e32 v55, 0x3f4c422a, v55
	v_add_f32_e32 v59, v59, v59
	v_add_f32_e32 v55, v55, v55
	v_mul_f32_e32 v59, 0x3fb8aa3b, v59
	v_mul_f32_e32 v55, 0x3fb8aa3b, v55
	v_exp_f32_e32 v59, v59
	v_exp_f32_e32 v55, v55
	v_add_f32_e32 v56, 1.0, v56
	v_add_f32_e32 v57, 1.0, v57
	v_rcp_f32_e32 v56, v56
	v_rcp_f32_e32 v57, v57
	v_add_f32_e32 v59, 1.0, v59
	v_add_f32_e32 v55, 1.0, v55
	v_rcp_f32_e32 v58, v58
	v_rcp_f32_e32 v59, v59
	v_rcp_f32_e32 v54, v54
	v_rcp_f32_e32 v55, v55
	v_pk_fma_f32 v[56:57], v[56:57], 2.0, 1.0 op_sel_hi:[1,0,0] neg_lo:[1,0,0] neg_hi:[1,0,0]
	v_pk_mul_f32 v[62:63], v[62:63], 0.5 op_sel_hi:[1,0]
	v_pk_add_f32 v[56:57], v[56:57], 1.0 op_sel_hi:[1,0]
	v_pk_fma_f32 v[58:59], v[58:59], 2.0, 1.0 op_sel_hi:[1,0,0] neg_lo:[1,0,0] neg_hi:[1,0,0]
	v_pk_mul_f32 v[56:57], v[62:63], v[56:57]
	v_mov_b32_e32 v63, v50
	v_mov_b32_e32 v50, v49
	v_pk_fma_f32 v[54:55], v[54:55], 2.0, 1.0 op_sel_hi:[1,0,0] neg_lo:[1,0,0] neg_hi:[1,0,0]
	v_mov_b32_e32 v62, v48
	v_pk_mul_f32 v[48:49], v[50:51], 0.5 op_sel_hi:[1,0]
	v_pk_add_f32 v[50:51], v[58:59], 1.0 op_sel_hi:[1,0]
	v_pk_mul_f32 v[62:63], v[62:63], 0.5 op_sel_hi:[1,0]
	v_pk_add_f32 v[54:55], v[54:55], 1.0 op_sel_hi:[1,0]
	v_pk_mul_f32 v[48:49], v[48:49], v[50:51]
	v_pk_mul_f32 v[54:55], v[62:63], v[54:55]
	v_cvt_pk_bf16_f32 v51, v55, v49
	v_cvt_pk_bf16_f32 v50, v54, v48
	v_cvt_pk_bf16_f32 v49, v57, v53
	v_cvt_pk_bf16_f32 v48, v56, v52
	v_lshl_add_u64 v[52:53], v[60:61], 0, v[112:113]
	v_lshl_add_u64 v[52:53], v[52:53], 0, s[20:21]
	v_lshl_add_u64 v[52:53], v[52:53], 0, v[168:169]
	global_store_dwordx4 v[52:53], v[48:51], off offset:1536
	v_mov_b32_e32 v53, v46
	v_mov_b32_e32 v52, v44
	v_mul_f32_e32 v49, 0x3d372713, v45
	v_mul_f32_e32 v51, 0x3d372713, v47
	v_mul_f32_e32 v49, v45, v49
	v_mul_f32_e32 v51, v47, v51
	v_fma_f32 v49, v45, v49, v45
	v_fma_f32 v51, v47, v51, v47
	v_mul_f32_e32 v49, 0x3f4c422a, v49
	v_mul_f32_e32 v51, 0x3f4c422a, v51
	v_add_f32_e32 v49, v49, v49
	v_add_f32_e32 v51, v51, v51
	v_mul_f32_e32 v49, 0x3fb8aa3b, v49
	v_mul_f32_e32 v51, 0x3fb8aa3b, v51
	v_exp_f32_e32 v49, v49
	v_exp_f32_e32 v51, v51
	v_mul_f32_e32 v48, 0x3d372713, v44
	v_mul_f32_e32 v48, v44, v48
	v_add_f32_e32 v50, 1.0, v49
	v_add_f32_e32 v51, 1.0, v51
	v_rcp_f32_e32 v50, v50
	v_rcp_f32_e32 v51, v51
	v_mul_f32_e32 v49, 0x3d372713, v46
	v_mul_f32_e32 v49, v46, v49
	v_fma_f32 v49, v46, v49, v46
	v_pk_fma_f32 v[50:51], v[50:51], 2.0, 1.0 op_sel_hi:[1,0,0] neg_lo:[1,0,0] neg_hi:[1,0,0]
	v_mov_b32_e32 v46, v45
	v_fma_f32 v48, v44, v48, v44
	v_pk_mul_f32 v[44:45], v[46:47], 0.5 op_sel_hi:[1,0]
	v_pk_add_f32 v[46:47], v[50:51], 1.0 op_sel_hi:[1,0]
	v_mul_f32_e32 v50, 0x3d372713, v40
	v_mul_f32_e32 v51, 0x3d372713, v41
	v_mul_f32_e32 v50, v40, v50
	v_mul_f32_e32 v51, v41, v51
	v_fma_f32 v50, v40, v50, v40
	v_fma_f32 v51, v41, v51, v41
	v_mul_f32_e32 v50, 0x3f4c422a, v50
	v_mul_f32_e32 v51, 0x3f4c422a, v51
	v_add_f32_e32 v50, v50, v50
	v_add_f32_e32 v51, v51, v51
	v_mul_f32_e32 v50, 0x3fb8aa3b, v50
	v_mul_f32_e32 v51, 0x3fb8aa3b, v51
	v_exp_f32_e32 v50, v50
	v_exp_f32_e32 v51, v51
	v_pk_mul_f32 v[44:45], v[44:45], v[46:47]
	v_mul_f32_e32 v48, 0x3f4c422a, v48
	v_add_f32_e32 v46, 1.0, v50
	v_add_f32_e32 v50, 1.0, v51
	v_mul_f32_e32 v51, 0x3d372713, v43
	v_mul_f32_e32 v49, 0x3f4c422a, v49
	v_mul_f32_e32 v47, 0x3d372713, v42
	v_mul_f32_e32 v51, v43, v51
	v_add_f32_e32 v48, v48, v48
	v_add_f32_e32 v49, v49, v49
	v_mul_f32_e32 v47, v42, v47
	v_fma_f32 v51, v43, v51, v43
	v_mul_f32_e32 v48, 0x3fb8aa3b, v48
	v_mul_f32_e32 v49, 0x3fb8aa3b, v49
	v_fma_f32 v47, v42, v47, v42
	v_mul_f32_e32 v51, 0x3f4c422a, v51
	v_exp_f32_e32 v48, v48
	v_exp_f32_e32 v49, v49
	v_mul_f32_e32 v47, 0x3f4c422a, v47
	v_add_f32_e32 v51, v51, v51
	v_add_f32_e32 v47, v47, v47
	v_mul_f32_e32 v51, 0x3fb8aa3b, v51
	v_mul_f32_e32 v47, 0x3fb8aa3b, v47
	v_exp_f32_e32 v51, v51
	v_exp_f32_e32 v47, v47
	v_add_f32_e32 v48, 1.0, v48
	v_add_f32_e32 v49, 1.0, v49
	v_rcp_f32_e32 v48, v48
	v_rcp_f32_e32 v49, v49
	v_add_f32_e32 v51, 1.0, v51
	v_add_f32_e32 v47, 1.0, v47
	v_rcp_f32_e32 v50, v50
	v_rcp_f32_e32 v51, v51
	v_rcp_f32_e32 v46, v46
	v_rcp_f32_e32 v47, v47
	v_pk_fma_f32 v[48:49], v[48:49], 2.0, 1.0 op_sel_hi:[1,0,0] neg_lo:[1,0,0] neg_hi:[1,0,0]
	v_pk_mul_f32 v[52:53], v[52:53], 0.5 op_sel_hi:[1,0]
	v_pk_add_f32 v[48:49], v[48:49], 1.0 op_sel_hi:[1,0]
	v_pk_fma_f32 v[50:51], v[50:51], 2.0, 1.0 op_sel_hi:[1,0,0] neg_lo:[1,0,0] neg_hi:[1,0,0]
	v_pk_mul_f32 v[48:49], v[52:53], v[48:49]
	v_mov_b32_e32 v53, v42
	v_mov_b32_e32 v42, v41
	v_pk_fma_f32 v[46:47], v[46:47], 2.0, 1.0 op_sel_hi:[1,0,0] neg_lo:[1,0,0] neg_hi:[1,0,0]
	v_mov_b32_e32 v52, v40
	v_pk_mul_f32 v[40:41], v[42:43], 0.5 op_sel_hi:[1,0]
	v_pk_add_f32 v[42:43], v[50:51], 1.0 op_sel_hi:[1,0]
	v_pk_mul_f32 v[52:53], v[52:53], 0.5 op_sel_hi:[1,0]
	v_pk_add_f32 v[46:47], v[46:47], 1.0 op_sel_hi:[1,0]
	v_pk_mul_f32 v[40:41], v[40:41], v[42:43]
	v_pk_mul_f32 v[46:47], v[52:53], v[46:47]
	s_mov_b64 s[2:3], 0x480000
	v_cvt_pk_bf16_f32 v43, v47, v41
	v_cvt_pk_bf16_f32 v42, v46, v40
	v_cvt_pk_bf16_f32 v41, v49, v45
	v_cvt_pk_bf16_f32 v40, v48, v44
	v_lshl_add_u64 v[44:45], v[120:121], 0, s[2:3]
	v_lshl_add_u64 v[46:47], v[44:45], 0, v[122:123]
	v_lshl_add_u64 v[46:47], v[46:47], 0, s[20:21]
	v_lshl_add_u64 v[46:47], v[46:47], 0, v[168:169]
	global_store_dwordx4 v[46:47], v[40:43], off offset:1536
	v_mov_b32_e32 v47, v38
	v_mov_b32_e32 v46, v36
	v_mul_f32_e32 v41, 0x3d372713, v37
	v_mul_f32_e32 v43, 0x3d372713, v39
	v_mul_f32_e32 v41, v37, v41
	v_mul_f32_e32 v43, v39, v43
	v_fma_f32 v41, v37, v41, v37
	v_fma_f32 v43, v39, v43, v39
	v_mul_f32_e32 v41, 0x3f4c422a, v41
	v_mul_f32_e32 v43, 0x3f4c422a, v43
	v_add_f32_e32 v41, v41, v41
	v_add_f32_e32 v43, v43, v43
	v_mul_f32_e32 v41, 0x3fb8aa3b, v41
	v_mul_f32_e32 v43, 0x3fb8aa3b, v43
	v_exp_f32_e32 v41, v41
	v_exp_f32_e32 v43, v43
	v_mul_f32_e32 v40, 0x3d372713, v36
	v_mul_f32_e32 v40, v36, v40
	v_add_f32_e32 v42, 1.0, v41
	v_add_f32_e32 v43, 1.0, v43
	v_rcp_f32_e32 v42, v42
	v_rcp_f32_e32 v43, v43
	v_mul_f32_e32 v41, 0x3d372713, v38
	v_mul_f32_e32 v41, v38, v41
	v_fma_f32 v41, v38, v41, v38
	v_pk_fma_f32 v[42:43], v[42:43], 2.0, 1.0 op_sel_hi:[1,0,0] neg_lo:[1,0,0] neg_hi:[1,0,0]
	v_mov_b32_e32 v38, v37
	v_fma_f32 v40, v36, v40, v36
	v_pk_mul_f32 v[36:37], v[38:39], 0.5 op_sel_hi:[1,0]
	v_pk_add_f32 v[38:39], v[42:43], 1.0 op_sel_hi:[1,0]
	v_mul_f32_e32 v42, 0x3d372713, v32
	v_mul_f32_e32 v43, 0x3d372713, v33
	v_mul_f32_e32 v42, v32, v42
	v_mul_f32_e32 v43, v33, v43
	v_fma_f32 v42, v32, v42, v32
	v_fma_f32 v43, v33, v43, v33
	v_mul_f32_e32 v42, 0x3f4c422a, v42
	v_mul_f32_e32 v43, 0x3f4c422a, v43
	v_add_f32_e32 v42, v42, v42
	v_add_f32_e32 v43, v43, v43
	v_mul_f32_e32 v42, 0x3fb8aa3b, v42
	v_mul_f32_e32 v43, 0x3fb8aa3b, v43
	v_exp_f32_e32 v42, v42
	v_exp_f32_e32 v43, v43
	v_pk_mul_f32 v[36:37], v[36:37], v[38:39]
	v_mul_f32_e32 v40, 0x3f4c422a, v40
	v_add_f32_e32 v38, 1.0, v42
	v_add_f32_e32 v42, 1.0, v43
	v_mul_f32_e32 v43, 0x3d372713, v35
	v_mul_f32_e32 v41, 0x3f4c422a, v41
	v_mul_f32_e32 v39, 0x3d372713, v34
	v_mul_f32_e32 v43, v35, v43
	v_add_f32_e32 v40, v40, v40
	v_add_f32_e32 v41, v41, v41
	v_mul_f32_e32 v39, v34, v39
	v_fma_f32 v43, v35, v43, v35
	v_mul_f32_e32 v40, 0x3fb8aa3b, v40
	v_mul_f32_e32 v41, 0x3fb8aa3b, v41
	v_fma_f32 v39, v34, v39, v34
	v_mul_f32_e32 v43, 0x3f4c422a, v43
	v_exp_f32_e32 v40, v40
	v_exp_f32_e32 v41, v41
	v_mul_f32_e32 v39, 0x3f4c422a, v39
	v_add_f32_e32 v43, v43, v43
	v_add_f32_e32 v39, v39, v39
	v_mul_f32_e32 v43, 0x3fb8aa3b, v43
	v_mul_f32_e32 v39, 0x3fb8aa3b, v39
	v_exp_f32_e32 v43, v43
	v_exp_f32_e32 v39, v39
	v_add_f32_e32 v40, 1.0, v40
	v_add_f32_e32 v41, 1.0, v41
	v_rcp_f32_e32 v40, v40
	v_rcp_f32_e32 v41, v41
	v_add_f32_e32 v43, 1.0, v43
	v_add_f32_e32 v39, 1.0, v39
	v_rcp_f32_e32 v42, v42
	v_rcp_f32_e32 v43, v43
	v_rcp_f32_e32 v38, v38
	v_rcp_f32_e32 v39, v39
	v_pk_fma_f32 v[40:41], v[40:41], 2.0, 1.0 op_sel_hi:[1,0,0] neg_lo:[1,0,0] neg_hi:[1,0,0]
	v_pk_mul_f32 v[46:47], v[46:47], 0.5 op_sel_hi:[1,0]
	v_pk_add_f32 v[40:41], v[40:41], 1.0 op_sel_hi:[1,0]
	v_pk_fma_f32 v[42:43], v[42:43], 2.0, 1.0 op_sel_hi:[1,0,0] neg_lo:[1,0,0] neg_hi:[1,0,0]
	v_pk_mul_f32 v[40:41], v[46:47], v[40:41]
	v_mov_b32_e32 v47, v34
	v_mov_b32_e32 v34, v33
	v_pk_fma_f32 v[38:39], v[38:39], 2.0, 1.0 op_sel_hi:[1,0,0] neg_lo:[1,0,0] neg_hi:[1,0,0]
	v_mov_b32_e32 v46, v32
	v_pk_mul_f32 v[32:33], v[34:35], 0.5 op_sel_hi:[1,0]
	v_pk_add_f32 v[34:35], v[42:43], 1.0 op_sel_hi:[1,0]
	v_pk_mul_f32 v[46:47], v[46:47], 0.5 op_sel_hi:[1,0]
	v_pk_add_f32 v[38:39], v[38:39], 1.0 op_sel_hi:[1,0]
	v_pk_mul_f32 v[32:33], v[32:33], v[34:35]
	v_pk_mul_f32 v[38:39], v[46:47], v[38:39]
	v_cvt_pk_bf16_f32 v35, v39, v33
	v_cvt_pk_bf16_f32 v34, v38, v32
	v_cvt_pk_bf16_f32 v33, v41, v37
	v_cvt_pk_bf16_f32 v32, v40, v36
	v_lshl_add_u64 v[36:37], v[44:45], 0, v[112:113]
	v_lshl_add_u64 v[36:37], v[36:37], 0, s[20:21]
	v_lshl_add_u64 v[36:37], v[36:37], 0, v[168:169]
	global_store_dwordx4 v[36:37], v[32:35], off offset:1536
	v_mov_b32_e32 v37, v30
	v_mov_b32_e32 v36, v28
	v_mul_f32_e32 v33, 0x3d372713, v29
	v_mul_f32_e32 v35, 0x3d372713, v31
	v_mul_f32_e32 v33, v29, v33
	v_mul_f32_e32 v35, v31, v35
	v_fma_f32 v33, v29, v33, v29
	v_fma_f32 v35, v31, v35, v31
	v_mul_f32_e32 v33, 0x3f4c422a, v33
	v_mul_f32_e32 v35, 0x3f4c422a, v35
	v_add_f32_e32 v33, v33, v33
	v_add_f32_e32 v35, v35, v35
	v_mul_f32_e32 v33, 0x3fb8aa3b, v33
	v_mul_f32_e32 v35, 0x3fb8aa3b, v35
	v_exp_f32_e32 v33, v33
	v_exp_f32_e32 v35, v35
	v_mul_f32_e32 v32, 0x3d372713, v28
	v_mul_f32_e32 v32, v28, v32
	v_add_f32_e32 v34, 1.0, v33
	v_add_f32_e32 v35, 1.0, v35
	v_rcp_f32_e32 v34, v34
	v_rcp_f32_e32 v35, v35
	v_mul_f32_e32 v33, 0x3d372713, v30
	v_mul_f32_e32 v33, v30, v33
	v_fma_f32 v33, v30, v33, v30
	v_pk_fma_f32 v[34:35], v[34:35], 2.0, 1.0 op_sel_hi:[1,0,0] neg_lo:[1,0,0] neg_hi:[1,0,0]
	v_mov_b32_e32 v30, v29
	v_fma_f32 v32, v28, v32, v28
	v_pk_mul_f32 v[28:29], v[30:31], 0.5 op_sel_hi:[1,0]
	v_pk_add_f32 v[30:31], v[34:35], 1.0 op_sel_hi:[1,0]
	v_mul_f32_e32 v34, 0x3d372713, v24
	v_mul_f32_e32 v35, 0x3d372713, v25
	v_mul_f32_e32 v34, v24, v34
	v_mul_f32_e32 v35, v25, v35
	v_fma_f32 v34, v24, v34, v24
	v_fma_f32 v35, v25, v35, v25
	v_mul_f32_e32 v34, 0x3f4c422a, v34
	v_mul_f32_e32 v35, 0x3f4c422a, v35
	v_add_f32_e32 v34, v34, v34
	v_add_f32_e32 v35, v35, v35
	v_mul_f32_e32 v34, 0x3fb8aa3b, v34
	v_mul_f32_e32 v35, 0x3fb8aa3b, v35
	v_exp_f32_e32 v34, v34
	v_exp_f32_e32 v35, v35
	v_pk_mul_f32 v[28:29], v[28:29], v[30:31]
	v_mul_f32_e32 v32, 0x3f4c422a, v32
	v_add_f32_e32 v30, 1.0, v34
	v_add_f32_e32 v34, 1.0, v35
	v_mul_f32_e32 v35, 0x3d372713, v27
	v_mul_f32_e32 v33, 0x3f4c422a, v33
	v_mul_f32_e32 v31, 0x3d372713, v26
	v_mul_f32_e32 v35, v27, v35
	v_add_f32_e32 v32, v32, v32
	v_add_f32_e32 v33, v33, v33
	v_mul_f32_e32 v31, v26, v31
	v_fma_f32 v35, v27, v35, v27
	v_mul_f32_e32 v32, 0x3fb8aa3b, v32
	v_mul_f32_e32 v33, 0x3fb8aa3b, v33
	v_fma_f32 v31, v26, v31, v26
	v_mul_f32_e32 v35, 0x3f4c422a, v35
	v_exp_f32_e32 v32, v32
	v_exp_f32_e32 v33, v33
	v_mul_f32_e32 v31, 0x3f4c422a, v31
	v_add_f32_e32 v35, v35, v35
	v_add_f32_e32 v31, v31, v31
	v_mul_f32_e32 v35, 0x3fb8aa3b, v35
	v_mul_f32_e32 v31, 0x3fb8aa3b, v31
	v_exp_f32_e32 v35, v35
	v_exp_f32_e32 v31, v31
	v_add_f32_e32 v32, 1.0, v32
	v_add_f32_e32 v33, 1.0, v33
	v_rcp_f32_e32 v32, v32
	v_rcp_f32_e32 v33, v33
	v_add_f32_e32 v35, 1.0, v35
	v_add_f32_e32 v31, 1.0, v31
	v_rcp_f32_e32 v34, v34
	v_rcp_f32_e32 v35, v35
	v_rcp_f32_e32 v30, v30
	v_rcp_f32_e32 v31, v31
	v_pk_fma_f32 v[32:33], v[32:33], 2.0, 1.0 op_sel_hi:[1,0,0] neg_lo:[1,0,0] neg_hi:[1,0,0]
	v_pk_mul_f32 v[36:37], v[36:37], 0.5 op_sel_hi:[1,0]
	v_pk_add_f32 v[32:33], v[32:33], 1.0 op_sel_hi:[1,0]
	v_pk_fma_f32 v[34:35], v[34:35], 2.0, 1.0 op_sel_hi:[1,0,0] neg_lo:[1,0,0] neg_hi:[1,0,0]
	v_pk_mul_f32 v[32:33], v[36:37], v[32:33]
	v_mov_b32_e32 v37, v26
	v_mov_b32_e32 v26, v25
	v_pk_fma_f32 v[30:31], v[30:31], 2.0, 1.0 op_sel_hi:[1,0,0] neg_lo:[1,0,0] neg_hi:[1,0,0]
	v_mov_b32_e32 v36, v24
	v_pk_mul_f32 v[24:25], v[26:27], 0.5 op_sel_hi:[1,0]
	v_pk_add_f32 v[26:27], v[34:35], 1.0 op_sel_hi:[1,0]
	v_pk_mul_f32 v[36:37], v[36:37], 0.5 op_sel_hi:[1,0]
	v_pk_add_f32 v[30:31], v[30:31], 1.0 op_sel_hi:[1,0]
	v_pk_mul_f32 v[24:25], v[24:25], v[26:27]
	v_pk_mul_f32 v[30:31], v[36:37], v[30:31]
	s_mov_b64 s[2:3], 0x500000
	v_cvt_pk_bf16_f32 v27, v31, v25
	v_cvt_pk_bf16_f32 v26, v30, v24
	v_cvt_pk_bf16_f32 v25, v33, v29
	v_cvt_pk_bf16_f32 v24, v32, v28
	v_lshl_add_u64 v[28:29], v[120:121], 0, s[2:3]
	v_lshl_add_u64 v[30:31], v[28:29], 0, v[122:123]
	v_lshl_add_u64 v[30:31], v[30:31], 0, s[20:21]
	v_lshl_add_u64 v[30:31], v[30:31], 0, v[168:169]
	global_store_dwordx4 v[30:31], v[24:27], off offset:1536
	v_mov_b32_e32 v31, v22
	v_mov_b32_e32 v30, v20
	v_mul_f32_e32 v25, 0x3d372713, v21
	v_mul_f32_e32 v27, 0x3d372713, v23
	v_mul_f32_e32 v25, v21, v25
	v_mul_f32_e32 v27, v23, v27
	v_fma_f32 v25, v21, v25, v21
	v_fma_f32 v27, v23, v27, v23
	v_mul_f32_e32 v25, 0x3f4c422a, v25
	v_mul_f32_e32 v27, 0x3f4c422a, v27
	v_add_f32_e32 v25, v25, v25
	v_add_f32_e32 v27, v27, v27
	v_mul_f32_e32 v25, 0x3fb8aa3b, v25
	v_mul_f32_e32 v27, 0x3fb8aa3b, v27
	v_exp_f32_e32 v25, v25
	v_exp_f32_e32 v27, v27
	v_mul_f32_e32 v24, 0x3d372713, v20
	v_mul_f32_e32 v24, v20, v24
	v_add_f32_e32 v26, 1.0, v25
	v_add_f32_e32 v27, 1.0, v27
	v_rcp_f32_e32 v26, v26
	v_rcp_f32_e32 v27, v27
	v_mul_f32_e32 v25, 0x3d372713, v22
	v_mul_f32_e32 v25, v22, v25
	v_fma_f32 v25, v22, v25, v22
	v_pk_fma_f32 v[26:27], v[26:27], 2.0, 1.0 op_sel_hi:[1,0,0] neg_lo:[1,0,0] neg_hi:[1,0,0]
	v_mov_b32_e32 v22, v21
	v_fma_f32 v24, v20, v24, v20
	v_pk_mul_f32 v[20:21], v[22:23], 0.5 op_sel_hi:[1,0]
	v_pk_add_f32 v[22:23], v[26:27], 1.0 op_sel_hi:[1,0]
	v_mul_f32_e32 v26, 0x3d372713, v16
	v_mul_f32_e32 v27, 0x3d372713, v17
	v_mul_f32_e32 v26, v16, v26
	v_mul_f32_e32 v27, v17, v27
	v_fma_f32 v26, v16, v26, v16
	v_fma_f32 v27, v17, v27, v17
	v_mul_f32_e32 v26, 0x3f4c422a, v26
	v_mul_f32_e32 v27, 0x3f4c422a, v27
	v_add_f32_e32 v26, v26, v26
	v_add_f32_e32 v27, v27, v27
	v_mul_f32_e32 v26, 0x3fb8aa3b, v26
	v_mul_f32_e32 v27, 0x3fb8aa3b, v27
	v_exp_f32_e32 v26, v26
	v_exp_f32_e32 v27, v27
	v_pk_mul_f32 v[20:21], v[20:21], v[22:23]
	v_mul_f32_e32 v24, 0x3f4c422a, v24
	v_add_f32_e32 v22, 1.0, v26
	v_add_f32_e32 v26, 1.0, v27
	v_mul_f32_e32 v27, 0x3d372713, v19
	v_mul_f32_e32 v25, 0x3f4c422a, v25
	v_mul_f32_e32 v23, 0x3d372713, v18
	v_mul_f32_e32 v27, v19, v27
	v_add_f32_e32 v24, v24, v24
	v_add_f32_e32 v25, v25, v25
	v_mul_f32_e32 v23, v18, v23
	v_fma_f32 v27, v19, v27, v19
	v_mul_f32_e32 v24, 0x3fb8aa3b, v24
	v_mul_f32_e32 v25, 0x3fb8aa3b, v25
	v_fma_f32 v23, v18, v23, v18
	v_mul_f32_e32 v27, 0x3f4c422a, v27
	v_exp_f32_e32 v24, v24
	v_exp_f32_e32 v25, v25
	v_mul_f32_e32 v23, 0x3f4c422a, v23
	v_add_f32_e32 v27, v27, v27
	v_add_f32_e32 v23, v23, v23
	v_mul_f32_e32 v27, 0x3fb8aa3b, v27
	v_mul_f32_e32 v23, 0x3fb8aa3b, v23
	v_exp_f32_e32 v27, v27
	v_exp_f32_e32 v23, v23
	v_add_f32_e32 v24, 1.0, v24
	v_add_f32_e32 v25, 1.0, v25
	v_rcp_f32_e32 v24, v24
	v_rcp_f32_e32 v25, v25
	v_add_f32_e32 v27, 1.0, v27
	v_add_f32_e32 v23, 1.0, v23
	v_rcp_f32_e32 v26, v26
	v_rcp_f32_e32 v27, v27
	v_rcp_f32_e32 v22, v22
	v_rcp_f32_e32 v23, v23
	v_pk_fma_f32 v[24:25], v[24:25], 2.0, 1.0 op_sel_hi:[1,0,0] neg_lo:[1,0,0] neg_hi:[1,0,0]
	v_pk_mul_f32 v[30:31], v[30:31], 0.5 op_sel_hi:[1,0]
	v_pk_add_f32 v[24:25], v[24:25], 1.0 op_sel_hi:[1,0]
	v_pk_fma_f32 v[26:27], v[26:27], 2.0, 1.0 op_sel_hi:[1,0,0] neg_lo:[1,0,0] neg_hi:[1,0,0]
	v_pk_mul_f32 v[24:25], v[30:31], v[24:25]
	v_mov_b32_e32 v31, v18
	v_mov_b32_e32 v18, v17
	v_pk_fma_f32 v[22:23], v[22:23], 2.0, 1.0 op_sel_hi:[1,0,0] neg_lo:[1,0,0] neg_hi:[1,0,0]
	v_mov_b32_e32 v30, v16
	v_pk_mul_f32 v[16:17], v[18:19], 0.5 op_sel_hi:[1,0]
	v_pk_add_f32 v[18:19], v[26:27], 1.0 op_sel_hi:[1,0]
	v_pk_mul_f32 v[30:31], v[30:31], 0.5 op_sel_hi:[1,0]
	v_pk_add_f32 v[22:23], v[22:23], 1.0 op_sel_hi:[1,0]
	v_pk_mul_f32 v[16:17], v[16:17], v[18:19]
	v_pk_mul_f32 v[22:23], v[30:31], v[22:23]
	v_cvt_pk_bf16_f32 v19, v23, v17
	v_cvt_pk_bf16_f32 v18, v22, v16
	v_cvt_pk_bf16_f32 v17, v25, v21
	v_cvt_pk_bf16_f32 v16, v24, v20
	v_lshl_add_u64 v[20:21], v[28:29], 0, v[112:113]
	v_lshl_add_u64 v[20:21], v[20:21], 0, s[20:21]
	v_lshl_add_u64 v[20:21], v[20:21], 0, v[168:169]
	global_store_dwordx4 v[20:21], v[16:19], off offset:1536
	v_mov_b32_e32 v21, v14
	v_mov_b32_e32 v20, v12
	v_mul_f32_e32 v17, 0x3d372713, v13
	v_mul_f32_e32 v19, 0x3d372713, v15
	v_mul_f32_e32 v17, v13, v17
	v_mul_f32_e32 v19, v15, v19
	v_fma_f32 v17, v13, v17, v13
	v_fma_f32 v19, v15, v19, v15
	v_mul_f32_e32 v17, 0x3f4c422a, v17
	v_mul_f32_e32 v19, 0x3f4c422a, v19
	v_add_f32_e32 v17, v17, v17
	v_add_f32_e32 v19, v19, v19
	v_mul_f32_e32 v17, 0x3fb8aa3b, v17
	v_mul_f32_e32 v19, 0x3fb8aa3b, v19
	v_exp_f32_e32 v17, v17
	v_exp_f32_e32 v19, v19
	v_mul_f32_e32 v16, 0x3d372713, v12
	v_mul_f32_e32 v16, v12, v16
	v_add_f32_e32 v18, 1.0, v17
	v_add_f32_e32 v19, 1.0, v19
	v_rcp_f32_e32 v18, v18
	v_rcp_f32_e32 v19, v19
	v_mul_f32_e32 v17, 0x3d372713, v14
	v_mul_f32_e32 v17, v14, v17
	v_fma_f32 v17, v14, v17, v14
	v_pk_fma_f32 v[18:19], v[18:19], 2.0, 1.0 op_sel_hi:[1,0,0] neg_lo:[1,0,0] neg_hi:[1,0,0]
	v_mov_b32_e32 v14, v13
	v_fma_f32 v16, v12, v16, v12
	v_pk_mul_f32 v[12:13], v[14:15], 0.5 op_sel_hi:[1,0]
	v_pk_add_f32 v[14:15], v[18:19], 1.0 op_sel_hi:[1,0]
	v_mul_f32_e32 v18, 0x3d372713, v8
	v_mul_f32_e32 v19, 0x3d372713, v9
	v_mul_f32_e32 v18, v8, v18
	v_mul_f32_e32 v19, v9, v19
	v_fma_f32 v18, v8, v18, v8
	v_fma_f32 v19, v9, v19, v9
	v_mul_f32_e32 v18, 0x3f4c422a, v18
	v_mul_f32_e32 v19, 0x3f4c422a, v19
	v_add_f32_e32 v18, v18, v18
	v_add_f32_e32 v19, v19, v19
	v_mul_f32_e32 v18, 0x3fb8aa3b, v18
	v_mul_f32_e32 v19, 0x3fb8aa3b, v19
	v_exp_f32_e32 v18, v18
	v_exp_f32_e32 v19, v19
	v_pk_mul_f32 v[12:13], v[12:13], v[14:15]
	v_mul_f32_e32 v16, 0x3f4c422a, v16
	v_add_f32_e32 v14, 1.0, v18
	v_add_f32_e32 v18, 1.0, v19
	v_mul_f32_e32 v19, 0x3d372713, v11
	v_mul_f32_e32 v17, 0x3f4c422a, v17
	v_mul_f32_e32 v15, 0x3d372713, v10
	v_mul_f32_e32 v19, v11, v19
	v_add_f32_e32 v16, v16, v16
	v_add_f32_e32 v17, v17, v17
	v_mul_f32_e32 v15, v10, v15
	v_fma_f32 v19, v11, v19, v11
	v_mul_f32_e32 v16, 0x3fb8aa3b, v16
	v_mul_f32_e32 v17, 0x3fb8aa3b, v17
	v_fma_f32 v15, v10, v15, v10
	v_mul_f32_e32 v19, 0x3f4c422a, v19
	v_exp_f32_e32 v16, v16
	v_exp_f32_e32 v17, v17
	v_mul_f32_e32 v15, 0x3f4c422a, v15
	v_add_f32_e32 v19, v19, v19
	v_add_f32_e32 v15, v15, v15
	v_mul_f32_e32 v19, 0x3fb8aa3b, v19
	v_mul_f32_e32 v15, 0x3fb8aa3b, v15
	v_exp_f32_e32 v19, v19
	v_exp_f32_e32 v15, v15
	v_add_f32_e32 v16, 1.0, v16
	v_add_f32_e32 v17, 1.0, v17
	v_rcp_f32_e32 v16, v16
	v_rcp_f32_e32 v17, v17
	v_add_f32_e32 v19, 1.0, v19
	v_add_f32_e32 v15, 1.0, v15
	v_rcp_f32_e32 v18, v18
	v_rcp_f32_e32 v19, v19
	v_rcp_f32_e32 v14, v14
	v_rcp_f32_e32 v15, v15
	v_pk_fma_f32 v[16:17], v[16:17], 2.0, 1.0 op_sel_hi:[1,0,0] neg_lo:[1,0,0] neg_hi:[1,0,0]
	v_pk_mul_f32 v[20:21], v[20:21], 0.5 op_sel_hi:[1,0]
	v_pk_add_f32 v[16:17], v[16:17], 1.0 op_sel_hi:[1,0]
	v_pk_fma_f32 v[18:19], v[18:19], 2.0, 1.0 op_sel_hi:[1,0,0] neg_lo:[1,0,0] neg_hi:[1,0,0]
	v_pk_mul_f32 v[16:17], v[20:21], v[16:17]
	v_mov_b32_e32 v21, v10
	v_mov_b32_e32 v10, v9
	v_pk_fma_f32 v[14:15], v[14:15], 2.0, 1.0 op_sel_hi:[1,0,0] neg_lo:[1,0,0] neg_hi:[1,0,0]
	v_mov_b32_e32 v20, v8
	v_pk_mul_f32 v[8:9], v[10:11], 0.5 op_sel_hi:[1,0]
	v_pk_add_f32 v[10:11], v[18:19], 1.0 op_sel_hi:[1,0]
	v_pk_mul_f32 v[20:21], v[20:21], 0.5 op_sel_hi:[1,0]
	v_pk_add_f32 v[14:15], v[14:15], 1.0 op_sel_hi:[1,0]
	v_pk_mul_f32 v[8:9], v[8:9], v[10:11]
	v_pk_mul_f32 v[14:15], v[20:21], v[14:15]
	s_mov_b64 s[2:3], 0x580000
	v_cvt_pk_bf16_f32 v11, v15, v9
	v_cvt_pk_bf16_f32 v10, v14, v8
	v_cvt_pk_bf16_f32 v9, v17, v13
	v_cvt_pk_bf16_f32 v8, v16, v12
	v_lshl_add_u64 v[12:13], v[120:121], 0, s[2:3]
	v_lshl_add_u64 v[14:15], v[12:13], 0, v[122:123]
	v_lshl_add_u64 v[14:15], v[14:15], 0, s[20:21]
	v_lshl_add_u64 v[14:15], v[14:15], 0, v[168:169]
	global_store_dwordx4 v[14:15], v[8:11], off offset:1536
	v_mov_b32_e32 v15, v6
	v_mov_b32_e32 v14, v4
	v_mul_f32_e32 v9, 0x3d372713, v5
	v_mul_f32_e32 v11, 0x3d372713, v7
	v_mul_f32_e32 v9, v5, v9
	v_mul_f32_e32 v11, v7, v11
	v_fma_f32 v9, v5, v9, v5
	v_fma_f32 v11, v7, v11, v7
	v_mul_f32_e32 v9, 0x3f4c422a, v9
	v_mul_f32_e32 v11, 0x3f4c422a, v11
	v_add_f32_e32 v9, v9, v9
	v_add_f32_e32 v11, v11, v11
	v_mul_f32_e32 v9, 0x3fb8aa3b, v9
	v_mul_f32_e32 v11, 0x3fb8aa3b, v11
	v_exp_f32_e32 v9, v9
	v_exp_f32_e32 v11, v11
	v_mul_f32_e32 v8, 0x3d372713, v4
	v_mul_f32_e32 v8, v4, v8
	v_add_f32_e32 v10, 1.0, v9
	v_add_f32_e32 v11, 1.0, v11
	v_rcp_f32_e32 v10, v10
	v_rcp_f32_e32 v11, v11
	v_mul_f32_e32 v9, 0x3d372713, v6
	v_mul_f32_e32 v9, v6, v9
	v_fma_f32 v9, v6, v9, v6
	v_pk_fma_f32 v[10:11], v[10:11], 2.0, 1.0 op_sel_hi:[1,0,0] neg_lo:[1,0,0] neg_hi:[1,0,0]
	v_mov_b32_e32 v6, v5
	v_fma_f32 v8, v4, v8, v4
	v_pk_mul_f32 v[4:5], v[6:7], 0.5 op_sel_hi:[1,0]
	v_pk_add_f32 v[6:7], v[10:11], 1.0 op_sel_hi:[1,0]
	v_mul_f32_e32 v10, 0x3d372713, v0
	v_mul_f32_e32 v11, 0x3d372713, v1
	v_mul_f32_e32 v10, v0, v10
	v_mul_f32_e32 v11, v1, v11
	v_fma_f32 v10, v0, v10, v0
	v_fma_f32 v11, v1, v11, v1
	v_mul_f32_e32 v10, 0x3f4c422a, v10
	v_mul_f32_e32 v11, 0x3f4c422a, v11
	v_add_f32_e32 v10, v10, v10
	v_add_f32_e32 v11, v11, v11
	v_mul_f32_e32 v10, 0x3fb8aa3b, v10
	v_mul_f32_e32 v11, 0x3fb8aa3b, v11
	v_exp_f32_e32 v10, v10
	v_exp_f32_e32 v11, v11
	v_pk_mul_f32 v[4:5], v[4:5], v[6:7]
	v_mul_f32_e32 v8, 0x3f4c422a, v8
	v_add_f32_e32 v6, 1.0, v10
	v_add_f32_e32 v10, 1.0, v11
	v_mul_f32_e32 v11, 0x3d372713, v3
	v_mul_f32_e32 v9, 0x3f4c422a, v9
	v_mul_f32_e32 v7, 0x3d372713, v2
	v_mul_f32_e32 v11, v3, v11
	v_add_f32_e32 v8, v8, v8
	v_add_f32_e32 v9, v9, v9
	v_mul_f32_e32 v7, v2, v7
	v_fma_f32 v11, v3, v11, v3
	v_mul_f32_e32 v8, 0x3fb8aa3b, v8
	v_mul_f32_e32 v9, 0x3fb8aa3b, v9
	v_fma_f32 v7, v2, v7, v2
	v_mul_f32_e32 v11, 0x3f4c422a, v11
	v_exp_f32_e32 v8, v8
	v_exp_f32_e32 v9, v9
	v_mul_f32_e32 v7, 0x3f4c422a, v7
	v_add_f32_e32 v11, v11, v11
	v_add_f32_e32 v7, v7, v7
	v_mul_f32_e32 v11, 0x3fb8aa3b, v11
	v_mul_f32_e32 v7, 0x3fb8aa3b, v7
	v_exp_f32_e32 v11, v11
	v_exp_f32_e32 v7, v7
	v_add_f32_e32 v8, 1.0, v8
	v_add_f32_e32 v9, 1.0, v9
	v_rcp_f32_e32 v8, v8
	v_rcp_f32_e32 v9, v9
	v_add_f32_e32 v11, 1.0, v11
	v_add_f32_e32 v7, 1.0, v7
	v_rcp_f32_e32 v10, v10
	v_rcp_f32_e32 v11, v11
	v_rcp_f32_e32 v6, v6
	v_rcp_f32_e32 v7, v7
	v_pk_fma_f32 v[8:9], v[8:9], 2.0, 1.0 op_sel_hi:[1,0,0] neg_lo:[1,0,0] neg_hi:[1,0,0]
	v_pk_mul_f32 v[14:15], v[14:15], 0.5 op_sel_hi:[1,0]
	v_pk_add_f32 v[8:9], v[8:9], 1.0 op_sel_hi:[1,0]
	v_pk_fma_f32 v[10:11], v[10:11], 2.0, 1.0 op_sel_hi:[1,0,0] neg_lo:[1,0,0] neg_hi:[1,0,0]
	v_pk_mul_f32 v[8:9], v[14:15], v[8:9]
	v_mov_b32_e32 v15, v2
	v_mov_b32_e32 v2, v1
	v_pk_fma_f32 v[6:7], v[6:7], 2.0, 1.0 op_sel_hi:[1,0,0] neg_lo:[1,0,0] neg_hi:[1,0,0]
	v_mov_b32_e32 v14, v0
	v_pk_mul_f32 v[0:1], v[2:3], 0.5 op_sel_hi:[1,0]
	v_pk_add_f32 v[2:3], v[10:11], 1.0 op_sel_hi:[1,0]
	v_pk_mul_f32 v[14:15], v[14:15], 0.5 op_sel_hi:[1,0]
	v_pk_add_f32 v[6:7], v[6:7], 1.0 op_sel_hi:[1,0]
	v_pk_mul_f32 v[0:1], v[0:1], v[2:3]
	v_pk_mul_f32 v[6:7], v[14:15], v[6:7]
	v_cvt_pk_bf16_f32 v3, v7, v1
	v_cvt_pk_bf16_f32 v2, v6, v0
	v_cvt_pk_bf16_f32 v1, v9, v5
	v_cvt_pk_bf16_f32 v0, v8, v4
	v_lshl_add_u64 v[4:5], v[12:13], 0, v[112:113]
	v_lshl_add_u64 v[4:5], v[4:5], 0, s[20:21]
	v_lshl_add_u64 v[4:5], v[4:5], 0, v[168:169]
	global_store_dwordx4 v[4:5], v[0:3], off offset:1536
	s_andn2_b64 vcc, exec, s[38:39]
	s_mov_b64 s[2:3], -1
	s_cbranch_vccnz .LBB0_565
	s_andn2_b64 vcc, exec, s[0:1]
	s_cbranch_vccnz .LBB0_564
	s_barrier
	s_branch .LBB0_564

.LBB0_594:
	s_add_i32 s22, s67, 15
	s_and_b64 s[70:71], s[2:3], exec
	s_cselect_b32 s22, s66, s22
	v_pk_mul_f32 v[14:15], v[4:5], v[10:11]
	v_pk_mul_f32 v[16:17], v[8:9], v[10:11]
	s_add_i32 s22, s22, s68
	s_add_i32 s24, s67, 14
	s_add_i32 s26, s66, 1
	s_lshl_b32 s34, s22, 9
	v_cvt_pk_bf16_f32 v22, v10, v11
	v_lshl_add_u64 v[10:11], v[6:7], 0, s[34:35]
	s_and_b64 s[70:71], s[2:3], exec
	global_load_dword v30, v[10:11], off
	s_cselect_b32 s22, s26, s24
	s_add_i32 s22, s22, s68
	s_add_i32 s24, s67, 13
	s_add_i32 s26, s66, 2
	s_lshl_b32 s60, s22, 9
	s_mov_b32 s61, s35
	s_and_b64 s[70:71], s[2:3], exec
	v_lshl_add_u64 v[10:11], v[6:7], 0, s[60:61]
	s_cselect_b32 s22, s26, s24
	global_load_dword v35, v[10:11], off
	s_add_i32 s22, s22, s68
	s_mov_b32 s59, s35
	s_add_i32 s24, s67, 12
	s_add_i32 s26, s66, 3
	s_lshl_b32 s58, s22, 9
	v_lshl_add_u64 v[10:11], v[6:7], 0, s[58:59]
	s_and_b64 s[70:71], s[2:3], exec
	global_load_dword v36, v[10:11], off
	s_cselect_b32 s22, s26, s24
	s_add_i32 s22, s22, s68
	s_add_i32 s24, s67, 11
	s_add_i32 s26, s66, 4
	s_lshl_b32 s56, s22, 9
	s_mov_b32 s57, s35
	s_and_b64 s[70:71], s[2:3], exec
	v_lshl_add_u64 v[10:11], v[6:7], 0, s[56:57]
	s_cselect_b32 s22, s26, s24
	global_load_dword v37, v[10:11], off
	s_add_i32 s22, s22, s68
	s_mov_b32 s55, s35
	s_add_i32 s24, s67, 10
	s_add_i32 s26, s66, 5
	s_lshl_b32 s54, s22, 9
	v_lshl_add_u64 v[10:11], v[6:7], 0, s[54:55]
	s_and_b64 s[70:71], s[2:3], exec
	global_load_dword v38, v[10:11], off
	s_cselect_b32 s22, s26, s24
	s_add_i32 s22, s22, s68
	s_add_i32 s24, s67, 9
	s_add_i32 s26, s66, 6
	s_lshl_b32 s52, s22, 9
	s_mov_b32 s53, s35
	s_and_b64 s[70:71], s[2:3], exec
	v_lshl_add_u64 v[10:11], v[6:7], 0, s[52:53]
	s_cselect_b32 s22, s26, s24
	global_load_dword v39, v[10:11], off
	s_add_i32 s22, s22, s68
	s_mov_b32 s51, s35
	s_lshl_b32 s50, s22, 9
	s_add_i32 s24, s67, 8
	s_add_i32 s26, s66, 7
	v_lshl_add_u64 v[10:11], v[6:7], 0, s[50:51]
	s_and_b64 s[70:71], s[2:3], exec
	global_load_dword v40, v[10:11], off
	s_cselect_b32 s22, s26, s24
	s_add_i32 s22, s22, s68
	s_mov_b32 s49, s35
	s_add_i32 s24, s67, 7
	s_add_i32 s26, s66, 8
	s_lshl_b32 s48, s22, 9
	v_lshl_add_u64 v[10:11], v[6:7], 0, s[48:49]
	s_and_b64 s[70:71], s[2:3], exec
	global_load_dword v19, v[10:11], off
	s_cselect_b32 s22, s26, s24
	s_add_i32 s22, s22, s68
	s_mov_b32 s47, s35
	s_add_i32 s24, s67, 6
	s_add_i32 s26, s66, 9
	s_lshl_b32 s46, s22, 9
	v_lshl_add_u64 v[10:11], v[6:7], 0, s[46:47]
	s_and_b64 s[70:71], s[2:3], exec
	global_load_dword v18, v[10:11], off
	s_cselect_b32 s22, s26, s24
	s_add_i32 s22, s22, s68
	s_add_i32 s24, s67, 5
	s_add_i32 s26, s66, 10
	s_lshl_b32 s44, s22, 9
	s_mov_b32 s45, s35
	s_and_b64 s[70:71], s[2:3], exec
	v_lshl_add_u64 v[10:11], v[6:7], 0, s[44:45]
	s_cselect_b32 s22, s26, s24
	v_add_f32_e32 v29, v16, v17
	global_load_dword v17, v[10:11], off
	s_add_i32 s22, s22, s68
	s_mov_b32 s43, s35
	s_add_i32 s24, s67, 4
	s_add_i32 s26, s66, 11
	s_lshl_b32 s42, s22, 9
	v_lshl_add_u64 v[10:11], v[6:7], 0, s[42:43]
	s_and_b64 s[70:71], s[2:3], exec
	global_load_dword v16, v[10:11], off
	s_cselect_b32 s22, s26, s24
	s_add_i32 s22, s22, s68
	s_add_i32 s24, s67, 3
	s_add_i32 s26, s66, 12
	s_lshl_b32 s40, s22, 9
	s_mov_b32 s41, s35
	s_and_b64 s[70:71], s[2:3], exec
	v_lshl_add_u64 v[10:11], v[6:7], 0, s[40:41]
	s_cselect_b32 s22, s26, s24
	v_sub_f32_e32 v28, v14, v15
	global_load_dword v15, v[10:11], off
	s_add_i32 s22, s22, s68
	s_add_i32 s24, s67, 2
	s_add_i32 s26, s66, 13
	s_lshl_b32 s38, s22, 9
	s_mov_b32 s39, s35
	s_and_b64 s[70:71], s[2:3], exec
	v_lshl_add_u64 v[10:11], v[6:7], 0, s[38:39]
	s_cselect_b32 s22, s26, s24
	global_load_dword v14, v[10:11], off
	s_add_i32 s22, s22, s68
	s_add_i32 s24, s67, 1
	s_add_i32 s69, s66, 14
	s_lshl_b32 s26, s22, 9
	s_and_b64 s[70:71], s[2:3], exec
	s_mov_b32 s27, s35
	s_cselect_b32 s22, s69, s24
	v_lshl_add_u64 v[10:11], v[6:7], 0, s[26:27]
	s_add_i32 s22, s22, s68
	global_load_dword v13, v[10:11], off
	s_add_i32 s69, s66, 15
	s_lshl_b32 s24, s22, 9
	s_and_b64 s[70:71], s[2:3], exec
	s_mov_b32 s25, s35
	s_cselect_b32 s22, s69, s67
	v_lshl_add_u64 v[10:11], v[6:7], 0, s[24:25]
	s_add_i32 s22, s22, s68
	global_load_dword v11, v[10:11], off
	s_lshl_b64 s[70:71], s[34:35], 1
	s_lshl_b32 s22, s22, 9
	s_add_u32 s34, s63, s70
	s_mov_b32 s23, s35
	s_addc_u32 s69, s64, s71
	v_lshl_add_u64 v[20:21], v[6:7], 0, s[22:23]
	s_add_u32 s70, s34, s20
	global_load_dword v10, v[20:21], off
	s_addc_u32 s71, s69, s21
	s_lshl_b64 s[60:61], s[60:61], 1
	s_add_u32 s34, s63, s60
	s_addc_u32 s61, s64, s61
	s_add_u32 s60, s34, s20
	s_addc_u32 s61, s61, s21
	s_lshl_b64 s[58:59], s[58:59], 1
	s_add_u32 s34, s63, s58
	s_addc_u32 s59, s64, s59
	s_add_u32 s58, s34, s20
	s_addc_u32 s59, s59, s21
	s_lshl_b64 s[56:57], s[56:57], 1
	s_add_u32 s34, s63, s56
	s_addc_u32 s57, s64, s57
	v_lshl_add_u64 v[20:21], s[70:71], 0, v[2:3]
	s_add_u32 s56, s34, s20
	v_add_co_u32_e32 v20, vcc, s72, v20
	s_addc_u32 s57, s57, s21
	s_lshl_b64 s[54:55], s[54:55], 1
	v_addc_co_u32_e32 v21, vcc, 0, v21, vcc
	s_add_u32 s34, s63, s54
	global_store_dword v[20:21], v22, off offset:512
	v_lshl_add_u64 v[20:21], s[60:61], 0, v[2:3]
	s_addc_u32 s55, s64, s55
	v_add_co_u32_e32 v20, vcc, s72, v20
	s_add_u32 s54, s34, s20
	s_nop 0
	v_addc_co_u32_e32 v21, vcc, 0, v21, vcc
	v_lshl_add_u64 v[22:23], s[58:59], 0, v[2:3]
	s_addc_u32 s55, s55, s21
	s_lshl_b64 s[52:53], s[52:53], 1
	v_add_co_u32_e32 v22, vcc, s72, v22
	s_add_u32 s34, s63, s52
	s_waitcnt vmcnt(16)
	v_lshlrev_b32_e32 v31, 16, v30
	v_and_b32_e32 v30, 0xffff0000, v30
	v_addc_co_u32_e32 v23, vcc, 0, v23, vcc
	v_lshl_add_u64 v[24:25], s[56:57], 0, v[2:3]
	s_addc_u32 s53, s64, s53
	v_add_f32_e32 v30, v29, v30
	v_add_co_u32_e32 v24, vcc, s72, v24
	v_add_f32_e32 v28, v28, v31
	s_add_u32 s52, s34, s20
	v_bfe_u32 v31, v30, 16, 1
	v_addc_co_u32_e32 v25, vcc, 0, v25, vcc
	v_lshl_add_u64 v[26:27], s[54:55], 0, v[2:3]
	v_bfe_u32 v29, v28, 16, 1
	v_pk_mul_f32 v[32:33], v[8:9], v[30:31] op_sel_hi:[1,0]
	s_addc_u32 s53, s53, s21
	s_lshl_b64 s[50:51], s[50:51], 1
	v_add_co_u32_e32 v26, vcc, s72, v26
	v_add3_u32 v41, v28, v29, s96
	v_add3_u32 v42, v30, v31, s96
	v_pk_fma_f32 v[30:31], v[4:5], v[28:29], v[32:33] neg_lo:[0,0,1] neg_hi:[0,0,1]
	v_pk_fma_f32 v[28:29], v[4:5], v[28:29], v[32:33] op_sel_hi:[1,0,1]
	s_add_u32 s34, s63, s50
	v_addc_co_u32_e32 v27, vcc, 0, v27, vcc
	v_lshl_add_u64 v[32:33], s[52:53], 0, v[2:3]
	s_waitcnt vmcnt(15)
	v_lshlrev_b32_e32 v34, 16, v35
	v_and_b32_e32 v35, 0xffff0000, v35
	v_lshrrev_b32_e32 v41, 16, v41
	v_mov_b32_e32 v31, v29
	s_addc_u32 s51, s64, s51
	v_add_co_u32_e32 v28, vcc, s72, v32
	v_and_or_b32 v32, v42, s97, v41
	v_pk_add_f32 v[30:31], v[30:31], v[34:35]
	s_add_u32 s50, s34, s20
	v_addc_co_u32_e32 v29, vcc, 0, v33, vcc
	global_store_dword v[20:21], v32, off offset:512
	v_pk_mul_f32 v[32:33], v[4:5], v[30:31] op_sel:[0,1] op_sel_hi:[1,0]
	s_addc_u32 s51, s51, s21
	s_lshl_b64 s[48:49], s[48:49], 1
	v_pk_mul_f32 v[20:21], v[4:5], v[30:31]
	v_add_f32_e32 v32, v32, v33
	s_add_u32 s34, s63, s48
	s_waitcnt vmcnt(15)
	v_and_b32_e32 v35, 0xffff0000, v36
	v_sub_f32_e32 v34, v20, v21
	v_lshlrev_b32_e32 v33, 16, v36
	s_addc_u32 s49, s64, s49
	v_add_f32_e32 v32, v32, v35
	v_lshl_add_u64 v[20:21], s[50:51], 0, v[2:3]
	v_cvt_pk_bf16_f32 v31, v30, v31
	v_add_f32_e32 v30, v34, v33
	s_add_u32 s48, s34, s20
	v_bfe_u32 v33, v32, 16, 1
	v_add_co_u32_e32 v20, vcc, s72, v20
	global_store_dword v[22:23], v31, off offset:512
	v_bfe_u32 v31, v30, 16, 1
	v_pk_mul_f32 v[22:23], v[8:9], v[32:33] op_sel_hi:[1,0]
	s_addc_u32 s49, s49, s21
	s_lshl_b64 s[46:47], s[46:47], 1
	v_addc_co_u32_e32 v21, vcc, 0, v21, vcc
	v_add3_u32 v36, v30, v31, s96
	v_add3_u32 v41, v32, v33, s96
	v_pk_fma_f32 v[32:33], v[4:5], v[30:31], v[22:23] neg_lo:[0,0,1] neg_hi:[0,0,1]
	v_pk_fma_f32 v[22:23], v[4:5], v[30:31], v[22:23] op_sel_hi:[1,0,1]
	v_lshl_add_u64 v[30:31], s[48:49], 0, v[2:3]
	s_add_u32 s34, s63, s46
	s_waitcnt vmcnt(15)
	v_lshlrev_b32_e32 v34, 16, v37
	v_and_b32_e32 v35, 0xffff0000, v37
	v_mov_b32_e32 v33, v23
	v_add_co_u32_e32 v22, vcc, s72, v30
	s_addc_u32 s47, s64, s47
	v_lshrrev_b32_e32 v36, 16, v36
	v_addc_co_u32_e32 v23, vcc, 0, v31, vcc
	v_pk_add_f32 v[30:31], v[32:33], v[34:35]
	s_add_u32 s46, s34, s20
	v_and_or_b32 v36, v41, s97, v36
	v_pk_mul_f32 v[32:33], v[4:5], v[30:31] op_sel:[0,1] op_sel_hi:[1,0]
	s_addc_u32 s47, s47, s21
	s_lshl_b64 s[44:45], s[44:45], 1
	global_store_dword v[24:25], v36, off offset:512
	v_pk_mul_f32 v[24:25], v[4:5], v[30:31]
	v_add_f32_e32 v32, v32, v33
	s_add_u32 s34, s63, s44
	s_waitcnt vmcnt(15)
	v_and_b32_e32 v35, 0xffff0000, v38
	v_sub_f32_e32 v34, v24, v25
	v_lshlrev_b32_e32 v33, 16, v38
	s_addc_u32 s45, s64, s45
	v_add_f32_e32 v32, v32, v35
	v_lshl_add_u64 v[24:25], s[46:47], 0, v[2:3]
	v_cvt_pk_bf16_f32 v31, v30, v31
	v_add_f32_e32 v30, v34, v33
	s_add_u32 s44, s34, s20
	v_bfe_u32 v33, v32, 16, 1
	v_add_co_u32_e32 v24, vcc, s72, v24
	global_store_dword v[26:27], v31, off offset:512
	v_bfe_u32 v31, v30, 16, 1
	v_pk_mul_f32 v[26:27], v[8:9], v[32:33] op_sel_hi:[1,0]
	s_addc_u32 s45, s45, s21
	s_lshl_b64 s[42:43], s[42:43], 1
	v_addc_co_u32_e32 v25, vcc, 0, v25, vcc
	v_add3_u32 v36, v30, v31, s96
	v_add3_u32 v37, v32, v33, s96
	v_pk_fma_f32 v[32:33], v[4:5], v[30:31], v[26:27] neg_lo:[0,0,1] neg_hi:[0,0,1]
	v_pk_fma_f32 v[26:27], v[4:5], v[30:31], v[26:27] op_sel_hi:[1,0,1]
	v_lshl_add_u64 v[30:31], s[44:45], 0, v[2:3]
	s_add_u32 s34, s63, s42
	s_waitcnt vmcnt(15)
	v_lshlrev_b32_e32 v34, 16, v39
	v_and_b32_e32 v35, 0xffff0000, v39
	v_mov_b32_e32 v33, v27
	v_add_co_u32_e32 v26, vcc, s72, v30
	s_addc_u32 s43, s64, s43
	v_lshrrev_b32_e32 v36, 16, v36
	v_addc_co_u32_e32 v27, vcc, 0, v31, vcc
	v_pk_add_f32 v[30:31], v[32:33], v[34:35]
	s_add_u32 s42, s34, s20
	v_and_or_b32 v36, v37, s97, v36
	v_pk_mul_f32 v[32:33], v[4:5], v[30:31] op_sel:[0,1] op_sel_hi:[1,0]
	s_addc_u32 s43, s43, s21
	s_lshl_b64 s[40:41], s[40:41], 1
	global_store_dword v[28:29], v36, off offset:512
	v_pk_mul_f32 v[28:29], v[4:5], v[30:31]
	v_add_f32_e32 v32, v32, v33
	s_add_u32 s34, s63, s40
	s_waitcnt vmcnt(15)
	v_and_b32_e32 v35, 0xffff0000, v40
	v_sub_f32_e32 v34, v28, v29
	v_lshlrev_b32_e32 v33, 16, v40
	s_addc_u32 s41, s64, s41
	v_add_f32_e32 v32, v32, v35
	v_lshl_add_u64 v[28:29], s[42:43], 0, v[2:3]
	v_cvt_pk_bf16_f32 v31, v30, v31
	v_add_f32_e32 v30, v34, v33
	s_add_u32 s40, s34, s20
	v_bfe_u32 v33, v32, 16, 1
	v_add_co_u32_e32 v28, vcc, s72, v28
	global_store_dword v[20:21], v31, off offset:512
	v_bfe_u32 v31, v30, 16, 1
	v_pk_mul_f32 v[20:21], v[8:9], v[32:33] op_sel_hi:[1,0]
	s_addc_u32 s41, s41, s21
	s_lshl_b64 s[38:39], s[38:39], 1
	v_addc_co_u32_e32 v29, vcc, 0, v29, vcc
	v_add3_u32 v36, v30, v31, s96
	v_add3_u32 v37, v32, v33, s96
	v_pk_fma_f32 v[32:33], v[4:5], v[30:31], v[20:21] neg_lo:[0,0,1] neg_hi:[0,0,1]
	v_pk_fma_f32 v[20:21], v[4:5], v[30:31], v[20:21] op_sel_hi:[1,0,1]
	v_lshl_add_u64 v[30:31], s[40:41], 0, v[2:3]
	s_add_u32 s34, s63, s38
	s_waitcnt vmcnt(15)
	v_lshlrev_b32_e32 v34, 16, v19
	v_and_b32_e32 v35, 0xffff0000, v19
	v_lshrrev_b32_e32 v19, 16, v36
	v_mov_b32_e32 v33, v21
	v_add_co_u32_e32 v20, vcc, s72, v30
	s_addc_u32 s39, s64, s39
	s_nop 0
	v_addc_co_u32_e32 v21, vcc, 0, v31, vcc
	v_and_or_b32 v19, v37, s97, v19
	v_pk_add_f32 v[30:31], v[32:33], v[34:35]
	s_add_u32 s38, s34, s20
	global_store_dword v[22:23], v19, off offset:512
	v_bfe_u32 v19, v30, 16, 1
	v_bfe_u32 v34, v31, 16, 1
	v_pk_mul_f32 v[22:23], v[4:5], v[30:31]
	s_addc_u32 s39, s39, s21
	v_pk_mul_f32 v[32:33], v[4:5], v[30:31] op_sel:[0,1] op_sel_hi:[1,0]
	s_lshl_b64 s[26:27], s[26:27], 1
	v_add3_u32 v19, v30, v19, s96
	v_add3_u32 v30, v31, v34, s96
	v_sub_f32_e32 v31, v22, v23
	v_lshl_add_u64 v[22:23], s[38:39], 0, v[2:3]
	v_add_f32_e32 v32, v32, v33
	s_add_u32 s26, s63, s26
	s_waitcnt vmcnt(15)
	v_lshlrev_b32_e32 v33, 16, v18
	v_and_b32_e32 v34, 0xffff0000, v18
	v_lshrrev_b32_e32 v35, 16, v19
	v_add_co_u32_e32 v18, vcc, s72, v22
	s_addc_u32 s27, s64, s27
	s_nop 0
	v_addc_co_u32_e32 v19, vcc, 0, v23, vcc
	v_and_or_b32 v23, v30, s97, v35
	v_add_f32_e32 v30, v32, v34
	v_add_f32_e32 v22, v31, v33
	s_add_u32 s26, s26, s20
	v_bfe_u32 v31, v30, 16, 1
	global_store_dword v[24:25], v23, off offset:512
	v_bfe_u32 v23, v22, 16, 1
	v_pk_mul_f32 v[24:25], v[8:9], v[30:31] op_sel_hi:[1,0]
	s_addc_u32 s27, s27, s21
	s_lshl_b64 s[24:25], s[24:25], 1
	v_add3_u32 v34, v22, v23, s96
	v_add3_u32 v35, v30, v31, s96
	v_pk_fma_f32 v[30:31], v[4:5], v[22:23], v[24:25] neg_lo:[0,0,1] neg_hi:[0,0,1]
	v_pk_fma_f32 v[22:23], v[4:5], v[22:23], v[24:25] op_sel_hi:[1,0,1]
	v_lshl_add_u64 v[24:25], s[26:27], 0, v[2:3]
	s_add_u32 s24, s63, s24
	s_waitcnt vmcnt(15)
	v_lshlrev_b32_e32 v32, 16, v17
	v_and_b32_e32 v33, 0xffff0000, v17
	v_lshrrev_b32_e32 v17, 16, v34
	v_mov_b32_e32 v31, v23
	v_add_co_u32_e32 v22, vcc, s72, v24
	s_addc_u32 s25, s64, s25
	s_nop 0
	v_addc_co_u32_e32 v23, vcc, 0, v25, vcc
	v_and_or_b32 v17, v35, s97, v17
	v_pk_add_f32 v[24:25], v[30:31], v[32:33]
	s_add_u32 s24, s24, s20
	global_store_dword v[26:27], v17, off offset:512
	v_bfe_u32 v17, v24, 16, 1
	v_bfe_u32 v32, v25, 16, 1
	v_pk_mul_f32 v[26:27], v[4:5], v[24:25]
	v_pk_mul_f32 v[30:31], v[4:5], v[24:25] op_sel:[0,1] op_sel_hi:[1,0]
	s_addc_u32 s25, s25, s21
	v_add3_u32 v17, v24, v17, s96
	v_add3_u32 v32, v25, v32, s96
	v_sub_f32_e32 v26, v26, v27
	v_add_f32_e32 v27, v30, v31
	v_lshl_add_u64 v[24:25], s[24:25], 0, v[2:3]
	s_waitcnt vmcnt(15)
	v_lshlrev_b32_e32 v30, 16, v16
	v_and_b32_e32 v31, 0xffff0000, v16
	s_lshl_b64 s[22:23], s[22:23], 1
	v_lshrrev_b32_e32 v33, 16, v17
	v_add_co_u32_e32 v16, vcc, s72, v24
	v_add_f32_e32 v24, v26, v30
	v_add_f32_e32 v26, v27, v31
	s_add_u32 s22, s63, s22
	v_addc_co_u32_e32 v17, vcc, 0, v25, vcc
	v_and_or_b32 v25, v32, s97, v33
	v_bfe_u32 v27, v26, 16, 1
	s_addc_u32 s23, s64, s23
	global_store_dword v[28:29], v25, off offset:512
	v_bfe_u32 v25, v24, 16, 1
	v_pk_mul_f32 v[28:29], v[8:9], v[26:27] op_sel_hi:[1,0]
	s_add_u32 s22, s22, s20
	v_add3_u32 v32, v24, v25, s96
	v_add3_u32 v33, v26, v27, s96
	v_pk_fma_f32 v[26:27], v[4:5], v[24:25], v[28:29] neg_lo:[0,0,1] neg_hi:[0,0,1]
	v_pk_fma_f32 v[24:25], v[4:5], v[24:25], v[28:29] op_sel_hi:[1,0,1]
	s_addc_u32 s23, s23, s21
	s_waitcnt vmcnt(15)
	v_lshlrev_b32_e32 v30, 16, v15
	v_and_b32_e32 v31, 0xffff0000, v15
	v_lshrrev_b32_e32 v15, 16, v32
	v_mov_b32_e32 v27, v25
	v_lshl_add_u64 v[28:29], s[22:23], 0, v[2:3]
	v_and_or_b32 v15, v33, s97, v15
	v_pk_add_f32 v[26:27], v[26:27], v[30:31]
	v_add_co_u32_e32 v24, vcc, s72, v28
	global_store_dword v[20:21], v15, off offset:512
	v_cvt_pk_bf16_f32 v15, v26, v27
	v_addc_co_u32_e32 v25, vcc, 0, v29, vcc
	v_pk_mul_f32 v[20:21], v[4:5], v[26:27]
	v_pk_mul_f32 v[28:29], v[4:5], v[26:27] op_sel:[0,1] op_sel_hi:[1,0]
	v_sub_f32_e32 v20, v20, v21
	v_add_f32_e32 v21, v28, v29
	s_waitcnt vmcnt(15)
	v_lshlrev_b32_e32 v27, 16, v14
	v_and_b32_e32 v28, 0xffff0000, v14
	v_add_f32_e32 v14, v20, v27
	v_add_f32_e32 v20, v21, v28
	v_bfe_u32 v21, v20, 16, 1
	global_store_dword v[18:19], v15, off offset:512
	v_bfe_u32 v15, v14, 16, 1
	v_pk_mul_f32 v[18:19], v[8:9], v[20:21] op_sel_hi:[1,0]
	v_add3_u32 v26, v14, v15, s96
	v_add3_u32 v27, v20, v21, s96
	v_pk_fma_f32 v[20:21], v[4:5], v[14:15], v[18:19] neg_lo:[0,0,1] neg_hi:[0,0,1]
	v_pk_fma_f32 v[14:15], v[4:5], v[14:15], v[18:19] op_sel_hi:[1,0,1]
	s_waitcnt vmcnt(15)
	v_lshlrev_b32_e32 v18, 16, v13
	v_and_b32_e32 v19, 0xffff0000, v13
	v_lshrrev_b32_e32 v13, 16, v26
	v_mov_b32_e32 v21, v15
	v_and_or_b32 v13, v27, s97, v13
	v_pk_add_f32 v[14:15], v[20:21], v[18:19]
	global_store_dword v[22:23], v13, off offset:512
	v_cvt_pk_bf16_f32 v13, v14, v15
	v_pk_mul_f32 v[18:19], v[4:5], v[14:15]
	v_pk_mul_f32 v[20:21], v[4:5], v[14:15] op_sel:[0,1] op_sel_hi:[1,0]
	v_sub_f32_e32 v15, v18, v19
	v_add_f32_e32 v18, v20, v21
	s_waitcnt vmcnt(15)
	v_lshlrev_b32_e32 v19, 16, v11
	v_and_b32_e32 v11, 0xffff0000, v11
	v_add_f32_e32 v14, v15, v19
	v_add_f32_e32 v18, v18, v11
	global_store_dword v[16:17], v13, off offset:512
	v_cvt_pk_bf16_f32 v13, v14, v18
	v_pk_mul_f32 v[16:17], v[8:9], v[18:19] op_sel_hi:[1,0]
	s_nop 0
	v_pk_fma_f32 v[18:19], v[4:5], v[14:15], v[16:17] neg_lo:[0,0,1] neg_hi:[0,0,1]
	v_pk_fma_f32 v[14:15], v[4:5], v[14:15], v[16:17] op_sel_hi:[1,0,1]
	s_add_i32 s67, s67, -16
	s_add_i32 s24, s66, 16
	s_waitcnt vmcnt(15)
	v_lshlrev_b32_e32 v16, 16, v10
	v_and_b32_e32 v17, 0xffff0000, v10
	v_mov_b32_e32 v19, v15
	s_cmpk_lt_u32 s66, 0x1f0
	s_mov_b32 s66, s24
	v_pk_add_f32 v[10:11], v[18:19], v[16:17]
	global_store_dword v[24:25], v13, off offset:512
	s_cbranch_scc1 .LBB0_594
	v_readlane_b32 s2, v254, 19
	s_add_i32 s62, s62, s2
	v_readlane_b32 s78, v254, 17
	s_cmpk_gt_i32 s62, 0xff
	v_readlane_b32 s79, v254, 18
	v_readlane_b32 s3, v254, 20
	s_cbranch_scc0 .LBB0_593
	v_readlane_b32 s68, v254, 16

.LBB0_604:
	s_or_b64 exec, exec, s[26:27]
	s_mov_b64 s[0:1], 0
	s_add_u32 s0, s6, s0
	s_addc_u32 s1, s7, s1
	v_mov_b32_e32 v85, v160
	s_mov_b32 s0, 0x3fb8aa3b
	v_and_b32_e32 v87, 64, v224
	v_add_u32_e32 v93, -1, v224
	v_add_u32_e32 v95, -2, v224
	v_add_u32_e32 v97, -4, v224
	v_add_u32_e32 v104, -8, v224
	v_add_u32_e32 v106, -16, v224
	v_subrev_u32_e32 v107, 32, v224
	s_cmp_eq_u32 s25, 0
	v_add_u32_e32 v81, 0x4400, v75
	v_add_u32_e32 v110, 0x2100, v77
	v_add_u32_e32 v111, 0x2108, v77
	v_lshlrev_b32_e32 v99, 16, v61
	v_lshlrev_b32_e32 v98, 16, v60
	v_and_b32_e32 v61, 0xffff0000, v61
	v_and_b32_e32 v60, 0xffff0000, v60
	v_lshlrev_b32_e32 v101, 16, v63
	v_lshlrev_b32_e32 v100, 16, v62
	v_and_b32_e32 v63, 0xffff0000, v63
	v_and_b32_e32 v62, 0xffff0000, v62
	v_lshlrev_b32_e32 v109, 16, v45
	v_lshlrev_b32_e32 v108, 16, v44
	v_and_b32_e32 v45, 0xffff0000, v45
	v_and_b32_e32 v44, 0xffff0000, v44
	s_waitcnt vmcnt(0)
	v_mul_f32_e32 v102, 0x3fb8aa3b, v85
	v_fma_f32 v103, v85, s0, -v102
	v_rndne_f32_e32 v105, v102
	v_fmac_f32_e32 v103, 0x32a5705f, v85
	v_sub_f32_e32 v102, v102, v105
	v_add_f32_e32 v102, v102, v103
	v_cvt_i32_f32_e32 v105, v105
	v_exp_f32_e32 v102, v102
	v_cmp_lt_i32_e64 s[0:1], v93, v87
	v_lshlrev_b32_e32 v103, 16, v57
	v_ldexp_f32 v102, v102, v105
	v_cndmask_b32_e64 v93, v93, v224, s[0:1]
	v_cmp_ngt_f32_e64 s[0:1], s37, v85
	v_lshlrev_b32_e32 v93, 2, v93
	v_and_b32_e32 v105, 0xffff0000, v57
	v_cndmask_b32_e64 v102, 0, v102, s[0:1]
	v_cmp_nlt_f32_e64 s[0:1], s30, v85
	s_nop 1
	v_cndmask_b32_e64 v85, v231, v102, s[0:1]
	v_mul_f32_e64 v102, v83, -v85
	ds_bpermute_b32 v93, v93, v102
	v_cmp_lt_i32_e64 s[0:1], v95, v87
	s_waitcnt lgkmcnt(0)
	v_fma_f32 v93, v83, -v85, v93
	v_cndmask_b32_e64 v95, v95, v224, s[0:1]
	v_lshlrev_b32_e32 v95, 2, v95
	v_cndmask_b32_e32 v93, v93, v102, vcc
	ds_bpermute_b32 v95, v95, v93
	v_cmp_lt_i32_e64 s[0:1], v97, v87
	v_lshlrev_b32_e32 v102, 16, v56
	s_waitcnt lgkmcnt(0)
	v_add_f32_e32 v95, v93, v95
	v_cndmask_b32_e64 v97, v97, v224, s[0:1]
	v_lshlrev_b32_e32 v97, 2, v97
	v_cndmask_b32_e64 v93, v95, v93, s[38:39]
	ds_bpermute_b32 v95, v97, v93
	v_cmp_lt_i32_e64 s[0:1], v104, v87
	s_waitcnt lgkmcnt(0)
	v_add_f32_e32 v95, v93, v95
	v_cndmask_b32_e64 v97, v104, v224, s[0:1]
	v_lshlrev_b32_e32 v97, 2, v97
	v_cndmask_b32_e64 v93, v95, v93, s[40:41]
	ds_bpermute_b32 v95, v97, v93
	v_cmp_lt_i32_e64 s[0:1], v106, v87
	v_and_b32_e32 v104, 0xffff0000, v56
	s_waitcnt lgkmcnt(0)
	v_add_f32_e32 v95, v93, v95
	v_cndmask_b32_e64 v57, v106, v224, s[0:1]
	v_lshlrev_b32_e32 v57, 2, v57
	v_cndmask_b32_e64 v93, v95, v93, s[42:43]
	ds_bpermute_b32 v57, v57, v93
	v_cmp_lt_i32_e64 s[0:1], v107, v87
	v_add_u32_e32 v95, 0x2520, v77
	v_lshlrev_b32_e32 v106, 16, v58
	v_cndmask_b32_e64 v56, v107, v224, s[0:1]
	s_waitcnt lgkmcnt(0)
	v_add_f32_e32 v57, v93, v57
	v_lshlrev_b32_e32 v56, 2, v56
	v_cndmask_b32_e64 v57, v57, v93, s[44:45]
	ds_bpermute_b32 v56, v56, v57
	s_cselect_b64 s[0:1], -1, 0
	v_lshlrev_b32_e32 v107, 16, v59
	v_and_b32_e32 v59, 0xffff0000, v59
	v_and_b32_e32 v58, 0xffff0000, v58
	s_waitcnt lgkmcnt(0)
	v_add_f32_e32 v56, v57, v56
	v_cndmask_b32_e64 v57, v56, v57, s[46:47]
	ds_bpermute_b32 v56, v230, v57
	v_add_u32_e32 v87, 0x420, v77
	v_add_u32_e32 v93, 0x428, v77
	s_waitcnt lgkmcnt(0)
	v_sub_f32_e32 v97, v56, v57
	v_fma_f32 v85, v83, -v85, v97
	v_cndmask_b32_e64 v57, v85, v57, s[0:1]
	v_sub_f32_e32 v57, v56, v57
	v_mul_f32_e32 v57, 0x3fb8aa3b, v57
	v_exp_f32_e32 v57, v57
	v_add_u32_e32 v85, 0x2528, v77
	s_mov_b32 s0, 0x5040100
	v_mul_f32_e32 v57, v83, v57
	ds_write_b32 v73, v57 offset:17664
	s_waitcnt lgkmcnt(0)
	ds_write2_b32 v110, v48, v49 offset1:1
	ds_read2_b32 v[48:49], v81 offset0:64 offset1:72
	ds_write2_b32 v111, v50, v51 offset1:1
	ds_write2_b32 v95, v52, v53 offset1:1
	ds_write2_b32 v85, v54, v55 offset1:1
	ds_read2_b32 v[50:51], v81 offset0:80 offset1:88
	s_waitcnt lgkmcnt(4)
	v_pk_mul_f32 v[52:53], v[48:49], v[98:99] op_sel_hi:[0,1]
	v_pk_mul_f32 v[54:55], v[48:49], v[60:61] op_sel_hi:[0,1]
	v_pk_mul_f32 v[60:61], v[48:49], v[100:101] op_sel_hi:[0,1]
	v_pk_mul_f32 v[62:63], v[48:49], v[62:63] op_sel_hi:[0,1]
	v_mov_b32_e32 v48, v49
	s_waitcnt lgkmcnt(0)
	v_pk_mul_f32 v[98:99], v[50:51], v[108:109] op_sel_hi:[0,1]
	v_and_b32_sdwa v108, v60, v228 dst_sel:DWORD dst_unused:UNUSED_PAD src0_sel:WORD_1 src1_sel:DWORD
	v_and_b32_sdwa v110, v62, v228 dst_sel:DWORD dst_unused:UNUSED_PAD src0_sel:WORD_1 src1_sel:DWORD
	v_pk_mul_f32 v[100:101], v[48:49], v[102:103] op_sel_hi:[0,1]
	v_pk_mul_f32 v[102:103], v[48:49], v[104:105] op_sel_hi:[0,1]
	v_pk_mul_f32 v[104:105], v[48:49], v[106:107] op_sel_hi:[0,1]
	v_pk_mul_f32 v[48:49], v[48:49], v[58:59] op_sel_hi:[0,1]
	v_add3_u32 v57, v60, v108, s96
	v_add3_u32 v60, v62, v110, s96
	v_and_b32_e32 v60, 0xffff0000, v60
	v_cvt_pk_bf16_f32 v53, v53, v55
	v_cvt_pk_bf16_f32 v52, v52, v54
	v_cvt_pk_bf16_f32 v54, v61, v63
	v_or_b32_sdwa v55, v60, v57 dst_sel:DWORD dst_unused:UNUSED_PAD src0_sel:DWORD src1_sel:WORD_1
	ds_write2_b32 v77, v52, v53 offset1:1
	ds_write2_b32 v77, v55, v54 offset0:2 offset1:3
	v_cvt_pk_bf16_f32 v52, v101, v103
	v_cvt_pk_bf16_f32 v53, v100, v102
	v_pk_mul_f32 v[44:45], v[50:51], v[44:45] op_sel_hi:[0,1]
	v_cvt_pk_bf16_f32 v49, v105, v49
	v_cvt_pk_bf16_f32 v48, v104, v48
	ds_write2_b32 v87, v53, v52 offset1:1
	ds_write2_b32 v93, v48, v49 offset1:1
	v_cvt_pk_bf16_f32 v45, v99, v45
	v_cvt_pk_bf16_f32 v44, v98, v44
	v_add_u32_e32 v48, 0x840, v77
	ds_write2_b32 v48, v44, v45 offset1:1
	v_lshlrev_b32_e32 v45, 16, v47
	v_lshlrev_b32_e32 v44, 16, v46
	v_pk_mul_f32 v[44:45], v[50:51], v[44:45] op_sel_hi:[0,1]
	v_and_b32_e32 v47, 0xffff0000, v47
	v_and_b32_e32 v46, 0xffff0000, v46
	v_pk_mul_f32 v[46:47], v[50:51], v[46:47] op_sel_hi:[0,1]
	s_nop 0
	v_cvt_pk_bf16_f32 v45, v45, v47
	v_cvt_pk_bf16_f32 v44, v44, v46
	v_add_u32_e32 v46, 0x848, v77
	ds_write2_b32 v46, v44, v45 offset1:1
	v_add_u32_e32 v44, 0x2940, v77
	ds_write2_b32 v44, v40, v41 offset1:1
	v_add_u32_e32 v40, 0x2948, v77
	ds_write2_b32 v40, v42, v43 offset1:1
	v_lshlrev_b32_e32 v41, 16, v37
	v_lshlrev_b32_e32 v40, 16, v36
	v_mov_b32_e32 v42, v51
	v_pk_mul_f32 v[40:41], v[42:43], v[40:41] op_sel_hi:[0,1]
	v_and_b32_e32 v37, 0xffff0000, v37
	v_and_b32_e32 v36, 0xffff0000, v36
	v_pk_mul_f32 v[36:37], v[42:43], v[36:37] op_sel_hi:[0,1]
	v_and_b32_sdwa v43, v41, v228 dst_sel:DWORD dst_unused:UNUSED_PAD src0_sel:WORD_1 src1_sel:DWORD
	s_nop 0
	v_add3_u32 v41, v41, v43, s96
	v_and_b32_sdwa v43, v37, v228 dst_sel:DWORD dst_unused:UNUSED_PAD src0_sel:WORD_1 src1_sel:DWORD
	s_nop 0
	v_add3_u32 v37, v37, v43, s96
	v_and_b32_e32 v37, 0xffff0000, v37
	v_or_b32_sdwa v37, v37, v41 dst_sel:DWORD dst_unused:UNUSED_PAD src0_sel:DWORD src1_sel:WORD_1
	v_cvt_pk_bf16_f32 v36, v40, v36
	v_add_u32_e32 v40, 0xc60, v77
	ds_write2_b32 v40, v36, v37 offset1:1
	v_lshlrev_b32_e32 v37, 16, v39
	v_lshlrev_b32_e32 v36, 16, v38
	v_pk_mul_f32 v[36:37], v[42:43], v[36:37] op_sel_hi:[0,1]
	v_and_b32_e32 v39, 0xffff0000, v39
	v_and_b32_e32 v38, 0xffff0000, v38
	v_pk_mul_f32 v[38:39], v[42:43], v[38:39] op_sel_hi:[0,1]
	s_nop 0
	v_cvt_pk_bf16_f32 v37, v37, v39
	v_cvt_pk_bf16_f32 v36, v36, v38
	v_add_u32_e32 v38, 0xc68, v77
	ds_write2_b32 v38, v36, v37 offset1:1
	v_add_u32_e32 v36, 0x2d60, v77
	ds_write2_b32 v36, v32, v33 offset1:1
	ds_read2_b32 v[32:33], v81 offset0:96 offset1:104
	v_add_u32_e32 v36, 0x2d68, v77
	ds_write2_b32 v36, v34, v35 offset1:1
	v_lshlrev_b32_e32 v35, 16, v29
	v_lshlrev_b32_e32 v34, 16, v28
	s_waitcnt lgkmcnt(1)
	v_pk_mul_f32 v[34:35], v[32:33], v[34:35] op_sel_hi:[0,1]
	v_and_b32_e32 v29, 0xffff0000, v29
	v_and_b32_e32 v28, 0xffff0000, v28
	v_pk_mul_f32 v[28:29], v[32:33], v[28:29] op_sel_hi:[0,1]
	s_nop 0
	v_cvt_pk_bf16_f32 v29, v35, v29
	v_cvt_pk_bf16_f32 v28, v34, v28
	v_add_u32_e32 v34, 0x1080, v77
	ds_write2_b32 v34, v28, v29 offset1:1
	v_lshlrev_b32_e32 v29, 16, v31
	v_lshlrev_b32_e32 v28, 16, v30
	v_pk_mul_f32 v[28:29], v[32:33], v[28:29] op_sel_hi:[0,1]
	v_and_b32_e32 v31, 0xffff0000, v31
	v_and_b32_e32 v30, 0xffff0000, v30
	v_pk_mul_f32 v[30:31], v[32:33], v[30:31] op_sel_hi:[0,1]
	s_nop 0
	v_cvt_pk_bf16_f32 v29, v29, v31
	v_cvt_pk_bf16_f32 v28, v28, v30
	v_add_u32_e32 v30, 0x1088, v77
	ds_write2_b32 v30, v28, v29 offset1:1
	v_add_u32_e32 v28, 0x3180, v77
	ds_write2_b32 v28, v24, v25 offset1:1
	v_add_u32_e32 v24, 0x3188, v77
	ds_write2_b32 v24, v26, v27 offset1:1
	v_lshlrev_b32_e32 v25, 16, v21
	v_lshlrev_b32_e32 v24, 16, v20
	v_mov_b32_e32 v26, v33
	v_pk_mul_f32 v[24:25], v[26:27], v[24:25] op_sel_hi:[0,1]
	v_and_b32_e32 v21, 0xffff0000, v21
	v_and_b32_e32 v20, 0xffff0000, v20
	v_pk_mul_f32 v[20:21], v[26:27], v[20:21] op_sel_hi:[0,1]
	v_and_b32_sdwa v27, v25, v228 dst_sel:DWORD dst_unused:UNUSED_PAD src0_sel:WORD_1 src1_sel:DWORD
	s_nop 0
	v_add3_u32 v25, v25, v27, s96
	v_and_b32_sdwa v27, v21, v228 dst_sel:DWORD dst_unused:UNUSED_PAD src0_sel:WORD_1 src1_sel:DWORD
	s_nop 0
	v_add3_u32 v21, v21, v27, s96
	v_and_b32_e32 v21, 0xffff0000, v21
	v_or_b32_sdwa v21, v21, v25 dst_sel:DWORD dst_unused:UNUSED_PAD src0_sel:DWORD src1_sel:WORD_1
	v_cvt_pk_bf16_f32 v20, v24, v20
	v_add_u32_e32 v24, 0x14a0, v77
	ds_write2_b32 v24, v20, v21 offset1:1
	v_lshlrev_b32_e32 v21, 16, v23
	v_lshlrev_b32_e32 v20, 16, v22
	v_pk_mul_f32 v[20:21], v[26:27], v[20:21] op_sel_hi:[0,1]
	v_and_b32_e32 v23, 0xffff0000, v23
	v_and_b32_e32 v22, 0xffff0000, v22
	v_pk_mul_f32 v[22:23], v[26:27], v[22:23] op_sel_hi:[0,1]
	s_nop 0
	v_cvt_pk_bf16_f32 v21, v21, v23
	v_cvt_pk_bf16_f32 v20, v20, v22
	v_add_u32_e32 v22, 0x14a8, v77
	ds_write2_b32 v22, v20, v21 offset1:1
	v_add_u32_e32 v20, 0x35a0, v77
	ds_write2_b32 v20, v16, v17 offset1:1
	ds_read2_b32 v[16:17], v81 offset0:112 offset1:120
	v_add_u32_e32 v20, 0x35a8, v77
	ds_write2_b32 v20, v18, v19 offset1:1
	v_lshlrev_b32_e32 v19, 16, v13
	v_lshlrev_b32_e32 v18, 16, v12
	s_waitcnt lgkmcnt(1)
	v_pk_mul_f32 v[18:19], v[16:17], v[18:19] op_sel_hi:[0,1]
	v_and_b32_e32 v13, 0xffff0000, v13
	v_and_b32_e32 v12, 0xffff0000, v12
	v_pk_mul_f32 v[12:13], v[16:17], v[12:13] op_sel_hi:[0,1]
	s_nop 0
	v_cvt_pk_bf16_f32 v13, v19, v13
	v_cvt_pk_bf16_f32 v12, v18, v12
	v_add_u32_e32 v18, 0x18c0, v77
	ds_write2_b32 v18, v12, v13 offset1:1
	v_lshlrev_b32_e32 v13, 16, v15
	v_lshlrev_b32_e32 v12, 16, v14
	v_pk_mul_f32 v[12:13], v[16:17], v[12:13] op_sel_hi:[0,1]
	v_and_b32_e32 v15, 0xffff0000, v15
	v_and_b32_e32 v14, 0xffff0000, v14
	v_pk_mul_f32 v[14:15], v[16:17], v[14:15] op_sel_hi:[0,1]
	s_nop 0
	v_cvt_pk_bf16_f32 v13, v13, v15
	v_cvt_pk_bf16_f32 v12, v12, v14
	v_add_u32_e32 v14, 0x18c8, v77
	ds_write2_b32 v14, v12, v13 offset1:1
	v_add_u32_e32 v12, 0x39c0, v77
	ds_write2_b32 v12, v8, v9 offset1:1
	v_add_u32_e32 v8, 0x39c8, v77
	ds_write2_b32 v8, v10, v11 offset1:1
	v_lshlrev_b32_e32 v9, 16, v5
	v_lshlrev_b32_e32 v8, 16, v4
	v_mov_b32_e32 v10, v17
	v_pk_mul_f32 v[8:9], v[10:11], v[8:9] op_sel_hi:[0,1]
	v_and_b32_e32 v5, 0xffff0000, v5
	v_and_b32_e32 v4, 0xffff0000, v4
	v_pk_mul_f32 v[4:5], v[10:11], v[4:5] op_sel_hi:[0,1]
	v_and_b32_sdwa v11, v9, v228 dst_sel:DWORD dst_unused:UNUSED_PAD src0_sel:WORD_1 src1_sel:DWORD
	s_nop 0
	v_add3_u32 v9, v9, v11, s96
	v_and_b32_sdwa v11, v5, v228 dst_sel:DWORD dst_unused:UNUSED_PAD src0_sel:WORD_1 src1_sel:DWORD
	s_nop 0
	v_add3_u32 v5, v5, v11, s96
	v_and_b32_e32 v5, 0xffff0000, v5
	v_or_b32_sdwa v5, v5, v9 dst_sel:DWORD dst_unused:UNUSED_PAD src0_sel:DWORD src1_sel:WORD_1
	v_cvt_pk_bf16_f32 v4, v8, v4
	v_add_u32_e32 v8, 0x1ce0, v77
	ds_write2_b32 v8, v4, v5 offset1:1
	v_lshlrev_b32_e32 v5, 16, v7
	v_lshlrev_b32_e32 v4, 16, v6
	v_pk_mul_f32 v[4:5], v[10:11], v[4:5] op_sel_hi:[0,1]
	v_and_b32_e32 v7, 0xffff0000, v7
	v_and_b32_e32 v6, 0xffff0000, v6
	v_pk_mul_f32 v[6:7], v[10:11], v[6:7] op_sel_hi:[0,1]
	s_nop 0
	v_cvt_pk_bf16_f32 v5, v5, v7
	v_cvt_pk_bf16_f32 v4, v4, v6
	v_add_u32_e32 v6, 0x1ce8, v77
	ds_write2_b32 v6, v4, v5 offset1:1
	v_add_u32_e32 v4, 0x3de0, v77
	ds_write2_b32 v4, v0, v1 offset1:1
	v_add_u32_e32 v0, 0x3de8, v77
	ds_write2_b32 v0, v2, v3 offset1:1
	s_waitcnt lgkmcnt(0)
	ds_read_u16 v0, v79 offset:8448
	ds_read_u16 v4, v79 offset:8580
	ds_read_u16 v32, v79 offset:8480
	ds_read_u16 v36, v79 offset:8612
	ds_read_u16 v48, v79 offset:8512
	ds_read_u16 v52, v79 offset:8644
	ds_read_u16 v57, v79 offset:8676
	ds_read_u16 v62, v79 offset:8544
	ds_read_u16 v1, v79 offset:8712
	ds_read_u16 v5, v79 offset:8844
	ds_read_u16 v33, v79 offset:8744
	ds_read_u16 v37, v79 offset:8876
	ds_read_u16 v49, v79 offset:8776
	ds_read_u16 v53, v79 offset:8908
	ds_read_u16 v63, v79 offset:8940
	ds_read_u16 v81, v79 offset:8808
	ds_read_u16 v2, v79 offset:8976
	ds_read_u16 v6, v79 offset:9108
	ds_read_u16 v34, v79 offset:9008
	ds_read_u16 v38, v79 offset:9140
	ds_read_u16 v50, v79 offset:9040
	ds_read_u16 v54, v79 offset:9172
	ds_read_u16 v83, v79 offset:9204
	ds_read_u16 v85, v79 offset:9072
	ds_read_u16 v3, v79 offset:9240
	ds_read_u16 v7, v79 offset:9372
	ds_read_u16 v35, v79 offset:9272
	ds_read_u16 v39, v79 offset:9404
	ds_read_u16 v51, v79 offset:9304
	ds_read_u16 v55, v79 offset:9436
	ds_read_u16 v87, v79 offset:9468
	ds_read_u16 v93, v79 offset:9336
	ds_read_u16 v8, v79 offset:132
	ds_read_u16 v9, v79
	ds_read_u16 v12, v79 offset:32
	ds_read_u16 v16, v79 offset:164
	ds_read_u16 v20, v79 offset:64
	ds_read_u16 v24, v79 offset:196
	ds_read_u16 v28, v79 offset:228
	ds_read_u16 v40, v79 offset:96
	ds_read_u16 v10, v79 offset:264
	ds_read_u16 v11, v79 offset:396
	ds_read_u16 v13, v79 offset:296
	ds_read_u16 v17, v79 offset:428
	ds_read_u16 v21, v79 offset:328
	ds_read_u16 v25, v79 offset:460
	ds_read_u16 v29, v79 offset:492
	ds_read_u16 v41, v79 offset:360
	ds_read_u16 v14, v79 offset:528
	ds_read_u16 v15, v79 offset:660
	ds_read_u16 v18, v79 offset:560
	ds_read_u16 v19, v79 offset:692
	ds_read_u16 v22, v79 offset:592
	ds_read_u16 v26, v79 offset:724
	ds_read_u16 v30, v79 offset:756
	ds_read_u16 v42, v79 offset:624
	ds_read_u16 v23, v79 offset:792
	ds_read_u16 v27, v79 offset:924
	ds_read_u16 v31, v79 offset:824
	ds_read_u16 v43, v79 offset:956
	ds_read_u16 v44, v79 offset:856
	ds_read_u16 v45, v79 offset:988
	ds_read_u16 v46, v79 offset:1020
	ds_read_u16 v47, v79 offset:888
	s_waitcnt lgkmcnt(14)
	v_perm_b32 v3, v7, v3, s0
	v_perm_b32 v2, v6, v2, s0
	v_perm_b32 v1, v5, v1, s0
	v_perm_b32 v0, v4, v0, s0
	v_perm_b32 v35, v39, v35, s0
	v_perm_b32 v34, v38, v34, s0
	v_perm_b32 v33, v37, v33, s0
	v_perm_b32 v32, v36, v32, s0
	v_perm_b32 v51, v55, v51, s0
	v_perm_b32 v50, v54, v50, s0
	v_perm_b32 v49, v53, v49, s0
	v_perm_b32 v48, v52, v48, s0
	v_perm_b32 v105, v87, v93, s0
	v_perm_b32 v104, v83, v85, s0
	v_perm_b32 v103, v63, v81, s0
	v_perm_b32 v102, v57, v62, s0
	s_waitcnt lgkmcnt(6)
	v_perm_b32 v7, v27, v23, s0
	v_perm_b32 v6, v15, v14, s0
	v_perm_b32 v5, v11, v10, s0
	v_perm_b32 v4, v8, v9, s0
	s_waitcnt lgkmcnt(4)
	v_perm_b32 v15, v43, v31, s0
	v_perm_b32 v14, v19, v18, s0
	v_perm_b32 v13, v17, v13, s0
	v_perm_b32 v12, v16, v12, s0
	s_waitcnt lgkmcnt(2)
	v_perm_b32 v23, v45, v44, s0
	v_perm_b32 v22, v26, v22, s0
	v_perm_b32 v21, v25, v21, s0
	v_perm_b32 v20, v24, v20, s0
	s_waitcnt lgkmcnt(0)
	v_perm_b32 v31, v46, v47, s0
	v_perm_b32 v30, v30, v42, s0
	v_perm_b32 v29, v29, v41, s0
	v_perm_b32 v28, v28, v40, s0
	v_mfma_f32_16x16x32_bf16 v[8:11], v[0:3], v[4:7], 0
	v_mfma_f32_16x16x32_bf16 v[16:19], v[0:3], v[12:15], 0
	v_mfma_f32_16x16x32_bf16 v[24:27], v[0:3], v[20:23], 0
	v_mfma_f32_16x16x32_bf16 v[0:3], v[0:3], v[28:31], 0
	v_mfma_f32_16x16x32_bf16 v[36:39], v[32:35], v[4:7], 0
	v_mfma_f32_16x16x32_bf16 v[40:43], v[32:35], v[12:15], 0
	v_mfma_f32_16x16x32_bf16 v[44:47], v[32:35], v[20:23], 0
	v_mfma_f32_16x16x32_bf16 v[32:35], v[32:35], v[28:31], 0
	v_mfma_f32_16x16x32_bf16 v[52:55], v[48:51], v[4:7], 0
	v_mfma_f32_16x16x32_bf16 v[58:61], v[48:51], v[12:15], 0
	v_mfma_f32_16x16x32_bf16 v[98:101], v[48:51], v[20:23], 0
	v_mfma_f32_16x16x32_bf16 v[48:51], v[48:51], v[28:31], 0
	v_mfma_f32_16x16x32_bf16 v[4:7], v[102:105], v[4:7], 0
	v_mfma_f32_16x16x32_bf16 v[12:15], v[102:105], v[12:15], 0
	v_mfma_f32_16x16x32_bf16 v[20:23], v[102:105], v[20:23], 0
	v_mfma_f32_16x16x32_bf16 v[28:31], v[102:105], v[28:31], 0
	ds_read_u16 v57, v79 offset:12672
	ds_read_u16 v62, v79 offset:12804
	ds_read_u16 v63, v79 offset:12704
	ds_read_u16 v81, v79 offset:12836
	ds_read_u16 v83, v79 offset:12736
	ds_read_u16 v85, v79 offset:12868
	ds_read_u16 v87, v79 offset:12900
	ds_read_u16 v93, v79 offset:12768
	ds_read_u16 v95, v79 offset:12936
	ds_read_u16 v97, v79 offset:13068
	ds_read_u16 v122, v79 offset:12968
	ds_read_u16 v123, v79 offset:13100
	ds_read_u16 v124, v79 offset:13000
	ds_read_u16 v125, v79 offset:13132
	ds_read_u16 v126, v79 offset:13164
	ds_read_u16 v127, v79 offset:13032
	ds_read_u16 v102, v79 offset:13200
	ds_read_u16 v103, v79 offset:13332
	ds_read_u16 v128, v79 offset:13232
	ds_read_u16 v129, v79 offset:13364
	ds_read_u16 v130, v79 offset:13264
	ds_read_u16 v131, v79 offset:13396
	ds_read_u16 v132, v79 offset:13428
	ds_read_u16 v133, v79 offset:13296
	ds_read_u16 v104, v79 offset:13464
	ds_read_u16 v105, v79 offset:13596
	ds_read_u16 v134, v79 offset:13496
	ds_read_u16 v135, v79 offset:13628
	ds_read_u16 v136, v79 offset:13528
	ds_read_u16 v137, v79 offset:13660
	ds_read_u16 v138, v79 offset:13692
	ds_read_u16 v139, v79 offset:13560
	ds_read_u16 v106, v79 offset:4224
	ds_read_u16 v110, v79 offset:4356
	ds_read_u16 v114, v79 offset:4256
	ds_read_u16 v115, v79 offset:4388
	ds_read_u16 v118, v79 offset:4288
	ds_read_u16 v119, v79 offset:4420
	ds_read_u16 v140, v79 offset:4452
	ds_read_u16 v141, v79 offset:4320
	ds_read_u16 v107, v79 offset:4488
	ds_read_u16 v111, v79 offset:4620
	ds_read_u16 v116, v79 offset:4520
	ds_read_u16 v117, v79 offset:4652
	ds_read_u16 v120, v79 offset:4552
	ds_read_u16 v121, v79 offset:4684
	ds_read_u16 v142, v79 offset:4716
	ds_read_u16 v143, v79 offset:4584
	ds_read_u16 v108, v79 offset:4752
	ds_read_u16 v112, v79 offset:4884
	ds_read_u16 v144, v79 offset:4784
	ds_read_u16 v145, v79 offset:4916
	ds_read_u16 v146, v79 offset:4816
	ds_read_u16 v147, v79 offset:4948
	ds_read_u16 v148, v79 offset:4980
	ds_read_u16 v149, v79 offset:4848
	ds_read_u16 v109, v79 offset:5016
	ds_read_u16 v113, v79 offset:5148
	ds_read_u16 v150, v79 offset:5048
	ds_read_u16 v151, v79 offset:5180
	ds_read_u16 v152, v79 offset:5080
	ds_read_u16 v153, v79 offset:5212
	ds_read_u16 v154, v79 offset:5244
	ds_read_u16 v155, v79 offset:5112
	s_waitcnt lgkmcnt(14)
	v_perm_b32 v105, v105, v104, s0
	v_perm_b32 v104, v103, v102, s0
	v_perm_b32 v103, v97, v95, s0
	v_perm_b32 v102, v62, v57, s0
	s_waitcnt lgkmcnt(6)
	v_perm_b32 v109, v113, v109, s0
	v_perm_b32 v108, v112, v108, s0
	v_perm_b32 v107, v111, v107, s0
	v_perm_b32 v106, v110, v106, s0
	s_waitcnt lgkmcnt(4)
	v_perm_b32 v113, v151, v150, s0
	v_perm_b32 v112, v145, v144, s0
	v_perm_b32 v111, v117, v116, s0
	v_perm_b32 v110, v115, v114, s0
	s_waitcnt lgkmcnt(2)
	v_perm_b32 v117, v153, v152, s0
	v_perm_b32 v116, v147, v146, s0
	v_perm_b32 v115, v121, v120, s0
	v_perm_b32 v114, v119, v118, s0
	s_waitcnt lgkmcnt(0)
	v_perm_b32 v121, v154, v155, s0
	v_perm_b32 v120, v148, v149, s0
	v_perm_b32 v119, v142, v143, s0
	v_perm_b32 v118, v140, v141, s0
	v_mfma_f32_16x16x32_bf16 v[8:11], v[102:105], v[106:109], v[8:11]
	v_mov_b32_e32 v95, v169
	v_mov_b32_e32 v97, v169
	v_mfma_f32_16x16x32_bf16 v[16:19], v[102:105], v[110:113], v[16:19]
	v_mfma_f32_16x16x32_bf16 v[24:27], v[102:105], v[114:117], v[24:27]
	v_mfma_f32_16x16x32_bf16 v[102:105], v[102:105], v[118:121], v[0:3]
	s_nop 2
	v_perm_b32 v3, v135, v134, s0
	v_perm_b32 v2, v129, v128, s0
	v_perm_b32 v1, v123, v122, s0
	v_perm_b32 v0, v81, v63, s0
	s_nop 1
	v_mfma_f32_16x16x32_bf16 v[36:39], v[0:3], v[106:109], v[36:39]
	v_mfma_f32_16x16x32_bf16 v[40:43], v[0:3], v[110:113], v[40:43]
	v_mfma_f32_16x16x32_bf16 v[44:47], v[0:3], v[114:117], v[44:47]
	v_mfma_f32_16x16x32_bf16 v[32:35], v[0:3], v[118:121], v[32:35]
	v_perm_b32 v3, v137, v136, s0
	v_perm_b32 v2, v131, v130, s0
	v_perm_b32 v1, v125, v124, s0
	v_perm_b32 v0, v85, v83, s0
	s_nop 1
	v_mfma_f32_16x16x32_bf16 v[52:55], v[0:3], v[106:109], v[52:55]
	v_mfma_f32_16x16x32_bf16 v[58:61], v[0:3], v[110:113], v[58:61]
	v_mfma_f32_16x16x32_bf16 v[98:101], v[0:3], v[114:117], v[98:101]
	v_mfma_f32_16x16x32_bf16 v[48:51], v[0:3], v[118:121], v[48:51]
	v_perm_b32 v3, v138, v139, s0
	v_perm_b32 v2, v132, v133, s0
	v_perm_b32 v1, v126, v127, s0
	v_perm_b32 v0, v87, v93, s0
	s_lshl_b32 s0, s24, 7
	s_or_b32 s0, s0, s49
	v_mfma_f32_16x16x32_bf16 v[106:109], v[0:3], v[106:109], v[4:7]
	s_ashr_i32 s1, s0, 31
	s_nop 1
	v_lshl_add_u64 v[4:5], s[0:1], 4, v[68:69]
	v_or_b32_e32 v4, s25, v4
	v_mfma_f32_16x16x32_bf16 v[12:15], v[0:3], v[110:113], v[12:15]
	v_lshlrev_b64 v[6:7], 13, v[4:5]
	v_lshl_add_u64 v[6:7], v[70:71], 0, v[6:7]
	v_mov_b32_e32 v93, v169
	v_mfma_f32_16x16x32_bf16 v[20:23], v[0:3], v[114:117], v[20:23]
	s_mov_b64 s[0:1], 0x60
	v_mfma_f32_16x16x32_bf16 v[0:3], v[0:3], v[118:121], v[28:31]
	s_nop 2
	v_cvt_pk_bf16_f32 v8, v8, v9
	v_cvt_pk_bf16_f32 v9, v10, v11
	v_lshl_add_u64 v[10:11], v[6:7], 0, v[92:93]
	global_store_dwordx2 v[10:11], v[8:9], off
	v_cvt_pk_bf16_f32 v8, v16, v17
	v_cvt_pk_bf16_f32 v9, v18, v19
	global_store_dwordx2 v[10:11], v[8:9], off offset:2048
	v_cvt_pk_bf16_f32 v8, v24, v25
	v_cvt_pk_bf16_f32 v9, v26, v27
	v_lshl_add_u64 v[16:17], v[6:7], 0, v[94:95]
	global_store_dwordx2 v[16:17], v[8:9], off
	v_cvt_pk_bf16_f32 v8, v102, v103
	v_cvt_pk_bf16_f32 v9, v104, v105
	v_lshl_add_u64 v[16:17], v[6:7], 0, v[96:97]
	global_store_dwordx2 v[16:17], v[8:9], off
	v_cvt_pk_bf16_f32 v16, v36, v37
	v_cvt_pk_bf16_f32 v17, v38, v39
	global_store_dwordx2 v[10:11], v[16:17], off offset:32
	v_cvt_pk_bf16_f32 v16, v40, v41
	v_cvt_pk_bf16_f32 v17, v42, v43
	global_store_dwordx2 v[10:11], v[16:17], off offset:2080
	v_cvt_pk_bf16_f32 v16, v44, v45
	v_lshl_add_u64 v[8:9], v[6:7], 0, 32
	v_cvt_pk_bf16_f32 v17, v46, v47
	v_lshl_add_u64 v[18:19], v[8:9], 0, v[94:95]
	global_store_dwordx2 v[18:19], v[16:17], off
	v_cvt_pk_bf16_f32 v16, v32, v33
	v_cvt_pk_bf16_f32 v17, v34, v35
	v_lshl_add_u64 v[8:9], v[8:9], 0, v[96:97]
	global_store_dwordx2 v[8:9], v[16:17], off
	v_cvt_pk_bf16_f32 v16, v52, v53
	v_cvt_pk_bf16_f32 v17, v54, v55
	global_store_dwordx2 v[10:11], v[16:17], off offset:64
	v_cvt_pk_bf16_f32 v16, v58, v59
	v_cvt_pk_bf16_f32 v17, v60, v61
	global_store_dwordx2 v[10:11], v[16:17], off offset:2112
	v_cvt_pk_bf16_f32 v16, v98, v99
	v_lshl_add_u64 v[8:9], v[6:7], 0, 64
	v_cvt_pk_bf16_f32 v17, v100, v101
	v_lshl_add_u64 v[18:19], v[8:9], 0, v[94:95]
	global_store_dwordx2 v[18:19], v[16:17], off
	v_cvt_pk_bf16_f32 v16, v48, v49
	v_cvt_pk_bf16_f32 v17, v50, v51
	v_lshl_add_u64 v[8:9], v[8:9], 0, v[96:97]
	global_store_dwordx2 v[8:9], v[16:17], off
	v_cvt_pk_bf16_f32 v8, v106, v107
	v_cvt_pk_bf16_f32 v9, v108, v109
	global_store_dwordx2 v[10:11], v[8:9], off offset:96
	v_cvt_pk_bf16_f32 v8, v12, v13
	v_cvt_pk_bf16_f32 v9, v14, v15
	global_store_dwordx2 v[10:11], v[8:9], off offset:2144
	v_cvt_pk_bf16_f32 v8, v20, v21
	v_lshl_add_u64 v[6:7], v[6:7], 0, s[0:1]
	v_cvt_pk_bf16_f32 v9, v22, v23
	v_lshl_add_u64 v[10:11], v[6:7], 0, v[94:95]
	global_store_dwordx2 v[10:11], v[8:9], off
	v_cvt_pk_bf16_f32 v0, v0, v1
	v_cvt_pk_bf16_f32 v1, v2, v3
	v_lshl_add_u64 v[2:3], v[6:7], 0, v[96:97]
	global_store_dwordx2 v[2:3], v[0:1], off
	s_and_saveexec_b64 s[0:1], vcc
	s_cbranch_execz .LBB0_601
	v_mul_f32_e32 v0, 0x3fb8aa3b, v56
	v_exp_f32_e32 v2, v0
	v_lshl_add_u64 v[0:1], v[4:5], 2, s[22:23]
	global_store_dword v[0:1], v2, off
	s_branch .LBB0_601

.LBB0_856:
	s_lshl_b32 s1, s2, 8
	s_lshl_b32 s0, s0, 8
	v_mov_b32_e32 v160, v179
	v_mov_b32_e32 v80, v210
	s_add_i32 s1, s1, s64
	s_or_b32 s0, s0, s65
	v_readlane_b32 s20, v254, 49
	v_lshl_add_u32 v196, v80, 3, s0
	v_add_u32_e32 v200, s1, v160
	v_ashrrev_i32_e32 v197, 31, v196
	v_ashrrev_i32_e32 v201, 31, v200
	v_lshlrev_b64 v[80:81], 2, v[196:197]
	v_lshlrev_b64 v[160:161], 5, v[200:201]
	v_readlane_b32 s21, v254, 50
	v_lshl_add_u64 v[82:83], s[44:45], 0, v[80:81]
	v_lshl_add_u64 v[88:89], s[46:47], 0, v[80:81]
	v_lshl_add_u64 v[164:165], s[20:21], 0, v[160:161]
	global_load_dwordx4 v[100:103], v[82:83], off offset:16
	global_load_dwordx4 v[108:111], v[82:83], off
	global_load_dwordx4 v[96:99], v[88:89], off offset:16
	global_load_dwordx4 v[104:107], v[88:89], off
	global_load_dwordx4 v[84:87], v[82:83], off offset:528
	global_load_dwordx4 v[92:95], v[82:83], off offset:512
	s_nop 0
	global_load_dwordx4 v[80:83], v[88:89], off offset:528
	s_nop 0
	global_load_dwordx4 v[88:91], v[88:89], off offset:512
	s_nop 0
	global_load_dwordx4 v[160:163], v[164:165], off offset:16
	s_nop 0
	global_load_dwordx4 v[164:167], v[164:165], off
	s_mov_b32 s0, 0x3a800000
	v_add_u32_e32 v202, 16, v200
	v_ashrrev_i32_e32 v203, 31, v202
	v_mov_b64_e32 v[198:199], s[24:25]
	s_waitcnt vmcnt(0)
	v_xor_b32_e32 v103, 0x80000000, v103
	v_xor_b32_e32 v102, 0x80000000, v102
	v_pk_add_f32 v[160:161], v[160:161], v[162:163]
	v_pk_add_f32 v[164:165], v[164:165], v[166:167]
	s_nop 0
	v_pk_add_f32 v[160:161], v[164:165], v[160:161]
	s_nop 0
	v_pk_mul_f32 v[204:205], v[160:161], s[0:1] op_sel_hi:[1,0]
	v_mad_i64_i32 v[198:199], s[0:1], v200, s78, v[198:199]
	v_fma_f32 v160, -v204, v204, v205
	v_max_f32_e32 v160, 0, v160
	v_add_f32_e32 v160, 0x3727c5ac, v160
	v_cmp_gt_f32_e32 vcc, s77, v160
	v_mul_f32_e32 v161, 0x4b800000, v160
	v_lshl_add_u64 v[208:209], v[196:197], 1, v[198:199]
	v_cndmask_b32_e32 v160, v160, v161, vcc
	v_rsq_f32_e32 v160, v160
	v_mov_b32_e32 v205, v204
	v_xor_b32_e32 v199, 0x80000000, v111
	v_xor_b32_e32 v198, 0x80000000, v110
	v_mul_f32_e32 v161, 0x45800000, v160
	v_cndmask_b32_e32 v206, v160, v161, vcc
	v_lshlrev_b64 v[160:161], 5, v[202:203]
	v_lshl_add_u64 v[164:165], s[20:21], 0, v[160:161]
	global_load_dwordx4 v[160:163], v[164:165], off offset:16
	s_nop 0
	global_load_dwordx4 v[164:167], v[164:165], off
	v_mov_b32_e32 v207, v206
	v_cmp_gt_i32_e32 vcc, s79, v196
	s_and_saveexec_b64 s[0:1], vcc
	s_cbranch_execz .LBB0_858
	v_pk_fma_f32 v[156:157], v[108:109], v[204:205], v[156:157] neg_lo:[1,0,0] neg_hi:[1,0,0]
	v_pk_fma_f32 v[156:157], v[156:157], v[206:207], v[104:105]
	v_pk_fma_f32 v[158:159], v[198:199], v[204:205], v[158:159]
	v_pk_fma_f32 v[152:153], v[100:101], v[204:205], v[152:153] neg_lo:[1,0,0] neg_hi:[1,0,0]
	v_pk_fma_f32 v[158:159], v[158:159], v[206:207], v[106:107]
	v_pk_fma_f32 v[152:153], v[152:153], v[206:207], v[96:97]
	v_cvt_pk_bf16_f32 v156, v156, v157
	v_pk_fma_f32 v[110:111], v[102:103], v[204:205], v[154:155]
	v_pk_fma_f32 v[110:111], v[110:111], v[206:207], v[98:99]
	v_cvt_pk_bf16_f32 v157, v158, v159
	v_cvt_pk_bf16_f32 v158, v152, v153
	v_cvt_pk_bf16_f32 v159, v110, v111
	global_store_dwordx4 v[208:209], v[156:159], off
.LBB0_858:
	s_or_b64 exec, exec, s[0:1]
	s_movk_i32 s0, 0x890
	v_cmp_gt_i32_e64 s[40:41], s0, v196
	v_xor_b32_e32 v95, 0x80000000, v95
	v_xor_b32_e32 v94, 0x80000000, v94
	v_xor_b32_e32 v87, 0x80000000, v87
	v_xor_b32_e32 v86, 0x80000000, v86
	s_and_saveexec_b64 s[0:1], s[40:41]
	s_cbranch_execz .LBB0_860
	v_pk_fma_f32 v[148:149], v[92:93], v[204:205], v[148:149] neg_lo:[1,0,0] neg_hi:[1,0,0]
	v_pk_fma_f32 v[148:149], v[148:149], v[206:207], v[88:89]
	v_pk_fma_f32 v[150:151], v[94:95], v[204:205], v[150:151]
	v_pk_fma_f32 v[144:145], v[84:85], v[204:205], v[144:145] neg_lo:[1,0,0] neg_hi:[1,0,0]
	v_pk_fma_f32 v[150:151], v[150:151], v[206:207], v[90:91]
	v_pk_fma_f32 v[144:145], v[144:145], v[206:207], v[80:81]
	v_cvt_pk_bf16_f32 v148, v148, v149
	v_pk_fma_f32 v[110:111], v[86:87], v[204:205], v[146:147]
	v_pk_fma_f32 v[110:111], v[110:111], v[206:207], v[82:83]
	v_cvt_pk_bf16_f32 v149, v150, v151
	v_cvt_pk_bf16_f32 v150, v144, v145
	v_cvt_pk_bf16_f32 v151, v110, v111
	global_store_dwordx4 v[208:209], v[148:151], off offset:256
.LBB0_860:
	s_or_b64 exec, exec, s[0:1]
	s_waitcnt vmcnt(0)
	v_pk_add_f32 v[110:111], v[164:165], v[166:167]
	v_pk_add_f32 v[144:145], v[160:161], v[162:163]
	s_mov_b32 s0, 0x3a800000
	v_pk_add_f32 v[110:111], v[110:111], v[144:145]
	v_mov_b64_e32 v[156:157], s[24:25]
	v_pk_mul_f32 v[152:153], v[110:111], s[0:1] op_sel_hi:[1,0]
	s_nop 0
	v_fma_f32 v110, -v152, v152, v153
	v_max_f32_e32 v110, 0, v110
	v_add_f32_e32 v110, 0x3727c5ac, v110
	v_cmp_gt_f32_e64 s[0:1], s77, v110
	v_mul_f32_e32 v111, 0x4b800000, v110
	v_mov_b32_e32 v153, v152
	v_cndmask_b32_e64 v110, v110, v111, s[0:1]
	v_rsq_f32_e32 v110, v110
	s_nop 0
	v_mul_f32_e32 v111, 0x45800000, v110
	v_cndmask_b32_e64 v154, v110, v111, s[0:1]
	v_add_u32_e32 v110, 32, v200
	v_ashrrev_i32_e32 v111, 31, v110
	v_readlane_b32 s0, v254, 49
	v_lshlrev_b64 v[144:145], 5, v[110:111]
	v_readlane_b32 s1, v254, 50
	v_mov_b32_e32 v155, v154
	s_nop 0
	v_lshl_add_u64 v[148:149], s[0:1], 0, v[144:145]
	global_load_dwordx4 v[144:147], v[148:149], off offset:16
	s_nop 0
	global_load_dwordx4 v[148:151], v[148:149], off
	v_mad_i64_i32 v[156:157], s[0:1], v202, s78, v[156:157]
	v_lshl_add_u64 v[156:157], v[196:197], 1, v[156:157]
	s_and_saveexec_b64 s[0:1], vcc
	s_cbranch_execz .LBB0_862
	v_pk_fma_f32 v[140:141], v[108:109], v[152:153], v[140:141] neg_lo:[1,0,0] neg_hi:[1,0,0]
	v_pk_fma_f32 v[140:141], v[140:141], v[154:155], v[104:105]
	v_cvt_pk_bf16_f32 v140, v140, v141
	v_pk_fma_f32 v[142:143], v[198:199], v[152:153], v[142:143]
	v_pk_fma_f32 v[142:143], v[142:143], v[154:155], v[106:107]
	v_pk_fma_f32 v[136:137], v[100:101], v[152:153], v[136:137] neg_lo:[1,0,0] neg_hi:[1,0,0]
	v_pk_fma_f32 v[136:137], v[136:137], v[154:155], v[96:97]
	v_cvt_pk_bf16_f32 v141, v142, v143
	v_pk_fma_f32 v[138:139], v[102:103], v[152:153], v[138:139]
	v_pk_fma_f32 v[138:139], v[138:139], v[154:155], v[98:99]
	v_cvt_pk_bf16_f32 v142, v136, v137
	v_cvt_pk_bf16_f32 v143, v138, v139
	global_store_dwordx4 v[156:157], v[140:143], off
.LBB0_862:
	s_or_b64 exec, exec, s[0:1]
	s_and_saveexec_b64 s[0:1], s[40:41]
	s_cbranch_execz .LBB0_864
	v_pk_fma_f32 v[132:133], v[92:93], v[152:153], v[132:133] neg_lo:[1,0,0] neg_hi:[1,0,0]
	v_pk_fma_f32 v[132:133], v[132:133], v[154:155], v[88:89]
	v_cvt_pk_bf16_f32 v132, v132, v133
	v_pk_fma_f32 v[134:135], v[94:95], v[152:153], v[134:135]
	v_pk_fma_f32 v[134:135], v[134:135], v[154:155], v[90:91]
	v_pk_fma_f32 v[128:129], v[84:85], v[152:153], v[128:129] neg_lo:[1,0,0] neg_hi:[1,0,0]
	v_pk_fma_f32 v[128:129], v[128:129], v[154:155], v[80:81]
	v_cvt_pk_bf16_f32 v133, v134, v135
	v_pk_fma_f32 v[130:131], v[86:87], v[152:153], v[130:131]
	v_pk_fma_f32 v[130:131], v[130:131], v[154:155], v[82:83]
	v_cvt_pk_bf16_f32 v134, v128, v129
	v_cvt_pk_bf16_f32 v135, v130, v131
	global_store_dwordx4 v[156:157], v[132:135], off offset:256
.LBB0_864:
	s_or_b64 exec, exec, s[0:1]
	s_waitcnt vmcnt(0)
	v_pk_add_f32 v[128:129], v[148:149], v[150:151]
	v_pk_add_f32 v[130:131], v[144:145], v[146:147]
	s_mov_b32 s0, 0x3a800000
	v_pk_add_f32 v[128:129], v[128:129], v[130:131]
	v_add_u32_e32 v136, 48, v200
	v_pk_mul_f32 v[138:139], v[128:129], s[0:1] op_sel_hi:[1,0]
	v_ashrrev_i32_e32 v137, 31, v136
	v_fma_f32 v111, -v138, v138, v139
	v_max_f32_e32 v111, 0, v111
	v_add_f32_e32 v111, 0x3727c5ac, v111
	v_cmp_gt_f32_e64 s[0:1], s77, v111
	v_mul_f32_e32 v128, 0x4b800000, v111
	v_mov_b64_e32 v[142:143], s[24:25]
	v_cndmask_b32_e64 v111, v111, v128, s[0:1]
	v_rsq_f32_e32 v111, v111
	v_mov_b32_e32 v139, v138
	v_mul_f32_e32 v128, 0x45800000, v111
	v_cndmask_b32_e64 v140, v111, v128, s[0:1]
	v_readlane_b32 s0, v254, 49
	v_lshlrev_b64 v[128:129], 5, v[136:137]
	v_readlane_b32 s1, v254, 50
	v_mov_b32_e32 v141, v140
	s_nop 0
	v_lshl_add_u64 v[132:133], s[0:1], 0, v[128:129]
	global_load_dwordx4 v[128:131], v[132:133], off offset:16
	s_nop 0
	global_load_dwordx4 v[132:135], v[132:133], off
	v_mad_i64_i32 v[110:111], s[0:1], v110, s78, v[142:143]
	v_lshl_add_u64 v[110:111], v[196:197], 1, v[110:111]
	s_and_saveexec_b64 s[0:1], vcc
	s_cbranch_execz .LBB0_866
	v_pk_fma_f32 v[124:125], v[108:109], v[138:139], v[124:125] neg_lo:[1,0,0] neg_hi:[1,0,0]
	v_pk_fma_f32 v[124:125], v[124:125], v[140:141], v[104:105]
	v_pk_fma_f32 v[126:127], v[198:199], v[138:139], v[126:127]
	v_pk_fma_f32 v[126:127], v[126:127], v[140:141], v[106:107]
	v_cvt_pk_bf16_f32 v124, v124, v125
	v_pk_fma_f32 v[120:121], v[100:101], v[138:139], v[120:121] neg_lo:[1,0,0] neg_hi:[1,0,0]
	v_pk_fma_f32 v[120:121], v[120:121], v[140:141], v[96:97]
	v_cvt_pk_bf16_f32 v125, v126, v127
	v_pk_fma_f32 v[122:123], v[102:103], v[138:139], v[122:123]
	v_pk_fma_f32 v[122:123], v[122:123], v[140:141], v[98:99]
	v_cvt_pk_bf16_f32 v126, v120, v121
	v_cvt_pk_bf16_f32 v127, v122, v123
	global_store_dwordx4 v[110:111], v[124:127], off
.LBB0_866:
	s_or_b64 exec, exec, s[0:1]
	s_and_saveexec_b64 s[0:1], s[40:41]
	s_cbranch_execz .LBB0_868
	v_pk_fma_f32 v[116:117], v[92:93], v[138:139], v[116:117] neg_lo:[1,0,0] neg_hi:[1,0,0]
	v_pk_fma_f32 v[116:117], v[116:117], v[140:141], v[88:89]
	v_pk_fma_f32 v[118:119], v[94:95], v[138:139], v[118:119]
	v_pk_fma_f32 v[118:119], v[118:119], v[140:141], v[90:91]
	v_cvt_pk_bf16_f32 v116, v116, v117
	v_pk_fma_f32 v[112:113], v[84:85], v[138:139], v[112:113] neg_lo:[1,0,0] neg_hi:[1,0,0]
	v_pk_fma_f32 v[112:113], v[112:113], v[140:141], v[80:81]
	v_cvt_pk_bf16_f32 v117, v118, v119
	v_pk_fma_f32 v[114:115], v[86:87], v[138:139], v[114:115]
	v_pk_fma_f32 v[114:115], v[114:115], v[140:141], v[82:83]
	v_cvt_pk_bf16_f32 v118, v112, v113
	v_cvt_pk_bf16_f32 v119, v114, v115
	global_store_dwordx4 v[110:111], v[116:119], off offset:256
.LBB0_868:
	s_or_b64 exec, exec, s[0:1]
	s_waitcnt vmcnt(0)
	v_pk_add_f32 v[110:111], v[132:133], v[134:135]
	v_pk_add_f32 v[112:113], v[128:129], v[130:131]
	s_mov_b32 s0, 0x3a800000
	v_pk_add_f32 v[110:111], v[110:111], v[112:113]
	v_add_u32_e32 v118, 0x80, v200
	v_pk_mul_f32 v[120:121], v[110:111], s[0:1] op_sel_hi:[1,0]
	v_ashrrev_i32_e32 v119, 31, v118
	v_fma_f32 v110, -v120, v120, v121
	v_max_f32_e32 v110, 0, v110
	v_add_f32_e32 v110, 0x3727c5ac, v110
	v_cmp_gt_f32_e64 s[0:1], s77, v110
	v_mul_f32_e32 v111, 0x4b800000, v110
	v_mov_b64_e32 v[124:125], s[24:25]
	v_cndmask_b32_e64 v110, v110, v111, s[0:1]
	v_rsq_f32_e32 v110, v110
	v_mov_b32_e32 v121, v120
	v_mul_f32_e32 v111, 0x45800000, v110
	v_cndmask_b32_e64 v122, v110, v111, s[0:1]
	v_readlane_b32 s0, v254, 49
	v_lshlrev_b64 v[110:111], 5, v[118:119]
	v_readlane_b32 s1, v254, 50
	v_mov_b32_e32 v123, v122
	s_nop 0
	v_lshl_add_u64 v[114:115], s[0:1], 0, v[110:111]
	global_load_dwordx4 v[110:113], v[114:115], off offset:16
	s_nop 0
	global_load_dwordx4 v[114:117], v[114:115], off
	v_mad_i64_i32 v[124:125], s[0:1], v136, s78, v[124:125]
	v_lshl_add_u64 v[124:125], v[196:197], 1, v[124:125]
	s_and_saveexec_b64 s[0:1], vcc
	s_cbranch_execz .LBB0_870
	v_pk_fma_f32 v[76:77], v[108:109], v[120:121], v[76:77] neg_lo:[1,0,0] neg_hi:[1,0,0]
	v_pk_fma_f32 v[76:77], v[76:77], v[122:123], v[104:105]
	v_pk_fma_f32 v[78:79], v[198:199], v[120:121], v[78:79]
	v_pk_fma_f32 v[78:79], v[78:79], v[122:123], v[106:107]
	v_cvt_pk_bf16_f32 v76, v76, v77
	v_pk_fma_f32 v[72:73], v[100:101], v[120:121], v[72:73] neg_lo:[1,0,0] neg_hi:[1,0,0]
	v_pk_fma_f32 v[72:73], v[72:73], v[122:123], v[96:97]
	v_cvt_pk_bf16_f32 v77, v78, v79
	v_pk_fma_f32 v[74:75], v[102:103], v[120:121], v[74:75]
	v_pk_fma_f32 v[74:75], v[74:75], v[122:123], v[98:99]
	v_cvt_pk_bf16_f32 v78, v72, v73
	v_cvt_pk_bf16_f32 v79, v74, v75
	global_store_dwordx4 v[124:125], v[76:79], off
.LBB0_870:
	s_or_b64 exec, exec, s[0:1]
	s_and_saveexec_b64 s[0:1], s[40:41]
	s_cbranch_execz .LBB0_872
	v_pk_fma_f32 v[68:69], v[92:93], v[120:121], v[68:69] neg_lo:[1,0,0] neg_hi:[1,0,0]
	v_pk_fma_f32 v[68:69], v[68:69], v[122:123], v[88:89]
	v_pk_fma_f32 v[70:71], v[94:95], v[120:121], v[70:71]
	v_pk_fma_f32 v[70:71], v[70:71], v[122:123], v[90:91]
	v_cvt_pk_bf16_f32 v68, v68, v69
	v_pk_fma_f32 v[64:65], v[84:85], v[120:121], v[64:65] neg_lo:[1,0,0] neg_hi:[1,0,0]
	v_pk_fma_f32 v[64:65], v[64:65], v[122:123], v[80:81]
	v_cvt_pk_bf16_f32 v69, v70, v71
	v_pk_fma_f32 v[66:67], v[86:87], v[120:121], v[66:67]
	v_pk_fma_f32 v[66:67], v[66:67], v[122:123], v[82:83]
	v_cvt_pk_bf16_f32 v70, v64, v65
	v_cvt_pk_bf16_f32 v71, v66, v67
	global_store_dwordx4 v[124:125], v[68:71], off offset:256
.LBB0_872:
	s_or_b64 exec, exec, s[0:1]
	s_waitcnt vmcnt(0)
	v_pk_add_f32 v[64:65], v[114:115], v[116:117]
	v_pk_add_f32 v[66:67], v[110:111], v[112:113]
	s_mov_b32 s0, 0x3a800000
	v_pk_add_f32 v[64:65], v[64:65], v[66:67]
	v_add_u32_e32 v72, 0x90, v200
	v_pk_mul_f32 v[74:75], v[64:65], s[0:1] op_sel_hi:[1,0]
	v_ashrrev_i32_e32 v73, 31, v72
	v_fma_f32 v64, -v74, v74, v75
	v_max_f32_e32 v64, 0, v64
	v_add_f32_e32 v64, 0x3727c5ac, v64
	v_cmp_gt_f32_e64 s[0:1], s77, v64
	v_mul_f32_e32 v65, 0x4b800000, v64
	v_mov_b64_e32 v[78:79], s[24:25]
	v_cndmask_b32_e64 v64, v64, v65, s[0:1]
	v_rsq_f32_e32 v64, v64
	v_mov_b32_e32 v75, v74
	v_mul_f32_e32 v65, 0x45800000, v64
	v_cndmask_b32_e64 v76, v64, v65, s[0:1]
	v_readlane_b32 s0, v254, 49
	v_lshlrev_b64 v[64:65], 5, v[72:73]
	v_readlane_b32 s1, v254, 50
	v_mov_b32_e32 v77, v76
	s_nop 0
	v_lshl_add_u64 v[68:69], s[0:1], 0, v[64:65]
	global_load_dwordx4 v[64:67], v[68:69], off offset:16
	s_nop 0
	global_load_dwordx4 v[68:71], v[68:69], off
	v_mad_i64_i32 v[78:79], s[0:1], v118, s78, v[78:79]
	v_lshl_add_u64 v[78:79], v[196:197], 1, v[78:79]
	s_and_saveexec_b64 s[0:1], vcc
	s_cbranch_execz .LBB0_874
	v_pk_fma_f32 v[60:61], v[108:109], v[74:75], v[60:61] neg_lo:[1,0,0] neg_hi:[1,0,0]
	v_pk_fma_f32 v[60:61], v[60:61], v[76:77], v[104:105]
	v_pk_fma_f32 v[62:63], v[198:199], v[74:75], v[62:63]
	v_pk_fma_f32 v[62:63], v[62:63], v[76:77], v[106:107]
	v_cvt_pk_bf16_f32 v60, v60, v61
	v_pk_fma_f32 v[56:57], v[100:101], v[74:75], v[56:57] neg_lo:[1,0,0] neg_hi:[1,0,0]
	v_pk_fma_f32 v[56:57], v[56:57], v[76:77], v[96:97]
	v_cvt_pk_bf16_f32 v61, v62, v63
	v_pk_fma_f32 v[58:59], v[102:103], v[74:75], v[58:59]
	v_pk_fma_f32 v[58:59], v[58:59], v[76:77], v[98:99]
	v_cvt_pk_bf16_f32 v62, v56, v57
	v_cvt_pk_bf16_f32 v63, v58, v59
	global_store_dwordx4 v[78:79], v[60:63], off
.LBB0_874:
	s_or_b64 exec, exec, s[0:1]
	s_and_saveexec_b64 s[0:1], s[40:41]
	s_cbranch_execz .LBB0_876
	v_pk_fma_f32 v[52:53], v[92:93], v[74:75], v[52:53] neg_lo:[1,0,0] neg_hi:[1,0,0]
	v_pk_fma_f32 v[52:53], v[52:53], v[76:77], v[88:89]
	v_pk_fma_f32 v[54:55], v[94:95], v[74:75], v[54:55]
	v_pk_fma_f32 v[54:55], v[54:55], v[76:77], v[90:91]
	v_cvt_pk_bf16_f32 v52, v52, v53
	v_pk_fma_f32 v[48:49], v[84:85], v[74:75], v[48:49] neg_lo:[1,0,0] neg_hi:[1,0,0]
	v_pk_fma_f32 v[48:49], v[48:49], v[76:77], v[80:81]
	v_cvt_pk_bf16_f32 v53, v54, v55
	v_pk_fma_f32 v[50:51], v[86:87], v[74:75], v[50:51]
	v_pk_fma_f32 v[50:51], v[50:51], v[76:77], v[82:83]
	v_cvt_pk_bf16_f32 v54, v48, v49
	v_cvt_pk_bf16_f32 v55, v50, v51
	global_store_dwordx4 v[78:79], v[52:55], off offset:256
.LBB0_876:
	s_or_b64 exec, exec, s[0:1]
	s_waitcnt vmcnt(0)
	v_pk_add_f32 v[48:49], v[68:69], v[70:71]
	v_pk_add_f32 v[50:51], v[64:65], v[66:67]
	s_mov_b32 s0, 0x3a800000
	v_pk_add_f32 v[48:49], v[48:49], v[50:51]
	v_add_u32_e32 v56, 0xa0, v200
	v_pk_mul_f32 v[58:59], v[48:49], s[0:1] op_sel_hi:[1,0]
	v_ashrrev_i32_e32 v57, 31, v56
	v_fma_f32 v48, -v58, v58, v59
	v_max_f32_e32 v48, 0, v48
	v_add_f32_e32 v48, 0x3727c5ac, v48
	v_cmp_gt_f32_e64 s[0:1], s77, v48
	v_mul_f32_e32 v49, 0x4b800000, v48
	v_mov_b64_e32 v[62:63], s[24:25]
	v_cndmask_b32_e64 v48, v48, v49, s[0:1]
	v_rsq_f32_e32 v48, v48
	v_mov_b32_e32 v59, v58
	v_mul_f32_e32 v49, 0x45800000, v48
	v_cndmask_b32_e64 v60, v48, v49, s[0:1]
	v_readlane_b32 s0, v254, 49
	v_lshlrev_b64 v[48:49], 5, v[56:57]
	v_readlane_b32 s1, v254, 50
	v_mov_b32_e32 v61, v60
	s_nop 0
	v_lshl_add_u64 v[52:53], s[0:1], 0, v[48:49]
	global_load_dwordx4 v[48:51], v[52:53], off offset:16
	s_nop 0
	global_load_dwordx4 v[52:55], v[52:53], off
	v_mad_i64_i32 v[62:63], s[0:1], v72, s78, v[62:63]
	v_lshl_add_u64 v[62:63], v[196:197], 1, v[62:63]
	s_and_saveexec_b64 s[0:1], vcc
	s_cbranch_execz .LBB0_878
	v_pk_fma_f32 v[44:45], v[108:109], v[58:59], v[44:45] neg_lo:[1,0,0] neg_hi:[1,0,0]
	v_pk_fma_f32 v[44:45], v[44:45], v[60:61], v[104:105]
	v_pk_fma_f32 v[46:47], v[198:199], v[58:59], v[46:47]
	v_pk_fma_f32 v[46:47], v[46:47], v[60:61], v[106:107]
	v_cvt_pk_bf16_f32 v44, v44, v45
	v_pk_fma_f32 v[40:41], v[100:101], v[58:59], v[40:41] neg_lo:[1,0,0] neg_hi:[1,0,0]
	v_pk_fma_f32 v[40:41], v[40:41], v[60:61], v[96:97]
	v_cvt_pk_bf16_f32 v45, v46, v47
	v_pk_fma_f32 v[42:43], v[102:103], v[58:59], v[42:43]
	v_pk_fma_f32 v[42:43], v[42:43], v[60:61], v[98:99]
	v_cvt_pk_bf16_f32 v46, v40, v41
	v_cvt_pk_bf16_f32 v47, v42, v43
	global_store_dwordx4 v[62:63], v[44:47], off
.LBB0_878:
	s_or_b64 exec, exec, s[0:1]
	s_and_saveexec_b64 s[0:1], s[40:41]
	s_cbranch_execz .LBB0_880
	v_pk_fma_f32 v[36:37], v[92:93], v[58:59], v[36:37] neg_lo:[1,0,0] neg_hi:[1,0,0]
	v_pk_fma_f32 v[36:37], v[36:37], v[60:61], v[88:89]
	v_pk_fma_f32 v[38:39], v[94:95], v[58:59], v[38:39]
	v_pk_fma_f32 v[38:39], v[38:39], v[60:61], v[90:91]
	v_cvt_pk_bf16_f32 v36, v36, v37
	v_pk_fma_f32 v[32:33], v[84:85], v[58:59], v[32:33] neg_lo:[1,0,0] neg_hi:[1,0,0]
	v_pk_fma_f32 v[32:33], v[32:33], v[60:61], v[80:81]
	v_cvt_pk_bf16_f32 v37, v38, v39
	v_pk_fma_f32 v[34:35], v[86:87], v[58:59], v[34:35]
	v_pk_fma_f32 v[34:35], v[34:35], v[60:61], v[82:83]
	v_cvt_pk_bf16_f32 v38, v32, v33
	v_cvt_pk_bf16_f32 v39, v34, v35
	global_store_dwordx4 v[62:63], v[36:39], off offset:256
.LBB0_880:
	s_or_b64 exec, exec, s[0:1]
	s_waitcnt vmcnt(0)
	v_pk_add_f32 v[32:33], v[52:53], v[54:55]
	v_pk_add_f32 v[34:35], v[48:49], v[50:51]
	s_mov_b32 s0, 0x3a800000
	v_pk_add_f32 v[32:33], v[32:33], v[34:35]
	v_add_u32_e32 v44, 0xb0, v200
	v_pk_mul_f32 v[40:41], v[32:33], s[0:1] op_sel_hi:[1,0]
	v_ashrrev_i32_e32 v45, 31, v44
	v_fma_f32 v32, -v40, v40, v41
	v_max_f32_e32 v32, 0, v32
	v_add_f32_e32 v32, 0x3727c5ac, v32
	v_cmp_gt_f32_e64 s[0:1], s77, v32
	v_mul_f32_e32 v33, 0x4b800000, v32
	v_mov_b64_e32 v[46:47], s[24:25]
	v_cndmask_b32_e64 v32, v32, v33, s[0:1]
	v_rsq_f32_e32 v32, v32
	v_mov_b32_e32 v41, v40
	v_mul_f32_e32 v33, 0x45800000, v32
	v_cndmask_b32_e64 v42, v32, v33, s[0:1]
	v_readlane_b32 s0, v254, 49
	v_lshlrev_b64 v[32:33], 5, v[44:45]
	v_readlane_b32 s1, v254, 50
	v_mov_b32_e32 v43, v42
	s_nop 0
	v_lshl_add_u64 v[32:33], s[0:1], 0, v[32:33]
	global_load_dwordx4 v[36:39], v[32:33], off offset:16
	s_nop 0
	global_load_dwordx4 v[32:35], v[32:33], off
	v_mad_i64_i32 v[46:47], s[0:1], v56, s78, v[46:47]
	v_lshl_add_u64 v[46:47], v[196:197], 1, v[46:47]
	s_and_saveexec_b64 s[0:1], vcc
	s_cbranch_execz .LBB0_882
	v_pk_fma_f32 v[28:29], v[108:109], v[40:41], v[28:29] neg_lo:[1,0,0] neg_hi:[1,0,0]
	v_mov_b32_e32 v48, v40
	v_pk_fma_f32 v[28:29], v[28:29], v[42:43], v[104:105]
	v_mov_b32_e32 v49, v40
	v_pk_fma_f32 v[30:31], v[198:199], v[40:41], v[30:31]
	v_mov_b32_e32 v50, v42
	v_mov_b32_e32 v51, v42
	v_pk_fma_f32 v[30:31], v[30:31], v[42:43], v[106:107]
	v_cvt_pk_bf16_f32 v28, v28, v29
	v_pk_fma_f32 v[24:25], v[100:101], v[40:41], v[24:25] neg_lo:[1,0,0] neg_hi:[1,0,0]
	v_pk_fma_f32 v[24:25], v[24:25], v[42:43], v[96:97]
	v_cvt_pk_bf16_f32 v29, v30, v31
	v_pk_fma_f32 v[26:27], v[102:103], v[40:41], v[26:27]
	v_pk_fma_f32 v[26:27], v[26:27], v[42:43], v[98:99]
	v_cvt_pk_bf16_f32 v30, v24, v25
	v_cvt_pk_bf16_f32 v31, v26, v27
	global_store_dwordx4 v[46:47], v[28:31], off
.LBB0_882:
	s_or_b64 exec, exec, s[0:1]
	s_and_saveexec_b64 s[0:1], s[40:41]
	s_cbranch_execz .LBB0_884
	v_pk_fma_f32 v[20:21], v[92:93], v[40:41], v[20:21] neg_lo:[1,0,0] neg_hi:[1,0,0]
	v_pk_fma_f32 v[20:21], v[20:21], v[42:43], v[88:89]
	v_pk_fma_f32 v[22:23], v[94:95], v[40:41], v[22:23]
	v_pk_fma_f32 v[22:23], v[22:23], v[42:43], v[90:91]
	v_cvt_pk_bf16_f32 v20, v20, v21
	v_pk_fma_f32 v[16:17], v[84:85], v[40:41], v[16:17] neg_lo:[1,0,0] neg_hi:[1,0,0]
	v_pk_fma_f32 v[16:17], v[16:17], v[42:43], v[80:81]
	v_cvt_pk_bf16_f32 v21, v22, v23
	v_pk_fma_f32 v[18:19], v[86:87], v[40:41], v[18:19]
	v_pk_fma_f32 v[18:19], v[18:19], v[42:43], v[82:83]
	v_cvt_pk_bf16_f32 v22, v16, v17
	v_cvt_pk_bf16_f32 v23, v18, v19
	global_store_dwordx4 v[46:47], v[20:23], off offset:256
.LBB0_884:
	s_or_b64 exec, exec, s[0:1]
	s_waitcnt vmcnt(0)
	v_pk_add_f32 v[16:17], v[36:37], v[38:39]
	v_pk_add_f32 v[18:19], v[32:33], v[34:35]
	s_mov_b32 s0, 0x3a800000
	v_pk_add_f32 v[16:17], v[18:19], v[16:17]
	s_nop 0
	v_pk_mul_f32 v[18:19], v[16:17], s[0:1] op_sel_hi:[1,0]
	s_nop 0
	v_fma_f32 v16, -v18, v18, v19
	v_max_f32_e32 v16, 0, v16
	v_add_f32_e32 v16, 0x3727c5ac, v16
	v_mul_f32_e32 v17, 0x4b800000, v16
	v_cmp_gt_f32_e64 s[0:1], s77, v16
	v_mov_b32_e32 v19, v18
	s_nop 0
	v_cndmask_b32_e64 v16, v16, v17, s[0:1]
	v_rsq_f32_e32 v16, v16
	s_nop 0
	v_mul_f32_e32 v17, 0x45800000, v16
	v_cndmask_b32_e64 v20, v16, v17, s[0:1]
	v_mov_b64_e32 v[16:17], s[24:25]
	v_mad_i64_i32 v[16:17], s[0:1], v44, s78, v[16:17]
	v_lshl_add_u64 v[16:17], v[196:197], 1, v[16:17]
	v_mov_b32_e32 v21, v20
	s_and_saveexec_b64 s[0:1], vcc
	s_cbranch_execz .LBB0_886
	v_pk_fma_f32 v[12:13], v[108:109], v[18:19], v[12:13] neg_lo:[1,0,0] neg_hi:[1,0,0]
	v_pk_fma_f32 v[12:13], v[12:13], v[20:21], v[104:105]
	v_pk_fma_f32 v[14:15], v[198:199], v[18:19], v[14:15]
	v_pk_fma_f32 v[14:15], v[14:15], v[20:21], v[106:107]
	v_cvt_pk_bf16_f32 v12, v12, v13
	v_pk_fma_f32 v[8:9], v[100:101], v[18:19], v[8:9] neg_lo:[1,0,0] neg_hi:[1,0,0]
	v_pk_fma_f32 v[8:9], v[8:9], v[20:21], v[96:97]
	v_cvt_pk_bf16_f32 v13, v14, v15
	v_pk_fma_f32 v[10:11], v[102:103], v[18:19], v[10:11]
	v_pk_fma_f32 v[10:11], v[10:11], v[20:21], v[98:99]
	v_cvt_pk_bf16_f32 v14, v8, v9
	v_cvt_pk_bf16_f32 v15, v10, v11
	global_store_dwordx4 v[16:17], v[12:15], off
.LBB0_886:
	s_or_b64 exec, exec, s[0:1]
	s_and_saveexec_b64 s[0:1], s[40:41]
	s_cbranch_execz .LBB0_888
	v_pk_fma_f32 v[4:5], v[92:93], v[18:19], v[4:5] neg_lo:[1,0,0] neg_hi:[1,0,0]
	v_pk_fma_f32 v[4:5], v[4:5], v[20:21], v[88:89]
	v_pk_fma_f32 v[6:7], v[94:95], v[18:19], v[6:7]
	v_pk_fma_f32 v[6:7], v[6:7], v[20:21], v[90:91]
	v_cvt_pk_bf16_f32 v4, v4, v5
	v_pk_fma_f32 v[0:1], v[84:85], v[18:19], v[0:1] neg_lo:[1,0,0] neg_hi:[1,0,0]
	v_pk_fma_f32 v[0:1], v[0:1], v[20:21], v[80:81]
	v_cvt_pk_bf16_f32 v5, v6, v7
	v_pk_fma_f32 v[2:3], v[86:87], v[18:19], v[2:3]
	v_pk_fma_f32 v[2:3], v[2:3], v[20:21], v[82:83]
	v_cvt_pk_bf16_f32 v6, v0, v1
	v_cvt_pk_bf16_f32 v7, v2, v3
	global_store_dwordx4 v[16:17], v[4:7], off offset:256

.LBB0_1682:
	global_load_dwordx4 v[8:11], v[4:5], off
	v_add_u32_e32 v2, s2, v2
	s_mov_b32 s3, 0x7ffff
	v_cmp_lt_i32_e32 vcc, s3, v2
	v_lshl_add_u64 v[4:5], v[4:5], 0, s[20:21]
	s_or_b64 s[26:27], vcc, s[26:27]
	s_waitcnt vmcnt(0)
	v_cvt_pk_bf16_f32 v8, v8, v9
	v_cvt_pk_bf16_f32 v9, v10, v11
	global_store_dwordx2 v[6:7], v[8:9], off
	v_lshl_add_u64 v[6:7], v[6:7], 0, s[24:25]
	s_andn2_b64 exec, exec, s[26:27]
	s_cbranch_execnz .LBB0_1682

.LBB0_1730:
	v_and_b32_e32 v18, 64, v224
	v_xor_b32_e32 v20, 1, v224
	v_add_u32_e32 v26, 64, v18
	v_xor_b32_e32 v21, 2, v224
	v_cmp_lt_i32_e32 vcc, v20, v26
	v_xor_b32_e32 v22, 4, v224
	v_xor_b32_e32 v23, 8, v224
	v_cndmask_b32_e32 v20, v224, v20, vcc
	v_cmp_lt_i32_e32 vcc, v21, v26
	v_add_u32_e32 v16, 0x8000, v28
	s_mov_b64 s[0:1], 0
	v_cndmask_b32_e32 v21, v224, v21, vcc
	v_cmp_lt_i32_e32 vcc, v22, v26
	s_mov_b64 s[38:39], 0
	v_xor_b32_e32 v24, 16, v224
	v_cndmask_b32_e32 v22, v224, v22, vcc
	v_cmp_lt_i32_e32 vcc, v23, v26
	v_xor_b32_e32 v25, 32, v224
	v_ashrrev_i32_e32 v17, 31, v16
	global_load_dwordx4 v[12:15], v[40:41], off
	global_load_dwordx4 v[8:11], v[40:41], off offset:1024
	global_load_dwordx4 v[4:7], v[40:41], off offset:2048
	global_load_dwordx4 v[0:3], v[40:41], off offset:3072
	v_cndmask_b32_e32 v23, v224, v23, vcc
	v_cmp_lt_i32_e32 vcc, v24, v26
	v_lshlrev_b64 v[18:19], 12, v[16:17]
	v_lshlrev_b64 v[16:17], 11, v[16:17]
	v_cndmask_b32_e32 v24, v224, v24, vcc
	v_cmp_lt_i32_e32 vcc, v25, v26
	v_lshl_add_u64 v[44:45], v[34:35], 0, s[0:1]
	v_lshl_add_u64 v[18:19], v[30:31], 0, v[18:19]
	v_cndmask_b32_e32 v25, v224, v25, vcc
	v_lshl_add_u64 v[46:47], v[36:37], 0, s[38:39]
	v_lshlrev_b32_e32 v29, 2, v20
	v_lshlrev_b32_e32 v80, 2, v21
	v_lshlrev_b32_e32 v81, 2, v22
	v_lshlrev_b32_e32 v82, 2, v23
	v_lshlrev_b32_e32 v83, 2, v24
	v_lshlrev_b32_e32 v84, 2, v25
	v_lshl_add_u64 v[42:43], v[32:33], 0, v[16:17]
	global_load_dwordx4 v[48:51], v[44:45], off
	global_load_dwordx4 v[52:55], v[46:47], off
	global_load_dwordx4 v[56:59], v[18:19], off
	global_load_dwordx4 v[24:27], v[18:19], off offset:1024
	global_load_dwordx4 v[20:23], v[18:19], off offset:2048
	s_nop 0
	global_load_dwordx4 v[16:19], v[18:19], off offset:3072
	v_add_u32_e32 v28, s22, v28
	v_lshl_add_u64 v[40:41], v[40:41], 0, s[24:25]
	s_waitcnt vmcnt(9)
	v_mov_b32_e32 v60, v13
	v_mov_b32_e32 v61, v14
	v_mov_b32_e32 v62, v12
	v_mov_b32_e32 v63, v15
	s_waitcnt vmcnt(8)
	v_mov_b32_e32 v64, v9
	v_mov_b32_e32 v65, v10
	v_mov_b32_e32 v66, v8
	v_mov_b32_e32 v67, v11
	v_pk_add_f32 v[60:61], v[60:61], v[62:63]
	v_pk_add_f32 v[62:63], v[64:65], v[66:67]
	s_waitcnt vmcnt(7)
	v_add_f32_e32 v68, v4, v5
	v_add_f32_e32 v70, v6, v7
	s_waitcnt vmcnt(6)
	v_mov_b32_e32 v69, v2
	v_mov_b32_e32 v71, v3
	v_add_f32_e32 v66, v60, v61
	v_pk_add_f32 v[60:61], v[62:63], v[62:63] op_sel:[0,1] op_sel_hi:[1,0]
	v_mov_b32_e32 v73, v0
	v_pk_add_f32 v[64:65], v[68:69], v[70:71]
	v_add_f32_e32 v72, 0, v66
	s_waitcnt vmcnt(3)
	v_mov_b32_e32 v62, v57
	v_mov_b32_e32 v63, v58
	v_mov_b32_e32 v66, v56
	v_mov_b32_e32 v67, v59
	s_waitcnt vmcnt(2)
	v_mov_b32_e32 v68, v25
	v_mov_b32_e32 v69, v26
	v_mov_b32_e32 v70, v24
	v_mov_b32_e32 v71, v27
	v_mov_b32_e32 v61, v1
	v_pk_add_f32 v[62:63], v[62:63], v[66:67]
	v_pk_add_f32 v[66:67], v[68:69], v[70:71]
	v_pk_add_f32 v[60:61], v[72:73], v[60:61]
	v_add_f32_e32 v70, v62, v63
	v_pk_add_f32 v[62:63], v[66:67], v[66:67] op_sel:[0,1] op_sel_hi:[1,0]
	v_pk_add_f32 v[60:61], v[60:61], v[64:65]
	s_waitcnt vmcnt(1)
	v_add_f32_e32 v74, v20, v21
	v_add_f32_e32 v76, v22, v23
	s_waitcnt vmcnt(0)
	v_mov_b32_e32 v79, v16
	v_mov_b32_e32 v75, v18
	v_mov_b32_e32 v77, v19
	v_add_f32_e32 v78, 0, v70
	v_add_f32_e32 v64, v60, v61
	v_mov_b32_e32 v63, v17
	v_pk_add_f32 v[68:69], v[74:75], v[76:77]
	ds_bpermute_b32 v65, v29, v64
	v_pk_add_f32 v[60:61], v[78:79], v[62:63]
	s_waitcnt lgkmcnt(0)
	v_add_f32_e32 v62, v64, v65
	v_pk_add_f32 v[60:61], v[60:61], v[68:69]
	ds_bpermute_b32 v63, v80, v62
	v_add_f32_e32 v60, v60, v61
	ds_bpermute_b32 v61, v29, v60
	s_waitcnt lgkmcnt(1)
	v_add_f32_e32 v62, v62, v63
	ds_bpermute_b32 v63, v81, v62
	s_waitcnt lgkmcnt(1)
	v_add_f32_e32 v60, v60, v61
	ds_bpermute_b32 v61, v80, v60
	s_waitcnt lgkmcnt(1)
	v_add_f32_e32 v62, v62, v63
	ds_bpermute_b32 v63, v82, v62
	s_waitcnt lgkmcnt(1)
	v_add_f32_e32 v60, v60, v61
	ds_bpermute_b32 v61, v81, v60
	s_waitcnt lgkmcnt(1)
	v_add_f32_e32 v62, v62, v63
	ds_bpermute_b32 v63, v83, v62
	s_waitcnt lgkmcnt(1)
	v_add_f32_e32 v60, v60, v61
	ds_bpermute_b32 v61, v82, v60
	s_waitcnt lgkmcnt(1)
	v_add_f32_e32 v62, v62, v63
	ds_bpermute_b32 v63, v84, v62
	s_waitcnt lgkmcnt(1)
	v_add_f32_e32 v60, v60, v61
	ds_bpermute_b32 v61, v83, v60
	s_waitcnt lgkmcnt(1)
	v_add_f32_e32 v62, v62, v63
	v_fmamk_f32 v13, v62, 0xba800000, v13
	s_waitcnt lgkmcnt(0)
	v_add_f32_e32 v69, v60, v61
	ds_bpermute_b32 v71, v84, v69
	v_fmamk_f32 v12, v62, 0xba800000, v12
	v_fmamk_f32 v15, v62, 0xba800000, v15
	v_fmac_f32_e32 v14, 0xba800000, v62
	v_fmamk_f32 v9, v62, 0xba800000, v9
	v_fmamk_f32 v8, v62, 0xba800000, v8
	v_fmamk_f32 v11, v62, 0xba800000, v11
	v_fmac_f32_e32 v10, 0xba800000, v62
	v_fmamk_f32 v61, v62, 0xba800000, v5
	v_fmamk_f32 v60, v62, 0xba800000, v4
	v_fmamk_f32 v7, v62, 0xba800000, v7
	v_fmac_f32_e32 v6, 0xba800000, v62
	v_fmamk_f32 v3, v62, 0xba800000, v3
	v_fmamk_f32 v2, v62, 0xba800000, v2
	v_fmamk_f32 v1, v62, 0xba800000, v1
	v_fmac_f32_e32 v0, 0xba800000, v62
	v_pk_mul_f32 v[4:5], v[14:15], v[14:15]
	v_pk_mul_f32 v[62:63], v[12:13], v[12:13]
	v_pk_mul_f32 v[64:65], v[10:11], v[10:11]
	v_pk_mul_f32 v[66:67], v[8:9], v[8:9]
	v_mul_f32_e32 v68, v60, v60
	v_mul_f32_e32 v70, v6, v6
	s_waitcnt lgkmcnt(0)
	v_add_f32_e32 v74, v69, v71
	v_pk_mov_b32 v[72:73], v[62:63], v[4:5] op_sel:[1,0]
	v_mov_b32_e32 v63, v5
	v_pk_mov_b32 v[4:5], v[66:67], v[64:65] op_sel:[1,0]
	v_mov_b32_e32 v67, v65
	v_pk_fma_f32 v[64:65], v[60:61], v[60:61], v[68:69] op_sel_hi:[1,1,0]
	v_pk_fma_f32 v[68:69], v[6:7], v[6:7], v[70:71] op_sel_hi:[1,1,0]
	v_fmamk_f32 v57, v74, 0xba800000, v57
	v_fmamk_f32 v56, v74, 0xba800000, v56
	v_fmamk_f32 v59, v74, 0xba800000, v59
	v_fmac_f32_e32 v58, 0xba800000, v74
	v_pk_add_f32 v[62:63], v[62:63], v[72:73]
	v_fmamk_f32 v25, v74, 0xba800000, v25
	v_fmamk_f32 v24, v74, 0xba800000, v24
	v_fmamk_f32 v27, v74, 0xba800000, v27
	v_fmac_f32_e32 v26, 0xba800000, v74
	v_pk_add_f32 v[66:67], v[66:67], v[4:5]
	v_fmamk_f32 v71, v74, 0xba800000, v21
	v_fmamk_f32 v70, v74, 0xba800000, v20
	v_fmamk_f32 v23, v74, 0xba800000, v23
	v_fmac_f32_e32 v22, 0xba800000, v74
	v_fmamk_f32 v5, v74, 0xba800000, v19
	v_fmamk_f32 v4, v74, 0xba800000, v18
	v_fmamk_f32 v17, v74, 0xba800000, v17
	v_fmac_f32_e32 v16, 0xba800000, v74
	v_mul_f32_e32 v64, v0, v0
	v_mul_f32_e32 v68, v1, v1
	v_pk_add_f32 v[18:19], v[62:63], v[62:63] op_sel_hi:[0,1]
	v_pk_mul_f32 v[20:21], v[58:59], v[58:59]
	v_pk_mul_f32 v[62:63], v[56:57], v[56:57]
	v_pk_mul_f32 v[72:73], v[26:27], v[26:27]
	v_pk_mul_f32 v[74:75], v[24:25], v[24:25]
	v_pk_add_f32 v[66:67], v[66:67], v[66:67] op_sel_hi:[0,1]
	v_pk_add_f32 v[64:65], v[64:65], v[68:69]
	v_pk_mov_b32 v[68:69], v[62:63], v[20:21] op_sel:[1,0]
	v_mov_b32_e32 v63, v21
	v_pk_mov_b32 v[20:21], v[74:75], v[72:73] op_sel:[1,0]
	v_mov_b32_e32 v75, v73
	v_mul_f32_e32 v18, v70, v70
	v_mul_f32_e32 v66, v22, v22
	v_pk_add_f32 v[62:63], v[68:69], v[62:63]
	v_pk_add_f32 v[20:21], v[20:21], v[74:75]
	v_pk_fma_f32 v[72:73], v[70:71], v[70:71], v[18:19] op_sel_hi:[1,1,0]
	v_pk_fma_f32 v[76:77], v[22:23], v[22:23], v[66:67] op_sel_hi:[1,1,0]
	v_mul_f32_e32 v66, v2, v2
	v_mul_f32_e32 v18, v3, v3
	v_pk_add_f32 v[62:63], v[62:63], v[62:63] op_sel_hi:[0,1]
	v_pk_add_f32 v[20:21], v[20:21], v[20:21] op_sel_hi:[0,1]
	v_pk_add_f32 v[18:19], v[18:19], v[66:67]
	v_mul_f32_e32 v72, v16, v16
	v_mul_f32_e32 v76, v17, v17
	v_mul_f32_e32 v62, v4, v4
	v_mul_f32_e32 v20, v5, v5
	v_pk_add_f32 v[18:19], v[64:65], v[18:19]
	v_pk_add_f32 v[64:65], v[72:73], v[76:77]
	v_pk_add_f32 v[20:21], v[62:63], v[20:21]
	v_mov_b32_e32 v67, v18
	v_pk_add_f32 v[20:21], v[64:65], v[20:21]
	s_nop 0
	v_mov_b32_e32 v66, v20
	v_mov_b32_e32 v18, v21
	v_pk_add_f32 v[18:19], v[66:67], v[18:19]
	ds_bpermute_b32 v21, v29, v19
	ds_bpermute_b32 v20, v29, v18
	s_waitcnt lgkmcnt(0)
	v_pk_add_f32 v[18:19], v[18:19], v[20:21]
	ds_bpermute_b32 v21, v80, v19
	ds_bpermute_b32 v20, v80, v18
	s_waitcnt lgkmcnt(0)
	v_pk_add_f32 v[18:19], v[18:19], v[20:21]
	ds_bpermute_b32 v21, v81, v19
	ds_bpermute_b32 v20, v81, v18
	s_waitcnt lgkmcnt(0)
	v_pk_add_f32 v[18:19], v[18:19], v[20:21]
	ds_bpermute_b32 v21, v82, v19
	ds_bpermute_b32 v20, v82, v18
	s_waitcnt lgkmcnt(0)
	v_pk_add_f32 v[18:19], v[18:19], v[20:21]
	ds_bpermute_b32 v21, v83, v19
	ds_bpermute_b32 v20, v83, v18
	s_waitcnt lgkmcnt(0)
	v_pk_add_f32 v[18:19], v[18:19], v[20:21]
	ds_bpermute_b32 v21, v84, v19
	ds_bpermute_b32 v20, v84, v18
	s_waitcnt lgkmcnt(0)
	v_pk_add_f32 v[18:19], v[18:19], v[20:21]
	s_nop 0
	v_pk_fma_f32 v[18:19], v[18:19], s[40:41], v[180:181] op_sel_hi:[1,0,0]
	s_nop 0
	v_mul_f32_e32 v20, 0x4b800000, v19
	v_cmp_gt_f32_e64 s[0:1], s34, v19
	v_mul_f32_e32 v21, 0x4b800000, v18
	v_cmp_gt_f32_e32 vcc, s34, v18
	v_cndmask_b32_e64 v19, v19, v20, s[0:1]
	v_rsq_f32_e32 v19, v19
	v_cndmask_b32_e32 v18, v18, v21, vcc
	v_rsq_f32_e32 v18, v18
	v_mul_f32_e32 v20, 0x45800000, v19
	v_cndmask_b32_e64 v62, v19, v20, s[0:1]
	v_mul_f32_e32 v21, 0x45800000, v18
	v_cndmask_b32_e32 v64, v18, v21, vcc
	v_pk_mul_f32 v[12:13], v[12:13], v[62:63] op_sel_hi:[1,0]
	v_pk_mul_f32 v[14:15], v[14:15], v[62:63] op_sel_hi:[1,0]
	v_pk_mul_f32 v[18:19], v[56:57], v[64:65] op_sel_hi:[1,0]
	v_pk_mul_f32 v[20:21], v[58:59], v[64:65] op_sel_hi:[1,0]
	v_pk_fma_f32 v[14:15], v[50:51], v[14:15], v[54:55]
	v_pk_fma_f32 v[12:13], v[48:49], v[12:13], v[52:53]
	v_pk_fma_f32 v[20:21], v[50:51], v[20:21], v[54:55]
	v_pk_fma_f32 v[18:19], v[48:49], v[18:19], v[52:53]
	v_cvt_pk_bf16_f32 v12, v12, v13
	v_cvt_pk_bf16_f32 v13, v14, v15
	v_cvt_pk_bf16_f32 v14, v18, v19
	v_cvt_pk_bf16_f32 v15, v20, v21
	global_store_dwordx2 v[38:39], v[12:13], off offset:-1024
	global_store_dwordx2 v[42:43], v[14:15], off
	global_load_dwordx4 v[12:15], v[44:45], off offset:1024
	s_nop 0
	global_load_dwordx4 v[18:21], v[46:47], off offset:1024
	v_pk_mul_f32 v[8:9], v[8:9], v[62:63] op_sel_hi:[1,0]
	v_pk_mul_f32 v[10:11], v[10:11], v[62:63] op_sel_hi:[1,0]
	v_pk_mul_f32 v[24:25], v[24:25], v[64:65] op_sel_hi:[1,0]
	v_pk_mul_f32 v[26:27], v[26:27], v[64:65] op_sel_hi:[1,0]
	v_pk_mul_f32 v[6:7], v[6:7], v[62:63] op_sel_hi:[1,0]
	v_pk_mul_f32 v[22:23], v[22:23], v[64:65] op_sel_hi:[1,0]
	v_pk_mul_f32 v[0:1], v[0:1], v[62:63] op_sel_hi:[1,0]
	v_pk_mul_f32 v[2:3], v[2:3], v[62:63] op_sel_hi:[1,0]
	v_pk_mul_f32 v[4:5], v[4:5], v[64:65] op_sel_hi:[1,0]
	v_cmp_lt_i32_e32 vcc, s96, v28
	s_or_b64 s[26:27], vcc, s[26:27]
	s_waitcnt vmcnt(0)
	v_pk_fma_f32 v[10:11], v[14:15], v[10:11], v[20:21]
	v_pk_fma_f32 v[8:9], v[12:13], v[8:9], v[18:19]
	v_pk_fma_f32 v[14:15], v[14:15], v[26:27], v[20:21]
	v_pk_fma_f32 v[12:13], v[12:13], v[24:25], v[18:19]
	v_cvt_pk_bf16_f32 v8, v8, v9
	v_cvt_pk_bf16_f32 v9, v10, v11
	v_cvt_pk_bf16_f32 v10, v12, v13
	v_cvt_pk_bf16_f32 v11, v14, v15
	global_store_dwordx2 v[38:39], v[8:9], off offset:-512
	global_store_dwordx2 v[42:43], v[10:11], off offset:512
	global_load_dwordx4 v[8:11], v[44:45], off offset:2048
	s_nop 0
	global_load_dwordx4 v[12:15], v[46:47], off offset:2048
	v_pk_mul_f32 v[18:19], v[60:61], v[62:63] op_sel_hi:[1,0]
	v_pk_mul_f32 v[20:21], v[70:71], v[64:65] op_sel_hi:[1,0]
	s_waitcnt vmcnt(0)
	v_pk_fma_f32 v[6:7], v[10:11], v[6:7], v[14:15]
	v_pk_fma_f32 v[18:19], v[8:9], v[18:19], v[12:13]
	v_pk_fma_f32 v[10:11], v[10:11], v[22:23], v[14:15]
	v_pk_fma_f32 v[8:9], v[8:9], v[20:21], v[12:13]
	v_cvt_pk_bf16_f32 v7, v6, v7
	v_cvt_pk_bf16_f32 v6, v18, v19
	v_cvt_pk_bf16_f32 v8, v8, v9
	v_cvt_pk_bf16_f32 v9, v10, v11
	global_store_dwordx2 v[38:39], v[6:7], off
	global_store_dwordx2 v[42:43], v[8:9], off offset:1024
	global_load_dwordx4 v[6:9], v[44:45], off offset:3072
	s_nop 0
	global_load_dwordx4 v[10:13], v[46:47], off offset:3072
	v_pk_mul_f32 v[14:15], v[16:17], v[64:65] op_sel_hi:[1,0]
	s_waitcnt vmcnt(0)
	v_pk_fma_f32 v[2:3], v[8:9], v[2:3], v[12:13]
	v_pk_fma_f32 v[0:1], v[6:7], v[0:1], v[10:11]
	v_pk_fma_f32 v[4:5], v[8:9], v[4:5], v[12:13]
	v_pk_fma_f32 v[6:7], v[6:7], v[14:15], v[10:11]
	v_cvt_pk_bf16_f32 v0, v0, v1
	v_cvt_pk_bf16_f32 v1, v2, v3
	v_cvt_pk_bf16_f32 v2, v6, v7
	v_cvt_pk_bf16_f32 v3, v4, v5
	global_store_dwordx2 v[38:39], v[0:1], off offset:512
	global_store_dwordx2 v[42:43], v[2:3], off offset:1536
	v_lshl_add_u64 v[38:39], v[38:39], 0, s[20:21]
	s_andn2_b64 exec, exec, s[26:27]
	s_cbranch_execnz .LBB0_1730

.LBB0_1804:
	s_or_b64 exec, exec, s[2:3]
	v_lshlrev_b64 v[44:45], 2, v[98:99]
	v_lshl_add_u64 v[16:17], s[22:23], 0, v[44:45]
	s_mov_b64 s[2:3], 0x1800
	v_lshl_add_u64 v[12:13], v[16:17], 0, s[2:3]
	s_movk_i32 s2, 0x1000
	v_add_co_u32_e32 v14, vcc, s2, v16
	s_mov_b64 s[2:3], 0x2400
	s_nop 0
	v_addc_co_u32_e32 v15, vcc, 0, v17, vcc
	v_lshl_add_u64 v[18:19], v[16:17], 0, s[2:3]
	s_movk_i32 s2, 0x2000
	v_add_co_u32_e32 v20, vcc, s2, v16
	s_mov_b64 s[2:3], 0x3000
	s_nop 0
	v_addc_co_u32_e32 v21, vcc, 0, v17, vcc
	global_load_dwordx4 v[4:7], v[16:17], off offset:16
	global_load_dwordx4 v[24:27], v[16:17], off
	global_load_dwordx4 v[8:11], v[16:17], off offset:3088
	global_load_dwordx4 v[28:31], v[16:17], off offset:3072
	global_load_dwordx4 v[32:35], v[14:15], off offset:2048
	s_nop 0
	global_load_dwordx4 v[12:15], v[12:13], off offset:16
	s_nop 0
	global_load_dwordx4 v[40:43], v[20:21], off offset:1024
	s_nop 0
	global_load_dwordx4 v[20:23], v[18:19], off offset:16
	v_lshl_add_u64 v[18:19], v[16:17], 0, s[2:3]
	s_movk_i32 s2, 0x3000
	v_add_co_u32_e32 v16, vcc, s2, v16
	v_lshl_add_u64 v[52:53], s[26:27], 0, v[44:45]
	s_nop 0
	v_addc_co_u32_e32 v17, vcc, 0, v17, vcc
	global_load_dwordx4 v[36:39], v[16:17], off
	s_nop 0
	global_load_dwordx4 v[16:19], v[18:19], off offset:16
	s_nop 0
	global_load_dwordx4 v[44:47], v[52:53], off offset:16
	s_nop 0
	global_load_dwordx4 v[52:55], v[52:53], off
	s_waitcnt vmcnt(0)
	v_and_b32_e32 v125, 0xffff0000, v89
	v_and_b32_e32 v124, 0xffff0000, v88
	v_lshlrev_b32_e32 v103, 16, v89
	v_lshlrev_b32_e32 v102, 16, v88
	v_lshlrev_b32_e32 v89, 16, v85
	v_lshlrev_b32_e32 v88, 16, v84
	v_and_b32_e32 v85, 0xffff0000, v85
	v_and_b32_e32 v84, 0xffff0000, v84
	v_lshlrev_b32_e32 v106, 16, v94
	v_and_b32_e32 v104, 0xffff0000, v94
	v_lshlrev_b32_e32 v107, 16, v95
	v_and_b32_e32 v105, 0xffff0000, v95
	v_lshlrev_b32_e32 v108, 16, v92
	v_and_b32_e32 v92, 0xffff0000, v92
	v_lshlrev_b32_e32 v109, 16, v93
	v_and_b32_e32 v93, 0xffff0000, v93
	v_lshlrev_b32_e32 v111, 16, v91
	v_lshlrev_b32_e32 v110, 16, v90
	v_and_b32_e32 v113, 0xffff0000, v91
	v_and_b32_e32 v112, 0xffff0000, v90
	v_lshlrev_b32_e32 v91, 16, v87
	v_lshlrev_b32_e32 v90, 16, v86
	v_and_b32_e32 v115, 0xffff0000, v87
	v_and_b32_e32 v114, 0xffff0000, v86
	v_lshl_add_u64 v[98:99], v[98:99], 1, s[38:39]
	s_movk_i32 s21, 0x600
	v_add_u32_e32 v97, s34, v97
	v_add_u32_e32 v96, s20, v96
	v_mov_b32_e32 v101, v26
	v_mov_b32_e32 v26, v25
	v_mov_b32_e32 v25, v6
	v_mov_b32_e32 v6, v5
	v_mov_b32_e32 v100, v24
	v_mov_b32_e32 v24, v4
	v_mov_b32_e32 v5, v54
	v_mov_b32_e32 v54, v53
	v_pk_fma_f32 v[94:95], v[26:27], v[124:125], v[54:55]
	v_mov_b32_e32 v53, v30
	v_mov_b32_e32 v30, v29
	v_mov_b32_e32 v4, v52
	v_pk_fma_f32 v[94:95], v[30:31], v[84:85], v[94:95]
	v_mov_b32_e32 v29, v34
	v_mov_b32_e32 v34, v33
	v_pk_fma_f32 v[86:87], v[100:101], v[102:103], v[4:5]
	v_pk_fma_f32 v[124:125], v[34:35], v[92:93], v[94:95]
	v_mov_b32_e32 v33, v42
	v_and_b32_e32 v103, 0xffff0000, v81
	v_and_b32_e32 v102, 0xffff0000, v80
	v_mov_b32_e32 v42, v41
	v_lshlrev_b32_e32 v95, 16, v81
	v_lshlrev_b32_e32 v94, 16, v80
	v_pk_fma_f32 v[124:125], v[42:43], v[102:103], v[124:125]
	v_lshlrev_b32_e32 v81, 16, v77
	v_lshlrev_b32_e32 v80, 16, v76
	v_mov_b32_e32 v41, v38
	v_and_b32_e32 v77, 0xffff0000, v77
	v_and_b32_e32 v76, 0xffff0000, v76
	v_mov_b32_e32 v38, v37
	v_mov_b32_e32 v52, v28
	v_mov_b32_e32 v28, v32
	v_mov_b32_e32 v32, v40
	v_mov_b32_e32 v40, v36
	v_pk_fma_f32 v[36:37], v[38:39], v[76:77], v[124:125]
	v_pk_fma_f32 v[86:87], v[52:53], v[88:89], v[86:87]
	v_mul_f32_e32 v125, 0xbfb8aa3b, v36
	v_exp_f32_e32 v125, v125
	v_pk_fma_f32 v[86:87], v[28:29], v[108:109], v[86:87]
	v_add_f32_e32 v125, 1.0, v125
	v_pk_fma_f32 v[86:87], v[32:33], v[94:95], v[86:87]
	v_rcp_f32_e32 v126, v125
	v_pk_fma_f32 v[86:87], v[40:41], v[80:81], v[86:87]
	s_nop 0
	v_mul_f32_e32 v124, 0xbfb8aa3b, v86
	v_mul_f32_e32 v125, 0xbfb8aa3b, v87
	v_exp_f32_e32 v124, v124
	v_exp_f32_e32 v125, v125
	v_add_f32_e32 v124, 1.0, v124
	v_add_f32_e32 v125, 1.0, v125
	v_rcp_f32_e32 v124, v124
	v_rcp_f32_e32 v125, v125
	s_nop 0
	v_pk_mul_f32 v[124:125], v[86:87], v[124:125]
	v_mul_f32_e32 v86, 0xbfb8aa3b, v37
	v_exp_f32_e32 v86, v86
	s_nop 0
	v_add_f32_e32 v86, 1.0, v86
	v_rcp_f32_e32 v127, v86
	s_nop 0
	v_pk_mul_f32 v[126:127], v[36:37], v[126:127]
	v_mov_b32_e32 v36, v44
	v_mov_b32_e32 v37, v46
	v_mov_b32_e32 v46, v45
	v_pk_fma_f32 v[86:87], v[24:25], v[110:111], v[36:37]
	v_pk_fma_f32 v[110:111], v[6:7], v[112:113], v[46:47]
	v_mov_b32_e32 v44, v8
	v_mov_b32_e32 v45, v10
	v_mov_b32_e32 v10, v9
	v_pk_fma_f32 v[86:87], v[44:45], v[90:91], v[86:87]
	v_pk_fma_f32 v[110:111], v[10:11], v[114:115], v[110:111]
	v_mov_b32_e32 v8, v12
	v_mov_b32_e32 v9, v14
	v_mov_b32_e32 v14, v13
	v_pk_fma_f32 v[86:87], v[8:9], v[106:107], v[86:87]
	v_pk_fma_f32 v[128:129], v[14:15], v[104:105], v[110:111]
	v_lshlrev_b32_e32 v111, 16, v83
	v_lshlrev_b32_e32 v110, 16, v82
	v_mov_b32_e32 v12, v20
	v_mov_b32_e32 v13, v22
	v_pk_fma_f32 v[86:87], v[12:13], v[110:111], v[86:87]
	v_and_b32_e32 v113, 0xffff0000, v83
	v_and_b32_e32 v112, 0xffff0000, v82
	v_mov_b32_e32 v22, v21
	v_lshlrev_b32_e32 v83, 16, v79
	v_lshlrev_b32_e32 v82, 16, v78
	v_mov_b32_e32 v20, v16
	v_mov_b32_e32 v21, v18
	v_pk_fma_f32 v[128:129], v[22:23], v[112:113], v[128:129]
	v_pk_fma_f32 v[130:131], v[20:21], v[82:83], v[86:87]
	v_and_b32_e32 v87, 0xffff0000, v79
	v_and_b32_e32 v86, 0xffff0000, v78
	v_mov_b32_e32 v18, v17
	v_pk_fma_f32 v[16:17], v[18:19], v[86:87], v[128:129]
	v_mul_f32_e32 v78, 0xbfb8aa3b, v130
	v_mul_f32_e32 v79, 0xbfb8aa3b, v16
	v_exp_f32_e32 v79, v79
	v_mul_f32_e32 v129, 0xbfb8aa3b, v17
	v_exp_f32_e32 v129, v129
	v_exp_f32_e32 v78, v78
	v_add_f32_e32 v79, 1.0, v79
	v_rcp_f32_e32 v128, v79
	v_mul_f32_e32 v79, 0xbfb8aa3b, v131
	v_exp_f32_e32 v79, v79
	v_add_f32_e32 v129, 1.0, v129
	v_add_f32_e32 v78, 1.0, v78
	v_rcp_f32_e32 v129, v129
	v_add_f32_e32 v79, 1.0, v79
	v_rcp_f32_e32 v78, v78
	v_rcp_f32_e32 v79, v79
	v_pk_mul_f32 v[16:17], v[16:17], v[128:129]
	v_pk_mul_f32 v[78:79], v[130:131], v[78:79]
	v_cvt_pk_bf16_f32 v125, v125, v127
	v_cvt_pk_bf16_f32 v124, v124, v126
	v_cvt_pk_bf16_f32 v127, v79, v17
	v_cvt_pk_bf16_f32 v126, v78, v16
	v_pk_fma_f32 v[78:79], v[26:27], v[84:85], v[54:55]
	v_pk_fma_f32 v[78:79], v[30:31], v[92:93], v[78:79]
	v_mad_i64_i32 v[16:17], s[2:3], v123, s21, v[98:99]
	v_pk_fma_f32 v[78:79], v[34:35], v[102:103], v[78:79]
	global_store_dwordx4 v[16:17], v[124:127], off
	v_pk_fma_f32 v[16:17], v[100:101], v[88:89], v[4:5]
	v_pk_fma_f32 v[78:79], v[42:43], v[76:77], v[78:79]
	v_and_b32_e32 v89, 0xffff0000, v73
	v_and_b32_e32 v88, 0xffff0000, v72
	v_lshlrev_b32_e32 v85, 16, v73
	v_lshlrev_b32_e32 v84, 16, v72
	v_pk_fma_f32 v[72:73], v[38:39], v[88:89], v[78:79]
	v_pk_fma_f32 v[16:17], v[52:53], v[108:109], v[16:17]
	v_mul_f32_e32 v79, 0xbfb8aa3b, v72
	v_exp_f32_e32 v79, v79
	v_pk_fma_f32 v[16:17], v[28:29], v[94:95], v[16:17]
	v_add_f32_e32 v79, 1.0, v79
	v_pk_fma_f32 v[16:17], v[32:33], v[80:81], v[16:17]
	v_rcp_f32_e32 v124, v79
	v_pk_fma_f32 v[16:17], v[40:41], v[84:85], v[16:17]
	s_nop 0
	v_mul_f32_e32 v78, 0xbfb8aa3b, v16
	v_mul_f32_e32 v79, 0xbfb8aa3b, v17
	v_exp_f32_e32 v78, v78
	v_exp_f32_e32 v79, v79
	v_add_f32_e32 v78, 1.0, v78
	v_add_f32_e32 v79, 1.0, v79
	v_rcp_f32_e32 v78, v78
	v_rcp_f32_e32 v79, v79
	s_nop 0
	v_pk_mul_f32 v[16:17], v[16:17], v[78:79]
	v_mul_f32_e32 v78, 0xbfb8aa3b, v73
	v_exp_f32_e32 v78, v78
	s_nop 0
	v_add_f32_e32 v78, 1.0, v78
	v_rcp_f32_e32 v125, v78
	v_pk_fma_f32 v[78:79], v[24:25], v[90:91], v[36:37]
	v_pk_fma_f32 v[90:91], v[6:7], v[114:115], v[46:47]
	v_pk_fma_f32 v[78:79], v[44:45], v[106:107], v[78:79]
	v_pk_fma_f32 v[90:91], v[10:11], v[104:105], v[90:91]
	v_pk_fma_f32 v[78:79], v[8:9], v[110:111], v[78:79]
	v_pk_fma_f32 v[90:91], v[14:15], v[112:113], v[90:91]
	v_pk_fma_f32 v[114:115], v[12:13], v[82:83], v[78:79]
	v_lshlrev_b32_e32 v79, 16, v75
	v_lshlrev_b32_e32 v78, 16, v74
	v_pk_fma_f32 v[114:115], v[20:21], v[78:79], v[114:115]
	v_pk_mul_f32 v[72:73], v[72:73], v[124:125]
	v_mul_f32_e32 v123, 0xbfb8aa3b, v114
	v_exp_f32_e32 v123, v123
	v_pk_fma_f32 v[124:125], v[22:23], v[86:87], v[90:91]
	v_and_b32_e32 v91, 0xffff0000, v75
	v_and_b32_e32 v90, 0xffff0000, v74
	v_pk_fma_f32 v[74:75], v[18:19], v[90:91], v[124:125]
	v_add_f32_e32 v123, 1.0, v123
	v_rcp_f32_e32 v124, v123
	v_mul_f32_e32 v123, 0xbfb8aa3b, v74
	v_exp_f32_e32 v123, v123
	v_pk_fma_f32 v[104:105], v[6:7], v[104:105], v[46:47]
	v_add_f32_e32 v123, 1.0, v123
	v_rcp_f32_e32 v126, v123
	v_mul_f32_e32 v123, 0xbfb8aa3b, v115
	v_exp_f32_e32 v123, v123
	v_pk_fma_f32 v[104:105], v[10:11], v[112:113], v[104:105]
	v_add_f32_e32 v123, 1.0, v123
	v_rcp_f32_e32 v125, v123
	v_mul_f32_e32 v123, 0xbfb8aa3b, v75
	v_exp_f32_e32 v123, v123
	v_pk_fma_f32 v[104:105], v[14:15], v[86:87], v[104:105]
	v_pk_mul_f32 v[114:115], v[114:115], v[124:125]
	v_add_f32_e32 v123, 1.0, v123
	v_rcp_f32_e32 v127, v123
	s_nop 0
	v_pk_mul_f32 v[74:75], v[74:75], v[126:127]
	v_cvt_pk_bf16_f32 v75, v115, v75
	v_cvt_pk_bf16_f32 v74, v114, v74
	v_cvt_pk_bf16_f32 v73, v17, v73
	v_cvt_pk_bf16_f32 v72, v16, v72
	v_mad_i64_i32 v[16:17], s[2:3], v122, s21, v[98:99]
	global_store_dwordx4 v[16:17], v[72:75], off
	v_pk_fma_f32 v[16:17], v[100:101], v[108:109], v[4:5]
	v_pk_fma_f32 v[104:105], v[22:23], v[90:91], v[104:105]
	v_pk_fma_f32 v[72:73], v[26:27], v[92:93], v[54:55]
	v_and_b32_e32 v93, 0xffff0000, v69
	v_pk_fma_f32 v[72:73], v[30:31], v[102:103], v[72:73]
	v_and_b32_e32 v92, 0xffff0000, v68
	v_pk_fma_f32 v[72:73], v[34:35], v[76:77], v[72:73]
	v_lshlrev_b32_e32 v75, 16, v69
	v_pk_fma_f32 v[72:73], v[42:43], v[88:89], v[72:73]
	v_lshlrev_b32_e32 v74, 16, v68
	v_pk_fma_f32 v[68:69], v[38:39], v[92:93], v[72:73]
	v_pk_fma_f32 v[16:17], v[52:53], v[94:95], v[16:17]
	v_mul_f32_e32 v73, 0xbfb8aa3b, v68
	v_exp_f32_e32 v73, v73
	v_pk_fma_f32 v[16:17], v[28:29], v[80:81], v[16:17]
	v_add_f32_e32 v73, 1.0, v73
	v_pk_fma_f32 v[16:17], v[32:33], v[84:85], v[16:17]
	v_rcp_f32_e32 v108, v73
	v_pk_fma_f32 v[16:17], v[40:41], v[74:75], v[16:17]
	s_nop 0
	v_mul_f32_e32 v72, 0xbfb8aa3b, v16
	v_mul_f32_e32 v73, 0xbfb8aa3b, v17
	v_exp_f32_e32 v72, v72
	v_exp_f32_e32 v73, v73
	v_add_f32_e32 v72, 1.0, v72
	v_add_f32_e32 v73, 1.0, v73
	v_rcp_f32_e32 v72, v72
	v_rcp_f32_e32 v73, v73
	s_nop 0
	v_pk_mul_f32 v[16:17], v[16:17], v[72:73]
	v_mul_f32_e32 v72, 0xbfb8aa3b, v69
	v_exp_f32_e32 v72, v72
	s_nop 0
	v_add_f32_e32 v72, 1.0, v72
	v_rcp_f32_e32 v109, v72
	v_pk_fma_f32 v[72:73], v[24:25], v[106:107], v[36:37]
	v_pk_mul_f32 v[68:69], v[68:69], v[108:109]
	v_pk_fma_f32 v[72:73], v[44:45], v[110:111], v[72:73]
	s_nop 0
	v_pk_fma_f32 v[72:73], v[8:9], v[82:83], v[72:73]
	s_nop 0
	v_pk_fma_f32 v[106:107], v[12:13], v[78:79], v[72:73]
	v_lshlrev_b32_e32 v73, 16, v71
	v_lshlrev_b32_e32 v72, 16, v70
	v_and_b32_e32 v71, 0xffff0000, v71
	v_and_b32_e32 v70, 0xffff0000, v70
	v_pk_fma_f32 v[104:105], v[18:19], v[70:71], v[104:105]
	v_pk_fma_f32 v[106:107], v[20:21], v[72:73], v[106:107]
	v_mul_f32_e32 v109, 0xbfb8aa3b, v104
	v_exp_f32_e32 v109, v109
	v_mul_f32_e32 v108, 0xbfb8aa3b, v106
	v_exp_f32_e32 v108, v108
	v_add_f32_e32 v109, 1.0, v109
	v_rcp_f32_e32 v114, v109
	v_mul_f32_e32 v109, 0xbfb8aa3b, v107
	v_exp_f32_e32 v109, v109
	v_add_f32_e32 v108, 1.0, v108
	v_rcp_f32_e32 v108, v108
	v_add_f32_e32 v109, 1.0, v109
	v_rcp_f32_e32 v109, v109
	s_nop 0
	v_pk_mul_f32 v[106:107], v[106:107], v[108:109]
	v_mul_f32_e32 v108, 0xbfb8aa3b, v105
	v_exp_f32_e32 v108, v108
	s_nop 0
	v_add_f32_e32 v108, 1.0, v108
	v_rcp_f32_e32 v115, v108
	s_nop 0
	v_pk_mul_f32 v[104:105], v[104:105], v[114:115]
	s_nop 0
	v_cvt_pk_bf16_f32 v107, v107, v105
	v_cvt_pk_bf16_f32 v106, v106, v104
	v_cvt_pk_bf16_f32 v105, v17, v69
	v_cvt_pk_bf16_f32 v104, v16, v68
	v_pk_fma_f32 v[68:69], v[26:27], v[102:103], v[54:55]
	v_mad_i64_i32 v[16:17], s[2:3], v121, s21, v[98:99]
	v_pk_fma_f32 v[68:69], v[30:31], v[76:77], v[68:69]
	global_store_dwordx4 v[16:17], v[104:107], off
	v_pk_fma_f32 v[68:69], v[34:35], v[88:89], v[68:69]
	v_pk_fma_f32 v[16:17], v[100:101], v[94:95], v[4:5]
	v_pk_fma_f32 v[94:95], v[42:43], v[92:93], v[68:69]
	v_lshlrev_b32_e32 v69, 16, v65
	v_lshlrev_b32_e32 v68, 16, v64
	v_and_b32_e32 v65, 0xffff0000, v65
	v_and_b32_e32 v64, 0xffff0000, v64
	v_pk_fma_f32 v[94:95], v[38:39], v[64:65], v[94:95]
	v_pk_fma_f32 v[16:17], v[52:53], v[80:81], v[16:17]
	v_mul_f32_e32 v103, 0xbfb8aa3b, v94
	v_exp_f32_e32 v103, v103
	v_pk_fma_f32 v[16:17], v[28:29], v[84:85], v[16:17]
	v_pk_fma_f32 v[80:81], v[100:101], v[80:81], v[4:5]
	v_pk_fma_f32 v[16:17], v[32:33], v[74:75], v[16:17]
	v_add_f32_e32 v103, 1.0, v103
	v_pk_fma_f32 v[16:17], v[40:41], v[68:69], v[16:17]
	v_rcp_f32_e32 v104, v103
	v_mul_f32_e32 v102, 0xbfb8aa3b, v16
	v_mul_f32_e32 v103, 0xbfb8aa3b, v17
	v_exp_f32_e32 v102, v102
	v_exp_f32_e32 v103, v103
	v_pk_fma_f32 v[76:77], v[26:27], v[76:77], v[54:55]
	v_pk_fma_f32 v[80:81], v[52:53], v[84:85], v[80:81]
	v_add_f32_e32 v102, 1.0, v102
	v_add_f32_e32 v103, 1.0, v103
	v_rcp_f32_e32 v102, v102
	v_rcp_f32_e32 v103, v103
	v_pk_fma_f32 v[76:77], v[30:31], v[88:89], v[76:77]
	v_pk_fma_f32 v[80:81], v[28:29], v[74:75], v[80:81]
	v_pk_fma_f32 v[76:77], v[34:35], v[92:93], v[76:77]
	v_pk_mul_f32 v[102:103], v[16:17], v[102:103]
	v_mul_f32_e32 v16, 0xbfb8aa3b, v95
	v_exp_f32_e32 v16, v16
	v_pk_fma_f32 v[80:81], v[32:33], v[68:69], v[80:81]
	v_add_f32_e32 v16, 1.0, v16
	v_rcp_f32_e32 v105, v16
	v_pk_fma_f32 v[16:17], v[24:25], v[110:111], v[36:37]
	v_pk_mul_f32 v[94:95], v[94:95], v[104:105]
	v_pk_fma_f32 v[104:105], v[6:7], v[112:113], v[46:47]
	v_pk_fma_f32 v[16:17], v[44:45], v[82:83], v[16:17]
	v_pk_fma_f32 v[104:105], v[10:11], v[86:87], v[104:105]
	v_pk_fma_f32 v[16:17], v[8:9], v[78:79], v[16:17]
	v_pk_fma_f32 v[104:105], v[14:15], v[90:91], v[104:105]
	v_pk_fma_f32 v[106:107], v[12:13], v[72:73], v[16:17]
	v_pk_fma_f32 v[104:105], v[22:23], v[70:71], v[104:105]
	v_lshlrev_b32_e32 v17, 16, v67
	v_lshlrev_b32_e32 v16, 16, v66
	v_and_b32_e32 v67, 0xffff0000, v67
	v_and_b32_e32 v66, 0xffff0000, v66
	v_pk_fma_f32 v[104:105], v[18:19], v[66:67], v[104:105]
	v_pk_fma_f32 v[106:107], v[20:21], v[16:17], v[106:107]
	v_mul_f32_e32 v109, 0xbfb8aa3b, v104
	v_exp_f32_e32 v109, v109
	v_mul_f32_e32 v108, 0xbfb8aa3b, v106
	v_exp_f32_e32 v108, v108
	v_add_f32_e32 v109, 1.0, v109
	v_rcp_f32_e32 v110, v109
	v_mul_f32_e32 v109, 0xbfb8aa3b, v107
	v_exp_f32_e32 v109, v109
	v_add_f32_e32 v108, 1.0, v108
	v_rcp_f32_e32 v108, v108
	v_add_f32_e32 v109, 1.0, v109
	v_rcp_f32_e32 v109, v109
	s_nop 0
	v_pk_mul_f32 v[106:107], v[106:107], v[108:109]
	v_mul_f32_e32 v108, 0xbfb8aa3b, v105
	v_exp_f32_e32 v108, v108
	s_nop 0
	v_add_f32_e32 v108, 1.0, v108
	v_rcp_f32_e32 v111, v108
	s_nop 0
	v_pk_mul_f32 v[104:105], v[104:105], v[110:111]
	s_nop 0
	v_cvt_pk_bf16_f32 v105, v107, v105
	v_cvt_pk_bf16_f32 v104, v106, v104
	v_cvt_pk_bf16_f32 v103, v103, v95
	v_cvt_pk_bf16_f32 v102, v102, v94
	v_mad_i64_i32 v[94:95], s[2:3], v120, s21, v[98:99]
	global_store_dwordx4 v[94:95], v[102:105], off
	v_pk_fma_f32 v[94:95], v[42:43], v[64:65], v[76:77]
	v_lshlrev_b32_e32 v77, 16, v61
	v_lshlrev_b32_e32 v76, 16, v60
	v_pk_fma_f32 v[102:103], v[40:41], v[76:77], v[80:81]
	v_and_b32_e32 v81, 0xffff0000, v61
	v_and_b32_e32 v80, 0xffff0000, v60
	v_pk_fma_f32 v[60:61], v[38:39], v[80:81], v[94:95]
	v_mul_f32_e32 v94, 0xbfb8aa3b, v102
	v_mul_f32_e32 v95, 0xbfb8aa3b, v60
	v_exp_f32_e32 v95, v95
	v_exp_f32_e32 v94, v94
	v_add_f32_e32 v95, 1.0, v95
	v_rcp_f32_e32 v104, v95
	v_mul_f32_e32 v95, 0xbfb8aa3b, v103
	v_exp_f32_e32 v95, v95
	v_add_f32_e32 v94, 1.0, v94
	v_rcp_f32_e32 v94, v94
	v_add_f32_e32 v95, 1.0, v95
	v_rcp_f32_e32 v95, v95
	s_nop 0
	v_pk_mul_f32 v[94:95], v[102:103], v[94:95]
	v_mul_f32_e32 v102, 0xbfb8aa3b, v61
	v_exp_f32_e32 v102, v102
	s_nop 0
	v_add_f32_e32 v102, 1.0, v102
	v_rcp_f32_e32 v105, v102
	s_nop 0
	v_pk_mul_f32 v[102:103], v[60:61], v[104:105]
	v_pk_fma_f32 v[60:61], v[24:25], v[82:83], v[36:37]
	v_pk_fma_f32 v[82:83], v[6:7], v[86:87], v[46:47]
	v_pk_fma_f32 v[60:61], v[44:45], v[78:79], v[60:61]
	v_pk_fma_f32 v[82:83], v[10:11], v[90:91], v[82:83]
	v_pk_fma_f32 v[60:61], v[8:9], v[72:73], v[60:61]
	v_pk_fma_f32 v[82:83], v[14:15], v[70:71], v[82:83]
	v_pk_fma_f32 v[86:87], v[12:13], v[16:17], v[60:61]
	v_pk_fma_f32 v[82:83], v[22:23], v[66:67], v[82:83]
	v_lshlrev_b32_e32 v61, 16, v63
	v_lshlrev_b32_e32 v60, 16, v62
	v_and_b32_e32 v63, 0xffff0000, v63
	v_and_b32_e32 v62, 0xffff0000, v62
	v_pk_fma_f32 v[82:83], v[18:19], v[62:63], v[82:83]
	v_pk_fma_f32 v[86:87], v[20:21], v[60:61], v[86:87]
	v_mul_f32_e32 v105, 0xbfb8aa3b, v82
	v_exp_f32_e32 v105, v105
	v_mul_f32_e32 v104, 0xbfb8aa3b, v86
	v_exp_f32_e32 v104, v104
	v_add_f32_e32 v105, 1.0, v105
	v_rcp_f32_e32 v106, v105
	v_mul_f32_e32 v105, 0xbfb8aa3b, v87
	v_exp_f32_e32 v105, v105
	v_add_f32_e32 v104, 1.0, v104
	v_rcp_f32_e32 v104, v104
	v_add_f32_e32 v105, 1.0, v105
	v_rcp_f32_e32 v105, v105
	s_nop 0
	v_pk_mul_f32 v[86:87], v[86:87], v[104:105]
	v_mul_f32_e32 v104, 0xbfb8aa3b, v83
	v_exp_f32_e32 v104, v104
	s_nop 0
	v_add_f32_e32 v104, 1.0, v104
	v_rcp_f32_e32 v107, v104
	s_nop 0
	v_pk_mul_f32 v[82:83], v[82:83], v[106:107]
	s_nop 0
	v_cvt_pk_bf16_f32 v105, v87, v83
	v_cvt_pk_bf16_f32 v104, v86, v82
	v_cvt_pk_bf16_f32 v103, v95, v103
	v_cvt_pk_bf16_f32 v102, v94, v102
	v_mad_i64_i32 v[82:83], s[2:3], v119, s21, v[98:99]
	global_store_dwordx4 v[82:83], v[102:105], off
	v_pk_fma_f32 v[82:83], v[100:101], v[84:85], v[4:5]
	v_pk_fma_f32 v[84:85], v[26:27], v[88:89], v[54:55]
	v_pk_fma_f32 v[82:83], v[52:53], v[74:75], v[82:83]
	v_pk_fma_f32 v[84:85], v[30:31], v[92:93], v[84:85]
	v_pk_fma_f32 v[82:83], v[28:29], v[68:69], v[82:83]
	v_pk_fma_f32 v[84:85], v[34:35], v[64:65], v[84:85]
	v_pk_fma_f32 v[86:87], v[32:33], v[76:77], v[82:83]
	v_pk_fma_f32 v[88:89], v[42:43], v[80:81], v[84:85]
	v_and_b32_e32 v85, 0xffff0000, v57
	v_and_b32_e32 v84, 0xffff0000, v56
	v_lshlrev_b32_e32 v83, 16, v57
	v_lshlrev_b32_e32 v82, 16, v56
	v_pk_fma_f32 v[56:57], v[38:39], v[84:85], v[88:89]
	v_pk_fma_f32 v[86:87], v[40:41], v[82:83], v[86:87]
	v_mul_f32_e32 v89, 0xbfb8aa3b, v56
	v_exp_f32_e32 v89, v89
	v_mul_f32_e32 v88, 0xbfb8aa3b, v86
	v_exp_f32_e32 v88, v88
	v_pk_fma_f32 v[74:75], v[100:101], v[74:75], v[4:5]
	v_add_f32_e32 v89, 1.0, v89
	v_rcp_f32_e32 v94, v89
	v_mul_f32_e32 v89, 0xbfb8aa3b, v87
	v_exp_f32_e32 v89, v89
	v_add_f32_e32 v88, 1.0, v88
	v_rcp_f32_e32 v88, v88
	v_pk_fma_f32 v[74:75], v[52:53], v[68:69], v[74:75]
	v_add_f32_e32 v89, 1.0, v89
	v_rcp_f32_e32 v89, v89
	v_pk_fma_f32 v[74:75], v[28:29], v[76:77], v[74:75]
	v_pk_fma_f32 v[4:5], v[100:101], v[68:69], v[4:5]
	v_pk_fma_f32 v[74:75], v[32:33], v[82:83], v[74:75]
	v_pk_mul_f32 v[86:87], v[86:87], v[88:89]
	v_mul_f32_e32 v88, 0xbfb8aa3b, v57
	v_exp_f32_e32 v88, v88
	v_pk_fma_f32 v[4:5], v[52:53], v[76:77], v[4:5]
	v_add_f32_e32 v88, 1.0, v88
	v_rcp_f32_e32 v95, v88
	v_pk_fma_f32 v[4:5], v[28:29], v[82:83], v[4:5]
	v_lshlrev_b32_e32 v29, 16, v1
	v_lshlrev_b32_e32 v28, 16, v0
	v_pk_mul_f32 v[88:89], v[56:57], v[94:95]
	v_pk_fma_f32 v[56:57], v[24:25], v[78:79], v[36:37]
	v_pk_fma_f32 v[78:79], v[6:7], v[90:91], v[46:47]
	v_pk_fma_f32 v[56:57], v[44:45], v[72:73], v[56:57]
	v_pk_fma_f32 v[78:79], v[10:11], v[70:71], v[78:79]
	v_pk_fma_f32 v[56:57], v[8:9], v[16:17], v[56:57]
	v_pk_fma_f32 v[78:79], v[14:15], v[66:67], v[78:79]
	v_pk_fma_f32 v[90:91], v[12:13], v[60:61], v[56:57]
	v_pk_fma_f32 v[78:79], v[22:23], v[62:63], v[78:79]
	v_lshlrev_b32_e32 v57, 16, v59
	v_lshlrev_b32_e32 v56, 16, v58
	v_and_b32_e32 v59, 0xffff0000, v59
	v_and_b32_e32 v58, 0xffff0000, v58
	v_pk_fma_f32 v[78:79], v[18:19], v[58:59], v[78:79]
	v_pk_fma_f32 v[90:91], v[20:21], v[56:57], v[90:91]
	v_mul_f32_e32 v95, 0xbfb8aa3b, v78
	v_exp_f32_e32 v95, v95
	v_mul_f32_e32 v94, 0xbfb8aa3b, v90
	v_exp_f32_e32 v94, v94
	v_pk_fma_f32 v[70:71], v[6:7], v[70:71], v[46:47]
	v_add_f32_e32 v95, 1.0, v95
	v_rcp_f32_e32 v102, v95
	v_mul_f32_e32 v95, 0xbfb8aa3b, v91
	v_exp_f32_e32 v95, v95
	v_add_f32_e32 v94, 1.0, v94
	v_rcp_f32_e32 v94, v94
	v_pk_fma_f32 v[6:7], v[6:7], v[66:67], v[46:47]
	v_add_f32_e32 v95, 1.0, v95
	v_rcp_f32_e32 v95, v95
	v_pk_fma_f32 v[6:7], v[10:11], v[62:63], v[6:7]
	v_pk_fma_f32 v[70:71], v[10:11], v[66:67], v[70:71]
	v_pk_fma_f32 v[6:7], v[14:15], v[58:59], v[6:7]
	v_pk_mul_f32 v[90:91], v[90:91], v[94:95]
	v_mul_f32_e32 v94, 0xbfb8aa3b, v79
	v_exp_f32_e32 v94, v94
	v_pk_fma_f32 v[70:71], v[14:15], v[62:63], v[70:71]
	v_lshlrev_b32_e32 v11, 16, v3
	v_lshlrev_b32_e32 v10, 16, v2
	v_add_f32_e32 v94, 1.0, v94
	v_rcp_f32_e32 v103, v94
	v_and_b32_e32 v3, 0xffff0000, v3
	v_and_b32_e32 v2, 0xffff0000, v2
	v_pk_fma_f32 v[70:71], v[22:23], v[58:59], v[70:71]
	v_pk_mul_f32 v[78:79], v[78:79], v[102:103]
	v_cvt_pk_bf16_f32 v87, v87, v89
	v_cvt_pk_bf16_f32 v86, v86, v88
	v_cvt_pk_bf16_f32 v89, v91, v79
	v_cvt_pk_bf16_f32 v88, v90, v78
	v_mad_i64_i32 v[78:79], s[2:3], v118, s21, v[98:99]
	global_store_dwordx4 v[78:79], v[86:89], off
	v_pk_fma_f32 v[78:79], v[26:27], v[92:93], v[54:55]
	v_pk_fma_f32 v[26:27], v[26:27], v[64:65], v[54:55]
	v_pk_fma_f32 v[78:79], v[30:31], v[64:65], v[78:79]
	v_and_b32_e32 v89, 0xffff0000, v49
	v_pk_fma_f32 v[78:79], v[34:35], v[80:81], v[78:79]
	v_and_b32_e32 v88, 0xffff0000, v48
	v_pk_fma_f32 v[78:79], v[42:43], v[84:85], v[78:79]
	v_lshlrev_b32_e32 v87, 16, v49
	v_lshlrev_b32_e32 v86, 16, v48
	v_pk_fma_f32 v[48:49], v[38:39], v[88:89], v[78:79]
	v_pk_fma_f32 v[74:75], v[40:41], v[86:87], v[74:75]
	v_mul_f32_e32 v79, 0xbfb8aa3b, v48
	v_exp_f32_e32 v79, v79
	v_mul_f32_e32 v78, 0xbfb8aa3b, v74
	v_exp_f32_e32 v78, v78
	v_pk_fma_f32 v[26:27], v[30:31], v[80:81], v[26:27]
	v_add_f32_e32 v79, 1.0, v79
	v_rcp_f32_e32 v90, v79
	v_mul_f32_e32 v79, 0xbfb8aa3b, v75
	v_exp_f32_e32 v79, v79
	v_add_f32_e32 v78, 1.0, v78
	v_rcp_f32_e32 v78, v78
	v_pk_fma_f32 v[26:27], v[34:35], v[84:85], v[26:27]
	v_add_f32_e32 v79, 1.0, v79
	v_rcp_f32_e32 v79, v79
	v_pk_fma_f32 v[72:73], v[24:25], v[72:73], v[36:37]
	v_pk_fma_f32 v[26:27], v[42:43], v[88:89], v[26:27]
	v_and_b32_e32 v1, 0xffff0000, v1
	v_pk_mul_f32 v[74:75], v[74:75], v[78:79]
	v_mul_f32_e32 v78, 0xbfb8aa3b, v49
	v_exp_f32_e32 v78, v78
	v_lshlrev_b32_e32 v79, 16, v51
	v_and_b32_e32 v0, 0xffff0000, v0
	v_pk_fma_f32 v[72:73], v[44:45], v[16:17], v[72:73]
	v_add_f32_e32 v78, 1.0, v78
	v_rcp_f32_e32 v91, v78
	v_lshlrev_b32_e32 v78, 16, v50
	v_pk_fma_f32 v[0:1], v[38:39], v[0:1], v[26:27]
	v_pk_fma_f32 v[16:17], v[24:25], v[16:17], v[36:37]
	v_pk_mul_f32 v[48:49], v[48:49], v[90:91]
	v_and_b32_e32 v91, 0xffff0000, v51
	v_and_b32_e32 v90, 0xffff0000, v50
	v_pk_fma_f32 v[6:7], v[22:23], v[90:91], v[6:7]
	v_pk_fma_f32 v[50:51], v[18:19], v[90:91], v[70:71]
	v_pk_fma_f32 v[2:3], v[18:19], v[2:3], v[6:7]
	v_mul_f32_e32 v71, 0xbfb8aa3b, v50
	v_mul_f32_e32 v7, 0xbfb8aa3b, v2
	v_exp_f32_e32 v7, v7
	v_exp_f32_e32 v71, v71
	v_mul_f32_e32 v27, 0xbfb8aa3b, v0
	v_pk_fma_f32 v[16:17], v[44:45], v[60:61], v[16:17]
	v_pk_fma_f32 v[72:73], v[8:9], v[60:61], v[72:73]
	v_exp_f32_e32 v27, v27
	v_pk_fma_f32 v[8:9], v[8:9], v[56:57], v[16:17]
	v_pk_fma_f32 v[72:73], v[12:13], v[56:57], v[72:73]
	v_pk_fma_f32 v[8:9], v[12:13], v[78:79], v[8:9]
	v_add_f32_e32 v7, 1.0, v7
	v_pk_fma_f32 v[8:9], v[20:21], v[10:11], v[8:9]
	v_pk_fma_f32 v[72:73], v[20:21], v[78:79], v[72:73]
	v_add_f32_e32 v71, 1.0, v71
	v_pk_fma_f32 v[4:5], v[32:33], v[86:87], v[4:5]
	v_mul_f32_e32 v6, 0xbfb8aa3b, v8
	v_rcp_f32_e32 v10, v7
	v_mul_f32_e32 v7, 0xbfb8aa3b, v9
	v_mul_f32_e32 v70, 0xbfb8aa3b, v72
	v_rcp_f32_e32 v92, v71
	v_mul_f32_e32 v71, 0xbfb8aa3b, v73
	v_pk_fma_f32 v[4:5], v[40:41], v[28:29], v[4:5]
	v_add_f32_e32 v27, 1.0, v27
	v_exp_f32_e32 v6, v6
	v_exp_f32_e32 v7, v7
	v_exp_f32_e32 v70, v70
	v_exp_f32_e32 v71, v71
	v_mul_f32_e32 v26, 0xbfb8aa3b, v4
	v_rcp_f32_e32 v28, v27
	v_mul_f32_e32 v27, 0xbfb8aa3b, v5
	v_exp_f32_e32 v26, v26
	v_exp_f32_e32 v27, v27
	v_add_f32_e32 v6, 1.0, v6
	v_add_f32_e32 v7, 1.0, v7
	v_add_f32_e32 v70, 1.0, v70
	v_add_f32_e32 v71, 1.0, v71
	v_rcp_f32_e32 v6, v6
	v_rcp_f32_e32 v7, v7
	v_rcp_f32_e32 v70, v70
	v_rcp_f32_e32 v71, v71
	v_add_f32_e32 v26, 1.0, v26
	v_add_f32_e32 v27, 1.0, v27
	v_rcp_f32_e32 v26, v26
	v_rcp_f32_e32 v27, v27
	v_pk_mul_f32 v[6:7], v[8:9], v[6:7]
	v_mul_f32_e32 v8, 0xbfb8aa3b, v3
	v_pk_mul_f32 v[70:71], v[72:73], v[70:71]
	v_mul_f32_e32 v72, 0xbfb8aa3b, v51
	v_exp_f32_e32 v8, v8
	v_exp_f32_e32 v72, v72
	v_pk_mul_f32 v[4:5], v[4:5], v[26:27]
	v_mul_f32_e32 v26, 0xbfb8aa3b, v1
	v_exp_f32_e32 v26, v26
	v_add_f32_e32 v8, 1.0, v8
	v_add_f32_e32 v72, 1.0, v72
	v_rcp_f32_e32 v11, v8
	v_rcp_f32_e32 v93, v72
	v_add_f32_e32 v26, 1.0, v26
	v_rcp_f32_e32 v29, v26
	v_pk_mul_f32 v[2:3], v[2:3], v[10:11]
	v_pk_mul_f32 v[50:51], v[50:51], v[92:93]
	v_pk_mul_f32 v[0:1], v[0:1], v[28:29]
	v_cvt_pk_bf16_f32 v51, v71, v51
	v_cvt_pk_bf16_f32 v50, v70, v50
	v_mad_i64_i32 v[70:71], s[2:3], v117, s21, v[98:99]
	v_cvt_pk_bf16_f32 v1, v5, v1
	v_cvt_pk_bf16_f32 v0, v4, v0
	v_mad_i64_i32 v[4:5], s[2:3], v116, s21, v[98:99]
	s_mov_b32 s2, 0xbffff
	s_nop 0
	v_cmp_lt_i32_e32 vcc, s2, v97
	v_cvt_pk_bf16_f32 v49, v75, v49
	v_cvt_pk_bf16_f32 v48, v74, v48
	v_cvt_pk_bf16_f32 v3, v7, v3
	v_cvt_pk_bf16_f32 v2, v6, v2
	s_or_b64 s[40:41], vcc, s[40:41]
	global_store_dwordx4 v[70:71], v[48:51], off
	global_store_dwordx4 v[4:5], v[0:3], off
	s_andn2_b64 exec, exec, s[40:41]
	s_cbranch_execz .LBB0_1813
